# baseline (speedup 1.0000x reference)
; #define STA(P, br, kt) STAGE(P, A, aoff0, aoff1, lda, br, kt)
; #define STB(P, br, kt) STAGE(P, Bt, boff0, boff1, ldb, br, kt)
; #define LDA(dst, b, h) _Pragma("unroll") for (int m = 0; m < 4; ++m) _Pragma("unroll") for (int k = 0; k < 2; ++k) \
;     dst[m][k] = *reinterpret_cast<const bf16x8*>((char*)SA(b, h) + lds_byte(wr * 64 + m * 16 + fr, k * 32 + fq * 8))
; #define LDB(dst, b, h) _Pragma("unroll") for (int n = 0; n < 2; ++n) _Pragma("unroll") for (int k = 0; k < 2; ++k) \
;     dst[n][k] = *reinterpret_cast<const bf16x8*>((char*)SB(b, h) + lds_byte(wc * 32 + n * 16 + fr, k * 32 + fq * 8))
; #define MMA(ai, bj, At, Bq) do { __builtin_amdgcn_s_setprio(1); \
;     _Pragma("unroll") for (int m = 0; m < 4; ++m) _Pragma("unroll") for (int n = 0; n < 2; ++n) _Pragma("unroll") for (int k = 0; k < 2; ++k) \
;       acc[ai][bj][m][n] = __builtin_amdgcn_mfma_f32_16x16x32_bf16(At[m][k], Bq[n][k], acc[ai][bj][m][n], 0, 0, 0); \
;     __builtin_amdgcn_s_setprio(0); } while (0)
; #define WAIT_V(n) asm volatile("s_waitcnt vmcnt(" #n ")" ::: "memory")
; #define WAIT_L(n) asm volatile("s_waitcnt lgkmcnt(" #n ")" ::: "memory")
; #define BAR __builtin_amdgcn_s_barrier()
; #define SCHED __builtin_amdgcn_sched_barrier(0)
; __device__ __forceinline__ void gemm256(const u16* __restrict__ A, int lda, const u16* __restrict__ Bt, int ldb, int K,
;                                         f32x4 (&acc)[2][2][4][2], const int g_wid) {
;     ...
;   for (int t = 0; t < nt - 2; t += 2) {
;     LDB(B0, 0, 0); SCHED; LDA(At, 0, 0); STA(SA(1, 1), HALF, t + 1);
;     WAIT_L(8); BAR; WAIT_L(0); MMA(0, 0, At, B0); BAR; SCHED;
;     LDB(B1, 0, 1); STB(SB(0, 0), 0, t + 2);
;     BAR; WAIT_L(0); MMA(0, 1, At, B1); BAR;
;     LDA(At, 0, 1); STA(SA(0, 0), 0, t + 2);
;     BAR; WAIT_L(0); MMA(1, 0, At, B0); BAR; SCHED;
;     STB(SB(0, 1), HALF, t + 2);
;     WAIT_V(6); BAR; MMA(1, 1, At, B1); BAR;
;     LDB(B0, 1, 0); SCHED; LDA(At, 1, 0); STA(SA(0, 1), HALF, t + 2);
;     WAIT_L(8); BAR; WAIT_L(0); MMA(0, 0, At, B0); BAR; SCHED;
;     LDB(B1, 1, 1); STB(SB(1, 0), 0, t + 3);
;     BAR; WAIT_L(0); MMA(0, 1, At, B1); BAR;
;     LDA(At, 1, 1); STA(SA(1, 0), 0, t + 3);
;     BAR; WAIT_L(0); MMA(1, 0, At, B0); BAR; SCHED;
;     STB(SB(1, 1), HALF, t + 3);
;     WAIT_V(6); BAR; MMA(1, 1, At, B1); BAR;
;   }
.LBB0_109:
	ds_read_b128 v[180:183], v177
	ds_read_b128 v[184:187], v177 offset:1024
	ds_read_b128 v[188:191], v177 offset:2048
	ds_read_b128 v[192:195], v177 offset:3072
	v_add_u32_e32 v178, 0xc000, v163
	v_lshl_add_u64 v[244:245], v[142:143], 0, s[36:37]
	v_readfirstlane_b32 s10, v178
	v_add_u32_e32 v179, 0xe000, v163
	v_lshl_add_u64 v[228:229], v[244:245], 0, s[72:73]
	s_mov_b32 m0, s10
	v_lshl_add_u64 v[246:247], v[138:139], 0, s[36:37]
	ds_read_b128 v[196:199], v159
	ds_read_b128 v[200:203], v159 offset:1024
	ds_read_b128 v[204:207], v147
	ds_read_b128 v[208:211], v147 offset:1024
	ds_read_b128 v[212:215], v146
	ds_read_b128 v[216:219], v146 offset:1024
	ds_read_b128 v[220:223], v145
	ds_read_b128 v[224:227], v145 offset:1024
	global_load_lds_dwordx4 v[228:229], off
	s_add_u32 m0, m0, 0x2000
	v_lshl_add_u64 v[228:229], v[246:247], 0, s[72:73]
	global_load_lds_dwordx4 v[228:229], off
	s_waitcnt lgkmcnt(8)
	s_barrier
	s_waitcnt lgkmcnt(0)
	v_mfma_f32_16x16x32_bf16 v[126:129], v[196:199], v[180:183], v[126:129]
	v_mfma_f32_16x16x32_bf16 v[122:125], v[196:199], v[188:191], v[122:125]
	v_mfma_f32_16x16x32_bf16 v[118:121], v[204:207], v[180:183], v[118:121]
	v_mfma_f32_16x16x32_bf16 v[114:117], v[204:207], v[188:191], v[114:117]
	v_mfma_f32_16x16x32_bf16 v[110:113], v[212:215], v[180:183], v[110:113]
	v_mfma_f32_16x16x32_bf16 v[106:109], v[212:215], v[188:191], v[106:109]
	v_mfma_f32_16x16x32_bf16 v[102:105], v[220:223], v[180:183], v[102:105]
	v_mfma_f32_16x16x32_bf16 v[98:101], v[220:223], v[188:191], v[98:101]
	v_mfma_f32_16x16x32_bf16 v[126:129], v[200:203], v[184:187], v[126:129]
	v_mfma_f32_16x16x32_bf16 v[122:125], v[200:203], v[192:195], v[122:125]
	v_mfma_f32_16x16x32_bf16 v[118:121], v[208:211], v[184:187], v[118:121]
	v_mfma_f32_16x16x32_bf16 v[114:117], v[208:211], v[192:195], v[114:117]
	v_mfma_f32_16x16x32_bf16 v[110:113], v[216:219], v[184:187], v[110:113]
	v_mfma_f32_16x16x32_bf16 v[106:109], v[216:219], v[192:195], v[106:109]
	v_mfma_f32_16x16x32_bf16 v[102:105], v[224:227], v[184:187], v[102:105]
	v_mfma_f32_16x16x32_bf16 v[98:101], v[224:227], v[192:195], v[98:101]
	s_barrier
	v_lshl_add_u64 v[248:249], v[136:137], 0, s[36:37]
	v_readfirstlane_b32 s10, v161
	v_lshl_add_u64 v[250:251], v[248:249], 0, s[74:75]
	s_mov_b32 m0, s10
	ds_read_b128 v[228:231], v176
	ds_read_b128 v[232:235], v176 offset:1024
	ds_read_b128 v[236:239], v176 offset:2048
	ds_read_b128 v[240:243], v176 offset:3072
	global_load_lds_dwordx4 v[250:251], off
	v_lshl_add_u64 v[250:251], v[134:135], 0, s[36:37]
	s_add_u32 m0, m0, 0x2000
	v_lshl_add_u64 v[252:253], v[250:251], 0, s[74:75]
	global_load_lds_dwordx4 v[252:253], off
	s_barrier
	s_waitcnt lgkmcnt(0)
	v_mfma_f32_16x16x32_bf16 v[94:97], v[196:199], v[228:231], v[94:97]
	v_mfma_f32_16x16x32_bf16 v[90:93], v[196:199], v[236:239], v[90:93]
	v_mfma_f32_16x16x32_bf16 v[86:89], v[204:207], v[228:231], v[86:89]
	v_mfma_f32_16x16x32_bf16 v[82:85], v[204:207], v[236:239], v[82:85]
	v_mfma_f32_16x16x32_bf16 v[78:81], v[212:215], v[228:231], v[78:81]
	v_mfma_f32_16x16x32_bf16 v[74:77], v[212:215], v[236:239], v[74:77]
	v_mfma_f32_16x16x32_bf16 v[70:73], v[220:223], v[228:231], v[70:73]
	v_mfma_f32_16x16x32_bf16 v[66:69], v[220:223], v[236:239], v[66:69]
	v_mfma_f32_16x16x32_bf16 v[94:97], v[200:203], v[232:235], v[94:97]
	v_mfma_f32_16x16x32_bf16 v[90:93], v[200:203], v[240:243], v[90:93]
	v_mfma_f32_16x16x32_bf16 v[86:89], v[208:211], v[232:235], v[86:89]
	v_mfma_f32_16x16x32_bf16 v[82:85], v[208:211], v[240:243], v[82:85]
	v_mfma_f32_16x16x32_bf16 v[78:81], v[216:219], v[232:235], v[78:81]
	v_mfma_f32_16x16x32_bf16 v[74:77], v[216:219], v[240:243], v[74:77]
	v_mfma_f32_16x16x32_bf16 v[70:73], v[224:227], v[232:235], v[70:73]
	v_mfma_f32_16x16x32_bf16 v[66:69], v[224:227], v[240:243], v[66:69]
	v_readfirstlane_b32 s10, v163
	v_lshl_add_u64 v[252:253], v[244:245], 0, s[76:77]
	s_mov_b32 m0, s10
	s_barrier
	ds_read_b128 v[196:199], v159 offset:16384
	ds_read_b128 v[200:203], v159 offset:17408
	ds_read_b128 v[204:207], v147 offset:16384
	ds_read_b128 v[208:211], v147 offset:17408
	ds_read_b128 v[212:215], v146 offset:16384
	ds_read_b128 v[216:219], v146 offset:17408
	ds_read_b128 v[220:223], v145 offset:16384
	ds_read_b128 v[224:227], v145 offset:17408
	global_load_lds_dwordx4 v[252:253], off
	s_add_u32 m0, m0, 0x2000
	v_lshl_add_u64 v[252:253], v[246:247], 0, s[76:77]
	global_load_lds_dwordx4 v[252:253], off
	s_barrier
	s_waitcnt lgkmcnt(0)
	v_mfma_f32_16x16x32_bf16 v[62:65], v[196:199], v[180:183], v[62:65]
	v_mfma_f32_16x16x32_bf16 v[58:61], v[196:199], v[188:191], v[58:61]
	v_mfma_f32_16x16x32_bf16 v[54:57], v[204:207], v[180:183], v[54:57]
	v_mfma_f32_16x16x32_bf16 v[50:53], v[204:207], v[188:191], v[50:53]
	v_mfma_f32_16x16x32_bf16 v[46:49], v[212:215], v[180:183], v[46:49]
	v_mfma_f32_16x16x32_bf16 v[42:45], v[212:215], v[188:191], v[42:45]
	v_mfma_f32_16x16x32_bf16 v[38:41], v[220:223], v[180:183], v[38:41]
	v_mfma_f32_16x16x32_bf16 v[34:37], v[220:223], v[188:191], v[34:37]
	v_mfma_f32_16x16x32_bf16 v[62:65], v[200:203], v[184:187], v[62:65]
	v_mfma_f32_16x16x32_bf16 v[58:61], v[200:203], v[192:195], v[58:61]
	v_mfma_f32_16x16x32_bf16 v[54:57], v[208:211], v[184:187], v[54:57]
	v_mfma_f32_16x16x32_bf16 v[50:53], v[208:211], v[192:195], v[50:53]
	v_mfma_f32_16x16x32_bf16 v[46:49], v[216:219], v[184:187], v[46:49]
	v_mfma_f32_16x16x32_bf16 v[42:45], v[216:219], v[192:195], v[42:45]
	v_mfma_f32_16x16x32_bf16 v[38:41], v[224:227], v[184:187], v[38:41]
	v_mfma_f32_16x16x32_bf16 v[34:37], v[224:227], v[192:195], v[34:37]
	s_barrier
; #define STA(P, br, kt) STAGE(P, A, aoff0, aoff1, lda, br, kt)
; #define STB(P, br, kt) STAGE(P, Bt, boff0, boff1, ldb, br, kt)
; #define LDA(dst, b, h) _Pragma("unroll") for (int m = 0; m < 4; ++m) _Pragma("unroll") for (int k = 0; k < 2; ++k) \
;     dst[m][k] = *reinterpret_cast<const bf16x8*>((char*)SA(b, h) + lds_byte(wr * 64 + m * 16 + fr, k * 32 + fq * 8))
; #define LDB(dst, b, h) _Pragma("unroll") for (int n = 0; n < 2; ++n) _Pragma("unroll") for (int k = 0; k < 2; ++k) \
;     dst[n][k] = *reinterpret_cast<const bf16x8*>((char*)SB(b, h) + lds_byte(wc * 32 + n * 16 + fr, k * 32 + fq * 8))
; #define MMA(ai, bj, At, Bq) do { __builtin_amdgcn_s_setprio(1); \
;     _Pragma("unroll") for (int m = 0; m < 4; ++m) _Pragma("unroll") for (int n = 0; n < 2; ++n) _Pragma("unroll") for (int k = 0; k < 2; ++k) \
;       acc[ai][bj][m][n] = __builtin_amdgcn_mfma_f32_16x16x32_bf16(At[m][k], Bq[n][k], acc[ai][bj][m][n], 0, 0, 0); \
;     __builtin_amdgcn_s_setprio(0); } while (0)
; #define WAIT_V(n) asm volatile("s_waitcnt vmcnt(" #n ")" ::: "memory")
; #define WAIT_L(n) asm volatile("s_waitcnt lgkmcnt(" #n ")" ::: "memory")
; #define BAR __builtin_amdgcn_s_barrier()
; #define SCHED __builtin_amdgcn_sched_barrier(0)
; __device__ __forceinline__ void gemm256(const u16* __restrict__ A, int lda, const u16* __restrict__ Bt, int ldb, int K,
;                                         f32x4 (&acc)[2][2][4][2], const int g_wid) {
;     ...
;   for (int t = 0; t < nt - 2; t += 2) {
;     LDB(B0, 0, 0); SCHED; LDA(At, 0, 0); STA(SA(1, 1), HALF, t + 1);
;     WAIT_L(8); BAR; WAIT_L(0); MMA(0, 0, At, B0); BAR; SCHED;
;     LDB(B1, 0, 1); STB(SB(0, 0), 0, t + 2);
;     BAR; WAIT_L(0); MMA(0, 1, At, B1); BAR;
;     LDA(At, 0, 1); STA(SA(0, 0), 0, t + 2);
;     BAR; WAIT_L(0); MMA(1, 0, At, B0); BAR; SCHED;
;     STB(SB(0, 1), HALF, t + 2);
;     WAIT_V(6); BAR; MMA(1, 1, At, B1); BAR;
;     LDB(B0, 1, 0); SCHED; LDA(At, 1, 0); STA(SA(0, 1), HALF, t + 2);
;     WAIT_L(8); BAR; WAIT_L(0); MMA(0, 0, At, B0); BAR; SCHED;
;     LDB(B1, 1, 1); STB(SB(1, 0), 0, t + 3);
;     BAR; WAIT_L(0); MMA(0, 1, At, B1); BAR;
;     LDA(At, 1, 1); STA(SA(1, 0), 0, t + 3);
;     BAR; WAIT_L(0); MMA(1, 0, At, B0); BAR; SCHED;
;     STB(SB(1, 1), HALF, t + 3);
;     WAIT_V(6); BAR; MMA(1, 1, At, B1); BAR;
;   }
	v_readfirstlane_b32 s10, v165
	v_lshl_add_u64 v[180:181], v[248:249], 0, s[78:79]
	s_mov_b32 m0, s10
	global_load_lds_dwordx4 v[180:181], off
	s_add_u32 m0, m0, 0x2000
	v_lshl_add_u64 v[180:181], v[250:251], 0, s[78:79]
	global_load_lds_dwordx4 v[180:181], off
	s_waitcnt vmcnt(6)
	s_barrier
	v_mfma_f32_16x16x32_bf16 v[30:33], v[196:199], v[228:231], v[30:33]
	v_mfma_f32_16x16x32_bf16 v[26:29], v[196:199], v[236:239], v[26:29]
	v_mfma_f32_16x16x32_bf16 v[22:25], v[204:207], v[228:231], v[22:25]
	v_mfma_f32_16x16x32_bf16 v[18:21], v[204:207], v[236:239], v[18:21]
	v_mfma_f32_16x16x32_bf16 v[14:17], v[212:215], v[228:231], v[14:17]
	v_mfma_f32_16x16x32_bf16 v[10:13], v[212:215], v[236:239], v[10:13]
	v_mfma_f32_16x16x32_bf16 v[6:9], v[220:223], v[228:231], v[6:9]
	v_mfma_f32_16x16x32_bf16 v[2:5], v[220:223], v[236:239], v[2:5]
	v_mfma_f32_16x16x32_bf16 v[30:33], v[200:203], v[232:235], v[30:33]
	v_mfma_f32_16x16x32_bf16 v[26:29], v[200:203], v[240:243], v[26:29]
	v_mfma_f32_16x16x32_bf16 v[22:25], v[208:211], v[232:235], v[22:25]
	v_mfma_f32_16x16x32_bf16 v[18:21], v[208:211], v[240:243], v[18:21]
	v_mfma_f32_16x16x32_bf16 v[14:17], v[216:219], v[232:235], v[14:17]
	v_mfma_f32_16x16x32_bf16 v[10:13], v[216:219], v[240:243], v[10:13]
	v_mfma_f32_16x16x32_bf16 v[6:9], v[224:227], v[232:235], v[6:9]
	v_mfma_f32_16x16x32_bf16 v[2:5], v[224:227], v[240:243], v[2:5]
	s_barrier
	ds_read_b128 v[180:183], v167
	ds_read_b128 v[184:187], v167 offset:1024
	ds_read_b128 v[188:191], v167 offset:2048
	ds_read_b128 v[192:195], v167 offset:3072
	v_readfirstlane_b32 s10, v168
	v_lshl_add_u64 v[228:229], v[244:245], 0, s[80:81]
	s_mov_b32 m0, s10
	ds_read_b128 v[196:199], v159 offset:32768
	ds_read_b128 v[200:203], v159 offset:33792
	ds_read_b128 v[204:207], v147 offset:32768
	ds_read_b128 v[208:211], v147 offset:33792
	ds_read_b128 v[212:215], v146 offset:32768
	ds_read_b128 v[216:219], v146 offset:33792
	ds_read_b128 v[220:223], v145 offset:32768
	ds_read_b128 v[224:227], v145 offset:33792
	global_load_lds_dwordx4 v[228:229], off
	s_add_u32 m0, m0, 0x2000
	v_lshl_add_u64 v[228:229], v[246:247], 0, s[80:81]
	global_load_lds_dwordx4 v[228:229], off
	s_waitcnt lgkmcnt(8)
	s_barrier
	s_waitcnt lgkmcnt(0)
	v_mfma_f32_16x16x32_bf16 v[126:129], v[196:199], v[180:183], v[126:129]
	v_mfma_f32_16x16x32_bf16 v[122:125], v[196:199], v[188:191], v[122:125]
	v_mfma_f32_16x16x32_bf16 v[118:121], v[204:207], v[180:183], v[118:121]
	v_mfma_f32_16x16x32_bf16 v[114:117], v[204:207], v[188:191], v[114:117]
	v_mfma_f32_16x16x32_bf16 v[110:113], v[212:215], v[180:183], v[110:113]
	v_mfma_f32_16x16x32_bf16 v[106:109], v[212:215], v[188:191], v[106:109]
	v_mfma_f32_16x16x32_bf16 v[102:105], v[220:223], v[180:183], v[102:105]
	v_mfma_f32_16x16x32_bf16 v[98:101], v[220:223], v[188:191], v[98:101]
	v_mfma_f32_16x16x32_bf16 v[126:129], v[200:203], v[184:187], v[126:129]
	v_mfma_f32_16x16x32_bf16 v[122:125], v[200:203], v[192:195], v[122:125]
	v_mfma_f32_16x16x32_bf16 v[118:121], v[208:211], v[184:187], v[118:121]
	v_mfma_f32_16x16x32_bf16 v[114:117], v[208:211], v[192:195], v[114:117]
	v_mfma_f32_16x16x32_bf16 v[110:113], v[216:219], v[184:187], v[110:113]
	v_mfma_f32_16x16x32_bf16 v[106:109], v[216:219], v[192:195], v[106:109]
	v_mfma_f32_16x16x32_bf16 v[102:105], v[224:227], v[184:187], v[102:105]
	v_mfma_f32_16x16x32_bf16 v[98:101], v[224:227], v[192:195], v[98:101]
	s_barrier
	v_readfirstlane_b32 s10, v170
	v_lshl_add_u64 v[252:253], v[248:249], 0, s[82:83]
	s_mov_b32 m0, s10
	ds_read_b128 v[228:231], v160
	ds_read_b128 v[232:235], v160 offset:1024
	ds_read_b128 v[236:239], v160 offset:2048
	ds_read_b128 v[240:243], v160 offset:3072
	global_load_lds_dwordx4 v[252:253], off
	s_add_u32 m0, m0, 0x2000
	v_lshl_add_u64 v[252:253], v[250:251], 0, s[82:83]
	global_load_lds_dwordx4 v[252:253], off
	s_barrier
	s_waitcnt lgkmcnt(0)
	v_mfma_f32_16x16x32_bf16 v[94:97], v[196:199], v[228:231], v[94:97]
	v_mfma_f32_16x16x32_bf16 v[90:93], v[196:199], v[236:239], v[90:93]
	v_mfma_f32_16x16x32_bf16 v[86:89], v[204:207], v[228:231], v[86:89]
	v_mfma_f32_16x16x32_bf16 v[82:85], v[204:207], v[236:239], v[82:85]
	v_mfma_f32_16x16x32_bf16 v[78:81], v[212:215], v[228:231], v[78:81]
	v_mfma_f32_16x16x32_bf16 v[74:77], v[212:215], v[236:239], v[74:77]
	v_mfma_f32_16x16x32_bf16 v[70:73], v[220:223], v[228:231], v[70:73]
	v_mfma_f32_16x16x32_bf16 v[66:69], v[220:223], v[236:239], v[66:69]
	v_mfma_f32_16x16x32_bf16 v[94:97], v[200:203], v[232:235], v[94:97]
	v_mfma_f32_16x16x32_bf16 v[90:93], v[200:203], v[240:243], v[90:93]
	v_mfma_f32_16x16x32_bf16 v[86:89], v[208:211], v[232:235], v[86:89]
	v_mfma_f32_16x16x32_bf16 v[82:85], v[208:211], v[240:243], v[82:85]
	v_mfma_f32_16x16x32_bf16 v[78:81], v[216:219], v[232:235], v[78:81]
	v_mfma_f32_16x16x32_bf16 v[74:77], v[216:219], v[240:243], v[74:77]
	v_mfma_f32_16x16x32_bf16 v[70:73], v[224:227], v[232:235], v[70:73]
	v_mfma_f32_16x16x32_bf16 v[66:69], v[224:227], v[240:243], v[66:69]
	v_readfirstlane_b32 s10, v172
	v_lshl_add_u64 v[244:245], v[244:245], 0, s[84:85]
	s_mov_b32 m0, s10
	s_barrier
	ds_read_b128 v[196:199], v159 offset:49152
	ds_read_b128 v[200:203], v159 offset:50176
	ds_read_b128 v[204:207], v147 offset:49152
	ds_read_b128 v[208:211], v147 offset:50176
	ds_read_b128 v[212:215], v146 offset:49152
	ds_read_b128 v[216:219], v146 offset:50176
	ds_read_b128 v[220:223], v145 offset:49152
	ds_read_b128 v[224:227], v145 offset:50176
	global_load_lds_dwordx4 v[244:245], off
	s_add_u32 m0, m0, 0x2000
	v_lshl_add_u64 v[244:245], v[246:247], 0, s[84:85]
	global_load_lds_dwordx4 v[244:245], off
	s_barrier
; #define STA(P, br, kt) STAGE(P, A, aoff0, aoff1, lda, br, kt)
; #define STB(P, br, kt) STAGE(P, Bt, boff0, boff1, ldb, br, kt)
; #define LDA(dst, b, h) _Pragma("unroll") for (int m = 0; m < 4; ++m) _Pragma("unroll") for (int k = 0; k < 2; ++k) \
;     dst[m][k] = *reinterpret_cast<const bf16x8*>((char*)SA(b, h) + lds_byte(wr * 64 + m * 16 + fr, k * 32 + fq * 8))
; #define LDB(dst, b, h) _Pragma("unroll") for (int n = 0; n < 2; ++n) _Pragma("unroll") for (int k = 0; k < 2; ++k) \
;     dst[n][k] = *reinterpret_cast<const bf16x8*>((char*)SB(b, h) + lds_byte(wc * 32 + n * 16 + fr, k * 32 + fq * 8))
; #define WAIT_V(n) asm volatile("s_waitcnt vmcnt(" #n ")" ::: "memory")
; #define WAIT_L(n) asm volatile("s_waitcnt lgkmcnt(" #n ")" ::: "memory")
; #define BAR __builtin_amdgcn_s_barrier()
; __device__ __forceinline__ void gemm256(const u16* __restrict__ A, int lda, const u16* __restrict__ Bt, int ldb, int K,
;                                         f32x4 (&acc)[2][2][4][2], const int g_wid) {
;     ...
;   for (int t = 0; t < nt - 2; t += 2) {
;     LDB(B0, 0, 0); SCHED; LDA(At, 0, 0); STA(SA(1, 1), HALF, t + 1);
;     WAIT_L(8); BAR; WAIT_L(0); MMA(0, 0, At, B0); BAR; SCHED;
;     LDB(B1, 0, 1); STB(SB(0, 0), 0, t + 2);
;     BAR; WAIT_L(0); MMA(0, 1, At, B1); BAR;
;     LDA(At, 0, 1); STA(SA(0, 0), 0, t + 2);
;     BAR; WAIT_L(0); MMA(1, 0, At, B0); BAR; SCHED;
;     STB(SB(0, 1), HALF, t + 2);
;     WAIT_V(6); BAR; MMA(1, 1, At, B1); BAR;
;     LDB(B0, 1, 0); SCHED; LDA(At, 1, 0); STA(SA(0, 1), HALF, t + 2);
;     WAIT_L(8); BAR; WAIT_L(0); MMA(0, 0, At, B0); BAR; SCHED;
;     LDB(B1, 1, 1); STB(SB(1, 0), 0, t + 3);
;     BAR; WAIT_L(0); MMA(0, 1, At, B1); BAR;
;     LDA(At, 1, 1); STA(SA(1, 0), 0, t + 3);
;     BAR; WAIT_L(0); MMA(1, 0, At, B0); BAR; SCHED;
;     STB(SB(1, 1), HALF, t + 3);
;     WAIT_V(6); BAR; MMA(1, 1, At, B1); BAR;
;   }
;   { LDB(B0, 0, 0); LDA(At, 0, 0); STA(SA(1, 1), HALF, nt - 1);
;     BAR; WAIT_L(0); MMA(0, 0, At, B0); BAR;
;     LDB(B1, 0, 1); BAR; WAIT_L(0); MMA(0, 1, At, B1); BAR;
;     LDA(At, 0, 1); WAIT_V(4); BAR; WAIT_L(0); MMA(1, 0, At, B0); MMA(1, 1, At, B1); BAR; }
;   { LDB(B0, 1, 0); LDA(At, 1, 0); WAIT_V(2); BAR; WAIT_L(0); MMA(0, 0, At, B0); BAR;
;     LDB(B1, 1, 1); WAIT_V(0); BAR; WAIT_L(0); MMA(0, 1, At, B1); BAR;
;     LDA(At, 1, 1); BAR; WAIT_L(0); MMA(1, 0, At, B0); MMA(1, 1, At, B1); BAR; }
;   if (wr == 0) BAR;
	s_waitcnt lgkmcnt(0)
	v_mfma_f32_16x16x32_bf16 v[62:65], v[196:199], v[180:183], v[62:65]
	v_mfma_f32_16x16x32_bf16 v[58:61], v[196:199], v[188:191], v[58:61]
	v_mfma_f32_16x16x32_bf16 v[54:57], v[204:207], v[180:183], v[54:57]
	v_mfma_f32_16x16x32_bf16 v[50:53], v[204:207], v[188:191], v[50:53]
	v_mfma_f32_16x16x32_bf16 v[46:49], v[212:215], v[180:183], v[46:49]
	v_mfma_f32_16x16x32_bf16 v[42:45], v[212:215], v[188:191], v[42:45]
	v_mfma_f32_16x16x32_bf16 v[38:41], v[220:223], v[180:183], v[38:41]
	v_mfma_f32_16x16x32_bf16 v[34:37], v[220:223], v[188:191], v[34:37]
	v_mfma_f32_16x16x32_bf16 v[62:65], v[200:203], v[184:187], v[62:65]
	v_mfma_f32_16x16x32_bf16 v[58:61], v[200:203], v[192:195], v[58:61]
	v_mfma_f32_16x16x32_bf16 v[54:57], v[208:211], v[184:187], v[54:57]
	v_mfma_f32_16x16x32_bf16 v[50:53], v[208:211], v[192:195], v[50:53]
	v_mfma_f32_16x16x32_bf16 v[46:49], v[216:219], v[184:187], v[46:49]
	v_mfma_f32_16x16x32_bf16 v[42:45], v[216:219], v[192:195], v[42:45]
	v_mfma_f32_16x16x32_bf16 v[38:41], v[224:227], v[184:187], v[38:41]
	v_mfma_f32_16x16x32_bf16 v[34:37], v[224:227], v[192:195], v[34:37]
	s_barrier
	v_readfirstlane_b32 s10, v174
	v_lshl_add_u64 v[180:181], v[248:249], 0, s[86:87]
	s_mov_b32 m0, s10
	global_load_lds_dwordx4 v[180:181], off
	s_add_u32 m0, m0, 0x2000
	v_lshl_add_u64 v[180:181], v[250:251], 0, s[86:87]
	global_load_lds_dwordx4 v[180:181], off
	s_waitcnt vmcnt(6)
	s_barrier
	v_mfma_f32_16x16x32_bf16 v[30:33], v[196:199], v[228:231], v[30:33]
	v_mfma_f32_16x16x32_bf16 v[26:29], v[196:199], v[236:239], v[26:29]
	v_mfma_f32_16x16x32_bf16 v[22:25], v[204:207], v[228:231], v[22:25]
	v_mfma_f32_16x16x32_bf16 v[18:21], v[204:207], v[236:239], v[18:21]
	v_mfma_f32_16x16x32_bf16 v[14:17], v[212:215], v[228:231], v[14:17]
	v_mfma_f32_16x16x32_bf16 v[10:13], v[212:215], v[236:239], v[10:13]
	v_mfma_f32_16x16x32_bf16 v[6:9], v[220:223], v[228:231], v[6:9]
	v_mfma_f32_16x16x32_bf16 v[2:5], v[220:223], v[236:239], v[2:5]
	v_mfma_f32_16x16x32_bf16 v[30:33], v[200:203], v[232:235], v[30:33]
	v_mfma_f32_16x16x32_bf16 v[26:29], v[200:203], v[240:243], v[26:29]
	v_mfma_f32_16x16x32_bf16 v[22:25], v[208:211], v[232:235], v[22:25]
	v_mfma_f32_16x16x32_bf16 v[18:21], v[208:211], v[240:243], v[18:21]
	v_mfma_f32_16x16x32_bf16 v[14:17], v[216:219], v[232:235], v[14:17]
	v_mfma_f32_16x16x32_bf16 v[10:13], v[216:219], v[240:243], v[10:13]
	v_mfma_f32_16x16x32_bf16 v[6:9], v[224:227], v[232:235], v[6:9]
	v_mfma_f32_16x16x32_bf16 v[2:5], v[224:227], v[240:243], v[2:5]
	s_add_i32 s54, s54, 2
	s_add_u32 s36, s36, 0x100
	s_addc_u32 s37, s37, 0
	s_cmp_lt_u32 s54, 12
	s_barrier
	s_cbranch_scc1 .LBB0_109
	s_add_u32 s34, s34, 0x40780
	s_addc_u32 s35, s35, 0
	v_readfirstlane_b32 s10, v178
	v_lshl_add_u64 v[132:133], v[132:133], 1, s[34:35]
	s_mov_b32 m0, s10
	v_readfirstlane_b32 s10, v179
	ds_read_b128 v[134:137], v177
	ds_read_b128 v[162:165], v177 offset:1024
	ds_read_b128 v[168:171], v177 offset:2048
	ds_read_b128 v[172:175], v177 offset:3072
	ds_read_b128 v[180:183], v159
	ds_read_b128 v[184:187], v159 offset:1024
	ds_read_b128 v[188:191], v147
	ds_read_b128 v[192:195], v147 offset:1024
	ds_read_b128 v[196:199], v146
	ds_read_b128 v[200:203], v146 offset:1024
	ds_read_b128 v[204:207], v145
	ds_read_b128 v[208:211], v145 offset:1024
	global_load_lds_dwordx4 v[132:133], off
	v_lshl_add_u64 v[130:131], v[130:131], 1, s[34:35]
	s_mov_b32 m0, s10
	s_nop 0
	global_load_lds_dwordx4 v[130:131], off
	s_barrier
	s_waitcnt lgkmcnt(0)
	v_mfma_f32_16x16x32_bf16 v[126:129], v[180:183], v[134:137], v[126:129]
	v_mfma_f32_16x16x32_bf16 v[122:125], v[180:183], v[168:171], v[122:125]
	v_mfma_f32_16x16x32_bf16 v[118:121], v[188:191], v[134:137], v[118:121]
	v_mfma_f32_16x16x32_bf16 v[114:117], v[188:191], v[168:171], v[114:117]
	v_mfma_f32_16x16x32_bf16 v[110:113], v[196:199], v[134:137], v[110:113]
	v_mfma_f32_16x16x32_bf16 v[106:109], v[196:199], v[168:171], v[106:109]
	v_mfma_f32_16x16x32_bf16 v[102:105], v[204:207], v[134:137], v[102:105]
	v_mfma_f32_16x16x32_bf16 v[98:101], v[204:207], v[168:171], v[98:101]
	v_mfma_f32_16x16x32_bf16 v[126:129], v[184:187], v[162:165], v[126:129]
	v_mfma_f32_16x16x32_bf16 v[122:125], v[184:187], v[172:175], v[122:125]
	v_mfma_f32_16x16x32_bf16 v[118:121], v[192:195], v[162:165], v[118:121]
	v_mfma_f32_16x16x32_bf16 v[114:117], v[192:195], v[172:175], v[114:117]
	v_mfma_f32_16x16x32_bf16 v[110:113], v[200:203], v[162:165], v[110:113]
	v_mfma_f32_16x16x32_bf16 v[106:109], v[200:203], v[172:175], v[106:109]
	v_mfma_f32_16x16x32_bf16 v[102:105], v[208:211], v[162:165], v[102:105]
	v_mfma_f32_16x16x32_bf16 v[98:101], v[208:211], v[172:175], v[98:101]
	s_barrier
	ds_read_b128 v[130:133], v176
	ds_read_b128 v[212:215], v176 offset:1024
	ds_read_b128 v[216:219], v176 offset:2048
	ds_read_b128 v[176:179], v176 offset:3072
	s_barrier
	s_waitcnt lgkmcnt(0)
	v_mfma_f32_16x16x32_bf16 v[94:97], v[180:183], v[130:133], v[94:97]
	v_mfma_f32_16x16x32_bf16 v[90:93], v[180:183], v[216:219], v[90:93]
	v_mfma_f32_16x16x32_bf16 v[86:89], v[188:191], v[130:133], v[86:89]
	v_mfma_f32_16x16x32_bf16 v[82:85], v[188:191], v[216:219], v[82:85]
	v_mfma_f32_16x16x32_bf16 v[78:81], v[196:199], v[130:133], v[78:81]
	v_mfma_f32_16x16x32_bf16 v[74:77], v[196:199], v[216:219], v[74:77]
	v_mfma_f32_16x16x32_bf16 v[70:73], v[204:207], v[130:133], v[70:73]
	v_mfma_f32_16x16x32_bf16 v[66:69], v[204:207], v[216:219], v[66:69]
	v_mfma_f32_16x16x32_bf16 v[94:97], v[184:187], v[212:215], v[94:97]
	v_mfma_f32_16x16x32_bf16 v[90:93], v[184:187], v[176:179], v[90:93]
	v_mfma_f32_16x16x32_bf16 v[86:89], v[192:195], v[212:215], v[86:89]
	v_mfma_f32_16x16x32_bf16 v[82:85], v[192:195], v[176:179], v[82:85]
	v_mfma_f32_16x16x32_bf16 v[78:81], v[200:203], v[212:215], v[78:81]
	v_mfma_f32_16x16x32_bf16 v[74:77], v[200:203], v[176:179], v[74:77]
	v_mfma_f32_16x16x32_bf16 v[70:73], v[208:211], v[212:215], v[70:73]
	v_mfma_f32_16x16x32_bf16 v[66:69], v[208:211], v[176:179], v[66:69]
	s_barrier
; #define STA(P, br, kt) STAGE(P, A, aoff0, aoff1, lda, br, kt)
; #define LDA(dst, b, h) _Pragma("unroll") for (int m = 0; m < 4; ++m) _Pragma("unroll") for (int k = 0; k < 2; ++k) \
;     dst[m][k] = *reinterpret_cast<const bf16x8*>((char*)SA(b, h) + lds_byte(wr * 64 + m * 16 + fr, k * 32 + fq * 8))
; #define LDB(dst, b, h) _Pragma("unroll") for (int n = 0; n < 2; ++n) _Pragma("unroll") for (int k = 0; k < 2; ++k) \
;     dst[n][k] = *reinterpret_cast<const bf16x8*>((char*)SB(b, h) + lds_byte(wc * 32 + n * 16 + fr, k * 32 + fq * 8))
; #define MMA(ai, bj, At, Bq) do { __builtin_amdgcn_s_setprio(1); \
;     _Pragma("unroll") for (int m = 0; m < 4; ++m) _Pragma("unroll") for (int n = 0; n < 2; ++n) _Pragma("unroll") for (int k = 0; k < 2; ++k) \
;       acc[ai][bj][m][n] = __builtin_amdgcn_mfma_f32_16x16x32_bf16(At[m][k], Bq[n][k], acc[ai][bj][m][n], 0, 0, 0); \
;     __builtin_amdgcn_s_setprio(0); } while (0)
; #define WAIT_V(n) asm volatile("s_waitcnt vmcnt(" #n ")" ::: "memory")
; #define WAIT_L(n) asm volatile("s_waitcnt lgkmcnt(" #n ")" ::: "memory")
; #define BAR __builtin_amdgcn_s_barrier()
; __device__ __forceinline__ void gemm256(const u16* __restrict__ A, int lda, const u16* __restrict__ Bt, int ldb, int K,
;                                         f32x4 (&acc)[2][2][4][2], const int g_wid) {
;     ...
;   { LDB(B0, 0, 0); LDA(At, 0, 0); STA(SA(1, 1), HALF, nt - 1);
;     BAR; WAIT_L(0); MMA(0, 0, At, B0); BAR;
;     LDB(B1, 0, 1); BAR; WAIT_L(0); MMA(0, 1, At, B1); BAR;
;     LDA(At, 0, 1); WAIT_V(4); BAR; WAIT_L(0); MMA(1, 0, At, B0); MMA(1, 1, At, B1); BAR; }
;   { LDB(B0, 1, 0); LDA(At, 1, 0); WAIT_V(2); BAR; WAIT_L(0); MMA(0, 0, At, B0); BAR;
;     LDB(B1, 1, 1); WAIT_V(0); BAR; WAIT_L(0); MMA(0, 1, At, B1); BAR;
;     LDA(At, 1, 1); BAR; WAIT_L(0); MMA(1, 0, At, B0); MMA(1, 1, At, B1); BAR; }
	ds_read_b128 v[180:183], v159 offset:16384
	ds_read_b128 v[184:187], v159 offset:17408
	ds_read_b128 v[188:191], v147 offset:16384
	ds_read_b128 v[192:195], v147 offset:17408
	ds_read_b128 v[196:199], v146 offset:16384
	ds_read_b128 v[200:203], v146 offset:17408
	ds_read_b128 v[204:207], v145 offset:16384
	ds_read_b128 v[208:211], v145 offset:17408
	s_waitcnt vmcnt(4)
	s_barrier
	s_waitcnt lgkmcnt(0)
	v_mfma_f32_16x16x32_bf16 v[62:65], v[180:183], v[134:137], v[62:65]
	v_mfma_f32_16x16x32_bf16 v[58:61], v[180:183], v[168:171], v[58:61]
	v_mfma_f32_16x16x32_bf16 v[54:57], v[188:191], v[134:137], v[54:57]
	v_mfma_f32_16x16x32_bf16 v[50:53], v[188:191], v[168:171], v[50:53]
	v_mfma_f32_16x16x32_bf16 v[46:49], v[196:199], v[134:137], v[46:49]
	v_mfma_f32_16x16x32_bf16 v[42:45], v[196:199], v[168:171], v[42:45]
	v_mfma_f32_16x16x32_bf16 v[38:41], v[204:207], v[134:137], v[38:41]
	v_mfma_f32_16x16x32_bf16 v[34:37], v[204:207], v[168:171], v[34:37]
	v_mfma_f32_16x16x32_bf16 v[220:223], v[184:187], v[162:165], v[62:65]
	v_mfma_f32_16x16x32_bf16 v[224:227], v[184:187], v[172:175], v[58:61]
	v_mfma_f32_16x16x32_bf16 v[228:231], v[192:195], v[162:165], v[54:57]
	v_mfma_f32_16x16x32_bf16 v[232:235], v[192:195], v[172:175], v[50:53]
	v_mfma_f32_16x16x32_bf16 v[236:239], v[200:203], v[162:165], v[46:49]
	v_mfma_f32_16x16x32_bf16 v[240:243], v[200:203], v[172:175], v[42:45]
	v_mfma_f32_16x16x32_bf16 v[134:137], v[208:211], v[162:165], v[38:41]
	v_mfma_f32_16x16x32_bf16 v[162:165], v[208:211], v[172:175], v[34:37]
	v_mfma_f32_16x16x32_bf16 v[30:33], v[180:183], v[130:133], v[30:33]
	v_mfma_f32_16x16x32_bf16 v[26:29], v[180:183], v[216:219], v[26:29]
	v_mfma_f32_16x16x32_bf16 v[22:25], v[188:191], v[130:133], v[22:25]
	v_mfma_f32_16x16x32_bf16 v[18:21], v[188:191], v[216:219], v[18:21]
	v_mfma_f32_16x16x32_bf16 v[14:17], v[196:199], v[130:133], v[14:17]
	v_mfma_f32_16x16x32_bf16 v[10:13], v[196:199], v[216:219], v[10:13]
	v_mfma_f32_16x16x32_bf16 v[6:9], v[204:207], v[130:133], v[6:9]
	v_mfma_f32_16x16x32_bf16 v[2:5], v[204:207], v[216:219], v[2:5]
	v_mfma_f32_16x16x32_bf16 v[30:33], v[184:187], v[212:215], v[30:33]
	v_mfma_f32_16x16x32_bf16 v[26:29], v[184:187], v[176:179], v[26:29]
	v_mfma_f32_16x16x32_bf16 v[22:25], v[192:195], v[212:215], v[22:25]
	v_mfma_f32_16x16x32_bf16 v[18:21], v[192:195], v[176:179], v[18:21]
	v_mfma_f32_16x16x32_bf16 v[14:17], v[200:203], v[212:215], v[14:17]
	v_mfma_f32_16x16x32_bf16 v[10:13], v[200:203], v[176:179], v[10:13]
	v_mfma_f32_16x16x32_bf16 v[6:9], v[208:211], v[212:215], v[6:9]
	v_mfma_f32_16x16x32_bf16 v[2:5], v[208:211], v[176:179], v[2:5]
	s_barrier
	ds_read_b128 v[130:133], v167
	ds_read_b128 v[168:171], v167 offset:1024
	ds_read_b128 v[172:175], v167 offset:2048
	ds_read_b128 v[176:179], v167 offset:3072
	ds_read_b128 v[34:37], v159 offset:32768
	ds_read_b128 v[38:41], v159 offset:33792
	ds_read_b128 v[42:45], v147 offset:32768
	ds_read_b128 v[46:49], v147 offset:33792
	ds_read_b128 v[180:183], v146 offset:32768
	ds_read_b128 v[184:187], v146 offset:33792
	ds_read_b128 v[188:191], v145 offset:32768
	ds_read_b128 v[192:195], v145 offset:33792
	s_waitcnt vmcnt(2)
	s_barrier
	s_waitcnt lgkmcnt(0)
	v_mfma_f32_16x16x32_bf16 v[50:53], v[34:37], v[130:133], v[126:129]
	v_mfma_f32_16x16x32_bf16 v[126:129], v[38:41], v[168:171], v[50:53]
	v_mfma_f32_16x16x32_bf16 v[50:53], v[34:37], v[172:175], v[122:125]
	v_mfma_f32_16x16x32_bf16 v[122:125], v[38:41], v[176:179], v[50:53]
	v_mfma_f32_16x16x32_bf16 v[50:53], v[42:45], v[130:133], v[118:121]
	v_mfma_f32_16x16x32_bf16 v[118:121], v[46:49], v[168:171], v[50:53]
	v_mfma_f32_16x16x32_bf16 v[50:53], v[42:45], v[172:175], v[114:117]
	v_mfma_f32_16x16x32_bf16 v[114:117], v[46:49], v[176:179], v[50:53]
	v_mfma_f32_16x16x32_bf16 v[50:53], v[180:183], v[130:133], v[110:113]
	v_mfma_f32_16x16x32_bf16 v[110:113], v[184:187], v[168:171], v[50:53]
	v_mfma_f32_16x16x32_bf16 v[50:53], v[180:183], v[172:175], v[106:109]
	v_mfma_f32_16x16x32_bf16 v[106:109], v[184:187], v[176:179], v[50:53]
	v_mfma_f32_16x16x32_bf16 v[50:53], v[188:191], v[130:133], v[102:105]
	v_mfma_f32_16x16x32_bf16 v[102:105], v[192:195], v[168:171], v[50:53]
	v_mfma_f32_16x16x32_bf16 v[50:53], v[188:191], v[172:175], v[98:101]
	v_mfma_f32_16x16x32_bf16 v[98:101], v[192:195], v[176:179], v[50:53]
	s_barrier
; #define STA(P, br, kt) STAGE(P, A, aoff0, aoff1, lda, br, kt)
; #define LDA(dst, b, h) _Pragma("unroll") for (int m = 0; m < 4; ++m) _Pragma("unroll") for (int k = 0; k < 2; ++k) \
;     dst[m][k] = *reinterpret_cast<const bf16x8*>((char*)SA(b, h) + lds_byte(wr * 64 + m * 16 + fr, k * 32 + fq * 8))
; #define LDB(dst, b, h) _Pragma("unroll") for (int n = 0; n < 2; ++n) _Pragma("unroll") for (int k = 0; k < 2; ++k) \
;     dst[n][k] = *reinterpret_cast<const bf16x8*>((char*)SB(b, h) + lds_byte(wc * 32 + n * 16 + fr, k * 32 + fq * 8))
; #define MMA(ai, bj, At, Bq) do { __builtin_amdgcn_s_setprio(1); \
;     _Pragma("unroll") for (int m = 0; m < 4; ++m) _Pragma("unroll") for (int n = 0; n < 2; ++n) _Pragma("unroll") for (int k = 0; k < 2; ++k) \
;       acc[ai][bj][m][n] = __builtin_amdgcn_mfma_f32_16x16x32_bf16(At[m][k], Bq[n][k], acc[ai][bj][m][n], 0, 0, 0); \
;     __builtin_amdgcn_s_setprio(0); } while (0)
; #define WAIT_V(n) asm volatile("s_waitcnt vmcnt(" #n ")" ::: "memory")
; #define WAIT_L(n) asm volatile("s_waitcnt lgkmcnt(" #n ")" ::: "memory")
; #define BAR __builtin_amdgcn_s_barrier()
; __device__ __forceinline__ void gemm256(const u16* __restrict__ A, int lda, const u16* __restrict__ Bt, int ldb, int K,
;                                         f32x4 (&acc)[2][2][4][2], const int g_wid) {
;     ...
;   { LDB(B0, 0, 0); LDA(At, 0, 0); STA(SA(1, 1), HALF, nt - 1);
;     BAR; WAIT_L(0); MMA(0, 0, At, B0); BAR;
;     LDB(B1, 0, 1); BAR; WAIT_L(0); MMA(0, 1, At, B1); BAR;
;     LDA(At, 0, 1); WAIT_V(4); BAR; WAIT_L(0); MMA(1, 0, At, B0); MMA(1, 1, At, B1); BAR; }
;   { LDB(B0, 1, 0); LDA(At, 1, 0); WAIT_V(2); BAR; WAIT_L(0); MMA(0, 0, At, B0); BAR;
;     LDB(B1, 1, 1); WAIT_V(0); BAR; WAIT_L(0); MMA(0, 1, At, B1); BAR;
;     LDA(At, 1, 1); BAR; WAIT_L(0); MMA(1, 0, At, B0); MMA(1, 1, At, B1); BAR; }
;   if (wr == 0) BAR;
	ds_read_b128 v[196:199], v160
	ds_read_b128 v[200:203], v160 offset:1024
	ds_read_b128 v[204:207], v160 offset:2048
	ds_read_b128 v[208:211], v160 offset:3072
	s_waitcnt vmcnt(0)
	s_barrier
	s_waitcnt lgkmcnt(0)
	v_mfma_f32_16x16x32_bf16 v[50:53], v[34:37], v[196:199], v[94:97]
	v_mfma_f32_16x16x32_bf16 v[34:37], v[34:37], v[204:207], v[90:93]
	v_mfma_f32_16x16x32_bf16 v[58:61], v[38:41], v[208:211], v[34:37]
	v_mfma_f32_16x16x32_bf16 v[34:37], v[42:45], v[196:199], v[86:89]
	v_mfma_f32_16x16x32_bf16 v[54:57], v[46:49], v[200:203], v[34:37]
	v_mfma_f32_16x16x32_bf16 v[34:37], v[42:45], v[204:207], v[82:85]
	v_mfma_f32_16x16x32_bf16 v[62:65], v[38:41], v[200:203], v[50:53]
	v_mfma_f32_16x16x32_bf16 v[50:53], v[46:49], v[208:211], v[34:37]
	v_mfma_f32_16x16x32_bf16 v[34:37], v[180:183], v[196:199], v[78:81]
	v_mfma_f32_16x16x32_bf16 v[46:49], v[184:187], v[200:203], v[34:37]
	v_mfma_f32_16x16x32_bf16 v[34:37], v[180:183], v[204:207], v[74:77]
	v_mfma_f32_16x16x32_bf16 v[42:45], v[184:187], v[208:211], v[34:37]
	v_mfma_f32_16x16x32_bf16 v[34:37], v[188:191], v[196:199], v[70:73]
	v_mfma_f32_16x16x32_bf16 v[38:41], v[192:195], v[200:203], v[34:37]
	v_mfma_f32_16x16x32_bf16 v[34:37], v[188:191], v[204:207], v[66:69]
	v_mfma_f32_16x16x32_bf16 v[34:37], v[192:195], v[208:211], v[34:37]
	s_barrier
	ds_read_b128 v[180:183], v159 offset:49152
	ds_read_b128 v[184:187], v159 offset:50176
	ds_read_b128 v[188:191], v147 offset:49152
	ds_read_b128 v[192:195], v147 offset:50176
	ds_read_b128 v[212:215], v146 offset:49152
	ds_read_b128 v[216:219], v146 offset:50176
	ds_read_b128 v[244:247], v145 offset:49152
	ds_read_b128 v[248:251], v145 offset:50176
	s_barrier
	s_waitcnt lgkmcnt(0)
	v_mfma_f32_16x16x32_bf16 v[66:69], v[180:183], v[130:133], v[220:223]
	v_mfma_f32_16x16x32_bf16 v[94:97], v[184:187], v[168:171], v[66:69]
	v_mfma_f32_16x16x32_bf16 v[66:69], v[180:183], v[172:175], v[224:227]
	v_mfma_f32_16x16x32_bf16 v[90:93], v[184:187], v[176:179], v[66:69]
	v_mfma_f32_16x16x32_bf16 v[66:69], v[188:191], v[130:133], v[228:231]
	v_mfma_f32_16x16x32_bf16 v[86:89], v[192:195], v[168:171], v[66:69]
	v_mfma_f32_16x16x32_bf16 v[66:69], v[188:191], v[172:175], v[232:235]
	v_mfma_f32_16x16x32_bf16 v[82:85], v[192:195], v[176:179], v[66:69]
	v_mfma_f32_16x16x32_bf16 v[66:69], v[212:215], v[130:133], v[236:239]
	v_mfma_f32_16x16x32_bf16 v[78:81], v[216:219], v[168:171], v[66:69]
	v_mfma_f32_16x16x32_bf16 v[66:69], v[212:215], v[172:175], v[240:243]
	v_mfma_f32_16x16x32_bf16 v[74:77], v[216:219], v[176:179], v[66:69]
	v_mfma_f32_16x16x32_bf16 v[66:69], v[244:247], v[130:133], v[134:137]
	v_mfma_f32_16x16x32_bf16 v[70:73], v[248:251], v[168:171], v[66:69]
	v_mfma_f32_16x16x32_bf16 v[66:69], v[244:247], v[172:175], v[162:165]
	v_mfma_f32_16x16x32_bf16 v[66:69], v[248:251], v[176:179], v[66:69]
	v_mfma_f32_16x16x32_bf16 v[30:33], v[180:183], v[196:199], v[30:33]
	v_mfma_f32_16x16x32_bf16 v[26:29], v[180:183], v[204:207], v[26:29]
	v_mfma_f32_16x16x32_bf16 v[22:25], v[188:191], v[196:199], v[22:25]
	v_mfma_f32_16x16x32_bf16 v[18:21], v[188:191], v[204:207], v[18:21]
	v_mfma_f32_16x16x32_bf16 v[14:17], v[212:215], v[196:199], v[14:17]
	v_mfma_f32_16x16x32_bf16 v[10:13], v[212:215], v[204:207], v[10:13]
	v_mfma_f32_16x16x32_bf16 v[6:9], v[244:247], v[196:199], v[6:9]
	v_mfma_f32_16x16x32_bf16 v[2:5], v[244:247], v[204:207], v[2:5]
	v_mfma_f32_16x16x32_bf16 v[30:33], v[184:187], v[200:203], v[30:33]
	v_mfma_f32_16x16x32_bf16 v[26:29], v[184:187], v[208:211], v[26:29]
	v_mfma_f32_16x16x32_bf16 v[22:25], v[192:195], v[200:203], v[22:25]
	v_mfma_f32_16x16x32_bf16 v[18:21], v[192:195], v[208:211], v[18:21]
	v_mfma_f32_16x16x32_bf16 v[14:17], v[216:219], v[200:203], v[14:17]
	v_mfma_f32_16x16x32_bf16 v[10:13], v[216:219], v[208:211], v[10:13]
	v_mfma_f32_16x16x32_bf16 v[6:9], v[248:251], v[200:203], v[6:9]
	v_mfma_f32_16x16x32_bf16 v[2:5], v[248:251], v[208:211], v[2:5]
	s_setprio 0
	s_movk_i32 s10, 0x100
	v_cmp_gt_u32_e32 vcc, s10, v0
	s_barrier
	s_and_saveexec_b64 s[34:35], vcc
	s_cbranch_execz .LBB0_105
	s_barrier
	s_branch .LBB0_105

; #define STA(P, br, kt) STAGE(P, A, aoff0, aoff1, lda, br, kt)
; #define STB(P, br, kt) STAGE(P, Bt, boff0, boff1, ldb, br, kt)
; #define LDA(dst, b, h) _Pragma("unroll") for (int m = 0; m < 4; ++m) _Pragma("unroll") for (int k = 0; k < 2; ++k) \
;     dst[m][k] = *reinterpret_cast<const bf16x8*>((char*)SA(b, h) + lds_byte(wr * 64 + m * 16 + fr, k * 32 + fq * 8))
; #define LDB(dst, b, h) _Pragma("unroll") for (int n = 0; n < 2; ++n) _Pragma("unroll") for (int k = 0; k < 2; ++k) \
;     dst[n][k] = *reinterpret_cast<const bf16x8*>((char*)SB(b, h) + lds_byte(wc * 32 + n * 16 + fr, k * 32 + fq * 8))
; #define MMA(ai, bj, At, Bq) do { __builtin_amdgcn_s_setprio(1); \
;     _Pragma("unroll") for (int m = 0; m < 4; ++m) _Pragma("unroll") for (int n = 0; n < 2; ++n) _Pragma("unroll") for (int k = 0; k < 2; ++k) \
;       acc[ai][bj][m][n] = __builtin_amdgcn_mfma_f32_16x16x32_bf16(At[m][k], Bq[n][k], acc[ai][bj][m][n], 0, 0, 0); \
;     __builtin_amdgcn_s_setprio(0); } while (0)
; #define WAIT_V(n) asm volatile("s_waitcnt vmcnt(" #n ")" ::: "memory")
; #define WAIT_L(n) asm volatile("s_waitcnt lgkmcnt(" #n ")" ::: "memory")
; #define BAR __builtin_amdgcn_s_barrier()
; #define SCHED __builtin_amdgcn_sched_barrier(0)
; __device__ __forceinline__ void gemm256(const u16* __restrict__ A, int lda, const u16* __restrict__ Bt, int ldb, int K,
;                                         f32x4 (&acc)[2][2][4][2], const int g_wid) {
;     ...
;   for (int t = 0; t < nt - 2; t += 2) {
;     LDB(B0, 0, 0); SCHED; LDA(At, 0, 0); STA(SA(1, 1), HALF, t + 1);
;     WAIT_L(8); BAR; WAIT_L(0); MMA(0, 0, At, B0); BAR; SCHED;
;     LDB(B1, 0, 1); STB(SB(0, 0), 0, t + 2);
;     BAR; WAIT_L(0); MMA(0, 1, At, B1); BAR;
;     LDA(At, 0, 1); STA(SA(0, 0), 0, t + 2);
;     BAR; WAIT_L(0); MMA(1, 0, At, B0); BAR; SCHED;
;     STB(SB(0, 1), HALF, t + 2);
;     WAIT_V(6); BAR; MMA(1, 1, At, B1); BAR;
;     LDB(B0, 1, 0); SCHED; LDA(At, 1, 0); STA(SA(0, 1), HALF, t + 2);
;     WAIT_L(8); BAR; WAIT_L(0); MMA(0, 0, At, B0); BAR; SCHED;
;     LDB(B1, 1, 1); STB(SB(1, 0), 0, t + 3);
;     BAR; WAIT_L(0); MMA(0, 1, At, B1); BAR;
;     LDA(At, 1, 1); STA(SA(1, 0), 0, t + 3);
;     BAR; WAIT_L(0); MMA(1, 0, At, B0); BAR; SCHED;
;     STB(SB(1, 1), HALF, t + 3);
;     WAIT_V(6); BAR; MMA(1, 1, At, B1); BAR;
;   }
.LBB0_117:
	ds_read_b128 v[180:183], v176
	ds_read_b128 v[184:187], v176 offset:1024
	ds_read_b128 v[188:191], v176 offset:2048
	ds_read_b128 v[192:195], v176 offset:3072
	v_add_u32_e32 v177, 0xc000, v161
	v_lshl_add_u64 v[244:245], v[142:143], 0, s[26:27]
	v_readfirstlane_b32 s10, v177
	v_lshl_add_u64 v[178:179], v[244:245], 0, s[88:89]
	s_mov_b32 m0, s10
	ds_read_b128 v[196:199], v147
	ds_read_b128 v[200:203], v147 offset:1024
	ds_read_b128 v[204:207], v146
	ds_read_b128 v[208:211], v146 offset:1024
	ds_read_b128 v[212:215], v145
	ds_read_b128 v[216:219], v145 offset:1024
	ds_read_b128 v[220:223], v144
	ds_read_b128 v[224:227], v144 offset:1024
	global_load_lds_dwordx4 v[178:179], off
	v_add_u32_e32 v178, 0xe000, v161
	v_lshl_add_u64 v[246:247], v[138:139], 0, s[26:27]
	s_add_u32 m0, m0, 0x2000
	v_lshl_add_u64 v[228:229], v[246:247], 0, s[88:89]
	global_load_lds_dwordx4 v[228:229], off
	s_waitcnt lgkmcnt(8)
	s_barrier
	s_waitcnt lgkmcnt(0)
	v_mfma_f32_16x16x32_bf16 v[8:11], v[196:199], v[180:183], v[8:11]
	v_mfma_f32_16x16x32_bf16 v[4:7], v[196:199], v[188:191], v[4:7]
	v_mfma_f32_16x16x32_bf16 v[24:27], v[204:207], v[180:183], v[24:27]
	v_mfma_f32_16x16x32_bf16 v[20:23], v[204:207], v[188:191], v[20:23]
	v_mfma_f32_16x16x32_bf16 v[56:59], v[212:215], v[180:183], v[56:59]
	v_mfma_f32_16x16x32_bf16 v[52:55], v[212:215], v[188:191], v[52:55]
	v_mfma_f32_16x16x32_bf16 v[88:91], v[220:223], v[180:183], v[88:91]
	v_mfma_f32_16x16x32_bf16 v[84:87], v[220:223], v[188:191], v[84:87]
	v_mfma_f32_16x16x32_bf16 v[8:11], v[200:203], v[184:187], v[8:11]
	v_mfma_f32_16x16x32_bf16 v[4:7], v[200:203], v[192:195], v[4:7]
	v_mfma_f32_16x16x32_bf16 v[24:27], v[208:211], v[184:187], v[24:27]
	v_mfma_f32_16x16x32_bf16 v[20:23], v[208:211], v[192:195], v[20:23]
	v_mfma_f32_16x16x32_bf16 v[56:59], v[216:219], v[184:187], v[56:59]
	v_mfma_f32_16x16x32_bf16 v[52:55], v[216:219], v[192:195], v[52:55]
	v_mfma_f32_16x16x32_bf16 v[88:91], v[224:227], v[184:187], v[88:91]
	v_mfma_f32_16x16x32_bf16 v[84:87], v[224:227], v[192:195], v[84:87]
	s_barrier
	v_lshl_add_u64 v[248:249], v[136:137], 0, s[26:27]
	v_readfirstlane_b32 s10, v159
	v_lshl_add_u64 v[250:251], v[248:249], 0, s[90:91]
	s_mov_b32 m0, s10
	ds_read_b128 v[228:231], v175
	ds_read_b128 v[232:235], v175 offset:1024
	ds_read_b128 v[236:239], v175 offset:2048
	ds_read_b128 v[240:243], v175 offset:3072
	global_load_lds_dwordx4 v[250:251], off
	v_lshl_add_u64 v[250:251], v[134:135], 0, s[26:27]
	s_add_u32 m0, m0, 0x2000
	v_lshl_add_u64 v[252:253], v[250:251], 0, s[90:91]
	global_load_lds_dwordx4 v[252:253], off
	s_barrier
	s_waitcnt lgkmcnt(0)
	v_mfma_f32_16x16x32_bf16 v[16:19], v[196:199], v[228:231], v[16:19]
	v_mfma_f32_16x16x32_bf16 v[12:15], v[196:199], v[236:239], v[12:15]
	v_mfma_f32_16x16x32_bf16 v[40:43], v[204:207], v[228:231], v[40:43]
	v_mfma_f32_16x16x32_bf16 v[36:39], v[204:207], v[236:239], v[36:39]
	v_mfma_f32_16x16x32_bf16 v[72:75], v[212:215], v[228:231], v[72:75]
	v_mfma_f32_16x16x32_bf16 v[64:67], v[212:215], v[236:239], v[64:67]
	v_mfma_f32_16x16x32_bf16 v[104:107], v[220:223], v[228:231], v[104:107]
	v_mfma_f32_16x16x32_bf16 v[92:95], v[220:223], v[236:239], v[92:95]
	v_mfma_f32_16x16x32_bf16 v[16:19], v[200:203], v[232:235], v[16:19]
	v_mfma_f32_16x16x32_bf16 v[12:15], v[200:203], v[240:243], v[12:15]
	v_mfma_f32_16x16x32_bf16 v[40:43], v[208:211], v[232:235], v[40:43]
	v_mfma_f32_16x16x32_bf16 v[36:39], v[208:211], v[240:243], v[36:39]
	v_mfma_f32_16x16x32_bf16 v[72:75], v[216:219], v[232:235], v[72:75]
	v_mfma_f32_16x16x32_bf16 v[64:67], v[216:219], v[240:243], v[64:67]
	v_mfma_f32_16x16x32_bf16 v[104:107], v[224:227], v[232:235], v[104:107]
	v_mfma_f32_16x16x32_bf16 v[92:95], v[224:227], v[240:243], v[92:95]
	v_readfirstlane_b32 s10, v161
	v_lshl_add_u64 v[252:253], v[244:245], 0, s[92:93]
	s_mov_b32 m0, s10
	s_barrier
	ds_read_b128 v[196:199], v147 offset:16384
	ds_read_b128 v[200:203], v147 offset:17408
	ds_read_b128 v[204:207], v146 offset:16384
	ds_read_b128 v[208:211], v146 offset:17408
	ds_read_b128 v[212:215], v145 offset:16384
	ds_read_b128 v[216:219], v145 offset:17408
	ds_read_b128 v[220:223], v144 offset:16384
	ds_read_b128 v[224:227], v144 offset:17408
	global_load_lds_dwordx4 v[252:253], off
	s_add_u32 m0, m0, 0x2000
	v_lshl_add_u64 v[252:253], v[246:247], 0, s[92:93]
	global_load_lds_dwordx4 v[252:253], off
	s_barrier
	s_waitcnt lgkmcnt(0)
	v_mfma_f32_16x16x32_bf16 v[120:123], v[196:199], v[180:183], v[120:123]
	v_mfma_f32_16x16x32_bf16 v[116:119], v[196:199], v[188:191], v[116:119]
	v_mfma_f32_16x16x32_bf16 v[112:115], v[204:207], v[180:183], v[112:115]
	v_mfma_f32_16x16x32_bf16 v[108:111], v[204:207], v[188:191], v[108:111]
	v_mfma_f32_16x16x32_bf16 v[80:83], v[212:215], v[180:183], v[80:83]
	v_mfma_f32_16x16x32_bf16 v[76:79], v[212:215], v[188:191], v[76:79]
	v_mfma_f32_16x16x32_bf16 v[48:51], v[220:223], v[180:183], v[48:51]
	v_mfma_f32_16x16x32_bf16 v[44:47], v[220:223], v[188:191], v[44:47]
	v_mfma_f32_16x16x32_bf16 v[120:123], v[200:203], v[184:187], v[120:123]
	v_mfma_f32_16x16x32_bf16 v[116:119], v[200:203], v[192:195], v[116:119]
	v_mfma_f32_16x16x32_bf16 v[112:115], v[208:211], v[184:187], v[112:115]
	v_mfma_f32_16x16x32_bf16 v[108:111], v[208:211], v[192:195], v[108:111]
	v_mfma_f32_16x16x32_bf16 v[80:83], v[216:219], v[184:187], v[80:83]
	v_mfma_f32_16x16x32_bf16 v[76:79], v[216:219], v[192:195], v[76:79]
	v_mfma_f32_16x16x32_bf16 v[48:51], v[224:227], v[184:187], v[48:51]
	v_mfma_f32_16x16x32_bf16 v[44:47], v[224:227], v[192:195], v[44:47]
	s_barrier
; #define STA(P, br, kt) STAGE(P, A, aoff0, aoff1, lda, br, kt)
; #define STB(P, br, kt) STAGE(P, Bt, boff0, boff1, ldb, br, kt)
; #define LDA(dst, b, h) _Pragma("unroll") for (int m = 0; m < 4; ++m) _Pragma("unroll") for (int k = 0; k < 2; ++k) \
;     dst[m][k] = *reinterpret_cast<const bf16x8*>((char*)SA(b, h) + lds_byte(wr * 64 + m * 16 + fr, k * 32 + fq * 8))
; #define LDB(dst, b, h) _Pragma("unroll") for (int n = 0; n < 2; ++n) _Pragma("unroll") for (int k = 0; k < 2; ++k) \
;     dst[n][k] = *reinterpret_cast<const bf16x8*>((char*)SB(b, h) + lds_byte(wc * 32 + n * 16 + fr, k * 32 + fq * 8))
; #define MMA(ai, bj, At, Bq) do { __builtin_amdgcn_s_setprio(1); \
;     _Pragma("unroll") for (int m = 0; m < 4; ++m) _Pragma("unroll") for (int n = 0; n < 2; ++n) _Pragma("unroll") for (int k = 0; k < 2; ++k) \
;       acc[ai][bj][m][n] = __builtin_amdgcn_mfma_f32_16x16x32_bf16(At[m][k], Bq[n][k], acc[ai][bj][m][n], 0, 0, 0); \
;     __builtin_amdgcn_s_setprio(0); } while (0)
; #define WAIT_V(n) asm volatile("s_waitcnt vmcnt(" #n ")" ::: "memory")
; #define WAIT_L(n) asm volatile("s_waitcnt lgkmcnt(" #n ")" ::: "memory")
; #define BAR __builtin_amdgcn_s_barrier()
; #define SCHED __builtin_amdgcn_sched_barrier(0)
; __device__ __forceinline__ void gemm256(const u16* __restrict__ A, int lda, const u16* __restrict__ Bt, int ldb, int K,
;                                         f32x4 (&acc)[2][2][4][2], const int g_wid) {
;     ...
;   for (int t = 0; t < nt - 2; t += 2) {
;     LDB(B0, 0, 0); SCHED; LDA(At, 0, 0); STA(SA(1, 1), HALF, t + 1);
;     WAIT_L(8); BAR; WAIT_L(0); MMA(0, 0, At, B0); BAR; SCHED;
;     LDB(B1, 0, 1); STB(SB(0, 0), 0, t + 2);
;     BAR; WAIT_L(0); MMA(0, 1, At, B1); BAR;
;     LDA(At, 0, 1); STA(SA(0, 0), 0, t + 2);
;     BAR; WAIT_L(0); MMA(1, 0, At, B0); BAR; SCHED;
;     STB(SB(0, 1), HALF, t + 2);
;     WAIT_V(6); BAR; MMA(1, 1, At, B1); BAR;
;     LDB(B0, 1, 0); SCHED; LDA(At, 1, 0); STA(SA(0, 1), HALF, t + 2);
;     WAIT_L(8); BAR; WAIT_L(0); MMA(0, 0, At, B0); BAR; SCHED;
;     LDB(B1, 1, 1); STB(SB(1, 0), 0, t + 3);
;     BAR; WAIT_L(0); MMA(0, 1, At, B1); BAR;
;     LDA(At, 1, 1); STA(SA(1, 0), 0, t + 3);
;     BAR; WAIT_L(0); MMA(1, 0, At, B0); BAR; SCHED;
;     STB(SB(1, 1), HALF, t + 3);
;     WAIT_V(6); BAR; MMA(1, 1, At, B1); BAR;
;   }
	v_readfirstlane_b32 s10, v164
	v_lshl_add_u64 v[180:181], v[248:249], 0, s[94:95]
	s_mov_b32 m0, s10
	global_load_lds_dwordx4 v[180:181], off
	s_add_u32 m0, m0, 0x2000
	v_lshl_add_u64 v[180:181], v[250:251], 0, s[94:95]
	global_load_lds_dwordx4 v[180:181], off
	s_waitcnt vmcnt(6)
	s_barrier
	v_mfma_f32_16x16x32_bf16 v[128:131], v[196:199], v[228:231], v[128:131]
	v_mfma_f32_16x16x32_bf16 v[124:127], v[196:199], v[236:239], v[124:127]
	v_mfma_f32_16x16x32_bf16 v[100:103], v[204:207], v[228:231], v[100:103]
	v_mfma_f32_16x16x32_bf16 v[96:99], v[204:207], v[236:239], v[96:99]
	v_mfma_f32_16x16x32_bf16 v[68:71], v[212:215], v[228:231], v[68:71]
	v_mfma_f32_16x16x32_bf16 v[60:63], v[212:215], v[236:239], v[60:63]
	v_mfma_f32_16x16x32_bf16 v[32:35], v[220:223], v[228:231], v[32:35]
	v_mfma_f32_16x16x32_bf16 v[28:31], v[220:223], v[236:239], v[28:31]
	v_mfma_f32_16x16x32_bf16 v[128:131], v[200:203], v[232:235], v[128:131]
	v_mfma_f32_16x16x32_bf16 v[124:127], v[200:203], v[240:243], v[124:127]
	v_mfma_f32_16x16x32_bf16 v[100:103], v[208:211], v[232:235], v[100:103]
	v_mfma_f32_16x16x32_bf16 v[96:99], v[208:211], v[240:243], v[96:99]
	v_mfma_f32_16x16x32_bf16 v[68:71], v[216:219], v[232:235], v[68:71]
	v_mfma_f32_16x16x32_bf16 v[60:63], v[216:219], v[240:243], v[60:63]
	v_mfma_f32_16x16x32_bf16 v[32:35], v[224:227], v[232:235], v[32:35]
	v_mfma_f32_16x16x32_bf16 v[28:31], v[224:227], v[240:243], v[28:31]
	s_barrier
	ds_read_b128 v[180:183], v168
	ds_read_b128 v[184:187], v168 offset:1024
	ds_read_b128 v[188:191], v168 offset:2048
	ds_read_b128 v[192:195], v168 offset:3072
	v_readfirstlane_b32 s10, v166
	v_lshl_add_u64 v[228:229], v[244:245], 0, s[96:97]
	s_mov_b32 m0, s10
	ds_read_b128 v[196:199], v147 offset:32768
	ds_read_b128 v[200:203], v147 offset:33792
	ds_read_b128 v[204:207], v146 offset:32768
	ds_read_b128 v[208:211], v146 offset:33792
	ds_read_b128 v[212:215], v145 offset:32768
	ds_read_b128 v[216:219], v145 offset:33792
	ds_read_b128 v[220:223], v144 offset:32768
	ds_read_b128 v[224:227], v144 offset:33792
	global_load_lds_dwordx4 v[228:229], off
	s_add_u32 m0, m0, 0x2000
	v_lshl_add_u64 v[228:229], v[246:247], 0, s[96:97]
	global_load_lds_dwordx4 v[228:229], off
	s_waitcnt lgkmcnt(8)
	s_barrier
	s_waitcnt lgkmcnt(0)
	v_mfma_f32_16x16x32_bf16 v[8:11], v[196:199], v[180:183], v[8:11]
	v_mfma_f32_16x16x32_bf16 v[4:7], v[196:199], v[188:191], v[4:7]
	v_mfma_f32_16x16x32_bf16 v[24:27], v[204:207], v[180:183], v[24:27]
	v_mfma_f32_16x16x32_bf16 v[20:23], v[204:207], v[188:191], v[20:23]
	v_mfma_f32_16x16x32_bf16 v[56:59], v[212:215], v[180:183], v[56:59]
	v_mfma_f32_16x16x32_bf16 v[52:55], v[212:215], v[188:191], v[52:55]
	v_mfma_f32_16x16x32_bf16 v[88:91], v[220:223], v[180:183], v[88:91]
	v_mfma_f32_16x16x32_bf16 v[84:87], v[220:223], v[188:191], v[84:87]
	v_mfma_f32_16x16x32_bf16 v[8:11], v[200:203], v[184:187], v[8:11]
	v_mfma_f32_16x16x32_bf16 v[4:7], v[200:203], v[192:195], v[4:7]
	v_mfma_f32_16x16x32_bf16 v[24:27], v[208:211], v[184:187], v[24:27]
	v_mfma_f32_16x16x32_bf16 v[20:23], v[208:211], v[192:195], v[20:23]
	v_mfma_f32_16x16x32_bf16 v[56:59], v[216:219], v[184:187], v[56:59]
	v_mfma_f32_16x16x32_bf16 v[52:55], v[216:219], v[192:195], v[52:55]
	v_mfma_f32_16x16x32_bf16 v[88:91], v[224:227], v[184:187], v[88:91]
	v_mfma_f32_16x16x32_bf16 v[84:87], v[224:227], v[192:195], v[84:87]
	s_barrier
	v_readfirstlane_b32 s10, v169
	v_lshl_add_u64 v[252:253], v[248:249], 0, s[66:67]
	s_mov_b32 m0, s10
	ds_read_b128 v[228:231], v162
	ds_read_b128 v[232:235], v162 offset:1024
	ds_read_b128 v[236:239], v162 offset:2048
	ds_read_b128 v[240:243], v162 offset:3072
	global_load_lds_dwordx4 v[252:253], off
	s_add_u32 m0, m0, 0x2000
	v_lshl_add_u64 v[252:253], v[250:251], 0, s[66:67]
	global_load_lds_dwordx4 v[252:253], off
	s_barrier
	s_waitcnt lgkmcnt(0)
	v_mfma_f32_16x16x32_bf16 v[16:19], v[196:199], v[228:231], v[16:19]
	v_mfma_f32_16x16x32_bf16 v[12:15], v[196:199], v[236:239], v[12:15]
	v_mfma_f32_16x16x32_bf16 v[40:43], v[204:207], v[228:231], v[40:43]
	v_mfma_f32_16x16x32_bf16 v[36:39], v[204:207], v[236:239], v[36:39]
	v_mfma_f32_16x16x32_bf16 v[72:75], v[212:215], v[228:231], v[72:75]
	v_mfma_f32_16x16x32_bf16 v[64:67], v[212:215], v[236:239], v[64:67]
	v_mfma_f32_16x16x32_bf16 v[104:107], v[220:223], v[228:231], v[104:107]
	v_mfma_f32_16x16x32_bf16 v[92:95], v[220:223], v[236:239], v[92:95]
	v_mfma_f32_16x16x32_bf16 v[16:19], v[200:203], v[232:235], v[16:19]
	v_mfma_f32_16x16x32_bf16 v[12:15], v[200:203], v[240:243], v[12:15]
	v_mfma_f32_16x16x32_bf16 v[40:43], v[208:211], v[232:235], v[40:43]
	v_mfma_f32_16x16x32_bf16 v[36:39], v[208:211], v[240:243], v[36:39]
	v_mfma_f32_16x16x32_bf16 v[72:75], v[216:219], v[232:235], v[72:75]
	v_mfma_f32_16x16x32_bf16 v[64:67], v[216:219], v[240:243], v[64:67]
	v_mfma_f32_16x16x32_bf16 v[104:107], v[224:227], v[232:235], v[104:107]
	v_mfma_f32_16x16x32_bf16 v[92:95], v[224:227], v[240:243], v[92:95]
	v_readfirstlane_b32 s10, v171
	v_lshl_add_u64 v[244:245], v[244:245], 0, s[62:63]
	s_mov_b32 m0, s10
	s_barrier
	ds_read_b128 v[196:199], v147 offset:49152
	ds_read_b128 v[200:203], v147 offset:50176
	ds_read_b128 v[204:207], v146 offset:49152
	ds_read_b128 v[208:211], v146 offset:50176
	ds_read_b128 v[212:215], v145 offset:49152
	ds_read_b128 v[216:219], v145 offset:50176
	ds_read_b128 v[220:223], v144 offset:49152
	ds_read_b128 v[224:227], v144 offset:50176
	global_load_lds_dwordx4 v[244:245], off
	s_add_u32 m0, m0, 0x2000
	v_lshl_add_u64 v[244:245], v[246:247], 0, s[62:63]
	global_load_lds_dwordx4 v[244:245], off
	s_barrier
; #define STA(P, br, kt) STAGE(P, A, aoff0, aoff1, lda, br, kt)
; #define STB(P, br, kt) STAGE(P, Bt, boff0, boff1, ldb, br, kt)
; #define LDA(dst, b, h) _Pragma("unroll") for (int m = 0; m < 4; ++m) _Pragma("unroll") for (int k = 0; k < 2; ++k) \
;     dst[m][k] = *reinterpret_cast<const bf16x8*>((char*)SA(b, h) + lds_byte(wr * 64 + m * 16 + fr, k * 32 + fq * 8))
; #define LDB(dst, b, h) _Pragma("unroll") for (int n = 0; n < 2; ++n) _Pragma("unroll") for (int k = 0; k < 2; ++k) \
;     dst[n][k] = *reinterpret_cast<const bf16x8*>((char*)SB(b, h) + lds_byte(wc * 32 + n * 16 + fr, k * 32 + fq * 8))
; #define WAIT_V(n) asm volatile("s_waitcnt vmcnt(" #n ")" ::: "memory")
; #define WAIT_L(n) asm volatile("s_waitcnt lgkmcnt(" #n ")" ::: "memory")
; #define BAR __builtin_amdgcn_s_barrier()
; __device__ __forceinline__ void gemm256(const u16* __restrict__ A, int lda, const u16* __restrict__ Bt, int ldb, int K,
;                                         f32x4 (&acc)[2][2][4][2], const int g_wid) {
;     ...
;   for (int t = 0; t < nt - 2; t += 2) {
;     LDB(B0, 0, 0); SCHED; LDA(At, 0, 0); STA(SA(1, 1), HALF, t + 1);
;     WAIT_L(8); BAR; WAIT_L(0); MMA(0, 0, At, B0); BAR; SCHED;
;     LDB(B1, 0, 1); STB(SB(0, 0), 0, t + 2);
;     BAR; WAIT_L(0); MMA(0, 1, At, B1); BAR;
;     LDA(At, 0, 1); STA(SA(0, 0), 0, t + 2);
;     BAR; WAIT_L(0); MMA(1, 0, At, B0); BAR; SCHED;
;     STB(SB(0, 1), HALF, t + 2);
;     WAIT_V(6); BAR; MMA(1, 1, At, B1); BAR;
;     LDB(B0, 1, 0); SCHED; LDA(At, 1, 0); STA(SA(0, 1), HALF, t + 2);
;     WAIT_L(8); BAR; WAIT_L(0); MMA(0, 0, At, B0); BAR; SCHED;
;     LDB(B1, 1, 1); STB(SB(1, 0), 0, t + 3);
;     BAR; WAIT_L(0); MMA(0, 1, At, B1); BAR;
;     LDA(At, 1, 1); STA(SA(1, 0), 0, t + 3);
;     BAR; WAIT_L(0); MMA(1, 0, At, B0); BAR; SCHED;
;     STB(SB(1, 1), HALF, t + 3);
;     WAIT_V(6); BAR; MMA(1, 1, At, B1); BAR;
;   }
;   { LDB(B0, 0, 0); LDA(At, 0, 0); STA(SA(1, 1), HALF, nt - 1);
;     BAR; WAIT_L(0); MMA(0, 0, At, B0); BAR;
;     LDB(B1, 0, 1); BAR; WAIT_L(0); MMA(0, 1, At, B1); BAR;
;     LDA(At, 0, 1); WAIT_V(4); BAR; WAIT_L(0); MMA(1, 0, At, B0); MMA(1, 1, At, B1); BAR; }
;   { LDB(B0, 1, 0); LDA(At, 1, 0); WAIT_V(2); BAR; WAIT_L(0); MMA(0, 0, At, B0); BAR;
;     LDB(B1, 1, 1); WAIT_V(0); BAR; WAIT_L(0); MMA(0, 1, At, B1); BAR;
;     LDA(At, 1, 1); BAR; WAIT_L(0); MMA(1, 0, At, B0); MMA(1, 1, At, B1); BAR; }
;   if (wr == 0) BAR;
	s_waitcnt lgkmcnt(0)
	v_mfma_f32_16x16x32_bf16 v[120:123], v[196:199], v[180:183], v[120:123]
	v_mfma_f32_16x16x32_bf16 v[116:119], v[196:199], v[188:191], v[116:119]
	v_mfma_f32_16x16x32_bf16 v[112:115], v[204:207], v[180:183], v[112:115]
	v_mfma_f32_16x16x32_bf16 v[108:111], v[204:207], v[188:191], v[108:111]
	v_mfma_f32_16x16x32_bf16 v[80:83], v[212:215], v[180:183], v[80:83]
	v_mfma_f32_16x16x32_bf16 v[76:79], v[212:215], v[188:191], v[76:79]
	v_mfma_f32_16x16x32_bf16 v[48:51], v[220:223], v[180:183], v[48:51]
	v_mfma_f32_16x16x32_bf16 v[44:47], v[220:223], v[188:191], v[44:47]
	v_mfma_f32_16x16x32_bf16 v[120:123], v[200:203], v[184:187], v[120:123]
	v_mfma_f32_16x16x32_bf16 v[116:119], v[200:203], v[192:195], v[116:119]
	v_mfma_f32_16x16x32_bf16 v[112:115], v[208:211], v[184:187], v[112:115]
	v_mfma_f32_16x16x32_bf16 v[108:111], v[208:211], v[192:195], v[108:111]
	v_mfma_f32_16x16x32_bf16 v[80:83], v[216:219], v[184:187], v[80:83]
	v_mfma_f32_16x16x32_bf16 v[76:79], v[216:219], v[192:195], v[76:79]
	v_mfma_f32_16x16x32_bf16 v[48:51], v[224:227], v[184:187], v[48:51]
	v_mfma_f32_16x16x32_bf16 v[44:47], v[224:227], v[192:195], v[44:47]
	s_barrier
	v_readfirstlane_b32 s10, v173
	v_lshl_add_u64 v[180:181], v[248:249], 0, s[56:57]
	s_mov_b32 m0, s10
	global_load_lds_dwordx4 v[180:181], off
	s_add_u32 m0, m0, 0x2000
	v_lshl_add_u64 v[180:181], v[250:251], 0, s[56:57]
	global_load_lds_dwordx4 v[180:181], off
	s_waitcnt vmcnt(6)
	s_barrier
	v_mfma_f32_16x16x32_bf16 v[128:131], v[196:199], v[228:231], v[128:131]
	v_mfma_f32_16x16x32_bf16 v[124:127], v[196:199], v[236:239], v[124:127]
	v_mfma_f32_16x16x32_bf16 v[100:103], v[204:207], v[228:231], v[100:103]
	v_mfma_f32_16x16x32_bf16 v[96:99], v[204:207], v[236:239], v[96:99]
	v_mfma_f32_16x16x32_bf16 v[68:71], v[212:215], v[228:231], v[68:71]
	v_mfma_f32_16x16x32_bf16 v[60:63], v[212:215], v[236:239], v[60:63]
	v_mfma_f32_16x16x32_bf16 v[32:35], v[220:223], v[228:231], v[32:35]
	v_mfma_f32_16x16x32_bf16 v[28:31], v[220:223], v[236:239], v[28:31]
	v_mfma_f32_16x16x32_bf16 v[128:131], v[200:203], v[232:235], v[128:131]
	v_mfma_f32_16x16x32_bf16 v[124:127], v[200:203], v[240:243], v[124:127]
	v_mfma_f32_16x16x32_bf16 v[100:103], v[208:211], v[232:235], v[100:103]
	v_mfma_f32_16x16x32_bf16 v[96:99], v[208:211], v[240:243], v[96:99]
	v_mfma_f32_16x16x32_bf16 v[68:71], v[216:219], v[232:235], v[68:71]
	v_mfma_f32_16x16x32_bf16 v[60:63], v[216:219], v[240:243], v[60:63]
	v_mfma_f32_16x16x32_bf16 v[32:35], v[224:227], v[232:235], v[32:35]
	v_mfma_f32_16x16x32_bf16 v[28:31], v[224:227], v[240:243], v[28:31]
	s_add_i32 s28, s28, 2
	s_add_u32 s26, s26, 0x100
	s_addc_u32 s27, s27, 0
	s_cmp_lt_u32 s28, 4
	s_barrier
	s_cbranch_scc1 .LBB0_117
	s_add_u32 s24, s24, 0x20380
	s_addc_u32 s25, s25, 0
	v_readfirstlane_b32 s10, v177
	v_lshl_add_u64 v[132:133], v[132:133], 1, s[24:25]
	s_mov_b32 m0, s10
	v_readfirstlane_b32 s10, v178
	ds_read_b128 v[134:137], v176
	ds_read_b128 v[164:167], v176 offset:1024
	ds_read_b128 v[170:173], v176 offset:2048
	ds_read_b128 v[180:183], v176 offset:3072
	ds_read_b128 v[184:187], v147
	ds_read_b128 v[188:191], v147 offset:1024
	ds_read_b128 v[192:195], v146
	ds_read_b128 v[196:199], v146 offset:1024
	ds_read_b128 v[200:203], v145
	ds_read_b128 v[204:207], v145 offset:1024
	ds_read_b128 v[208:211], v144
	ds_read_b128 v[212:215], v144 offset:1024
	global_load_lds_dwordx4 v[132:133], off
	v_lshl_add_u64 v[2:3], v[2:3], 1, s[24:25]
	s_mov_b32 m0, s10
	s_nop 0
	global_load_lds_dwordx4 v[2:3], off
	s_barrier
	s_waitcnt lgkmcnt(0)
	v_mfma_f32_16x16x32_bf16 v[8:11], v[184:187], v[134:137], v[8:11]
	v_mfma_f32_16x16x32_bf16 v[2:5], v[184:187], v[170:173], v[4:7]
	v_mfma_f32_16x16x32_bf16 v[24:27], v[192:195], v[134:137], v[24:27]
	v_mfma_f32_16x16x32_bf16 v[20:23], v[192:195], v[170:173], v[20:23]
	v_mfma_f32_16x16x32_bf16 v[56:59], v[200:203], v[134:137], v[56:59]
	v_mfma_f32_16x16x32_bf16 v[52:55], v[200:203], v[170:173], v[52:55]
	v_mfma_f32_16x16x32_bf16 v[88:91], v[208:211], v[134:137], v[88:91]
	v_mfma_f32_16x16x32_bf16 v[84:87], v[208:211], v[170:173], v[84:87]
	v_mfma_f32_16x16x32_bf16 v[8:11], v[188:191], v[164:167], v[8:11]
	v_mfma_f32_16x16x32_bf16 v[2:5], v[188:191], v[180:183], v[2:5]
	v_mfma_f32_16x16x32_bf16 v[24:27], v[196:199], v[164:167], v[24:27]
	v_mfma_f32_16x16x32_bf16 v[20:23], v[196:199], v[180:183], v[20:23]
	v_mfma_f32_16x16x32_bf16 v[56:59], v[204:207], v[164:167], v[56:59]
	v_mfma_f32_16x16x32_bf16 v[52:55], v[204:207], v[180:183], v[52:55]
	v_mfma_f32_16x16x32_bf16 v[88:91], v[212:215], v[164:167], v[88:91]
	v_mfma_f32_16x16x32_bf16 v[84:87], v[212:215], v[180:183], v[84:87]
	s_barrier
	ds_read_b128 v[176:179], v175
	ds_read_b128 v[216:219], v175 offset:1024
	ds_read_b128 v[220:223], v175 offset:2048
	ds_read_b128 v[224:227], v175 offset:3072
	s_barrier
	s_waitcnt lgkmcnt(0)
	v_mfma_f32_16x16x32_bf16 v[16:19], v[184:187], v[176:179], v[16:19]
	v_mfma_f32_16x16x32_bf16 v[12:15], v[184:187], v[220:223], v[12:15]
	v_mfma_f32_16x16x32_bf16 v[40:43], v[192:195], v[176:179], v[40:43]
	v_mfma_f32_16x16x32_bf16 v[36:39], v[192:195], v[220:223], v[36:39]
	v_mfma_f32_16x16x32_bf16 v[72:75], v[200:203], v[176:179], v[72:75]
	v_mfma_f32_16x16x32_bf16 v[64:67], v[200:203], v[220:223], v[64:67]
	v_mfma_f32_16x16x32_bf16 v[104:107], v[208:211], v[176:179], v[104:107]
	v_mfma_f32_16x16x32_bf16 v[92:95], v[208:211], v[220:223], v[92:95]
	v_mfma_f32_16x16x32_bf16 v[16:19], v[188:191], v[216:219], v[16:19]
	v_mfma_f32_16x16x32_bf16 v[12:15], v[188:191], v[224:227], v[12:15]
	v_mfma_f32_16x16x32_bf16 v[40:43], v[196:199], v[216:219], v[40:43]
	v_mfma_f32_16x16x32_bf16 v[36:39], v[196:199], v[224:227], v[36:39]
	v_mfma_f32_16x16x32_bf16 v[72:75], v[204:207], v[216:219], v[72:75]
	v_mfma_f32_16x16x32_bf16 v[64:67], v[204:207], v[224:227], v[64:67]
	v_mfma_f32_16x16x32_bf16 v[104:107], v[212:215], v[216:219], v[104:107]
	v_mfma_f32_16x16x32_bf16 v[92:95], v[212:215], v[224:227], v[92:95]
	s_barrier
; #define STA(P, br, kt) STAGE(P, A, aoff0, aoff1, lda, br, kt)
; #define LDA(dst, b, h) _Pragma("unroll") for (int m = 0; m < 4; ++m) _Pragma("unroll") for (int k = 0; k < 2; ++k) \
;     dst[m][k] = *reinterpret_cast<const bf16x8*>((char*)SA(b, h) + lds_byte(wr * 64 + m * 16 + fr, k * 32 + fq * 8))
; #define LDB(dst, b, h) _Pragma("unroll") for (int n = 0; n < 2; ++n) _Pragma("unroll") for (int k = 0; k < 2; ++k) \
;     dst[n][k] = *reinterpret_cast<const bf16x8*>((char*)SB(b, h) + lds_byte(wc * 32 + n * 16 + fr, k * 32 + fq * 8))
; #define MMA(ai, bj, At, Bq) do { __builtin_amdgcn_s_setprio(1); \
;     _Pragma("unroll") for (int m = 0; m < 4; ++m) _Pragma("unroll") for (int n = 0; n < 2; ++n) _Pragma("unroll") for (int k = 0; k < 2; ++k) \
;       acc[ai][bj][m][n] = __builtin_amdgcn_mfma_f32_16x16x32_bf16(At[m][k], Bq[n][k], acc[ai][bj][m][n], 0, 0, 0); \
;     __builtin_amdgcn_s_setprio(0); } while (0)
; #define WAIT_V(n) asm volatile("s_waitcnt vmcnt(" #n ")" ::: "memory")
; #define WAIT_L(n) asm volatile("s_waitcnt lgkmcnt(" #n ")" ::: "memory")
; #define BAR __builtin_amdgcn_s_barrier()
; __device__ __forceinline__ void gemm256(const u16* __restrict__ A, int lda, const u16* __restrict__ Bt, int ldb, int K,
;                                         f32x4 (&acc)[2][2][4][2], const int g_wid) {
;     ...
;   { LDB(B0, 0, 0); LDA(At, 0, 0); STA(SA(1, 1), HALF, nt - 1);
;     BAR; WAIT_L(0); MMA(0, 0, At, B0); BAR;
;     LDB(B1, 0, 1); BAR; WAIT_L(0); MMA(0, 1, At, B1); BAR;
;     LDA(At, 0, 1); WAIT_V(4); BAR; WAIT_L(0); MMA(1, 0, At, B0); MMA(1, 1, At, B1); BAR; }
;   { LDB(B0, 1, 0); LDA(At, 1, 0); WAIT_V(2); BAR; WAIT_L(0); MMA(0, 0, At, B0); BAR;
;     LDB(B1, 1, 1); WAIT_V(0); BAR; WAIT_L(0); MMA(0, 1, At, B1); BAR;
;     LDA(At, 1, 1); BAR; WAIT_L(0); MMA(1, 0, At, B0); MMA(1, 1, At, B1); BAR; }
	ds_read_b128 v[184:187], v147 offset:16384
	ds_read_b128 v[188:191], v147 offset:17408
	ds_read_b128 v[192:195], v146 offset:16384
	ds_read_b128 v[196:199], v146 offset:17408
	ds_read_b128 v[200:203], v145 offset:16384
	ds_read_b128 v[204:207], v145 offset:17408
	ds_read_b128 v[208:211], v144 offset:16384
	ds_read_b128 v[212:215], v144 offset:17408
	s_waitcnt vmcnt(4)
	s_barrier
	s_waitcnt lgkmcnt(0)
	v_mfma_f32_16x16x32_bf16 v[120:123], v[184:187], v[134:137], v[120:123]
	v_mfma_f32_16x16x32_bf16 v[116:119], v[184:187], v[170:173], v[116:119]
	v_mfma_f32_16x16x32_bf16 v[112:115], v[192:195], v[134:137], v[112:115]
	v_mfma_f32_16x16x32_bf16 v[108:111], v[192:195], v[170:173], v[108:111]
	v_mfma_f32_16x16x32_bf16 v[80:83], v[200:203], v[134:137], v[80:83]
	v_mfma_f32_16x16x32_bf16 v[76:79], v[200:203], v[170:173], v[76:79]
	v_mfma_f32_16x16x32_bf16 v[48:51], v[208:211], v[134:137], v[48:51]
	v_mfma_f32_16x16x32_bf16 v[44:47], v[208:211], v[170:173], v[44:47]
	v_mfma_f32_16x16x32_bf16 v[120:123], v[188:191], v[164:167], v[120:123]
	v_mfma_f32_16x16x32_bf16 v[116:119], v[188:191], v[180:183], v[116:119]
	v_mfma_f32_16x16x32_bf16 v[112:115], v[196:199], v[164:167], v[112:115]
	v_mfma_f32_16x16x32_bf16 v[108:111], v[196:199], v[180:183], v[108:111]
	v_mfma_f32_16x16x32_bf16 v[80:83], v[204:207], v[164:167], v[80:83]
	v_mfma_f32_16x16x32_bf16 v[76:79], v[204:207], v[180:183], v[76:79]
	v_mfma_f32_16x16x32_bf16 v[48:51], v[212:215], v[164:167], v[48:51]
	v_mfma_f32_16x16x32_bf16 v[44:47], v[212:215], v[180:183], v[44:47]
	v_mfma_f32_16x16x32_bf16 v[128:131], v[184:187], v[176:179], v[128:131]
	v_mfma_f32_16x16x32_bf16 v[124:127], v[184:187], v[220:223], v[124:127]
	v_mfma_f32_16x16x32_bf16 v[100:103], v[192:195], v[176:179], v[100:103]
	v_mfma_f32_16x16x32_bf16 v[96:99], v[192:195], v[220:223], v[96:99]
	v_mfma_f32_16x16x32_bf16 v[68:71], v[200:203], v[176:179], v[68:71]
	v_mfma_f32_16x16x32_bf16 v[60:63], v[200:203], v[220:223], v[60:63]
	v_mfma_f32_16x16x32_bf16 v[32:35], v[208:211], v[176:179], v[32:35]
	v_mfma_f32_16x16x32_bf16 v[28:31], v[208:211], v[220:223], v[28:31]
	v_mfma_f32_16x16x32_bf16 v[128:131], v[188:191], v[216:219], v[128:131]
	v_mfma_f32_16x16x32_bf16 v[124:127], v[188:191], v[224:227], v[124:127]
	v_mfma_f32_16x16x32_bf16 v[100:103], v[196:199], v[216:219], v[100:103]
	v_mfma_f32_16x16x32_bf16 v[96:99], v[196:199], v[224:227], v[96:99]
	v_mfma_f32_16x16x32_bf16 v[68:71], v[204:207], v[216:219], v[68:71]
	v_mfma_f32_16x16x32_bf16 v[60:63], v[204:207], v[224:227], v[60:63]
	v_mfma_f32_16x16x32_bf16 v[32:35], v[212:215], v[216:219], v[32:35]
	v_mfma_f32_16x16x32_bf16 v[28:31], v[212:215], v[224:227], v[28:31]
	s_barrier
	ds_read_b128 v[132:135], v168
	ds_read_b128 v[136:139], v168 offset:1024
	ds_read_b128 v[164:167], v168 offset:2048
	ds_read_b128 v[168:171], v168 offset:3072
	ds_read_b128 v[172:175], v147 offset:32768
	ds_read_b128 v[176:179], v147 offset:33792
	ds_read_b128 v[180:183], v146 offset:32768
	ds_read_b128 v[184:187], v146 offset:33792
	ds_read_b128 v[188:191], v145 offset:32768
	ds_read_b128 v[192:195], v145 offset:33792
	ds_read_b128 v[196:199], v144 offset:32768
	ds_read_b128 v[200:203], v144 offset:33792
	s_waitcnt vmcnt(2)
	s_barrier
	s_waitcnt lgkmcnt(0)
	v_mfma_f32_16x16x32_bf16 v[6:9], v[172:175], v[132:135], v[8:11]
	v_mfma_f32_16x16x32_bf16 v[2:5], v[172:175], v[164:167], v[2:5]
	v_mfma_f32_16x16x32_bf16 v[24:27], v[180:183], v[132:135], v[24:27]
	v_mfma_f32_16x16x32_bf16 v[20:23], v[180:183], v[164:167], v[20:23]
	v_mfma_f32_16x16x32_bf16 v[56:59], v[188:191], v[132:135], v[56:59]
	v_mfma_f32_16x16x32_bf16 v[52:55], v[188:191], v[164:167], v[52:55]
	v_mfma_f32_16x16x32_bf16 v[88:91], v[196:199], v[132:135], v[88:91]
	v_mfma_f32_16x16x32_bf16 v[84:87], v[196:199], v[164:167], v[84:87]
	v_mfma_f32_16x16x32_bf16 v[8:11], v[176:179], v[136:139], v[6:9]
	v_mfma_f32_16x16x32_bf16 v[4:7], v[176:179], v[168:171], v[2:5]
	v_mfma_f32_16x16x32_bf16 v[24:27], v[184:187], v[136:139], v[24:27]
	v_mfma_f32_16x16x32_bf16 v[20:23], v[184:187], v[168:171], v[20:23]
	v_mfma_f32_16x16x32_bf16 v[56:59], v[192:195], v[136:139], v[56:59]
	v_mfma_f32_16x16x32_bf16 v[52:55], v[192:195], v[168:171], v[52:55]
	v_mfma_f32_16x16x32_bf16 v[88:91], v[200:203], v[136:139], v[88:91]
	v_mfma_f32_16x16x32_bf16 v[84:87], v[200:203], v[168:171], v[84:87]
	s_barrier
; #define STA(P, br, kt) STAGE(P, A, aoff0, aoff1, lda, br, kt)
; #define LDA(dst, b, h) _Pragma("unroll") for (int m = 0; m < 4; ++m) _Pragma("unroll") for (int k = 0; k < 2; ++k) \
;     dst[m][k] = *reinterpret_cast<const bf16x8*>((char*)SA(b, h) + lds_byte(wr * 64 + m * 16 + fr, k * 32 + fq * 8))
; #define LDB(dst, b, h) _Pragma("unroll") for (int n = 0; n < 2; ++n) _Pragma("unroll") for (int k = 0; k < 2; ++k) \
;     dst[n][k] = *reinterpret_cast<const bf16x8*>((char*)SB(b, h) + lds_byte(wc * 32 + n * 16 + fr, k * 32 + fq * 8))
; #define MMA(ai, bj, At, Bq) do { __builtin_amdgcn_s_setprio(1); \
;     _Pragma("unroll") for (int m = 0; m < 4; ++m) _Pragma("unroll") for (int n = 0; n < 2; ++n) _Pragma("unroll") for (int k = 0; k < 2; ++k) \
;       acc[ai][bj][m][n] = __builtin_amdgcn_mfma_f32_16x16x32_bf16(At[m][k], Bq[n][k], acc[ai][bj][m][n], 0, 0, 0); \
;     __builtin_amdgcn_s_setprio(0); } while (0)
; #define WAIT_V(n) asm volatile("s_waitcnt vmcnt(" #n ")" ::: "memory")
; #define WAIT_L(n) asm volatile("s_waitcnt lgkmcnt(" #n ")" ::: "memory")
; #define BAR __builtin_amdgcn_s_barrier()
; __device__ __forceinline__ void gemm256(const u16* __restrict__ A, int lda, const u16* __restrict__ Bt, int ldb, int K,
;                                         f32x4 (&acc)[2][2][4][2], const int g_wid) {
;     ...
;   { LDB(B0, 0, 0); LDA(At, 0, 0); STA(SA(1, 1), HALF, nt - 1);
;     BAR; WAIT_L(0); MMA(0, 0, At, B0); BAR;
;     LDB(B1, 0, 1); BAR; WAIT_L(0); MMA(0, 1, At, B1); BAR;
;     LDA(At, 0, 1); WAIT_V(4); BAR; WAIT_L(0); MMA(1, 0, At, B0); MMA(1, 1, At, B1); BAR; }
;   { LDB(B0, 1, 0); LDA(At, 1, 0); WAIT_V(2); BAR; WAIT_L(0); MMA(0, 0, At, B0); BAR;
;     LDB(B1, 1, 1); WAIT_V(0); BAR; WAIT_L(0); MMA(0, 1, At, B1); BAR;
;     LDA(At, 1, 1); BAR; WAIT_L(0); MMA(1, 0, At, B0); MMA(1, 1, At, B1); BAR; }
;   if (wr == 0) BAR;
	ds_read_b128 v[204:207], v162
	ds_read_b128 v[208:211], v162 offset:1024
	ds_read_b128 v[212:215], v162 offset:2048
	ds_read_b128 v[160:163], v162 offset:3072
	s_waitcnt vmcnt(0)
	s_barrier
	s_waitcnt lgkmcnt(0)
	v_mfma_f32_16x16x32_bf16 v[16:19], v[172:175], v[204:207], v[16:19]
	v_mfma_f32_16x16x32_bf16 v[12:15], v[172:175], v[212:215], v[12:15]
	v_mfma_f32_16x16x32_bf16 v[40:43], v[180:183], v[204:207], v[40:43]
	v_mfma_f32_16x16x32_bf16 v[36:39], v[180:183], v[212:215], v[36:39]
	v_mfma_f32_16x16x32_bf16 v[72:75], v[188:191], v[204:207], v[72:75]
	v_mfma_f32_16x16x32_bf16 v[64:67], v[188:191], v[212:215], v[64:67]
	v_mfma_f32_16x16x32_bf16 v[104:107], v[196:199], v[204:207], v[104:107]
	v_mfma_f32_16x16x32_bf16 v[92:95], v[196:199], v[212:215], v[92:95]
	v_mfma_f32_16x16x32_bf16 v[16:19], v[176:179], v[208:211], v[16:19]
	v_mfma_f32_16x16x32_bf16 v[12:15], v[176:179], v[160:163], v[12:15]
	v_mfma_f32_16x16x32_bf16 v[40:43], v[184:187], v[208:211], v[40:43]
	v_mfma_f32_16x16x32_bf16 v[36:39], v[184:187], v[160:163], v[36:39]
	v_mfma_f32_16x16x32_bf16 v[72:75], v[192:195], v[208:211], v[72:75]
	v_mfma_f32_16x16x32_bf16 v[64:67], v[192:195], v[160:163], v[64:67]
	v_mfma_f32_16x16x32_bf16 v[104:107], v[200:203], v[208:211], v[104:107]
	v_mfma_f32_16x16x32_bf16 v[92:95], v[200:203], v[160:163], v[92:95]
	s_barrier
	ds_read_b128 v[172:175], v147 offset:49152
	ds_read_b128 v[176:179], v147 offset:50176
	ds_read_b128 v[180:183], v146 offset:49152
	ds_read_b128 v[184:187], v146 offset:50176
	ds_read_b128 v[188:191], v145 offset:49152
	ds_read_b128 v[192:195], v145 offset:50176
	ds_read_b128 v[196:199], v144 offset:49152
	ds_read_b128 v[142:145], v144 offset:50176
	s_barrier
	s_waitcnt lgkmcnt(0)
	v_mfma_f32_16x16x32_bf16 v[120:123], v[172:175], v[132:135], v[120:123]
	v_mfma_f32_16x16x32_bf16 v[116:119], v[172:175], v[164:167], v[116:119]
	v_mfma_f32_16x16x32_bf16 v[112:115], v[180:183], v[132:135], v[112:115]
	v_mfma_f32_16x16x32_bf16 v[108:111], v[180:183], v[164:167], v[108:111]
	v_mfma_f32_16x16x32_bf16 v[80:83], v[188:191], v[132:135], v[80:83]
	v_mfma_f32_16x16x32_bf16 v[76:79], v[188:191], v[164:167], v[76:79]
	v_mfma_f32_16x16x32_bf16 v[48:51], v[196:199], v[132:135], v[48:51]
	v_mfma_f32_16x16x32_bf16 v[44:47], v[196:199], v[164:167], v[44:47]
	v_mfma_f32_16x16x32_bf16 v[120:123], v[176:179], v[136:139], v[120:123]
	v_mfma_f32_16x16x32_bf16 v[116:119], v[176:179], v[168:171], v[116:119]
	v_mfma_f32_16x16x32_bf16 v[112:115], v[184:187], v[136:139], v[112:115]
	v_mfma_f32_16x16x32_bf16 v[108:111], v[184:187], v[168:171], v[108:111]
	v_mfma_f32_16x16x32_bf16 v[80:83], v[192:195], v[136:139], v[80:83]
	v_mfma_f32_16x16x32_bf16 v[76:79], v[192:195], v[168:171], v[76:79]
	v_mfma_f32_16x16x32_bf16 v[48:51], v[142:145], v[136:139], v[48:51]
	v_mfma_f32_16x16x32_bf16 v[44:47], v[142:145], v[168:171], v[44:47]
	v_mfma_f32_16x16x32_bf16 v[128:131], v[172:175], v[204:207], v[128:131]
	v_mfma_f32_16x16x32_bf16 v[124:127], v[172:175], v[212:215], v[124:127]
	v_mfma_f32_16x16x32_bf16 v[100:103], v[180:183], v[204:207], v[100:103]
	v_mfma_f32_16x16x32_bf16 v[96:99], v[180:183], v[212:215], v[96:99]
	v_mfma_f32_16x16x32_bf16 v[68:71], v[188:191], v[204:207], v[68:71]
	v_mfma_f32_16x16x32_bf16 v[60:63], v[188:191], v[212:215], v[60:63]
	v_mfma_f32_16x16x32_bf16 v[32:35], v[196:199], v[204:207], v[32:35]
	v_mfma_f32_16x16x32_bf16 v[28:31], v[196:199], v[212:215], v[28:31]
	v_mfma_f32_16x16x32_bf16 v[128:131], v[176:179], v[208:211], v[128:131]
	v_mfma_f32_16x16x32_bf16 v[124:127], v[176:179], v[160:163], v[124:127]
	v_mfma_f32_16x16x32_bf16 v[100:103], v[184:187], v[208:211], v[100:103]
	v_mfma_f32_16x16x32_bf16 v[96:99], v[184:187], v[160:163], v[96:99]
	v_mfma_f32_16x16x32_bf16 v[68:71], v[192:195], v[208:211], v[68:71]
	v_mfma_f32_16x16x32_bf16 v[60:63], v[192:195], v[160:163], v[60:63]
	v_mfma_f32_16x16x32_bf16 v[32:35], v[142:145], v[208:211], v[32:35]
	v_mfma_f32_16x16x32_bf16 v[28:31], v[142:145], v[160:163], v[28:31]
	s_setprio 0
	s_movk_i32 s10, 0x100
	v_cmp_gt_u32_e32 vcc, s10, v0
	s_barrier
	s_and_saveexec_b64 s[24:25], vcc
	s_cbranch_execz .LBB0_113
	s_barrier
	s_branch .LBB0_113

; #define STA(P, br, kt) STAGE(P, A, aoff0, aoff1, lda, br, kt)
; #define STB(P, br, kt) STAGE(P, Bt, boff0, boff1, ldb, br, kt)
; #define LDA(dst, b, h) _Pragma("unroll") for (int m = 0; m < 4; ++m) _Pragma("unroll") for (int k = 0; k < 2; ++k) \
;     dst[m][k] = *reinterpret_cast<const bf16x8*>((char*)SA(b, h) + lds_byte(wr * 64 + m * 16 + fr, k * 32 + fq * 8))
; #define LDB(dst, b, h) _Pragma("unroll") for (int n = 0; n < 2; ++n) _Pragma("unroll") for (int k = 0; k < 2; ++k) \
;     dst[n][k] = *reinterpret_cast<const bf16x8*>((char*)SB(b, h) + lds_byte(wc * 32 + n * 16 + fr, k * 32 + fq * 8))
; #define MMA(ai, bj, At, Bq) do { __builtin_amdgcn_s_setprio(1); \
;     _Pragma("unroll") for (int m = 0; m < 4; ++m) _Pragma("unroll") for (int n = 0; n < 2; ++n) _Pragma("unroll") for (int k = 0; k < 2; ++k) \
;       acc[ai][bj][m][n] = __builtin_amdgcn_mfma_f32_16x16x32_bf16(At[m][k], Bq[n][k], acc[ai][bj][m][n], 0, 0, 0); \
;     __builtin_amdgcn_s_setprio(0); } while (0)
; #define WAIT_L(n) asm volatile("s_waitcnt lgkmcnt(" #n ")" ::: "memory")
; #define BAR __builtin_amdgcn_s_barrier()
; #define SCHED __builtin_amdgcn_sched_barrier(0)
; __device__ __forceinline__ void gemm256(const u16* __restrict__ A, int lda, const u16* __restrict__ Bt, int ldb, int K,
;                                         f32x4 (&acc)[2][2][4][2], const int g_wid) {
;     ...
;     LDB(B0, 0, 0); SCHED; LDA(At, 0, 0); STA(SA(1, 1), HALF, t + 1);
;     WAIT_L(8); BAR; WAIT_L(0); MMA(0, 0, At, B0); BAR; SCHED;
;     LDB(B1, 0, 1); STB(SB(0, 0), 0, t + 2);
;     BAR; WAIT_L(0); MMA(0, 1, At, B1); BAR;
;     LDA(At, 0, 1); STA(SA(0, 0), 0, t + 2);
;     BAR; WAIT_L(0); MMA(1, 0, At, B0); BAR; SCHED;
.LBB0_128:
	ds_read_b128 v[178:181], v174
	ds_read_b128 v[182:185], v174 offset:1024
	ds_read_b128 v[186:189], v174 offset:2048
	ds_read_b128 v[190:193], v174 offset:3072
	v_add_u32_e32 v175, 0xc000, v159
	v_lshl_add_u64 v[242:243], v[140:141], 0, s[14:15]
	v_readfirstlane_b32 s10, v175
	v_lshl_add_u64 v[176:177], v[242:243], 0, s[88:89]
	s_mov_b32 m0, s10
	ds_read_b128 v[194:197], v146
	ds_read_b128 v[198:201], v146 offset:1024
	ds_read_b128 v[202:205], v145
	ds_read_b128 v[206:209], v145 offset:1024
	ds_read_b128 v[210:213], v144
	ds_read_b128 v[214:217], v144 offset:1024
	ds_read_b128 v[218:221], v143
	ds_read_b128 v[222:225], v143 offset:1024
	global_load_lds_dwordx4 v[176:177], off
	v_add_u32_e32 v176, 0xe000, v159
	v_lshl_add_u64 v[244:245], v[138:139], 0, s[14:15]
	s_add_u32 m0, m0, 0x2000
	v_lshl_add_u64 v[226:227], v[244:245], 0, s[88:89]
	global_load_lds_dwordx4 v[226:227], off
	s_waitcnt lgkmcnt(8)
	s_barrier
	s_waitcnt lgkmcnt(0)
	v_mfma_f32_16x16x32_bf16 v[126:129], v[194:197], v[178:181], v[126:129]
	v_mfma_f32_16x16x32_bf16 v[122:125], v[194:197], v[186:189], v[122:125]
	v_mfma_f32_16x16x32_bf16 v[118:121], v[202:205], v[178:181], v[118:121]
	v_mfma_f32_16x16x32_bf16 v[114:117], v[202:205], v[186:189], v[114:117]
	v_mfma_f32_16x16x32_bf16 v[110:113], v[210:213], v[178:181], v[110:113]
	v_mfma_f32_16x16x32_bf16 v[106:109], v[210:213], v[186:189], v[106:109]
	v_mfma_f32_16x16x32_bf16 v[102:105], v[218:221], v[178:181], v[102:105]
	v_mfma_f32_16x16x32_bf16 v[98:101], v[218:221], v[186:189], v[98:101]
	v_mfma_f32_16x16x32_bf16 v[126:129], v[198:201], v[182:185], v[126:129]
	v_mfma_f32_16x16x32_bf16 v[122:125], v[198:201], v[190:193], v[122:125]
	v_mfma_f32_16x16x32_bf16 v[118:121], v[206:209], v[182:185], v[118:121]
	v_mfma_f32_16x16x32_bf16 v[114:117], v[206:209], v[190:193], v[114:117]
	v_mfma_f32_16x16x32_bf16 v[110:113], v[214:217], v[182:185], v[110:113]
	v_mfma_f32_16x16x32_bf16 v[106:109], v[214:217], v[190:193], v[106:109]
	v_mfma_f32_16x16x32_bf16 v[102:105], v[222:225], v[182:185], v[102:105]
	v_mfma_f32_16x16x32_bf16 v[98:101], v[222:225], v[190:193], v[98:101]
	s_barrier
	v_lshl_add_u64 v[246:247], v[136:137], 0, s[14:15]
	v_readfirstlane_b32 s10, v142
	v_lshl_add_u64 v[248:249], v[246:247], 0, s[8:9]
	s_mov_b32 m0, s10
	ds_read_b128 v[226:229], v173
	ds_read_b128 v[230:233], v173 offset:1024
	ds_read_b128 v[234:237], v173 offset:2048
	ds_read_b128 v[238:241], v173 offset:3072
	global_load_lds_dwordx4 v[248:249], off
	v_lshl_add_u64 v[248:249], v[134:135], 0, s[14:15]
	s_add_u32 m0, m0, 0x2000
	v_lshl_add_u64 v[250:251], v[248:249], 0, s[8:9]
	global_load_lds_dwordx4 v[250:251], off
	s_barrier
	s_waitcnt lgkmcnt(0)
	v_mfma_f32_16x16x32_bf16 v[94:97], v[194:197], v[226:229], v[94:97]
	v_mfma_f32_16x16x32_bf16 v[90:93], v[194:197], v[234:237], v[90:93]
	v_mfma_f32_16x16x32_bf16 v[86:89], v[202:205], v[226:229], v[86:89]
	v_mfma_f32_16x16x32_bf16 v[82:85], v[202:205], v[234:237], v[82:85]
	v_mfma_f32_16x16x32_bf16 v[78:81], v[210:213], v[226:229], v[78:81]
	v_mfma_f32_16x16x32_bf16 v[74:77], v[210:213], v[234:237], v[74:77]
	v_mfma_f32_16x16x32_bf16 v[70:73], v[218:221], v[226:229], v[70:73]
	v_mfma_f32_16x16x32_bf16 v[66:69], v[218:221], v[234:237], v[66:69]
	v_mfma_f32_16x16x32_bf16 v[94:97], v[198:201], v[230:233], v[94:97]
	v_mfma_f32_16x16x32_bf16 v[90:93], v[198:201], v[238:241], v[90:93]
	v_mfma_f32_16x16x32_bf16 v[86:89], v[206:209], v[230:233], v[86:89]
	v_mfma_f32_16x16x32_bf16 v[82:85], v[206:209], v[238:241], v[82:85]
	v_mfma_f32_16x16x32_bf16 v[78:81], v[214:217], v[230:233], v[78:81]
	v_mfma_f32_16x16x32_bf16 v[74:77], v[214:217], v[238:241], v[74:77]
	v_mfma_f32_16x16x32_bf16 v[70:73], v[222:225], v[230:233], v[70:73]
	v_mfma_f32_16x16x32_bf16 v[66:69], v[222:225], v[238:241], v[66:69]
	v_readfirstlane_b32 s10, v159
	v_lshl_add_u64 v[250:251], v[242:243], 0, s[92:93]
	s_mov_b32 m0, s10
	s_barrier
	ds_read_b128 v[194:197], v146 offset:16384
	ds_read_b128 v[198:201], v146 offset:17408
	ds_read_b128 v[202:205], v145 offset:16384
	ds_read_b128 v[206:209], v145 offset:17408
	ds_read_b128 v[210:213], v144 offset:16384
	ds_read_b128 v[214:217], v144 offset:17408
	ds_read_b128 v[218:221], v143 offset:16384
	ds_read_b128 v[222:225], v143 offset:17408
	global_load_lds_dwordx4 v[250:251], off
	s_add_u32 m0, m0, 0x2000
	v_lshl_add_u64 v[250:251], v[244:245], 0, s[92:93]
	global_load_lds_dwordx4 v[250:251], off
	s_barrier
	s_waitcnt lgkmcnt(0)
	v_mfma_f32_16x16x32_bf16 v[62:65], v[194:197], v[178:181], v[62:65]
	v_mfma_f32_16x16x32_bf16 v[58:61], v[194:197], v[186:189], v[58:61]
	v_mfma_f32_16x16x32_bf16 v[54:57], v[202:205], v[178:181], v[54:57]
	v_mfma_f32_16x16x32_bf16 v[50:53], v[202:205], v[186:189], v[50:53]
	v_mfma_f32_16x16x32_bf16 v[46:49], v[210:213], v[178:181], v[46:49]
	v_mfma_f32_16x16x32_bf16 v[42:45], v[210:213], v[186:189], v[42:45]
	v_mfma_f32_16x16x32_bf16 v[38:41], v[218:221], v[178:181], v[38:41]
	v_mfma_f32_16x16x32_bf16 v[34:37], v[218:221], v[186:189], v[34:37]
	v_mfma_f32_16x16x32_bf16 v[62:65], v[198:201], v[182:185], v[62:65]
	v_mfma_f32_16x16x32_bf16 v[58:61], v[198:201], v[190:193], v[58:61]
	v_mfma_f32_16x16x32_bf16 v[54:57], v[206:209], v[182:185], v[54:57]
	v_mfma_f32_16x16x32_bf16 v[50:53], v[206:209], v[190:193], v[50:53]
	v_mfma_f32_16x16x32_bf16 v[46:49], v[214:217], v[182:185], v[46:49]
	v_mfma_f32_16x16x32_bf16 v[42:45], v[214:217], v[190:193], v[42:45]
	v_mfma_f32_16x16x32_bf16 v[38:41], v[222:225], v[182:185], v[38:41]
	v_mfma_f32_16x16x32_bf16 v[34:37], v[222:225], v[190:193], v[34:37]
	s_barrier
; #define STA(P, br, kt) STAGE(P, A, aoff0, aoff1, lda, br, kt)
; #define STB(P, br, kt) STAGE(P, Bt, boff0, boff1, ldb, br, kt)
; #define LDA(dst, b, h) _Pragma("unroll") for (int m = 0; m < 4; ++m) _Pragma("unroll") for (int k = 0; k < 2; ++k) \
;     dst[m][k] = *reinterpret_cast<const bf16x8*>((char*)SA(b, h) + lds_byte(wr * 64 + m * 16 + fr, k * 32 + fq * 8))
; #define LDB(dst, b, h) _Pragma("unroll") for (int n = 0; n < 2; ++n) _Pragma("unroll") for (int k = 0; k < 2; ++k) \
;     dst[n][k] = *reinterpret_cast<const bf16x8*>((char*)SB(b, h) + lds_byte(wc * 32 + n * 16 + fr, k * 32 + fq * 8))
; #define MMA(ai, bj, At, Bq) do { __builtin_amdgcn_s_setprio(1); \
;     _Pragma("unroll") for (int m = 0; m < 4; ++m) _Pragma("unroll") for (int n = 0; n < 2; ++n) _Pragma("unroll") for (int k = 0; k < 2; ++k) \
;       acc[ai][bj][m][n] = __builtin_amdgcn_mfma_f32_16x16x32_bf16(At[m][k], Bq[n][k], acc[ai][bj][m][n], 0, 0, 0); \
;     __builtin_amdgcn_s_setprio(0); } while (0)
; #define WAIT_V(n) asm volatile("s_waitcnt vmcnt(" #n ")" ::: "memory")
; #define WAIT_L(n) asm volatile("s_waitcnt lgkmcnt(" #n ")" ::: "memory")
; #define BAR __builtin_amdgcn_s_barrier()
; #define SCHED __builtin_amdgcn_sched_barrier(0)
; __device__ __forceinline__ void gemm256(const u16* __restrict__ A, int lda, const u16* __restrict__ Bt, int ldb, int K,
;                                         f32x4 (&acc)[2][2][4][2], const int g_wid) {
;     ...
;     STB(SB(0, 1), HALF, t + 2);
;     WAIT_V(6); BAR; MMA(1, 1, At, B1); BAR;
;     LDB(B0, 1, 0); SCHED; LDA(At, 1, 0); STA(SA(0, 1), HALF, t + 2);
;     WAIT_L(8); BAR; WAIT_L(0); MMA(0, 0, At, B0); BAR; SCHED;
;     LDB(B1, 1, 1); STB(SB(1, 0), 0, t + 3);
;     BAR; WAIT_L(0); MMA(0, 1, At, B1); BAR;
;     LDA(At, 1, 1); STA(SA(1, 0), 0, t + 3);
	v_readfirstlane_b32 s10, v162
	v_lshl_add_u64 v[178:179], v[246:247], 0, s[18:19]
	s_mov_b32 m0, s10
	global_load_lds_dwordx4 v[178:179], off
	s_add_u32 m0, m0, 0x2000
	v_lshl_add_u64 v[178:179], v[248:249], 0, s[18:19]
	global_load_lds_dwordx4 v[178:179], off
	s_waitcnt vmcnt(6)
	s_barrier
	v_mfma_f32_16x16x32_bf16 v[30:33], v[194:197], v[226:229], v[30:33]
	v_mfma_f32_16x16x32_bf16 v[26:29], v[194:197], v[234:237], v[26:29]
	v_mfma_f32_16x16x32_bf16 v[22:25], v[202:205], v[226:229], v[22:25]
	v_mfma_f32_16x16x32_bf16 v[18:21], v[202:205], v[234:237], v[18:21]
	v_mfma_f32_16x16x32_bf16 v[14:17], v[210:213], v[226:229], v[14:17]
	v_mfma_f32_16x16x32_bf16 v[10:13], v[210:213], v[234:237], v[10:13]
	v_mfma_f32_16x16x32_bf16 v[6:9], v[218:221], v[226:229], v[6:9]
	v_mfma_f32_16x16x32_bf16 v[2:5], v[218:221], v[234:237], v[2:5]
	v_mfma_f32_16x16x32_bf16 v[30:33], v[198:201], v[230:233], v[30:33]
	v_mfma_f32_16x16x32_bf16 v[26:29], v[198:201], v[238:241], v[26:29]
	v_mfma_f32_16x16x32_bf16 v[22:25], v[206:209], v[230:233], v[22:25]
	v_mfma_f32_16x16x32_bf16 v[18:21], v[206:209], v[238:241], v[18:21]
	v_mfma_f32_16x16x32_bf16 v[14:17], v[214:217], v[230:233], v[14:17]
	v_mfma_f32_16x16x32_bf16 v[10:13], v[214:217], v[238:241], v[10:13]
	v_mfma_f32_16x16x32_bf16 v[6:9], v[222:225], v[230:233], v[6:9]
	v_mfma_f32_16x16x32_bf16 v[2:5], v[222:225], v[238:241], v[2:5]
	s_barrier
	ds_read_b128 v[178:181], v166
	ds_read_b128 v[182:185], v166 offset:1024
	ds_read_b128 v[186:189], v166 offset:2048
	ds_read_b128 v[190:193], v166 offset:3072
	v_readfirstlane_b32 s10, v164
	v_lshl_add_u64 v[226:227], v[242:243], 0, s[96:97]
	s_mov_b32 m0, s10
	ds_read_b128 v[194:197], v146 offset:32768
	ds_read_b128 v[198:201], v146 offset:33792
	ds_read_b128 v[202:205], v145 offset:32768
	ds_read_b128 v[206:209], v145 offset:33792
	ds_read_b128 v[210:213], v144 offset:32768
	ds_read_b128 v[214:217], v144 offset:33792
	ds_read_b128 v[218:221], v143 offset:32768
	ds_read_b128 v[222:225], v143 offset:33792
	global_load_lds_dwordx4 v[226:227], off
	s_add_u32 m0, m0, 0x2000
	v_lshl_add_u64 v[226:227], v[244:245], 0, s[96:97]
	global_load_lds_dwordx4 v[226:227], off
	s_waitcnt lgkmcnt(8)
	s_barrier
	s_waitcnt lgkmcnt(0)
	v_mfma_f32_16x16x32_bf16 v[126:129], v[194:197], v[178:181], v[126:129]
	v_mfma_f32_16x16x32_bf16 v[122:125], v[194:197], v[186:189], v[122:125]
	v_mfma_f32_16x16x32_bf16 v[118:121], v[202:205], v[178:181], v[118:121]
	v_mfma_f32_16x16x32_bf16 v[114:117], v[202:205], v[186:189], v[114:117]
	v_mfma_f32_16x16x32_bf16 v[110:113], v[210:213], v[178:181], v[110:113]
	v_mfma_f32_16x16x32_bf16 v[106:109], v[210:213], v[186:189], v[106:109]
	v_mfma_f32_16x16x32_bf16 v[102:105], v[218:221], v[178:181], v[102:105]
	v_mfma_f32_16x16x32_bf16 v[98:101], v[218:221], v[186:189], v[98:101]
	v_mfma_f32_16x16x32_bf16 v[126:129], v[198:201], v[182:185], v[126:129]
	v_mfma_f32_16x16x32_bf16 v[122:125], v[198:201], v[190:193], v[122:125]
	v_mfma_f32_16x16x32_bf16 v[118:121], v[206:209], v[182:185], v[118:121]
	v_mfma_f32_16x16x32_bf16 v[114:117], v[206:209], v[190:193], v[114:117]
	v_mfma_f32_16x16x32_bf16 v[110:113], v[214:217], v[182:185], v[110:113]
	v_mfma_f32_16x16x32_bf16 v[106:109], v[214:217], v[190:193], v[106:109]
	v_mfma_f32_16x16x32_bf16 v[102:105], v[222:225], v[182:185], v[102:105]
	v_mfma_f32_16x16x32_bf16 v[98:101], v[222:225], v[190:193], v[98:101]
	s_barrier
	v_readfirstlane_b32 s10, v167
	v_lshl_add_u64 v[250:251], v[246:247], 0, s[20:21]
	s_mov_b32 m0, s10
	ds_read_b128 v[226:229], v161
	ds_read_b128 v[230:233], v161 offset:1024
	ds_read_b128 v[234:237], v161 offset:2048
	ds_read_b128 v[238:241], v161 offset:3072
	global_load_lds_dwordx4 v[250:251], off
	s_add_u32 m0, m0, 0x2000
	v_lshl_add_u64 v[250:251], v[248:249], 0, s[20:21]
	global_load_lds_dwordx4 v[250:251], off
	s_barrier
	s_waitcnt lgkmcnt(0)
	v_mfma_f32_16x16x32_bf16 v[94:97], v[194:197], v[226:229], v[94:97]
	v_mfma_f32_16x16x32_bf16 v[90:93], v[194:197], v[234:237], v[90:93]
	v_mfma_f32_16x16x32_bf16 v[86:89], v[202:205], v[226:229], v[86:89]
	v_mfma_f32_16x16x32_bf16 v[82:85], v[202:205], v[234:237], v[82:85]
	v_mfma_f32_16x16x32_bf16 v[78:81], v[210:213], v[226:229], v[78:81]
	v_mfma_f32_16x16x32_bf16 v[74:77], v[210:213], v[234:237], v[74:77]
	v_mfma_f32_16x16x32_bf16 v[70:73], v[218:221], v[226:229], v[70:73]
	v_mfma_f32_16x16x32_bf16 v[66:69], v[218:221], v[234:237], v[66:69]
	v_mfma_f32_16x16x32_bf16 v[94:97], v[198:201], v[230:233], v[94:97]
	v_mfma_f32_16x16x32_bf16 v[90:93], v[198:201], v[238:241], v[90:93]
	v_mfma_f32_16x16x32_bf16 v[86:89], v[206:209], v[230:233], v[86:89]
	v_mfma_f32_16x16x32_bf16 v[82:85], v[206:209], v[238:241], v[82:85]
	v_mfma_f32_16x16x32_bf16 v[78:81], v[214:217], v[230:233], v[78:81]
	v_mfma_f32_16x16x32_bf16 v[74:77], v[214:217], v[238:241], v[74:77]
	v_mfma_f32_16x16x32_bf16 v[70:73], v[222:225], v[230:233], v[70:73]
	v_mfma_f32_16x16x32_bf16 v[66:69], v[222:225], v[238:241], v[66:69]
	v_readfirstlane_b32 s10, v169
	v_lshl_add_u64 v[242:243], v[242:243], 0, s[62:63]
	s_mov_b32 m0, s10
	s_barrier
	ds_read_b128 v[194:197], v146 offset:49152
	ds_read_b128 v[198:201], v146 offset:50176
	ds_read_b128 v[202:205], v145 offset:49152
	ds_read_b128 v[206:209], v145 offset:50176
	ds_read_b128 v[210:213], v144 offset:49152
	ds_read_b128 v[214:217], v144 offset:50176
	ds_read_b128 v[218:221], v143 offset:49152
	ds_read_b128 v[222:225], v143 offset:50176
	global_load_lds_dwordx4 v[242:243], off
	s_add_u32 m0, m0, 0x2000
	v_lshl_add_u64 v[242:243], v[244:245], 0, s[62:63]
	global_load_lds_dwordx4 v[242:243], off
	s_barrier
; #define STA(P, br, kt) STAGE(P, A, aoff0, aoff1, lda, br, kt)
; #define STB(P, br, kt) STAGE(P, Bt, boff0, boff1, ldb, br, kt)
; #define LDA(dst, b, h) _Pragma("unroll") for (int m = 0; m < 4; ++m) _Pragma("unroll") for (int k = 0; k < 2; ++k) \
;     dst[m][k] = *reinterpret_cast<const bf16x8*>((char*)SA(b, h) + lds_byte(wr * 64 + m * 16 + fr, k * 32 + fq * 8))
; #define LDB(dst, b, h) _Pragma("unroll") for (int n = 0; n < 2; ++n) _Pragma("unroll") for (int k = 0; k < 2; ++k) \
;     dst[n][k] = *reinterpret_cast<const bf16x8*>((char*)SB(b, h) + lds_byte(wc * 32 + n * 16 + fr, k * 32 + fq * 8))
; #define MMA(ai, bj, At, Bq) do { __builtin_amdgcn_s_setprio(1); \
;     _Pragma("unroll") for (int m = 0; m < 4; ++m) _Pragma("unroll") for (int n = 0; n < 2; ++n) _Pragma("unroll") for (int k = 0; k < 2; ++k) \
;       acc[ai][bj][m][n] = __builtin_amdgcn_mfma_f32_16x16x32_bf16(At[m][k], Bq[n][k], acc[ai][bj][m][n], 0, 0, 0); \
;     __builtin_amdgcn_s_setprio(0); } while (0)
; #define WAIT_V(n) asm volatile("s_waitcnt vmcnt(" #n ")" ::: "memory")
; #define WAIT_L(n) asm volatile("s_waitcnt lgkmcnt(" #n ")" ::: "memory")
; #define BAR __builtin_amdgcn_s_barrier()
; #define SCHED __builtin_amdgcn_sched_barrier(0)
; __device__ __forceinline__ void gemm256(const u16* __restrict__ A, int lda, const u16* __restrict__ Bt, int ldb, int K,
;                                         f32x4 (&acc)[2][2][4][2], const int g_wid) {
;     ...
;     BAR; WAIT_L(0); MMA(1, 0, At, B0); BAR; SCHED;
;     STB(SB(1, 1), HALF, t + 3);
;     WAIT_V(6); BAR; MMA(1, 1, At, B1); BAR;
;   }
;   { LDB(B0, 0, 0); LDA(At, 0, 0); STA(SA(1, 1), HALF, nt - 1);
;     BAR; WAIT_L(0); MMA(0, 0, At, B0); BAR;
;     LDB(B1, 0, 1); BAR; WAIT_L(0); MMA(0, 1, At, B1); BAR;
;     LDA(At, 0, 1); WAIT_V(4); BAR; WAIT_L(0); MMA(1, 0, At, B0); MMA(1, 1, At, B1); BAR; }
	s_waitcnt lgkmcnt(0)
	v_mfma_f32_16x16x32_bf16 v[62:65], v[194:197], v[178:181], v[62:65]
	v_mfma_f32_16x16x32_bf16 v[58:61], v[194:197], v[186:189], v[58:61]
	v_mfma_f32_16x16x32_bf16 v[54:57], v[202:205], v[178:181], v[54:57]
	v_mfma_f32_16x16x32_bf16 v[50:53], v[202:205], v[186:189], v[50:53]
	v_mfma_f32_16x16x32_bf16 v[46:49], v[210:213], v[178:181], v[46:49]
	v_mfma_f32_16x16x32_bf16 v[42:45], v[210:213], v[186:189], v[42:45]
	v_mfma_f32_16x16x32_bf16 v[38:41], v[218:221], v[178:181], v[38:41]
	v_mfma_f32_16x16x32_bf16 v[34:37], v[218:221], v[186:189], v[34:37]
	v_mfma_f32_16x16x32_bf16 v[62:65], v[198:201], v[182:185], v[62:65]
	v_mfma_f32_16x16x32_bf16 v[58:61], v[198:201], v[190:193], v[58:61]
	v_mfma_f32_16x16x32_bf16 v[54:57], v[206:209], v[182:185], v[54:57]
	v_mfma_f32_16x16x32_bf16 v[50:53], v[206:209], v[190:193], v[50:53]
	v_mfma_f32_16x16x32_bf16 v[46:49], v[214:217], v[182:185], v[46:49]
	v_mfma_f32_16x16x32_bf16 v[42:45], v[214:217], v[190:193], v[42:45]
	v_mfma_f32_16x16x32_bf16 v[38:41], v[222:225], v[182:185], v[38:41]
	v_mfma_f32_16x16x32_bf16 v[34:37], v[222:225], v[190:193], v[34:37]
	s_barrier
	v_readfirstlane_b32 s10, v171
	v_lshl_add_u64 v[178:179], v[246:247], 0, s[26:27]
	s_mov_b32 m0, s10
	global_load_lds_dwordx4 v[178:179], off
	s_add_u32 m0, m0, 0x2000
	v_lshl_add_u64 v[178:179], v[248:249], 0, s[26:27]
	global_load_lds_dwordx4 v[178:179], off
	s_waitcnt vmcnt(6)
	s_barrier
	v_mfma_f32_16x16x32_bf16 v[30:33], v[194:197], v[226:229], v[30:33]
	v_mfma_f32_16x16x32_bf16 v[26:29], v[194:197], v[234:237], v[26:29]
	v_mfma_f32_16x16x32_bf16 v[22:25], v[202:205], v[226:229], v[22:25]
	v_mfma_f32_16x16x32_bf16 v[18:21], v[202:205], v[234:237], v[18:21]
	v_mfma_f32_16x16x32_bf16 v[14:17], v[210:213], v[226:229], v[14:17]
	v_mfma_f32_16x16x32_bf16 v[10:13], v[210:213], v[234:237], v[10:13]
	v_mfma_f32_16x16x32_bf16 v[6:9], v[218:221], v[226:229], v[6:9]
	v_mfma_f32_16x16x32_bf16 v[2:5], v[218:221], v[234:237], v[2:5]
	v_mfma_f32_16x16x32_bf16 v[30:33], v[198:201], v[230:233], v[30:33]
	v_mfma_f32_16x16x32_bf16 v[26:29], v[198:201], v[238:241], v[26:29]
	v_mfma_f32_16x16x32_bf16 v[22:25], v[206:209], v[230:233], v[22:25]
	v_mfma_f32_16x16x32_bf16 v[18:21], v[206:209], v[238:241], v[18:21]
	v_mfma_f32_16x16x32_bf16 v[14:17], v[214:217], v[230:233], v[14:17]
	v_mfma_f32_16x16x32_bf16 v[10:13], v[214:217], v[238:241], v[10:13]
	v_mfma_f32_16x16x32_bf16 v[6:9], v[222:225], v[230:233], v[6:9]
	v_mfma_f32_16x16x32_bf16 v[2:5], v[222:225], v[238:241], v[2:5]
	s_add_i32 s16, s16, 2
	s_add_u32 s14, s14, 0x100
	s_addc_u32 s15, s15, 0
	s_cmp_lt_u32 s16, 4
	s_barrier
	s_cbranch_scc1 .LBB0_128
	s_add_u32 s12, s12, 0x20380
	s_addc_u32 s13, s13, 0
	v_readfirstlane_b32 s10, v175
	v_lshl_add_u64 v[132:133], v[132:133], 1, s[12:13]
	s_mov_b32 m0, s10
	v_readfirstlane_b32 s10, v176
	ds_read_b128 v[134:137], v174
	ds_read_b128 v[138:141], v174 offset:1024
	ds_read_b128 v[162:165], v174 offset:2048
	ds_read_b128 v[168:171], v174 offset:3072
	ds_read_b128 v[178:181], v146
	ds_read_b128 v[182:185], v146 offset:1024
	ds_read_b128 v[186:189], v145
	ds_read_b128 v[190:193], v145 offset:1024
	ds_read_b128 v[194:197], v144
	ds_read_b128 v[198:201], v144 offset:1024
	ds_read_b128 v[202:205], v143
	ds_read_b128 v[206:209], v143 offset:1024
	global_load_lds_dwordx4 v[132:133], off
	v_lshl_add_u64 v[130:131], v[130:131], 1, s[12:13]
	s_mov_b32 m0, s10
	s_nop 0
	global_load_lds_dwordx4 v[130:131], off
	s_barrier
	s_waitcnt lgkmcnt(0)
	v_mfma_f32_16x16x32_bf16 v[126:129], v[178:181], v[134:137], v[126:129]
	v_mfma_f32_16x16x32_bf16 v[122:125], v[178:181], v[162:165], v[122:125]
	v_mfma_f32_16x16x32_bf16 v[118:121], v[186:189], v[134:137], v[118:121]
	v_mfma_f32_16x16x32_bf16 v[114:117], v[186:189], v[162:165], v[114:117]
	v_mfma_f32_16x16x32_bf16 v[110:113], v[194:197], v[134:137], v[110:113]
	v_mfma_f32_16x16x32_bf16 v[106:109], v[194:197], v[162:165], v[106:109]
	v_mfma_f32_16x16x32_bf16 v[102:105], v[202:205], v[134:137], v[102:105]
	v_mfma_f32_16x16x32_bf16 v[98:101], v[202:205], v[162:165], v[98:101]
	v_mfma_f32_16x16x32_bf16 v[126:129], v[182:185], v[138:141], v[126:129]
	v_mfma_f32_16x16x32_bf16 v[122:125], v[182:185], v[168:171], v[122:125]
	v_mfma_f32_16x16x32_bf16 v[118:121], v[190:193], v[138:141], v[118:121]
	v_mfma_f32_16x16x32_bf16 v[114:117], v[190:193], v[168:171], v[114:117]
	v_mfma_f32_16x16x32_bf16 v[110:113], v[198:201], v[138:141], v[110:113]
	v_mfma_f32_16x16x32_bf16 v[106:109], v[198:201], v[168:171], v[106:109]
	v_mfma_f32_16x16x32_bf16 v[102:105], v[206:209], v[138:141], v[102:105]
	v_mfma_f32_16x16x32_bf16 v[98:101], v[206:209], v[168:171], v[98:101]
	s_barrier
	ds_read_b128 v[130:133], v173
	ds_read_b128 v[174:177], v173 offset:1024
	ds_read_b128 v[210:213], v173 offset:2048
	ds_read_b128 v[214:217], v173 offset:3072
	s_barrier
	s_waitcnt lgkmcnt(0)
	v_mfma_f32_16x16x32_bf16 v[86:89], v[186:189], v[130:133], v[86:89]
	v_mfma_f32_16x16x32_bf16 v[74:77], v[194:197], v[210:213], v[74:77]
	v_mfma_f32_16x16x32_bf16 v[70:73], v[202:205], v[130:133], v[70:73]
	v_mfma_f32_16x16x32_bf16 v[66:69], v[202:205], v[210:213], v[66:69]
	v_mfma_f32_16x16x32_bf16 v[94:97], v[178:181], v[130:133], v[94:97]
	v_mfma_f32_16x16x32_bf16 v[90:93], v[178:181], v[210:213], v[90:93]
	v_mfma_f32_16x16x32_bf16 v[86:89], v[190:193], v[174:177], v[86:89]
	v_mfma_f32_16x16x32_bf16 v[82:85], v[186:189], v[210:213], v[82:85]
	v_mfma_f32_16x16x32_bf16 v[78:81], v[194:197], v[130:133], v[78:81]
	v_mfma_f32_16x16x32_bf16 v[74:77], v[198:201], v[214:217], v[74:77]
	v_mfma_f32_16x16x32_bf16 v[70:73], v[206:209], v[174:177], v[70:73]
	v_mfma_f32_16x16x32_bf16 v[66:69], v[206:209], v[214:217], v[66:69]
	v_mfma_f32_16x16x32_bf16 v[218:221], v[182:185], v[174:177], v[94:97]
	v_mfma_f32_16x16x32_bf16 v[178:181], v[182:185], v[214:217], v[90:93]
	v_mfma_f32_16x16x32_bf16 v[182:185], v[190:193], v[214:217], v[82:85]
	v_mfma_f32_16x16x32_bf16 v[186:189], v[198:201], v[174:177], v[78:81]
	s_barrier
; #define LDA(dst, b, h) _Pragma("unroll") for (int m = 0; m < 4; ++m) _Pragma("unroll") for (int k = 0; k < 2; ++k) \
;     dst[m][k] = *reinterpret_cast<const bf16x8*>((char*)SA(b, h) + lds_byte(wr * 64 + m * 16 + fr, k * 32 + fq * 8))
; #define LDB(dst, b, h) _Pragma("unroll") for (int n = 0; n < 2; ++n) _Pragma("unroll") for (int k = 0; k < 2; ++k) \
;     dst[n][k] = *reinterpret_cast<const bf16x8*>((char*)SB(b, h) + lds_byte(wc * 32 + n * 16 + fr, k * 32 + fq * 8))
; #define MMA(ai, bj, At, Bq) do { __builtin_amdgcn_s_setprio(1); \
;     _Pragma("unroll") for (int m = 0; m < 4; ++m) _Pragma("unroll") for (int n = 0; n < 2; ++n) _Pragma("unroll") for (int k = 0; k < 2; ++k) \
;       acc[ai][bj][m][n] = __builtin_amdgcn_mfma_f32_16x16x32_bf16(At[m][k], Bq[n][k], acc[ai][bj][m][n], 0, 0, 0); \
;     __builtin_amdgcn_s_setprio(0); } while (0)
; #define WAIT_V(n) asm volatile("s_waitcnt vmcnt(" #n ")" ::: "memory")
; #define WAIT_L(n) asm volatile("s_waitcnt lgkmcnt(" #n ")" ::: "memory")
; #define BAR __builtin_amdgcn_s_barrier()
; __device__ __forceinline__ void gemm256(const u16* __restrict__ A, int lda, const u16* __restrict__ Bt, int ldb, int K,
;                                         f32x4 (&acc)[2][2][4][2], const int g_wid) {
;     ...
;     LDA(At, 0, 1); WAIT_V(4); BAR; WAIT_L(0); MMA(1, 0, At, B0); MMA(1, 1, At, B1); BAR; }
;   { LDB(B0, 1, 0); LDA(At, 1, 0); WAIT_V(2); BAR; WAIT_L(0); MMA(0, 0, At, B0); BAR;
	s_nop 0
	ds_read_b128 v[78:81], v146 offset:16384
	ds_read_b128 v[82:85], v146 offset:17408
	ds_read_b128 v[90:93], v145 offset:16384
	ds_read_b128 v[94:97], v145 offset:17408
	ds_read_b128 v[190:193], v144 offset:16384
	ds_read_b128 v[194:197], v144 offset:17408
	ds_read_b128 v[198:201], v143 offset:16384
	ds_read_b128 v[202:205], v143 offset:17408
	s_waitcnt vmcnt(4)
	s_barrier
	s_waitcnt lgkmcnt(0)
	v_mfma_f32_16x16x32_bf16 v[54:57], v[90:93], v[134:137], v[54:57]
	v_mfma_f32_16x16x32_bf16 v[42:45], v[190:193], v[162:165], v[42:45]
	v_mfma_f32_16x16x32_bf16 v[38:41], v[198:201], v[134:137], v[38:41]
	v_mfma_f32_16x16x32_bf16 v[34:37], v[198:201], v[162:165], v[34:37]
	v_mfma_f32_16x16x32_bf16 v[62:65], v[78:81], v[134:137], v[62:65]
	v_mfma_f32_16x16x32_bf16 v[58:61], v[78:81], v[162:165], v[58:61]
	v_mfma_f32_16x16x32_bf16 v[54:57], v[94:97], v[138:141], v[54:57]
	v_mfma_f32_16x16x32_bf16 v[50:53], v[90:93], v[162:165], v[50:53]
	v_mfma_f32_16x16x32_bf16 v[46:49], v[190:193], v[134:137], v[46:49]
	v_mfma_f32_16x16x32_bf16 v[42:45], v[194:197], v[168:171], v[42:45]
	v_mfma_f32_16x16x32_bf16 v[38:41], v[202:205], v[138:141], v[38:41]
	v_mfma_f32_16x16x32_bf16 v[34:37], v[202:205], v[168:171], v[34:37]
	v_mfma_f32_16x16x32_bf16 v[206:209], v[82:85], v[138:141], v[62:65]
	v_mfma_f32_16x16x32_bf16 v[222:225], v[82:85], v[168:171], v[58:61]
	v_mfma_f32_16x16x32_bf16 v[226:229], v[94:97], v[168:171], v[50:53]
	v_mfma_f32_16x16x32_bf16 v[230:233], v[194:197], v[138:141], v[46:49]
	v_mfma_f32_16x16x32_bf16 v[2:5], v[198:201], v[210:213], v[2:5]
	v_mfma_f32_16x16x32_bf16 v[30:33], v[78:81], v[130:133], v[30:33]
	v_mfma_f32_16x16x32_bf16 v[26:29], v[78:81], v[210:213], v[26:29]
	v_mfma_f32_16x16x32_bf16 v[22:25], v[90:93], v[130:133], v[22:25]
	v_mfma_f32_16x16x32_bf16 v[18:21], v[90:93], v[210:213], v[18:21]
	v_mfma_f32_16x16x32_bf16 v[14:17], v[190:193], v[130:133], v[14:17]
	v_mfma_f32_16x16x32_bf16 v[10:13], v[190:193], v[210:213], v[10:13]
	v_mfma_f32_16x16x32_bf16 v[6:9], v[198:201], v[130:133], v[6:9]
	v_mfma_f32_16x16x32_bf16 v[2:5], v[202:205], v[214:217], v[2:5]
	v_mfma_f32_16x16x32_bf16 v[134:137], v[82:85], v[174:177], v[30:33]
	v_mfma_f32_16x16x32_bf16 v[138:141], v[82:85], v[214:217], v[26:29]
	v_mfma_f32_16x16x32_bf16 v[162:165], v[94:97], v[174:177], v[22:25]
	v_mfma_f32_16x16x32_bf16 v[168:171], v[94:97], v[214:217], v[18:21]
	v_mfma_f32_16x16x32_bf16 v[234:237], v[194:197], v[174:177], v[14:17]
	v_mfma_f32_16x16x32_bf16 v[190:193], v[194:197], v[214:217], v[10:13]
	v_mfma_f32_16x16x32_bf16 v[130:133], v[202:205], v[174:177], v[6:9]
	s_barrier
	s_nop 0
	ds_read_b128 v[6:9], v166
	ds_read_b128 v[10:13], v166 offset:1024
	ds_read_b128 v[22:25], v166 offset:2048
	ds_read_b128 v[172:175], v166 offset:3072
	ds_read_b128 v[14:17], v146 offset:32768
	ds_read_b128 v[18:21], v146 offset:33792
	ds_read_b128 v[26:29], v145 offset:32768
	ds_read_b128 v[46:49], v145 offset:33792
	ds_read_b128 v[194:197], v144 offset:32768
	ds_read_b128 v[198:201], v144 offset:33792
	ds_read_b128 v[202:205], v143 offset:32768
	ds_read_b128 v[210:213], v143 offset:33792
	s_waitcnt vmcnt(2)
	s_barrier
	s_waitcnt lgkmcnt(0)
	v_mfma_f32_16x16x32_bf16 v[30:33], v[14:17], v[6:9], v[126:129]
	v_mfma_f32_16x16x32_bf16 v[126:129], v[18:21], v[10:13], v[30:33]
	v_mfma_f32_16x16x32_bf16 v[30:33], v[14:17], v[22:25], v[122:125]
	v_mfma_f32_16x16x32_bf16 v[94:97], v[18:21], v[172:175], v[30:33]
	v_mfma_f32_16x16x32_bf16 v[30:33], v[26:29], v[6:9], v[118:121]
	v_mfma_f32_16x16x32_bf16 v[122:125], v[46:49], v[10:13], v[30:33]
	v_mfma_f32_16x16x32_bf16 v[30:33], v[26:29], v[22:25], v[114:117]
	v_mfma_f32_16x16x32_bf16 v[90:93], v[46:49], v[172:175], v[30:33]
	v_mfma_f32_16x16x32_bf16 v[30:33], v[194:197], v[6:9], v[110:113]
	v_mfma_f32_16x16x32_bf16 v[114:117], v[198:201], v[10:13], v[30:33]
	v_mfma_f32_16x16x32_bf16 v[30:33], v[194:197], v[22:25], v[106:109]
	v_mfma_f32_16x16x32_bf16 v[82:85], v[198:201], v[172:175], v[30:33]
	v_mfma_f32_16x16x32_bf16 v[30:33], v[202:205], v[6:9], v[102:105]
	v_mfma_f32_16x16x32_bf16 v[110:113], v[210:213], v[10:13], v[30:33]
	v_mfma_f32_16x16x32_bf16 v[30:33], v[202:205], v[22:25], v[98:101]
	v_mfma_f32_16x16x32_bf16 v[78:81], v[210:213], v[172:175], v[30:33]
	s_barrier
; #define LDA(dst, b, h) _Pragma("unroll") for (int m = 0; m < 4; ++m) _Pragma("unroll") for (int k = 0; k < 2; ++k) \
;     dst[m][k] = *reinterpret_cast<const bf16x8*>((char*)SA(b, h) + lds_byte(wr * 64 + m * 16 + fr, k * 32 + fq * 8))
; #define LDB(dst, b, h) _Pragma("unroll") for (int n = 0; n < 2; ++n) _Pragma("unroll") for (int k = 0; k < 2; ++k) \
;     dst[n][k] = *reinterpret_cast<const bf16x8*>((char*)SB(b, h) + lds_byte(wc * 32 + n * 16 + fr, k * 32 + fq * 8))
; #define MMA(ai, bj, At, Bq) do { __builtin_amdgcn_s_setprio(1); \
;     _Pragma("unroll") for (int m = 0; m < 4; ++m) _Pragma("unroll") for (int n = 0; n < 2; ++n) _Pragma("unroll") for (int k = 0; k < 2; ++k) \
;       acc[ai][bj][m][n] = __builtin_amdgcn_mfma_f32_16x16x32_bf16(At[m][k], Bq[n][k], acc[ai][bj][m][n], 0, 0, 0); \
;     __builtin_amdgcn_s_setprio(0); } while (0)
; #define WAIT_V(n) asm volatile("s_waitcnt vmcnt(" #n ")" ::: "memory")
; #define WAIT_L(n) asm volatile("s_waitcnt lgkmcnt(" #n ")" ::: "memory")
; #define BAR __builtin_amdgcn_s_barrier()
; __device__ __forceinline__ void gemm256(const u16* __restrict__ A, int lda, const u16* __restrict__ Bt, int ldb, int K,
;                                         f32x4 (&acc)[2][2][4][2], const int g_wid) {
;     ...
;     LDB(B1, 1, 1); WAIT_V(0); BAR; WAIT_L(0); MMA(0, 1, At, B1); BAR;
;     LDA(At, 1, 1); BAR; WAIT_L(0); MMA(1, 0, At, B0); MMA(1, 1, At, B1); BAR; }
;   if (wr == 0) BAR;
	ds_read_b128 v[214:217], v161
	ds_read_b128 v[238:241], v161 offset:1024
	ds_read_b128 v[242:245], v161 offset:2048
	ds_read_b128 v[246:249], v161 offset:3072
	s_waitcnt vmcnt(0)
	s_barrier
	s_waitcnt lgkmcnt(0)
	v_mfma_f32_16x16x32_bf16 v[30:33], v[14:17], v[214:217], v[218:221]
	v_mfma_f32_16x16x32_bf16 v[14:17], v[14:17], v[242:245], v[178:181]
	v_mfma_f32_16x16x32_bf16 v[62:65], v[18:21], v[238:241], v[30:33]
	v_mfma_f32_16x16x32_bf16 v[30:33], v[18:21], v[246:249], v[14:17]
	v_mfma_f32_16x16x32_bf16 v[14:17], v[26:29], v[214:217], v[86:89]
	v_mfma_f32_16x16x32_bf16 v[58:61], v[46:49], v[238:241], v[14:17]
	v_mfma_f32_16x16x32_bf16 v[14:17], v[26:29], v[242:245], v[182:185]
	v_mfma_f32_16x16x32_bf16 v[26:29], v[46:49], v[246:249], v[14:17]
	v_mfma_f32_16x16x32_bf16 v[14:17], v[194:197], v[214:217], v[186:189]
	v_mfma_f32_16x16x32_bf16 v[50:53], v[198:201], v[238:241], v[14:17]
	v_mfma_f32_16x16x32_bf16 v[14:17], v[194:197], v[242:245], v[74:77]
	v_mfma_f32_16x16x32_bf16 v[18:21], v[198:201], v[246:249], v[14:17]
	v_mfma_f32_16x16x32_bf16 v[14:17], v[202:205], v[214:217], v[70:73]
	v_mfma_f32_16x16x32_bf16 v[46:49], v[210:213], v[238:241], v[14:17]
	v_mfma_f32_16x16x32_bf16 v[14:17], v[202:205], v[242:245], v[66:69]
	v_mfma_f32_16x16x32_bf16 v[14:17], v[210:213], v[246:249], v[14:17]
	s_barrier
	ds_read_b128 v[176:179], v146 offset:49152
	ds_read_b128 v[180:183], v146 offset:50176
	ds_read_b128 v[184:187], v145 offset:49152
	ds_read_b128 v[194:197], v145 offset:50176
	ds_read_b128 v[198:201], v144 offset:49152
	ds_read_b128 v[144:147], v144 offset:50176
	ds_read_b128 v[202:205], v143 offset:49152
	ds_read_b128 v[210:213], v143 offset:50176
	s_barrier
	s_waitcnt lgkmcnt(0)
	v_mfma_f32_16x16x32_bf16 v[54:57], v[184:187], v[6:9], v[54:57]
	v_mfma_f32_16x16x32_bf16 v[106:109], v[194:197], v[10:13], v[54:57]
	v_mfma_f32_16x16x32_bf16 v[54:57], v[184:187], v[22:25], v[226:229]
	v_mfma_f32_16x16x32_bf16 v[66:69], v[176:179], v[6:9], v[206:209]
	v_mfma_f32_16x16x32_bf16 v[74:77], v[194:197], v[172:175], v[54:57]
	v_mfma_f32_16x16x32_bf16 v[54:57], v[198:201], v[6:9], v[230:233]
	v_mfma_f32_16x16x32_bf16 v[6:9], v[202:205], v[6:9], v[38:41]
	v_mfma_f32_16x16x32_bf16 v[118:121], v[180:183], v[10:13], v[66:69]
	v_mfma_f32_16x16x32_bf16 v[66:69], v[176:179], v[22:25], v[222:225]
	v_mfma_f32_16x16x32_bf16 v[42:45], v[198:201], v[22:25], v[42:45]
	v_mfma_f32_16x16x32_bf16 v[98:101], v[210:213], v[10:13], v[6:9]
	v_mfma_f32_16x16x32_bf16 v[6:9], v[202:205], v[22:25], v[34:37]
	v_mfma_f32_16x16x32_bf16 v[86:89], v[180:183], v[172:175], v[66:69]
	v_mfma_f32_16x16x32_bf16 v[102:105], v[144:147], v[10:13], v[54:57]
	v_mfma_f32_16x16x32_bf16 v[70:73], v[144:147], v[172:175], v[42:45]
	v_mfma_f32_16x16x32_bf16 v[66:69], v[210:213], v[172:175], v[6:9]
	v_mfma_f32_16x16x32_bf16 v[6:9], v[176:179], v[214:217], v[134:137]
	v_mfma_f32_16x16x32_bf16 v[54:57], v[180:183], v[238:241], v[6:9]
	v_mfma_f32_16x16x32_bf16 v[6:9], v[176:179], v[242:245], v[138:141]
	v_mfma_f32_16x16x32_bf16 v[22:25], v[180:183], v[246:249], v[6:9]
	v_mfma_f32_16x16x32_bf16 v[6:9], v[184:187], v[214:217], v[162:165]
	v_mfma_f32_16x16x32_bf16 v[42:45], v[194:197], v[238:241], v[6:9]
	v_mfma_f32_16x16x32_bf16 v[6:9], v[184:187], v[242:245], v[168:171]
	v_mfma_f32_16x16x32_bf16 v[10:13], v[194:197], v[246:249], v[6:9]
	v_mfma_f32_16x16x32_bf16 v[6:9], v[198:201], v[214:217], v[234:237]
	v_mfma_f32_16x16x32_bf16 v[38:41], v[144:147], v[238:241], v[6:9]
	v_mfma_f32_16x16x32_bf16 v[6:9], v[198:201], v[242:245], v[190:193]
	v_mfma_f32_16x16x32_bf16 v[34:37], v[202:205], v[214:217], v[130:133]
	v_mfma_f32_16x16x32_bf16 v[2:5], v[202:205], v[242:245], v[2:5]
	v_mfma_f32_16x16x32_bf16 v[6:9], v[144:147], v[246:249], v[6:9]
	v_mfma_f32_16x16x32_bf16 v[34:37], v[210:213], v[238:241], v[34:37]
	v_mfma_f32_16x16x32_bf16 v[2:5], v[210:213], v[246:249], v[2:5]
	s_setprio 0
	s_movk_i32 s10, 0x100
	v_cmp_gt_u32_e32 vcc, s10, v0
	s_barrier
	s_and_saveexec_b64 s[12:13], vcc
	s_cbranch_execz .LBB0_131
	s_barrier

; #define STA(P, br, kt) STAGE(P, A, aoff0, aoff1, lda, br, kt)
; #define STB(P, br, kt) STAGE(P, Bt, boff0, boff1, ldb, br, kt)
; #define LDA(dst, b, h) _Pragma("unroll") for (int m = 0; m < 4; ++m) _Pragma("unroll") for (int k = 0; k < 2; ++k) \
;     dst[m][k] = *reinterpret_cast<const bf16x8*>((char*)SA(b, h) + lds_byte(wr * 64 + m * 16 + fr, k * 32 + fq * 8))
; #define LDB(dst, b, h) _Pragma("unroll") for (int n = 0; n < 2; ++n) _Pragma("unroll") for (int k = 0; k < 2; ++k) \
;     dst[n][k] = *reinterpret_cast<const bf16x8*>((char*)SB(b, h) + lds_byte(wc * 32 + n * 16 + fr, k * 32 + fq * 8))
; #define MMA(ai, bj, At, Bq) do { __builtin_amdgcn_s_setprio(1); \
;     _Pragma("unroll") for (int m = 0; m < 4; ++m) _Pragma("unroll") for (int n = 0; n < 2; ++n) _Pragma("unroll") for (int k = 0; k < 2; ++k) \
;       acc[ai][bj][m][n] = __builtin_amdgcn_mfma_f32_16x16x32_bf16(At[m][k], Bq[n][k], acc[ai][bj][m][n], 0, 0, 0); \
;     __builtin_amdgcn_s_setprio(0); } while (0)
; #define WAIT_L(n) asm volatile("s_waitcnt lgkmcnt(" #n ")" ::: "memory")
; #define BAR __builtin_amdgcn_s_barrier()
; #define SCHED __builtin_amdgcn_sched_barrier(0)
; __device__ __forceinline__ void gemm256(const u16* __restrict__ A, int lda, const u16* __restrict__ Bt, int ldb, int K,
;                                         f32x4 (&acc)[2][2][4][2], const int g_wid) {
;     ...
;     LDB(B0, 0, 0); SCHED; LDA(At, 0, 0); STA(SA(1, 1), HALF, t + 1);
;     WAIT_L(8); BAR; WAIT_L(0); MMA(0, 0, At, B0); BAR; SCHED;
;     LDB(B1, 0, 1); STB(SB(0, 0), 0, t + 2);
;     BAR; WAIT_L(0); MMA(0, 1, At, B1); BAR;
;     LDA(At, 0, 1); STA(SA(0, 0), 0, t + 2);
;     BAR; WAIT_L(0); MMA(1, 0, At, B0); BAR; SCHED;
.LBB0_136:
	ds_read_b128 v[178:181], v174
	ds_read_b128 v[182:185], v174 offset:1024
	ds_read_b128 v[186:189], v174 offset:2048
	ds_read_b128 v[190:193], v174 offset:3072
	v_add_u32_e32 v175, 0xc000, v160
	v_lshl_add_u64 v[242:243], v[140:141], 0, s[6:7]
	v_readfirstlane_b32 s10, v175
	v_lshl_add_u64 v[176:177], v[242:243], 0, s[68:69]
	s_mov_b32 m0, s10
	ds_read_b128 v[194:197], v145
	ds_read_b128 v[198:201], v145 offset:1024
	ds_read_b128 v[202:205], v144
	ds_read_b128 v[206:209], v144 offset:1024
	ds_read_b128 v[210:213], v143
	ds_read_b128 v[214:217], v143 offset:1024
	ds_read_b128 v[218:221], v142
	ds_read_b128 v[222:225], v142 offset:1024
	global_load_lds_dwordx4 v[176:177], off
	v_add_u32_e32 v176, 0xe000, v160
	v_lshl_add_u64 v[244:245], v[138:139], 0, s[6:7]
	s_add_u32 m0, m0, 0x2000
	v_lshl_add_u64 v[226:227], v[244:245], 0, s[68:69]
	global_load_lds_dwordx4 v[226:227], off
	s_waitcnt lgkmcnt(8)
	s_barrier
	s_waitcnt lgkmcnt(0)
	v_mfma_f32_16x16x32_bf16 v[126:129], v[194:197], v[178:181], v[126:129]
	v_mfma_f32_16x16x32_bf16 v[122:125], v[194:197], v[186:189], v[122:125]
	v_mfma_f32_16x16x32_bf16 v[118:121], v[202:205], v[178:181], v[118:121]
	v_mfma_f32_16x16x32_bf16 v[114:117], v[202:205], v[186:189], v[114:117]
	v_mfma_f32_16x16x32_bf16 v[110:113], v[210:213], v[178:181], v[110:113]
	v_mfma_f32_16x16x32_bf16 v[106:109], v[210:213], v[186:189], v[106:109]
	v_mfma_f32_16x16x32_bf16 v[102:105], v[218:221], v[178:181], v[102:105]
	v_mfma_f32_16x16x32_bf16 v[98:101], v[218:221], v[186:189], v[98:101]
	v_mfma_f32_16x16x32_bf16 v[126:129], v[198:201], v[182:185], v[126:129]
	v_mfma_f32_16x16x32_bf16 v[122:125], v[198:201], v[190:193], v[122:125]
	v_mfma_f32_16x16x32_bf16 v[118:121], v[206:209], v[182:185], v[118:121]
	v_mfma_f32_16x16x32_bf16 v[114:117], v[206:209], v[190:193], v[114:117]
	v_mfma_f32_16x16x32_bf16 v[110:113], v[214:217], v[182:185], v[110:113]
	v_mfma_f32_16x16x32_bf16 v[106:109], v[214:217], v[190:193], v[106:109]
	v_mfma_f32_16x16x32_bf16 v[102:105], v[222:225], v[182:185], v[102:105]
	v_mfma_f32_16x16x32_bf16 v[98:101], v[222:225], v[190:193], v[98:101]
	s_barrier
	v_lshl_add_u64 v[246:247], v[136:137], 0, s[6:7]
	v_readfirstlane_b32 s10, v146
	v_lshl_add_u64 v[248:249], v[246:247], 0, s[8:9]
	s_mov_b32 m0, s10
	ds_read_b128 v[226:229], v173
	ds_read_b128 v[230:233], v173 offset:1024
	ds_read_b128 v[234:237], v173 offset:2048
	ds_read_b128 v[238:241], v173 offset:3072
	global_load_lds_dwordx4 v[248:249], off
	v_lshl_add_u64 v[248:249], v[134:135], 0, s[6:7]
	s_add_u32 m0, m0, 0x2000
	v_lshl_add_u64 v[250:251], v[248:249], 0, s[8:9]
	global_load_lds_dwordx4 v[250:251], off
	s_barrier
	s_waitcnt lgkmcnt(0)
	v_mfma_f32_16x16x32_bf16 v[94:97], v[194:197], v[226:229], v[94:97]
	v_mfma_f32_16x16x32_bf16 v[90:93], v[194:197], v[234:237], v[90:93]
	v_mfma_f32_16x16x32_bf16 v[86:89], v[202:205], v[226:229], v[86:89]
	v_mfma_f32_16x16x32_bf16 v[82:85], v[202:205], v[234:237], v[82:85]
	v_mfma_f32_16x16x32_bf16 v[78:81], v[210:213], v[226:229], v[78:81]
	v_mfma_f32_16x16x32_bf16 v[74:77], v[210:213], v[234:237], v[74:77]
	v_mfma_f32_16x16x32_bf16 v[70:73], v[218:221], v[226:229], v[70:73]
	v_mfma_f32_16x16x32_bf16 v[66:69], v[218:221], v[234:237], v[66:69]
	v_mfma_f32_16x16x32_bf16 v[94:97], v[198:201], v[230:233], v[94:97]
	v_mfma_f32_16x16x32_bf16 v[90:93], v[198:201], v[238:241], v[90:93]
	v_mfma_f32_16x16x32_bf16 v[86:89], v[206:209], v[230:233], v[86:89]
	v_mfma_f32_16x16x32_bf16 v[82:85], v[206:209], v[238:241], v[82:85]
	v_mfma_f32_16x16x32_bf16 v[78:81], v[214:217], v[230:233], v[78:81]
	v_mfma_f32_16x16x32_bf16 v[74:77], v[214:217], v[238:241], v[74:77]
	v_mfma_f32_16x16x32_bf16 v[70:73], v[222:225], v[230:233], v[70:73]
	v_mfma_f32_16x16x32_bf16 v[66:69], v[222:225], v[238:241], v[66:69]
	v_readfirstlane_b32 s10, v160
	v_lshl_add_u64 v[250:251], v[242:243], 0, s[74:75]
	s_mov_b32 m0, s10
	s_barrier
	ds_read_b128 v[194:197], v145 offset:16384
	ds_read_b128 v[198:201], v145 offset:17408
	ds_read_b128 v[202:205], v144 offset:16384
	ds_read_b128 v[206:209], v144 offset:17408
	ds_read_b128 v[210:213], v143 offset:16384
	ds_read_b128 v[214:217], v143 offset:17408
	ds_read_b128 v[218:221], v142 offset:16384
	ds_read_b128 v[222:225], v142 offset:17408
	global_load_lds_dwordx4 v[250:251], off
	s_add_u32 m0, m0, 0x2000
	v_lshl_add_u64 v[250:251], v[244:245], 0, s[74:75]
	global_load_lds_dwordx4 v[250:251], off
	s_barrier
	s_waitcnt lgkmcnt(0)
	v_mfma_f32_16x16x32_bf16 v[62:65], v[194:197], v[178:181], v[62:65]
	v_mfma_f32_16x16x32_bf16 v[58:61], v[194:197], v[186:189], v[58:61]
	v_mfma_f32_16x16x32_bf16 v[54:57], v[202:205], v[178:181], v[54:57]
	v_mfma_f32_16x16x32_bf16 v[50:53], v[202:205], v[186:189], v[50:53]
	v_mfma_f32_16x16x32_bf16 v[46:49], v[210:213], v[178:181], v[46:49]
	v_mfma_f32_16x16x32_bf16 v[42:45], v[210:213], v[186:189], v[42:45]
	v_mfma_f32_16x16x32_bf16 v[38:41], v[218:221], v[178:181], v[38:41]
	v_mfma_f32_16x16x32_bf16 v[34:37], v[218:221], v[186:189], v[34:37]
	v_mfma_f32_16x16x32_bf16 v[62:65], v[198:201], v[182:185], v[62:65]
	v_mfma_f32_16x16x32_bf16 v[58:61], v[198:201], v[190:193], v[58:61]
	v_mfma_f32_16x16x32_bf16 v[54:57], v[206:209], v[182:185], v[54:57]
	v_mfma_f32_16x16x32_bf16 v[50:53], v[206:209], v[190:193], v[50:53]
	v_mfma_f32_16x16x32_bf16 v[46:49], v[214:217], v[182:185], v[46:49]
	v_mfma_f32_16x16x32_bf16 v[42:45], v[214:217], v[190:193], v[42:45]
	v_mfma_f32_16x16x32_bf16 v[38:41], v[222:225], v[182:185], v[38:41]
	v_mfma_f32_16x16x32_bf16 v[34:37], v[222:225], v[190:193], v[34:37]
	s_barrier
; #define STA(P, br, kt) STAGE(P, A, aoff0, aoff1, lda, br, kt)
; #define STB(P, br, kt) STAGE(P, Bt, boff0, boff1, ldb, br, kt)
; #define LDA(dst, b, h) _Pragma("unroll") for (int m = 0; m < 4; ++m) _Pragma("unroll") for (int k = 0; k < 2; ++k) \
;     dst[m][k] = *reinterpret_cast<const bf16x8*>((char*)SA(b, h) + lds_byte(wr * 64 + m * 16 + fr, k * 32 + fq * 8))
; #define LDB(dst, b, h) _Pragma("unroll") for (int n = 0; n < 2; ++n) _Pragma("unroll") for (int k = 0; k < 2; ++k) \
;     dst[n][k] = *reinterpret_cast<const bf16x8*>((char*)SB(b, h) + lds_byte(wc * 32 + n * 16 + fr, k * 32 + fq * 8))
; #define MMA(ai, bj, At, Bq) do { __builtin_amdgcn_s_setprio(1); \
;     _Pragma("unroll") for (int m = 0; m < 4; ++m) _Pragma("unroll") for (int n = 0; n < 2; ++n) _Pragma("unroll") for (int k = 0; k < 2; ++k) \
;       acc[ai][bj][m][n] = __builtin_amdgcn_mfma_f32_16x16x32_bf16(At[m][k], Bq[n][k], acc[ai][bj][m][n], 0, 0, 0); \
;     __builtin_amdgcn_s_setprio(0); } while (0)
; #define WAIT_V(n) asm volatile("s_waitcnt vmcnt(" #n ")" ::: "memory")
; #define WAIT_L(n) asm volatile("s_waitcnt lgkmcnt(" #n ")" ::: "memory")
; #define BAR __builtin_amdgcn_s_barrier()
; #define SCHED __builtin_amdgcn_sched_barrier(0)
; __device__ __forceinline__ void gemm256(const u16* __restrict__ A, int lda, const u16* __restrict__ Bt, int ldb, int K,
;                                         f32x4 (&acc)[2][2][4][2], const int g_wid) {
;     ...
;     STB(SB(0, 1), HALF, t + 2);
;     WAIT_V(6); BAR; MMA(1, 1, At, B1); BAR;
;     LDB(B0, 1, 0); SCHED; LDA(At, 1, 0); STA(SA(0, 1), HALF, t + 2);
;     WAIT_L(8); BAR; WAIT_L(0); MMA(0, 0, At, B0); BAR; SCHED;
;     LDB(B1, 1, 1); STB(SB(1, 0), 0, t + 3);
;     BAR; WAIT_L(0); MMA(0, 1, At, B1); BAR;
;     LDA(At, 1, 1); STA(SA(1, 0), 0, t + 3);
	v_readfirstlane_b32 s10, v162
	v_lshl_add_u64 v[178:179], v[246:247], 0, s[16:17]
	s_mov_b32 m0, s10
	global_load_lds_dwordx4 v[178:179], off
	s_add_u32 m0, m0, 0x2000
	v_lshl_add_u64 v[178:179], v[248:249], 0, s[16:17]
	global_load_lds_dwordx4 v[178:179], off
	s_waitcnt vmcnt(6)
	s_barrier
	v_mfma_f32_16x16x32_bf16 v[30:33], v[194:197], v[226:229], v[30:33]
	v_mfma_f32_16x16x32_bf16 v[26:29], v[194:197], v[234:237], v[26:29]
	v_mfma_f32_16x16x32_bf16 v[22:25], v[202:205], v[226:229], v[22:25]
	v_mfma_f32_16x16x32_bf16 v[18:21], v[202:205], v[234:237], v[18:21]
	v_mfma_f32_16x16x32_bf16 v[14:17], v[210:213], v[226:229], v[14:17]
	v_mfma_f32_16x16x32_bf16 v[10:13], v[210:213], v[234:237], v[10:13]
	v_mfma_f32_16x16x32_bf16 v[6:9], v[218:221], v[226:229], v[6:9]
	v_mfma_f32_16x16x32_bf16 v[2:5], v[218:221], v[234:237], v[2:5]
	v_mfma_f32_16x16x32_bf16 v[30:33], v[198:201], v[230:233], v[30:33]
	v_mfma_f32_16x16x32_bf16 v[26:29], v[198:201], v[238:241], v[26:29]
	v_mfma_f32_16x16x32_bf16 v[22:25], v[206:209], v[230:233], v[22:25]
	v_mfma_f32_16x16x32_bf16 v[18:21], v[206:209], v[238:241], v[18:21]
	v_mfma_f32_16x16x32_bf16 v[14:17], v[214:217], v[230:233], v[14:17]
	v_mfma_f32_16x16x32_bf16 v[10:13], v[214:217], v[238:241], v[10:13]
	v_mfma_f32_16x16x32_bf16 v[6:9], v[222:225], v[230:233], v[6:9]
	v_mfma_f32_16x16x32_bf16 v[2:5], v[222:225], v[238:241], v[2:5]
	s_barrier
	ds_read_b128 v[178:181], v165
	ds_read_b128 v[182:185], v165 offset:1024
	ds_read_b128 v[186:189], v165 offset:2048
	ds_read_b128 v[190:193], v165 offset:3072
	v_readfirstlane_b32 s10, v164
	v_lshl_add_u64 v[226:227], v[242:243], 0, s[78:79]
	s_mov_b32 m0, s10
	ds_read_b128 v[194:197], v145 offset:32768
	ds_read_b128 v[198:201], v145 offset:33792
	ds_read_b128 v[202:205], v144 offset:32768
	ds_read_b128 v[206:209], v144 offset:33792
	ds_read_b128 v[210:213], v143 offset:32768
	ds_read_b128 v[214:217], v143 offset:33792
	ds_read_b128 v[218:221], v142 offset:32768
	ds_read_b128 v[222:225], v142 offset:33792
	global_load_lds_dwordx4 v[226:227], off
	s_add_u32 m0, m0, 0x2000
	v_lshl_add_u64 v[226:227], v[244:245], 0, s[78:79]
	global_load_lds_dwordx4 v[226:227], off
	s_waitcnt lgkmcnt(8)
	s_barrier
	s_waitcnt lgkmcnt(0)
	v_mfma_f32_16x16x32_bf16 v[126:129], v[194:197], v[178:181], v[126:129]
	v_mfma_f32_16x16x32_bf16 v[122:125], v[194:197], v[186:189], v[122:125]
	v_mfma_f32_16x16x32_bf16 v[118:121], v[202:205], v[178:181], v[118:121]
	v_mfma_f32_16x16x32_bf16 v[114:117], v[202:205], v[186:189], v[114:117]
	v_mfma_f32_16x16x32_bf16 v[110:113], v[210:213], v[178:181], v[110:113]
	v_mfma_f32_16x16x32_bf16 v[106:109], v[210:213], v[186:189], v[106:109]
	v_mfma_f32_16x16x32_bf16 v[102:105], v[218:221], v[178:181], v[102:105]
	v_mfma_f32_16x16x32_bf16 v[98:101], v[218:221], v[186:189], v[98:101]
	v_mfma_f32_16x16x32_bf16 v[126:129], v[198:201], v[182:185], v[126:129]
	v_mfma_f32_16x16x32_bf16 v[122:125], v[198:201], v[190:193], v[122:125]
	v_mfma_f32_16x16x32_bf16 v[118:121], v[206:209], v[182:185], v[118:121]
	v_mfma_f32_16x16x32_bf16 v[114:117], v[206:209], v[190:193], v[114:117]
	v_mfma_f32_16x16x32_bf16 v[110:113], v[214:217], v[182:185], v[110:113]
	v_mfma_f32_16x16x32_bf16 v[106:109], v[214:217], v[190:193], v[106:109]
	v_mfma_f32_16x16x32_bf16 v[102:105], v[222:225], v[182:185], v[102:105]
	v_mfma_f32_16x16x32_bf16 v[98:101], v[222:225], v[190:193], v[98:101]
	s_barrier
	v_readfirstlane_b32 s10, v167
	v_lshl_add_u64 v[250:251], v[246:247], 0, s[18:19]
	s_mov_b32 m0, s10
	ds_read_b128 v[226:229], v159
	ds_read_b128 v[230:233], v159 offset:1024
	ds_read_b128 v[234:237], v159 offset:2048
	ds_read_b128 v[238:241], v159 offset:3072
	global_load_lds_dwordx4 v[250:251], off
	s_add_u32 m0, m0, 0x2000
	v_lshl_add_u64 v[250:251], v[248:249], 0, s[18:19]
	global_load_lds_dwordx4 v[250:251], off
	s_barrier
	s_waitcnt lgkmcnt(0)
	v_mfma_f32_16x16x32_bf16 v[94:97], v[194:197], v[226:229], v[94:97]
	v_mfma_f32_16x16x32_bf16 v[90:93], v[194:197], v[234:237], v[90:93]
	v_mfma_f32_16x16x32_bf16 v[86:89], v[202:205], v[226:229], v[86:89]
	v_mfma_f32_16x16x32_bf16 v[82:85], v[202:205], v[234:237], v[82:85]
	v_mfma_f32_16x16x32_bf16 v[78:81], v[210:213], v[226:229], v[78:81]
	v_mfma_f32_16x16x32_bf16 v[74:77], v[210:213], v[234:237], v[74:77]
	v_mfma_f32_16x16x32_bf16 v[70:73], v[218:221], v[226:229], v[70:73]
	v_mfma_f32_16x16x32_bf16 v[66:69], v[218:221], v[234:237], v[66:69]
	v_mfma_f32_16x16x32_bf16 v[94:97], v[198:201], v[230:233], v[94:97]
	v_mfma_f32_16x16x32_bf16 v[90:93], v[198:201], v[238:241], v[90:93]
	v_mfma_f32_16x16x32_bf16 v[86:89], v[206:209], v[230:233], v[86:89]
	v_mfma_f32_16x16x32_bf16 v[82:85], v[206:209], v[238:241], v[82:85]
	v_mfma_f32_16x16x32_bf16 v[78:81], v[214:217], v[230:233], v[78:81]
	v_mfma_f32_16x16x32_bf16 v[74:77], v[214:217], v[238:241], v[74:77]
	v_mfma_f32_16x16x32_bf16 v[70:73], v[222:225], v[230:233], v[70:73]
	v_mfma_f32_16x16x32_bf16 v[66:69], v[222:225], v[238:241], v[66:69]
	v_readfirstlane_b32 s10, v169
	v_lshl_add_u64 v[242:243], v[242:243], 0, s[82:83]
	s_mov_b32 m0, s10
	s_barrier
	ds_read_b128 v[194:197], v145 offset:49152
	ds_read_b128 v[198:201], v145 offset:50176
	ds_read_b128 v[202:205], v144 offset:49152
	ds_read_b128 v[206:209], v144 offset:50176
	ds_read_b128 v[210:213], v143 offset:49152
	ds_read_b128 v[214:217], v143 offset:50176
	ds_read_b128 v[218:221], v142 offset:49152
	ds_read_b128 v[222:225], v142 offset:50176
	global_load_lds_dwordx4 v[242:243], off
	s_add_u32 m0, m0, 0x2000
	v_lshl_add_u64 v[242:243], v[244:245], 0, s[82:83]
	global_load_lds_dwordx4 v[242:243], off
	s_barrier
; #define STA(P, br, kt) STAGE(P, A, aoff0, aoff1, lda, br, kt)
; #define STB(P, br, kt) STAGE(P, Bt, boff0, boff1, ldb, br, kt)
; #define LDA(dst, b, h) _Pragma("unroll") for (int m = 0; m < 4; ++m) _Pragma("unroll") for (int k = 0; k < 2; ++k) \
;     dst[m][k] = *reinterpret_cast<const bf16x8*>((char*)SA(b, h) + lds_byte(wr * 64 + m * 16 + fr, k * 32 + fq * 8))
; #define LDB(dst, b, h) _Pragma("unroll") for (int n = 0; n < 2; ++n) _Pragma("unroll") for (int k = 0; k < 2; ++k) \
;     dst[n][k] = *reinterpret_cast<const bf16x8*>((char*)SB(b, h) + lds_byte(wc * 32 + n * 16 + fr, k * 32 + fq * 8))
; #define MMA(ai, bj, At, Bq) do { __builtin_amdgcn_s_setprio(1); \
;     _Pragma("unroll") for (int m = 0; m < 4; ++m) _Pragma("unroll") for (int n = 0; n < 2; ++n) _Pragma("unroll") for (int k = 0; k < 2; ++k) \
;       acc[ai][bj][m][n] = __builtin_amdgcn_mfma_f32_16x16x32_bf16(At[m][k], Bq[n][k], acc[ai][bj][m][n], 0, 0, 0); \
;     __builtin_amdgcn_s_setprio(0); } while (0)
; #define WAIT_V(n) asm volatile("s_waitcnt vmcnt(" #n ")" ::: "memory")
; #define WAIT_L(n) asm volatile("s_waitcnt lgkmcnt(" #n ")" ::: "memory")
; #define BAR __builtin_amdgcn_s_barrier()
; #define SCHED __builtin_amdgcn_sched_barrier(0)
; __device__ __forceinline__ void gemm256(const u16* __restrict__ A, int lda, const u16* __restrict__ Bt, int ldb, int K,
;                                         f32x4 (&acc)[2][2][4][2], const int g_wid) {
;     ...
;     BAR; WAIT_L(0); MMA(1, 0, At, B0); BAR; SCHED;
;     STB(SB(1, 1), HALF, t + 3);
;     WAIT_V(6); BAR; MMA(1, 1, At, B1); BAR;
;   }
;   { LDB(B0, 0, 0); LDA(At, 0, 0); STA(SA(1, 1), HALF, nt - 1);
;     BAR; WAIT_L(0); MMA(0, 0, At, B0); BAR;
;     LDB(B1, 0, 1); BAR; WAIT_L(0); MMA(0, 1, At, B1); BAR;
;     LDA(At, 0, 1); WAIT_V(4); BAR; WAIT_L(0); MMA(1, 0, At, B0); MMA(1, 1, At, B1); BAR; }
	s_waitcnt lgkmcnt(0)
	v_mfma_f32_16x16x32_bf16 v[62:65], v[194:197], v[178:181], v[62:65]
	v_mfma_f32_16x16x32_bf16 v[58:61], v[194:197], v[186:189], v[58:61]
	v_mfma_f32_16x16x32_bf16 v[54:57], v[202:205], v[178:181], v[54:57]
	v_mfma_f32_16x16x32_bf16 v[50:53], v[202:205], v[186:189], v[50:53]
	v_mfma_f32_16x16x32_bf16 v[46:49], v[210:213], v[178:181], v[46:49]
	v_mfma_f32_16x16x32_bf16 v[42:45], v[210:213], v[186:189], v[42:45]
	v_mfma_f32_16x16x32_bf16 v[38:41], v[218:221], v[178:181], v[38:41]
	v_mfma_f32_16x16x32_bf16 v[34:37], v[218:221], v[186:189], v[34:37]
	v_mfma_f32_16x16x32_bf16 v[62:65], v[198:201], v[182:185], v[62:65]
	v_mfma_f32_16x16x32_bf16 v[58:61], v[198:201], v[190:193], v[58:61]
	v_mfma_f32_16x16x32_bf16 v[54:57], v[206:209], v[182:185], v[54:57]
	v_mfma_f32_16x16x32_bf16 v[50:53], v[206:209], v[190:193], v[50:53]
	v_mfma_f32_16x16x32_bf16 v[46:49], v[214:217], v[182:185], v[46:49]
	v_mfma_f32_16x16x32_bf16 v[42:45], v[214:217], v[190:193], v[42:45]
	v_mfma_f32_16x16x32_bf16 v[38:41], v[222:225], v[182:185], v[38:41]
	v_mfma_f32_16x16x32_bf16 v[34:37], v[222:225], v[190:193], v[34:37]
	s_barrier
	v_readfirstlane_b32 s10, v171
	v_lshl_add_u64 v[178:179], v[246:247], 0, s[20:21]
	s_mov_b32 m0, s10
	global_load_lds_dwordx4 v[178:179], off
	s_add_u32 m0, m0, 0x2000
	v_lshl_add_u64 v[178:179], v[248:249], 0, s[20:21]
	global_load_lds_dwordx4 v[178:179], off
	s_waitcnt vmcnt(6)
	s_barrier
	v_mfma_f32_16x16x32_bf16 v[30:33], v[194:197], v[226:229], v[30:33]
	v_mfma_f32_16x16x32_bf16 v[26:29], v[194:197], v[234:237], v[26:29]
	v_mfma_f32_16x16x32_bf16 v[22:25], v[202:205], v[226:229], v[22:25]
	v_mfma_f32_16x16x32_bf16 v[18:21], v[202:205], v[234:237], v[18:21]
	v_mfma_f32_16x16x32_bf16 v[14:17], v[210:213], v[226:229], v[14:17]
	v_mfma_f32_16x16x32_bf16 v[10:13], v[210:213], v[234:237], v[10:13]
	v_mfma_f32_16x16x32_bf16 v[6:9], v[218:221], v[226:229], v[6:9]
	v_mfma_f32_16x16x32_bf16 v[2:5], v[218:221], v[234:237], v[2:5]
	v_mfma_f32_16x16x32_bf16 v[30:33], v[198:201], v[230:233], v[30:33]
	v_mfma_f32_16x16x32_bf16 v[26:29], v[198:201], v[238:241], v[26:29]
	v_mfma_f32_16x16x32_bf16 v[22:25], v[206:209], v[230:233], v[22:25]
	v_mfma_f32_16x16x32_bf16 v[18:21], v[206:209], v[238:241], v[18:21]
	v_mfma_f32_16x16x32_bf16 v[14:17], v[214:217], v[230:233], v[14:17]
	v_mfma_f32_16x16x32_bf16 v[10:13], v[214:217], v[238:241], v[10:13]
	v_mfma_f32_16x16x32_bf16 v[6:9], v[222:225], v[230:233], v[6:9]
	v_mfma_f32_16x16x32_bf16 v[2:5], v[222:225], v[238:241], v[2:5]
	s_add_i32 s14, s14, 2
	s_add_u32 s6, s6, 0x100
	s_addc_u32 s7, s7, 0
	s_cmp_lt_u32 s14, 12
	s_barrier
	s_cbranch_scc1 .LBB0_136
	s_add_u32 s6, s12, 0x40780
	s_addc_u32 s7, s13, 0
	v_readfirstlane_b32 s10, v175
	v_lshl_add_u64 v[132:133], v[132:133], 1, s[6:7]
	s_mov_b32 m0, s10
	v_lshl_add_u64 v[130:131], v[130:131], 1, s[6:7]
	v_readfirstlane_b32 s6, v176
	ds_read_b128 v[134:137], v174
	ds_read_b128 v[138:141], v174 offset:1024
	ds_read_b128 v[160:163], v174 offset:2048
	ds_read_b128 v[166:169], v174 offset:3072
	ds_read_b128 v[178:181], v145
	ds_read_b128 v[182:185], v145 offset:1024
	ds_read_b128 v[186:189], v144
	ds_read_b128 v[190:193], v144 offset:1024
	ds_read_b128 v[194:197], v143
	ds_read_b128 v[198:201], v143 offset:1024
	ds_read_b128 v[202:205], v142
	ds_read_b128 v[206:209], v142 offset:1024
	global_load_lds_dwordx4 v[132:133], off
	s_mov_b32 m0, s6
	s_nop 0
	global_load_lds_dwordx4 v[130:131], off
	s_barrier
	s_waitcnt lgkmcnt(0)
	v_mfma_f32_16x16x32_bf16 v[126:129], v[178:181], v[134:137], v[126:129]
	v_mfma_f32_16x16x32_bf16 v[122:125], v[178:181], v[160:163], v[122:125]
	v_mfma_f32_16x16x32_bf16 v[118:121], v[186:189], v[134:137], v[118:121]
	v_mfma_f32_16x16x32_bf16 v[114:117], v[186:189], v[160:163], v[114:117]
	v_mfma_f32_16x16x32_bf16 v[110:113], v[194:197], v[134:137], v[110:113]
	v_mfma_f32_16x16x32_bf16 v[106:109], v[194:197], v[160:163], v[106:109]
	v_mfma_f32_16x16x32_bf16 v[102:105], v[202:205], v[134:137], v[102:105]
	v_mfma_f32_16x16x32_bf16 v[98:101], v[202:205], v[160:163], v[98:101]
	v_mfma_f32_16x16x32_bf16 v[126:129], v[182:185], v[138:141], v[126:129]
	v_mfma_f32_16x16x32_bf16 v[122:125], v[182:185], v[166:169], v[122:125]
	v_mfma_f32_16x16x32_bf16 v[118:121], v[190:193], v[138:141], v[118:121]
	v_mfma_f32_16x16x32_bf16 v[114:117], v[190:193], v[166:169], v[114:117]
	v_mfma_f32_16x16x32_bf16 v[110:113], v[198:201], v[138:141], v[110:113]
	v_mfma_f32_16x16x32_bf16 v[106:109], v[198:201], v[166:169], v[106:109]
	v_mfma_f32_16x16x32_bf16 v[102:105], v[206:209], v[138:141], v[102:105]
	v_mfma_f32_16x16x32_bf16 v[98:101], v[206:209], v[166:169], v[98:101]
	s_barrier
	ds_read_b128 v[130:133], v173
	ds_read_b128 v[174:177], v173 offset:1024
	ds_read_b128 v[210:213], v173 offset:2048
	ds_read_b128 v[170:173], v173 offset:3072
	s_barrier
	s_waitcnt lgkmcnt(0)
	v_mfma_f32_16x16x32_bf16 v[86:89], v[186:189], v[130:133], v[86:89]
	v_mfma_f32_16x16x32_bf16 v[74:77], v[194:197], v[210:213], v[74:77]
	v_mfma_f32_16x16x32_bf16 v[70:73], v[202:205], v[130:133], v[70:73]
	v_mfma_f32_16x16x32_bf16 v[66:69], v[202:205], v[210:213], v[66:69]
	v_mfma_f32_16x16x32_bf16 v[94:97], v[178:181], v[130:133], v[94:97]
	v_mfma_f32_16x16x32_bf16 v[90:93], v[178:181], v[210:213], v[90:93]
	v_mfma_f32_16x16x32_bf16 v[86:89], v[190:193], v[174:177], v[86:89]
	v_mfma_f32_16x16x32_bf16 v[82:85], v[186:189], v[210:213], v[82:85]
	v_mfma_f32_16x16x32_bf16 v[78:81], v[194:197], v[130:133], v[78:81]
	v_mfma_f32_16x16x32_bf16 v[74:77], v[198:201], v[170:173], v[74:77]
	v_mfma_f32_16x16x32_bf16 v[70:73], v[206:209], v[174:177], v[70:73]
	v_mfma_f32_16x16x32_bf16 v[66:69], v[206:209], v[170:173], v[66:69]
	v_mfma_f32_16x16x32_bf16 v[214:217], v[182:185], v[174:177], v[94:97]
	v_mfma_f32_16x16x32_bf16 v[178:181], v[182:185], v[170:173], v[90:93]
	v_mfma_f32_16x16x32_bf16 v[182:185], v[190:193], v[170:173], v[82:85]
	v_mfma_f32_16x16x32_bf16 v[186:189], v[198:201], v[174:177], v[78:81]
	s_barrier
; #define LDA(dst, b, h) _Pragma("unroll") for (int m = 0; m < 4; ++m) _Pragma("unroll") for (int k = 0; k < 2; ++k) \
;     dst[m][k] = *reinterpret_cast<const bf16x8*>((char*)SA(b, h) + lds_byte(wr * 64 + m * 16 + fr, k * 32 + fq * 8))
; #define LDB(dst, b, h) _Pragma("unroll") for (int n = 0; n < 2; ++n) _Pragma("unroll") for (int k = 0; k < 2; ++k) \
;     dst[n][k] = *reinterpret_cast<const bf16x8*>((char*)SB(b, h) + lds_byte(wc * 32 + n * 16 + fr, k * 32 + fq * 8))
; #define MMA(ai, bj, At, Bq) do { __builtin_amdgcn_s_setprio(1); \
;     _Pragma("unroll") for (int m = 0; m < 4; ++m) _Pragma("unroll") for (int n = 0; n < 2; ++n) _Pragma("unroll") for (int k = 0; k < 2; ++k) \
;       acc[ai][bj][m][n] = __builtin_amdgcn_mfma_f32_16x16x32_bf16(At[m][k], Bq[n][k], acc[ai][bj][m][n], 0, 0, 0); \
;     __builtin_amdgcn_s_setprio(0); } while (0)
; #define WAIT_V(n) asm volatile("s_waitcnt vmcnt(" #n ")" ::: "memory")
; #define WAIT_L(n) asm volatile("s_waitcnt lgkmcnt(" #n ")" ::: "memory")
; #define BAR __builtin_amdgcn_s_barrier()
; __device__ __forceinline__ void gemm256(const u16* __restrict__ A, int lda, const u16* __restrict__ Bt, int ldb, int K,
;                                         f32x4 (&acc)[2][2][4][2], const int g_wid) {
;     ...
;     LDA(At, 0, 1); WAIT_V(4); BAR; WAIT_L(0); MMA(1, 0, At, B0); MMA(1, 1, At, B1); BAR; }
;   { LDB(B0, 1, 0); LDA(At, 1, 0); WAIT_V(2); BAR; WAIT_L(0); MMA(0, 0, At, B0); BAR;
	s_nop 0
	ds_read_b128 v[78:81], v145 offset:16384
	ds_read_b128 v[82:85], v145 offset:17408
	ds_read_b128 v[90:93], v144 offset:16384
	ds_read_b128 v[94:97], v144 offset:17408
	ds_read_b128 v[190:193], v143 offset:16384
	ds_read_b128 v[194:197], v143 offset:17408
	ds_read_b128 v[198:201], v142 offset:16384
	ds_read_b128 v[202:205], v142 offset:17408
	s_waitcnt vmcnt(4)
	s_barrier
	s_waitcnt lgkmcnt(0)
	v_mfma_f32_16x16x32_bf16 v[54:57], v[90:93], v[134:137], v[54:57]
	v_mfma_f32_16x16x32_bf16 v[42:45], v[190:193], v[160:163], v[42:45]
	v_mfma_f32_16x16x32_bf16 v[38:41], v[198:201], v[134:137], v[38:41]
	v_mfma_f32_16x16x32_bf16 v[34:37], v[198:201], v[160:163], v[34:37]
	v_mfma_f32_16x16x32_bf16 v[62:65], v[78:81], v[134:137], v[62:65]
	v_mfma_f32_16x16x32_bf16 v[58:61], v[78:81], v[160:163], v[58:61]
	v_mfma_f32_16x16x32_bf16 v[54:57], v[94:97], v[138:141], v[54:57]
	v_mfma_f32_16x16x32_bf16 v[50:53], v[90:93], v[160:163], v[50:53]
	v_mfma_f32_16x16x32_bf16 v[46:49], v[190:193], v[134:137], v[46:49]
	v_mfma_f32_16x16x32_bf16 v[42:45], v[194:197], v[166:169], v[42:45]
	v_mfma_f32_16x16x32_bf16 v[38:41], v[202:205], v[138:141], v[38:41]
	v_mfma_f32_16x16x32_bf16 v[34:37], v[202:205], v[166:169], v[34:37]
	v_mfma_f32_16x16x32_bf16 v[206:209], v[82:85], v[138:141], v[62:65]
	v_mfma_f32_16x16x32_bf16 v[218:221], v[82:85], v[166:169], v[58:61]
	v_mfma_f32_16x16x32_bf16 v[222:225], v[94:97], v[166:169], v[50:53]
	v_mfma_f32_16x16x32_bf16 v[226:229], v[194:197], v[138:141], v[46:49]
	v_mfma_f32_16x16x32_bf16 v[2:5], v[198:201], v[210:213], v[2:5]
	v_mfma_f32_16x16x32_bf16 v[30:33], v[78:81], v[130:133], v[30:33]
	v_mfma_f32_16x16x32_bf16 v[26:29], v[78:81], v[210:213], v[26:29]
	v_mfma_f32_16x16x32_bf16 v[22:25], v[90:93], v[130:133], v[22:25]
	v_mfma_f32_16x16x32_bf16 v[18:21], v[90:93], v[210:213], v[18:21]
	v_mfma_f32_16x16x32_bf16 v[14:17], v[190:193], v[130:133], v[14:17]
	v_mfma_f32_16x16x32_bf16 v[10:13], v[190:193], v[210:213], v[10:13]
	v_mfma_f32_16x16x32_bf16 v[6:9], v[198:201], v[130:133], v[6:9]
	v_mfma_f32_16x16x32_bf16 v[2:5], v[202:205], v[170:173], v[2:5]
	v_mfma_f32_16x16x32_bf16 v[134:137], v[82:85], v[174:177], v[30:33]
	v_mfma_f32_16x16x32_bf16 v[138:141], v[82:85], v[170:173], v[26:29]
	v_mfma_f32_16x16x32_bf16 v[160:163], v[94:97], v[174:177], v[22:25]
	v_mfma_f32_16x16x32_bf16 v[166:169], v[94:97], v[170:173], v[18:21]
	v_mfma_f32_16x16x32_bf16 v[230:233], v[194:197], v[174:177], v[14:17]
	v_mfma_f32_16x16x32_bf16 v[190:193], v[194:197], v[170:173], v[10:13]
	v_mfma_f32_16x16x32_bf16 v[130:133], v[202:205], v[174:177], v[6:9]
	s_barrier
	s_nop 0
	ds_read_b128 v[6:9], v165
	ds_read_b128 v[10:13], v165 offset:1024
	ds_read_b128 v[22:25], v165 offset:2048
	ds_read_b128 v[170:173], v165 offset:3072
	ds_read_b128 v[14:17], v145 offset:32768
	ds_read_b128 v[18:21], v145 offset:33792
	ds_read_b128 v[26:29], v144 offset:32768
	ds_read_b128 v[46:49], v144 offset:33792
	ds_read_b128 v[174:177], v143 offset:32768
	ds_read_b128 v[194:197], v143 offset:33792
	ds_read_b128 v[198:201], v142 offset:32768
	ds_read_b128 v[202:205], v142 offset:33792
	s_waitcnt vmcnt(2)
	s_barrier
	s_waitcnt lgkmcnt(0)
	v_mfma_f32_16x16x32_bf16 v[30:33], v[14:17], v[6:9], v[126:129]
	v_mfma_f32_16x16x32_bf16 v[126:129], v[18:21], v[10:13], v[30:33]
	v_mfma_f32_16x16x32_bf16 v[30:33], v[14:17], v[22:25], v[122:125]
	v_mfma_f32_16x16x32_bf16 v[94:97], v[18:21], v[170:173], v[30:33]
	v_mfma_f32_16x16x32_bf16 v[30:33], v[26:29], v[6:9], v[118:121]
	v_mfma_f32_16x16x32_bf16 v[122:125], v[46:49], v[10:13], v[30:33]
	v_mfma_f32_16x16x32_bf16 v[30:33], v[26:29], v[22:25], v[114:117]
	v_mfma_f32_16x16x32_bf16 v[90:93], v[46:49], v[170:173], v[30:33]
	v_mfma_f32_16x16x32_bf16 v[30:33], v[174:177], v[6:9], v[110:113]
	v_mfma_f32_16x16x32_bf16 v[114:117], v[194:197], v[10:13], v[30:33]
	v_mfma_f32_16x16x32_bf16 v[30:33], v[174:177], v[22:25], v[106:109]
	v_mfma_f32_16x16x32_bf16 v[82:85], v[194:197], v[170:173], v[30:33]
	v_mfma_f32_16x16x32_bf16 v[30:33], v[198:201], v[6:9], v[102:105]
	v_mfma_f32_16x16x32_bf16 v[110:113], v[202:205], v[10:13], v[30:33]
	v_mfma_f32_16x16x32_bf16 v[30:33], v[198:201], v[22:25], v[98:101]
	v_mfma_f32_16x16x32_bf16 v[78:81], v[202:205], v[170:173], v[30:33]
	s_barrier
; #define LDA(dst, b, h) _Pragma("unroll") for (int m = 0; m < 4; ++m) _Pragma("unroll") for (int k = 0; k < 2; ++k) \
;     dst[m][k] = *reinterpret_cast<const bf16x8*>((char*)SA(b, h) + lds_byte(wr * 64 + m * 16 + fr, k * 32 + fq * 8))
; #define LDB(dst, b, h) _Pragma("unroll") for (int n = 0; n < 2; ++n) _Pragma("unroll") for (int k = 0; k < 2; ++k) \
;     dst[n][k] = *reinterpret_cast<const bf16x8*>((char*)SB(b, h) + lds_byte(wc * 32 + n * 16 + fr, k * 32 + fq * 8))
; #define MMA(ai, bj, At, Bq) do { __builtin_amdgcn_s_setprio(1); \
;     _Pragma("unroll") for (int m = 0; m < 4; ++m) _Pragma("unroll") for (int n = 0; n < 2; ++n) _Pragma("unroll") for (int k = 0; k < 2; ++k) \
;       acc[ai][bj][m][n] = __builtin_amdgcn_mfma_f32_16x16x32_bf16(At[m][k], Bq[n][k], acc[ai][bj][m][n], 0, 0, 0); \
;     __builtin_amdgcn_s_setprio(0); } while (0)
; #define WAIT_V(n) asm volatile("s_waitcnt vmcnt(" #n ")" ::: "memory")
; #define WAIT_L(n) asm volatile("s_waitcnt lgkmcnt(" #n ")" ::: "memory")
; #define BAR __builtin_amdgcn_s_barrier()
; __device__ __forceinline__ void gemm256(const u16* __restrict__ A, int lda, const u16* __restrict__ Bt, int ldb, int K,
;                                         f32x4 (&acc)[2][2][4][2], const int g_wid) {
;     ...
;     LDB(B1, 1, 1); WAIT_V(0); BAR; WAIT_L(0); MMA(0, 1, At, B1); BAR;
;     LDA(At, 1, 1); BAR; WAIT_L(0); MMA(1, 0, At, B0); MMA(1, 1, At, B1); BAR; }
;   if (wr == 0) BAR;
	ds_read_b128 v[210:213], v159
	ds_read_b128 v[234:237], v159 offset:1024
	ds_read_b128 v[238:241], v159 offset:2048
	ds_read_b128 v[242:245], v159 offset:3072
	s_waitcnt vmcnt(0)
	s_barrier
	s_waitcnt lgkmcnt(0)
	v_mfma_f32_16x16x32_bf16 v[30:33], v[14:17], v[210:213], v[214:217]
	v_mfma_f32_16x16x32_bf16 v[14:17], v[14:17], v[238:241], v[178:181]
	v_mfma_f32_16x16x32_bf16 v[62:65], v[18:21], v[234:237], v[30:33]
	v_mfma_f32_16x16x32_bf16 v[30:33], v[18:21], v[242:245], v[14:17]
	v_mfma_f32_16x16x32_bf16 v[14:17], v[26:29], v[210:213], v[86:89]
	v_mfma_f32_16x16x32_bf16 v[58:61], v[46:49], v[234:237], v[14:17]
	v_mfma_f32_16x16x32_bf16 v[14:17], v[26:29], v[238:241], v[182:185]
	v_mfma_f32_16x16x32_bf16 v[26:29], v[46:49], v[242:245], v[14:17]
	v_mfma_f32_16x16x32_bf16 v[14:17], v[174:177], v[210:213], v[186:189]
	v_mfma_f32_16x16x32_bf16 v[50:53], v[194:197], v[234:237], v[14:17]
	v_mfma_f32_16x16x32_bf16 v[14:17], v[174:177], v[238:241], v[74:77]
	v_mfma_f32_16x16x32_bf16 v[18:21], v[194:197], v[242:245], v[14:17]
	v_mfma_f32_16x16x32_bf16 v[14:17], v[198:201], v[210:213], v[70:73]
	v_mfma_f32_16x16x32_bf16 v[46:49], v[202:205], v[234:237], v[14:17]
	v_mfma_f32_16x16x32_bf16 v[14:17], v[198:201], v[238:241], v[66:69]
	v_mfma_f32_16x16x32_bf16 v[14:17], v[202:205], v[242:245], v[14:17]
	s_barrier
	ds_read_b128 v[174:177], v145 offset:49152
	ds_read_b128 v[178:181], v145 offset:50176
	ds_read_b128 v[182:185], v144 offset:49152
	ds_read_b128 v[144:147], v144 offset:50176
	ds_read_b128 v[186:189], v143 offset:49152
	ds_read_b128 v[194:197], v143 offset:50176
	ds_read_b128 v[198:201], v142 offset:49152
	ds_read_b128 v[202:205], v142 offset:50176
	s_barrier
	s_waitcnt lgkmcnt(0)
	v_mfma_f32_16x16x32_bf16 v[54:57], v[182:185], v[6:9], v[54:57]
	v_mfma_f32_16x16x32_bf16 v[106:109], v[144:147], v[10:13], v[54:57]
	v_mfma_f32_16x16x32_bf16 v[54:57], v[182:185], v[22:25], v[222:225]
	v_mfma_f32_16x16x32_bf16 v[66:69], v[174:177], v[6:9], v[206:209]
	v_mfma_f32_16x16x32_bf16 v[74:77], v[144:147], v[170:173], v[54:57]
	v_mfma_f32_16x16x32_bf16 v[54:57], v[186:189], v[6:9], v[226:229]
	v_mfma_f32_16x16x32_bf16 v[6:9], v[198:201], v[6:9], v[38:41]
	v_mfma_f32_16x16x32_bf16 v[118:121], v[178:181], v[10:13], v[66:69]
	v_mfma_f32_16x16x32_bf16 v[66:69], v[174:177], v[22:25], v[218:221]
	v_mfma_f32_16x16x32_bf16 v[42:45], v[186:189], v[22:25], v[42:45]
	v_mfma_f32_16x16x32_bf16 v[98:101], v[202:205], v[10:13], v[6:9]
	v_mfma_f32_16x16x32_bf16 v[6:9], v[198:201], v[22:25], v[34:37]
	v_mfma_f32_16x16x32_bf16 v[86:89], v[178:181], v[170:173], v[66:69]
	v_mfma_f32_16x16x32_bf16 v[102:105], v[194:197], v[10:13], v[54:57]
	v_mfma_f32_16x16x32_bf16 v[70:73], v[194:197], v[170:173], v[42:45]
	v_mfma_f32_16x16x32_bf16 v[66:69], v[202:205], v[170:173], v[6:9]
	v_mfma_f32_16x16x32_bf16 v[6:9], v[174:177], v[210:213], v[134:137]
	v_mfma_f32_16x16x32_bf16 v[54:57], v[178:181], v[234:237], v[6:9]
	v_mfma_f32_16x16x32_bf16 v[6:9], v[174:177], v[238:241], v[138:141]
	v_mfma_f32_16x16x32_bf16 v[22:25], v[178:181], v[242:245], v[6:9]
	v_mfma_f32_16x16x32_bf16 v[6:9], v[182:185], v[210:213], v[160:163]
	v_mfma_f32_16x16x32_bf16 v[42:45], v[144:147], v[234:237], v[6:9]
	v_mfma_f32_16x16x32_bf16 v[6:9], v[182:185], v[238:241], v[166:169]
	v_mfma_f32_16x16x32_bf16 v[10:13], v[144:147], v[242:245], v[6:9]
	v_mfma_f32_16x16x32_bf16 v[6:9], v[186:189], v[210:213], v[230:233]
	v_mfma_f32_16x16x32_bf16 v[38:41], v[194:197], v[234:237], v[6:9]
	v_mfma_f32_16x16x32_bf16 v[6:9], v[186:189], v[238:241], v[190:193]
	v_mfma_f32_16x16x32_bf16 v[34:37], v[198:201], v[210:213], v[130:133]
	v_mfma_f32_16x16x32_bf16 v[2:5], v[198:201], v[238:241], v[2:5]
	v_mfma_f32_16x16x32_bf16 v[6:9], v[194:197], v[242:245], v[6:9]
	v_mfma_f32_16x16x32_bf16 v[34:37], v[202:205], v[234:237], v[34:37]
	v_mfma_f32_16x16x32_bf16 v[2:5], v[202:205], v[242:245], v[2:5]
	s_setprio 0
	s_movk_i32 s6, 0x100
	v_cmp_gt_u32_e32 vcc, s6, v0
	s_barrier
	s_and_saveexec_b64 s[6:7], vcc
	s_cbranch_execz .LBB0_139
	s_barrier

; #define STA(P, br, kt) STAGE(P, A, aoff0, aoff1, lda, br, kt)
; #define STB(P, br, kt) STAGE(P, Bt, boff0, boff1, ldb, br, kt)
; #define LDA(dst, b, h) _Pragma("unroll") for (int m = 0; m < 4; ++m) _Pragma("unroll") for (int k = 0; k < 2; ++k) \
;     dst[m][k] = *reinterpret_cast<const bf16x8*>((char*)SA(b, h) + lds_byte(wr * 64 + m * 16 + fr, k * 32 + fq * 8))
; #define LDB(dst, b, h) _Pragma("unroll") for (int n = 0; n < 2; ++n) _Pragma("unroll") for (int k = 0; k < 2; ++k) \
;     dst[n][k] = *reinterpret_cast<const bf16x8*>((char*)SB(b, h) + lds_byte(wc * 32 + n * 16 + fr, k * 32 + fq * 8))
; #define MMA(ai, bj, At, Bq) do { __builtin_amdgcn_s_setprio(1); \
;     _Pragma("unroll") for (int m = 0; m < 4; ++m) _Pragma("unroll") for (int n = 0; n < 2; ++n) _Pragma("unroll") for (int k = 0; k < 2; ++k) \
;       acc[ai][bj][m][n] = __builtin_amdgcn_mfma_f32_16x16x32_bf16(At[m][k], Bq[n][k], acc[ai][bj][m][n], 0, 0, 0); \
;     __builtin_amdgcn_s_setprio(0); } while (0)
; #define WAIT_L(n) asm volatile("s_waitcnt lgkmcnt(" #n ")" ::: "memory")
; #define BAR __builtin_amdgcn_s_barrier()
; #define SCHED __builtin_amdgcn_sched_barrier(0)
; __device__ __forceinline__ void gemm256(const u16* __restrict__ A, int lda, const u16* __restrict__ Bt, int ldb, int K,
;                                         f32x4 (&acc)[2][2][4][2], const int g_wid) {
;     ...
;     LDB(B0, 0, 0); SCHED; LDA(At, 0, 0); STA(SA(1, 1), HALF, t + 1);
;     WAIT_L(8); BAR; WAIT_L(0); MMA(0, 0, At, B0); BAR; SCHED;
;     LDB(B1, 0, 1); STB(SB(0, 0), 0, t + 2);
;     BAR; WAIT_L(0); MMA(0, 1, At, B1); BAR;
;     LDA(At, 0, 1); STA(SA(0, 0), 0, t + 2);
;     BAR; WAIT_L(0); MMA(1, 0, At, B0); BAR; SCHED;
.LBB0_319:
	ds_read_b128 v[180:183], v176
	ds_read_b128 v[184:187], v176 offset:1024
	ds_read_b128 v[188:191], v176 offset:2048
	ds_read_b128 v[192:195], v176 offset:3072
	v_add_u32_e32 v177, 0xc000, v161
	v_lshl_add_u64 v[244:245], v[140:141], 0, s[18:19]
	v_readfirstlane_b32 s13, v177
	v_lshl_add_u64 v[178:179], v[244:245], 0, s[68:69]
	s_mov_b32 m0, s13
	ds_read_b128 v[196:199], v147
	ds_read_b128 v[200:203], v147 offset:1024
	ds_read_b128 v[204:207], v146
	ds_read_b128 v[208:211], v146 offset:1024
	ds_read_b128 v[212:215], v145
	ds_read_b128 v[216:219], v145 offset:1024
	ds_read_b128 v[220:223], v144
	ds_read_b128 v[224:227], v144 offset:1024
	global_load_lds_dwordx4 v[178:179], off
	v_add_u32_e32 v178, 0xe000, v161
	v_lshl_add_u64 v[246:247], v[138:139], 0, s[18:19]
	s_add_u32 m0, m0, 0x2000
	v_lshl_add_u64 v[228:229], v[246:247], 0, s[68:69]
	global_load_lds_dwordx4 v[228:229], off
	s_waitcnt lgkmcnt(8)
	s_barrier
	s_waitcnt lgkmcnt(0)
	v_mfma_f32_16x16x32_bf16 v[126:129], v[196:199], v[180:183], v[126:129]
	v_mfma_f32_16x16x32_bf16 v[122:125], v[196:199], v[188:191], v[122:125]
	v_mfma_f32_16x16x32_bf16 v[118:121], v[204:207], v[180:183], v[118:121]
	v_mfma_f32_16x16x32_bf16 v[114:117], v[204:207], v[188:191], v[114:117]
	v_mfma_f32_16x16x32_bf16 v[110:113], v[212:215], v[180:183], v[110:113]
	v_mfma_f32_16x16x32_bf16 v[106:109], v[212:215], v[188:191], v[106:109]
	v_mfma_f32_16x16x32_bf16 v[102:105], v[220:223], v[180:183], v[102:105]
	v_mfma_f32_16x16x32_bf16 v[98:101], v[220:223], v[188:191], v[98:101]
	v_mfma_f32_16x16x32_bf16 v[126:129], v[200:203], v[184:187], v[126:129]
	v_mfma_f32_16x16x32_bf16 v[122:125], v[200:203], v[192:195], v[122:125]
	v_mfma_f32_16x16x32_bf16 v[118:121], v[208:211], v[184:187], v[118:121]
	v_mfma_f32_16x16x32_bf16 v[114:117], v[208:211], v[192:195], v[114:117]
	v_mfma_f32_16x16x32_bf16 v[110:113], v[216:219], v[184:187], v[110:113]
	v_mfma_f32_16x16x32_bf16 v[106:109], v[216:219], v[192:195], v[106:109]
	v_mfma_f32_16x16x32_bf16 v[102:105], v[224:227], v[184:187], v[102:105]
	v_mfma_f32_16x16x32_bf16 v[98:101], v[224:227], v[192:195], v[98:101]
	s_barrier
	v_lshl_add_u64 v[248:249], v[136:137], 0, s[18:19]
	v_readfirstlane_b32 s13, v159
	v_lshl_add_u64 v[250:251], v[248:249], 0, s[74:75]
	s_mov_b32 m0, s13
	ds_read_b128 v[228:231], v175
	ds_read_b128 v[232:235], v175 offset:1024
	ds_read_b128 v[236:239], v175 offset:2048
	ds_read_b128 v[240:243], v175 offset:3072
	global_load_lds_dwordx4 v[250:251], off
	v_lshl_add_u64 v[250:251], v[134:135], 0, s[18:19]
	s_add_u32 m0, m0, 0x2000
	v_lshl_add_u64 v[252:253], v[250:251], 0, s[74:75]
	global_load_lds_dwordx4 v[252:253], off
	s_barrier
	s_waitcnt lgkmcnt(0)
	v_mfma_f32_16x16x32_bf16 v[94:97], v[196:199], v[228:231], v[94:97]
	v_mfma_f32_16x16x32_bf16 v[90:93], v[196:199], v[236:239], v[90:93]
	v_mfma_f32_16x16x32_bf16 v[86:89], v[204:207], v[228:231], v[86:89]
	v_mfma_f32_16x16x32_bf16 v[82:85], v[204:207], v[236:239], v[82:85]
	v_mfma_f32_16x16x32_bf16 v[78:81], v[212:215], v[228:231], v[78:81]
	v_mfma_f32_16x16x32_bf16 v[74:77], v[212:215], v[236:239], v[74:77]
	v_mfma_f32_16x16x32_bf16 v[70:73], v[220:223], v[228:231], v[70:73]
	v_mfma_f32_16x16x32_bf16 v[66:69], v[220:223], v[236:239], v[66:69]
	v_mfma_f32_16x16x32_bf16 v[94:97], v[200:203], v[232:235], v[94:97]
	v_mfma_f32_16x16x32_bf16 v[90:93], v[200:203], v[240:243], v[90:93]
	v_mfma_f32_16x16x32_bf16 v[86:89], v[208:211], v[232:235], v[86:89]
	v_mfma_f32_16x16x32_bf16 v[82:85], v[208:211], v[240:243], v[82:85]
	v_mfma_f32_16x16x32_bf16 v[78:81], v[216:219], v[232:235], v[78:81]
	v_mfma_f32_16x16x32_bf16 v[74:77], v[216:219], v[240:243], v[74:77]
	v_mfma_f32_16x16x32_bf16 v[70:73], v[224:227], v[232:235], v[70:73]
	v_mfma_f32_16x16x32_bf16 v[66:69], v[224:227], v[240:243], v[66:69]
	v_readfirstlane_b32 s13, v161
	v_lshl_add_u64 v[252:253], v[244:245], 0, s[74:75]
	s_mov_b32 m0, s13
	s_barrier
	ds_read_b128 v[196:199], v147 offset:16384
	ds_read_b128 v[200:203], v147 offset:17408
	ds_read_b128 v[204:207], v146 offset:16384
	ds_read_b128 v[208:211], v146 offset:17408
	ds_read_b128 v[212:215], v145 offset:16384
	ds_read_b128 v[216:219], v145 offset:17408
	ds_read_b128 v[220:223], v144 offset:16384
	ds_read_b128 v[224:227], v144 offset:17408
	global_load_lds_dwordx4 v[252:253], off
	s_add_u32 m0, m0, 0x2000
	v_lshl_add_u64 v[252:253], v[246:247], 0, s[74:75]
	global_load_lds_dwordx4 v[252:253], off
	s_barrier
	s_waitcnt lgkmcnt(0)
	v_mfma_f32_16x16x32_bf16 v[62:65], v[196:199], v[180:183], v[62:65]
	v_mfma_f32_16x16x32_bf16 v[58:61], v[196:199], v[188:191], v[58:61]
	v_mfma_f32_16x16x32_bf16 v[54:57], v[204:207], v[180:183], v[54:57]
	v_mfma_f32_16x16x32_bf16 v[50:53], v[204:207], v[188:191], v[50:53]
	v_mfma_f32_16x16x32_bf16 v[46:49], v[212:215], v[180:183], v[46:49]
	v_mfma_f32_16x16x32_bf16 v[42:45], v[212:215], v[188:191], v[42:45]
	v_mfma_f32_16x16x32_bf16 v[38:41], v[220:223], v[180:183], v[38:41]
	v_mfma_f32_16x16x32_bf16 v[34:37], v[220:223], v[188:191], v[34:37]
	v_mfma_f32_16x16x32_bf16 v[62:65], v[200:203], v[184:187], v[62:65]
	v_mfma_f32_16x16x32_bf16 v[58:61], v[200:203], v[192:195], v[58:61]
	v_mfma_f32_16x16x32_bf16 v[54:57], v[208:211], v[184:187], v[54:57]
	v_mfma_f32_16x16x32_bf16 v[50:53], v[208:211], v[192:195], v[50:53]
	v_mfma_f32_16x16x32_bf16 v[46:49], v[216:219], v[184:187], v[46:49]
	v_mfma_f32_16x16x32_bf16 v[42:45], v[216:219], v[192:195], v[42:45]
	v_mfma_f32_16x16x32_bf16 v[38:41], v[224:227], v[184:187], v[38:41]
	v_mfma_f32_16x16x32_bf16 v[34:37], v[224:227], v[192:195], v[34:37]
	s_barrier
; #define STA(P, br, kt) STAGE(P, A, aoff0, aoff1, lda, br, kt)
; #define STB(P, br, kt) STAGE(P, Bt, boff0, boff1, ldb, br, kt)
; #define LDA(dst, b, h) _Pragma("unroll") for (int m = 0; m < 4; ++m) _Pragma("unroll") for (int k = 0; k < 2; ++k) \
;     dst[m][k] = *reinterpret_cast<const bf16x8*>((char*)SA(b, h) + lds_byte(wr * 64 + m * 16 + fr, k * 32 + fq * 8))
; #define LDB(dst, b, h) _Pragma("unroll") for (int n = 0; n < 2; ++n) _Pragma("unroll") for (int k = 0; k < 2; ++k) \
;     dst[n][k] = *reinterpret_cast<const bf16x8*>((char*)SB(b, h) + lds_byte(wc * 32 + n * 16 + fr, k * 32 + fq * 8))
; #define MMA(ai, bj, At, Bq) do { __builtin_amdgcn_s_setprio(1); \
;     _Pragma("unroll") for (int m = 0; m < 4; ++m) _Pragma("unroll") for (int n = 0; n < 2; ++n) _Pragma("unroll") for (int k = 0; k < 2; ++k) \
;       acc[ai][bj][m][n] = __builtin_amdgcn_mfma_f32_16x16x32_bf16(At[m][k], Bq[n][k], acc[ai][bj][m][n], 0, 0, 0); \
;     __builtin_amdgcn_s_setprio(0); } while (0)
; #define WAIT_V(n) asm volatile("s_waitcnt vmcnt(" #n ")" ::: "memory")
; #define WAIT_L(n) asm volatile("s_waitcnt lgkmcnt(" #n ")" ::: "memory")
; #define BAR __builtin_amdgcn_s_barrier()
; #define SCHED __builtin_amdgcn_sched_barrier(0)
; __device__ __forceinline__ void gemm256(const u16* __restrict__ A, int lda, const u16* __restrict__ Bt, int ldb, int K,
;                                         f32x4 (&acc)[2][2][4][2], const int g_wid) {
;     ...
;     STB(SB(0, 1), HALF, t + 2);
;     WAIT_V(6); BAR; MMA(1, 1, At, B1); BAR;
;     LDB(B0, 1, 0); SCHED; LDA(At, 1, 0); STA(SA(0, 1), HALF, t + 2);
;     WAIT_L(8); BAR; WAIT_L(0); MMA(0, 0, At, B0); BAR; SCHED;
;     LDB(B1, 1, 1); STB(SB(1, 0), 0, t + 3);
;     BAR; WAIT_L(0); MMA(0, 1, At, B1); BAR;
;     LDA(At, 1, 1); STA(SA(1, 0), 0, t + 3);
	v_readfirstlane_b32 s13, v164
	v_lshl_add_u64 v[180:181], v[248:249], 0, s[78:79]
	s_mov_b32 m0, s13
	global_load_lds_dwordx4 v[180:181], off
	s_add_u32 m0, m0, 0x2000
	v_lshl_add_u64 v[180:181], v[250:251], 0, s[78:79]
	global_load_lds_dwordx4 v[180:181], off
	s_waitcnt vmcnt(6)
	s_barrier
	v_mfma_f32_16x16x32_bf16 v[30:33], v[196:199], v[228:231], v[30:33]
	v_mfma_f32_16x16x32_bf16 v[26:29], v[196:199], v[236:239], v[26:29]
	v_mfma_f32_16x16x32_bf16 v[22:25], v[204:207], v[228:231], v[22:25]
	v_mfma_f32_16x16x32_bf16 v[18:21], v[204:207], v[236:239], v[18:21]
	v_mfma_f32_16x16x32_bf16 v[14:17], v[212:215], v[228:231], v[14:17]
	v_mfma_f32_16x16x32_bf16 v[10:13], v[212:215], v[236:239], v[10:13]
	v_mfma_f32_16x16x32_bf16 v[6:9], v[220:223], v[228:231], v[6:9]
	v_mfma_f32_16x16x32_bf16 v[2:5], v[220:223], v[236:239], v[2:5]
	v_mfma_f32_16x16x32_bf16 v[30:33], v[200:203], v[232:235], v[30:33]
	v_mfma_f32_16x16x32_bf16 v[26:29], v[200:203], v[240:243], v[26:29]
	v_mfma_f32_16x16x32_bf16 v[22:25], v[208:211], v[232:235], v[22:25]
	v_mfma_f32_16x16x32_bf16 v[18:21], v[208:211], v[240:243], v[18:21]
	v_mfma_f32_16x16x32_bf16 v[14:17], v[216:219], v[232:235], v[14:17]
	v_mfma_f32_16x16x32_bf16 v[10:13], v[216:219], v[240:243], v[10:13]
	v_mfma_f32_16x16x32_bf16 v[6:9], v[224:227], v[232:235], v[6:9]
	v_mfma_f32_16x16x32_bf16 v[2:5], v[224:227], v[240:243], v[2:5]
	s_barrier
	ds_read_b128 v[180:183], v168
	ds_read_b128 v[184:187], v168 offset:1024
	ds_read_b128 v[188:191], v168 offset:2048
	ds_read_b128 v[192:195], v168 offset:3072
	v_readfirstlane_b32 s13, v166
	v_lshl_add_u64 v[228:229], v[244:245], 0, s[78:79]
	s_mov_b32 m0, s13
	ds_read_b128 v[196:199], v147 offset:32768
	ds_read_b128 v[200:203], v147 offset:33792
	ds_read_b128 v[204:207], v146 offset:32768
	ds_read_b128 v[208:211], v146 offset:33792
	ds_read_b128 v[212:215], v145 offset:32768
	ds_read_b128 v[216:219], v145 offset:33792
	ds_read_b128 v[220:223], v144 offset:32768
	ds_read_b128 v[224:227], v144 offset:33792
	global_load_lds_dwordx4 v[228:229], off
	s_add_u32 m0, m0, 0x2000
	v_lshl_add_u64 v[228:229], v[246:247], 0, s[78:79]
	global_load_lds_dwordx4 v[228:229], off
	s_waitcnt lgkmcnt(8)
	s_barrier
	s_waitcnt lgkmcnt(0)
	v_mfma_f32_16x16x32_bf16 v[126:129], v[196:199], v[180:183], v[126:129]
	v_mfma_f32_16x16x32_bf16 v[122:125], v[196:199], v[188:191], v[122:125]
	v_mfma_f32_16x16x32_bf16 v[118:121], v[204:207], v[180:183], v[118:121]
	v_mfma_f32_16x16x32_bf16 v[114:117], v[204:207], v[188:191], v[114:117]
	v_mfma_f32_16x16x32_bf16 v[110:113], v[212:215], v[180:183], v[110:113]
	v_mfma_f32_16x16x32_bf16 v[106:109], v[212:215], v[188:191], v[106:109]
	v_mfma_f32_16x16x32_bf16 v[102:105], v[220:223], v[180:183], v[102:105]
	v_mfma_f32_16x16x32_bf16 v[98:101], v[220:223], v[188:191], v[98:101]
	v_mfma_f32_16x16x32_bf16 v[126:129], v[200:203], v[184:187], v[126:129]
	v_mfma_f32_16x16x32_bf16 v[122:125], v[200:203], v[192:195], v[122:125]
	v_mfma_f32_16x16x32_bf16 v[118:121], v[208:211], v[184:187], v[118:121]
	v_mfma_f32_16x16x32_bf16 v[114:117], v[208:211], v[192:195], v[114:117]
	v_mfma_f32_16x16x32_bf16 v[110:113], v[216:219], v[184:187], v[110:113]
	v_mfma_f32_16x16x32_bf16 v[106:109], v[216:219], v[192:195], v[106:109]
	v_mfma_f32_16x16x32_bf16 v[102:105], v[224:227], v[184:187], v[102:105]
	v_mfma_f32_16x16x32_bf16 v[98:101], v[224:227], v[192:195], v[98:101]
	s_barrier
	v_readfirstlane_b32 s13, v169
	v_lshl_add_u64 v[252:253], v[248:249], 0, s[82:83]
	s_mov_b32 m0, s13
	ds_read_b128 v[228:231], v162
	ds_read_b128 v[232:235], v162 offset:1024
	ds_read_b128 v[236:239], v162 offset:2048
	ds_read_b128 v[240:243], v162 offset:3072
	global_load_lds_dwordx4 v[252:253], off
	s_add_u32 m0, m0, 0x2000
	v_lshl_add_u64 v[252:253], v[250:251], 0, s[82:83]
	global_load_lds_dwordx4 v[252:253], off
	s_barrier
	s_waitcnt lgkmcnt(0)
	v_mfma_f32_16x16x32_bf16 v[94:97], v[196:199], v[228:231], v[94:97]
	v_mfma_f32_16x16x32_bf16 v[90:93], v[196:199], v[236:239], v[90:93]
	v_mfma_f32_16x16x32_bf16 v[86:89], v[204:207], v[228:231], v[86:89]
	v_mfma_f32_16x16x32_bf16 v[82:85], v[204:207], v[236:239], v[82:85]
	v_mfma_f32_16x16x32_bf16 v[78:81], v[212:215], v[228:231], v[78:81]
	v_mfma_f32_16x16x32_bf16 v[74:77], v[212:215], v[236:239], v[74:77]
	v_mfma_f32_16x16x32_bf16 v[70:73], v[220:223], v[228:231], v[70:73]
	v_mfma_f32_16x16x32_bf16 v[66:69], v[220:223], v[236:239], v[66:69]
	v_mfma_f32_16x16x32_bf16 v[94:97], v[200:203], v[232:235], v[94:97]
	v_mfma_f32_16x16x32_bf16 v[90:93], v[200:203], v[240:243], v[90:93]
	v_mfma_f32_16x16x32_bf16 v[86:89], v[208:211], v[232:235], v[86:89]
	v_mfma_f32_16x16x32_bf16 v[82:85], v[208:211], v[240:243], v[82:85]
	v_mfma_f32_16x16x32_bf16 v[78:81], v[216:219], v[232:235], v[78:81]
	v_mfma_f32_16x16x32_bf16 v[74:77], v[216:219], v[240:243], v[74:77]
	v_mfma_f32_16x16x32_bf16 v[70:73], v[224:227], v[232:235], v[70:73]
	v_mfma_f32_16x16x32_bf16 v[66:69], v[224:227], v[240:243], v[66:69]
	v_readfirstlane_b32 s13, v171
	v_lshl_add_u64 v[244:245], v[244:245], 0, s[82:83]
	s_mov_b32 m0, s13
	s_barrier
	ds_read_b128 v[196:199], v147 offset:49152
	ds_read_b128 v[200:203], v147 offset:50176
	ds_read_b128 v[204:207], v146 offset:49152
	ds_read_b128 v[208:211], v146 offset:50176
	ds_read_b128 v[212:215], v145 offset:49152
	ds_read_b128 v[216:219], v145 offset:50176
	ds_read_b128 v[220:223], v144 offset:49152
	ds_read_b128 v[224:227], v144 offset:50176
	global_load_lds_dwordx4 v[244:245], off
	s_add_u32 m0, m0, 0x2000
	v_lshl_add_u64 v[244:245], v[246:247], 0, s[82:83]
	global_load_lds_dwordx4 v[244:245], off
	s_barrier
; #define STA(P, br, kt) STAGE(P, A, aoff0, aoff1, lda, br, kt)
; #define STB(P, br, kt) STAGE(P, Bt, boff0, boff1, ldb, br, kt)
; #define LDA(dst, b, h) _Pragma("unroll") for (int m = 0; m < 4; ++m) _Pragma("unroll") for (int k = 0; k < 2; ++k) \
;     dst[m][k] = *reinterpret_cast<const bf16x8*>((char*)SA(b, h) + lds_byte(wr * 64 + m * 16 + fr, k * 32 + fq * 8))
; #define LDB(dst, b, h) _Pragma("unroll") for (int n = 0; n < 2; ++n) _Pragma("unroll") for (int k = 0; k < 2; ++k) \
;     dst[n][k] = *reinterpret_cast<const bf16x8*>((char*)SB(b, h) + lds_byte(wc * 32 + n * 16 + fr, k * 32 + fq * 8))
; #define MMA(ai, bj, At, Bq) do { __builtin_amdgcn_s_setprio(1); \
;     _Pragma("unroll") for (int m = 0; m < 4; ++m) _Pragma("unroll") for (int n = 0; n < 2; ++n) _Pragma("unroll") for (int k = 0; k < 2; ++k) \
;       acc[ai][bj][m][n] = __builtin_amdgcn_mfma_f32_16x16x32_bf16(At[m][k], Bq[n][k], acc[ai][bj][m][n], 0, 0, 0); \
;     __builtin_amdgcn_s_setprio(0); } while (0)
; #define WAIT_V(n) asm volatile("s_waitcnt vmcnt(" #n ")" ::: "memory")
; #define WAIT_L(n) asm volatile("s_waitcnt lgkmcnt(" #n ")" ::: "memory")
; #define BAR __builtin_amdgcn_s_barrier()
; #define SCHED __builtin_amdgcn_sched_barrier(0)
; __device__ __forceinline__ void gemm256(const u16* __restrict__ A, int lda, const u16* __restrict__ Bt, int ldb, int K,
;                                         f32x4 (&acc)[2][2][4][2], const int g_wid) {
;     ...
;     BAR; WAIT_L(0); MMA(1, 0, At, B0); BAR; SCHED;
;     STB(SB(1, 1), HALF, t + 3);
;     WAIT_V(6); BAR; MMA(1, 1, At, B1); BAR;
;   }
;   { LDB(B0, 0, 0); LDA(At, 0, 0); STA(SA(1, 1), HALF, nt - 1);
;     BAR; WAIT_L(0); MMA(0, 0, At, B0); BAR;
;     LDB(B1, 0, 1); BAR; WAIT_L(0); MMA(0, 1, At, B1); BAR;
;     LDA(At, 0, 1); WAIT_V(4); BAR; WAIT_L(0); MMA(1, 0, At, B0); MMA(1, 1, At, B1); BAR; }
	s_waitcnt lgkmcnt(0)
	v_mfma_f32_16x16x32_bf16 v[62:65], v[196:199], v[180:183], v[62:65]
	v_mfma_f32_16x16x32_bf16 v[58:61], v[196:199], v[188:191], v[58:61]
	v_mfma_f32_16x16x32_bf16 v[54:57], v[204:207], v[180:183], v[54:57]
	v_mfma_f32_16x16x32_bf16 v[50:53], v[204:207], v[188:191], v[50:53]
	v_mfma_f32_16x16x32_bf16 v[46:49], v[212:215], v[180:183], v[46:49]
	v_mfma_f32_16x16x32_bf16 v[42:45], v[212:215], v[188:191], v[42:45]
	v_mfma_f32_16x16x32_bf16 v[38:41], v[220:223], v[180:183], v[38:41]
	v_mfma_f32_16x16x32_bf16 v[34:37], v[220:223], v[188:191], v[34:37]
	v_mfma_f32_16x16x32_bf16 v[62:65], v[200:203], v[184:187], v[62:65]
	v_mfma_f32_16x16x32_bf16 v[58:61], v[200:203], v[192:195], v[58:61]
	v_mfma_f32_16x16x32_bf16 v[54:57], v[208:211], v[184:187], v[54:57]
	v_mfma_f32_16x16x32_bf16 v[50:53], v[208:211], v[192:195], v[50:53]
	v_mfma_f32_16x16x32_bf16 v[46:49], v[216:219], v[184:187], v[46:49]
	v_mfma_f32_16x16x32_bf16 v[42:45], v[216:219], v[192:195], v[42:45]
	v_mfma_f32_16x16x32_bf16 v[38:41], v[224:227], v[184:187], v[38:41]
	v_mfma_f32_16x16x32_bf16 v[34:37], v[224:227], v[192:195], v[34:37]
	s_barrier
	v_readfirstlane_b32 s13, v173
	v_lshl_add_u64 v[180:181], v[248:249], 0, s[86:87]
	s_mov_b32 m0, s13
	global_load_lds_dwordx4 v[180:181], off
	s_add_u32 m0, m0, 0x2000
	v_lshl_add_u64 v[180:181], v[250:251], 0, s[86:87]
	global_load_lds_dwordx4 v[180:181], off
	s_waitcnt vmcnt(6)
	s_barrier
	v_mfma_f32_16x16x32_bf16 v[30:33], v[196:199], v[228:231], v[30:33]
	v_mfma_f32_16x16x32_bf16 v[26:29], v[196:199], v[236:239], v[26:29]
	v_mfma_f32_16x16x32_bf16 v[22:25], v[204:207], v[228:231], v[22:25]
	v_mfma_f32_16x16x32_bf16 v[18:21], v[204:207], v[236:239], v[18:21]
	v_mfma_f32_16x16x32_bf16 v[14:17], v[212:215], v[228:231], v[14:17]
	v_mfma_f32_16x16x32_bf16 v[10:13], v[212:215], v[236:239], v[10:13]
	v_mfma_f32_16x16x32_bf16 v[6:9], v[220:223], v[228:231], v[6:9]
	v_mfma_f32_16x16x32_bf16 v[2:5], v[220:223], v[236:239], v[2:5]
	v_mfma_f32_16x16x32_bf16 v[30:33], v[200:203], v[232:235], v[30:33]
	v_mfma_f32_16x16x32_bf16 v[26:29], v[200:203], v[240:243], v[26:29]
	v_mfma_f32_16x16x32_bf16 v[22:25], v[208:211], v[232:235], v[22:25]
	v_mfma_f32_16x16x32_bf16 v[18:21], v[208:211], v[240:243], v[18:21]
	v_mfma_f32_16x16x32_bf16 v[14:17], v[216:219], v[232:235], v[14:17]
	v_mfma_f32_16x16x32_bf16 v[10:13], v[216:219], v[240:243], v[10:13]
	v_mfma_f32_16x16x32_bf16 v[6:9], v[224:227], v[232:235], v[6:9]
	v_mfma_f32_16x16x32_bf16 v[2:5], v[224:227], v[240:243], v[2:5]
	s_add_i32 s11, s11, 2
	s_add_u32 s18, s18, 0x100
	s_addc_u32 s19, s19, 0
	s_cmp_lt_u32 s11, 12
	s_barrier
	s_cbranch_scc1 .LBB0_319
	s_add_u32 s16, s16, 0x40780
	s_addc_u32 s17, s17, 0
	v_readfirstlane_b32 s11, v177
	v_lshl_add_u64 v[132:133], v[132:133], 1, s[16:17]
	s_mov_b32 m0, s11
	v_readfirstlane_b32 s11, v178
	ds_read_b128 v[134:137], v176
	ds_read_b128 v[138:141], v176 offset:1024
	ds_read_b128 v[164:167], v176 offset:2048
	ds_read_b128 v[170:173], v176 offset:3072
	ds_read_b128 v[180:183], v147
	ds_read_b128 v[184:187], v147 offset:1024
	ds_read_b128 v[188:191], v146
	ds_read_b128 v[192:195], v146 offset:1024
	ds_read_b128 v[196:199], v145
	ds_read_b128 v[200:203], v145 offset:1024
	ds_read_b128 v[204:207], v144
	ds_read_b128 v[208:211], v144 offset:1024
	global_load_lds_dwordx4 v[132:133], off
	v_lshl_add_u64 v[130:131], v[130:131], 1, s[16:17]
	s_mov_b32 m0, s11
	s_nop 0
	global_load_lds_dwordx4 v[130:131], off
	s_barrier
	s_waitcnt lgkmcnt(0)
	v_mfma_f32_16x16x32_bf16 v[126:129], v[180:183], v[134:137], v[126:129]
	v_mfma_f32_16x16x32_bf16 v[122:125], v[180:183], v[164:167], v[122:125]
	v_mfma_f32_16x16x32_bf16 v[110:113], v[196:199], v[134:137], v[110:113]
	v_mfma_f32_16x16x32_bf16 v[106:109], v[196:199], v[164:167], v[106:109]
	v_mfma_f32_16x16x32_bf16 v[126:129], v[184:187], v[138:141], v[126:129]
	v_mfma_f32_16x16x32_bf16 v[122:125], v[184:187], v[170:173], v[122:125]
	v_mfma_f32_16x16x32_bf16 v[118:121], v[188:191], v[134:137], v[118:121]
	v_mfma_f32_16x16x32_bf16 v[114:117], v[188:191], v[164:167], v[114:117]
	v_mfma_f32_16x16x32_bf16 v[110:113], v[200:203], v[138:141], v[110:113]
	v_mfma_f32_16x16x32_bf16 v[106:109], v[200:203], v[170:173], v[106:109]
	v_mfma_f32_16x16x32_bf16 v[102:105], v[204:207], v[134:137], v[102:105]
	v_mfma_f32_16x16x32_bf16 v[98:101], v[204:207], v[164:167], v[98:101]
	v_mfma_f32_16x16x32_bf16 v[130:133], v[192:195], v[138:141], v[118:121]
	v_mfma_f32_16x16x32_bf16 v[176:179], v[192:195], v[170:173], v[114:117]
	v_mfma_f32_16x16x32_bf16 v[212:215], v[208:211], v[138:141], v[102:105]
	v_mfma_f32_16x16x32_bf16 v[216:219], v[208:211], v[170:173], v[98:101]
	s_barrier
	s_nop 1
	ds_read_b128 v[98:101], v175
	ds_read_b128 v[102:105], v175 offset:1024
	ds_read_b128 v[114:117], v175 offset:2048
	ds_read_b128 v[118:121], v175 offset:3072
	s_barrier
	s_waitcnt lgkmcnt(0)
	v_mfma_f32_16x16x32_bf16 v[94:97], v[180:183], v[98:101], v[94:97]
	v_mfma_f32_16x16x32_bf16 v[90:93], v[180:183], v[114:117], v[90:93]
	v_mfma_f32_16x16x32_bf16 v[78:81], v[196:199], v[98:101], v[78:81]
	v_mfma_f32_16x16x32_bf16 v[74:77], v[196:199], v[114:117], v[74:77]
	v_mfma_f32_16x16x32_bf16 v[94:97], v[184:187], v[102:105], v[94:97]
	v_mfma_f32_16x16x32_bf16 v[90:93], v[184:187], v[118:121], v[90:93]
	v_mfma_f32_16x16x32_bf16 v[86:89], v[188:191], v[98:101], v[86:89]
	v_mfma_f32_16x16x32_bf16 v[82:85], v[188:191], v[114:117], v[82:85]
	v_mfma_f32_16x16x32_bf16 v[78:81], v[200:203], v[102:105], v[78:81]
	v_mfma_f32_16x16x32_bf16 v[74:77], v[200:203], v[118:121], v[74:77]
	v_mfma_f32_16x16x32_bf16 v[70:73], v[204:207], v[98:101], v[70:73]
	v_mfma_f32_16x16x32_bf16 v[66:69], v[204:207], v[114:117], v[66:69]
	v_mfma_f32_16x16x32_bf16 v[180:183], v[192:195], v[102:105], v[86:89]
	v_mfma_f32_16x16x32_bf16 v[184:187], v[192:195], v[118:121], v[82:85]
	v_mfma_f32_16x16x32_bf16 v[188:191], v[208:211], v[102:105], v[70:73]
	v_mfma_f32_16x16x32_bf16 v[192:195], v[208:211], v[118:121], v[66:69]
	s_barrier
; #define LDA(dst, b, h) _Pragma("unroll") for (int m = 0; m < 4; ++m) _Pragma("unroll") for (int k = 0; k < 2; ++k) \
;     dst[m][k] = *reinterpret_cast<const bf16x8*>((char*)SA(b, h) + lds_byte(wr * 64 + m * 16 + fr, k * 32 + fq * 8))
; #define LDB(dst, b, h) _Pragma("unroll") for (int n = 0; n < 2; ++n) _Pragma("unroll") for (int k = 0; k < 2; ++k) \
;     dst[n][k] = *reinterpret_cast<const bf16x8*>((char*)SB(b, h) + lds_byte(wc * 32 + n * 16 + fr, k * 32 + fq * 8))
; #define MMA(ai, bj, At, Bq) do { __builtin_amdgcn_s_setprio(1); \
;     _Pragma("unroll") for (int m = 0; m < 4; ++m) _Pragma("unroll") for (int n = 0; n < 2; ++n) _Pragma("unroll") for (int k = 0; k < 2; ++k) \
;       acc[ai][bj][m][n] = __builtin_amdgcn_mfma_f32_16x16x32_bf16(At[m][k], Bq[n][k], acc[ai][bj][m][n], 0, 0, 0); \
;     __builtin_amdgcn_s_setprio(0); } while (0)
; #define WAIT_V(n) asm volatile("s_waitcnt vmcnt(" #n ")" ::: "memory")
; #define WAIT_L(n) asm volatile("s_waitcnt lgkmcnt(" #n ")" ::: "memory")
; #define BAR __builtin_amdgcn_s_barrier()
; __device__ __forceinline__ void gemm256(const u16* __restrict__ A, int lda, const u16* __restrict__ Bt, int ldb, int K,
;                                         f32x4 (&acc)[2][2][4][2], const int g_wid) {
;     ...
;     LDA(At, 0, 1); WAIT_V(4); BAR; WAIT_L(0); MMA(1, 0, At, B0); MMA(1, 1, At, B1); BAR; }
;   { LDB(B0, 1, 0); LDA(At, 1, 0); WAIT_V(2); BAR; WAIT_L(0); MMA(0, 0, At, B0); BAR;
	s_nop 1
	ds_read_b128 v[66:69], v147 offset:16384
	ds_read_b128 v[70:73], v147 offset:17408
	ds_read_b128 v[82:85], v146 offset:16384
	ds_read_b128 v[86:89], v146 offset:17408
	ds_read_b128 v[196:199], v145 offset:16384
	ds_read_b128 v[200:203], v145 offset:17408
	ds_read_b128 v[204:207], v144 offset:16384
	ds_read_b128 v[208:211], v144 offset:17408
	s_waitcnt vmcnt(4)
	s_barrier
	s_waitcnt lgkmcnt(0)
	v_mfma_f32_16x16x32_bf16 v[62:65], v[66:69], v[134:137], v[62:65]
	v_mfma_f32_16x16x32_bf16 v[54:57], v[82:85], v[134:137], v[54:57]
	v_mfma_f32_16x16x32_bf16 v[46:49], v[196:199], v[134:137], v[46:49]
	v_mfma_f32_16x16x32_bf16 v[38:41], v[204:207], v[134:137], v[38:41]
	v_mfma_f32_16x16x32_bf16 v[62:65], v[70:73], v[138:141], v[62:65]
	v_mfma_f32_16x16x32_bf16 v[58:61], v[66:69], v[164:167], v[58:61]
	v_mfma_f32_16x16x32_bf16 v[54:57], v[86:89], v[138:141], v[54:57]
	v_mfma_f32_16x16x32_bf16 v[50:53], v[82:85], v[164:167], v[50:53]
	v_mfma_f32_16x16x32_bf16 v[46:49], v[200:203], v[138:141], v[46:49]
	v_mfma_f32_16x16x32_bf16 v[42:45], v[196:199], v[164:167], v[42:45]
	v_mfma_f32_16x16x32_bf16 v[38:41], v[208:211], v[138:141], v[38:41]
	v_mfma_f32_16x16x32_bf16 v[34:37], v[204:207], v[164:167], v[34:37]
	v_mfma_f32_16x16x32_bf16 v[220:223], v[70:73], v[170:173], v[58:61]
	v_mfma_f32_16x16x32_bf16 v[224:227], v[86:89], v[170:173], v[50:53]
	v_mfma_f32_16x16x32_bf16 v[228:231], v[200:203], v[170:173], v[42:45]
	v_mfma_f32_16x16x32_bf16 v[134:137], v[208:211], v[170:173], v[34:37]
	v_mfma_f32_16x16x32_bf16 v[30:33], v[66:69], v[98:101], v[30:33]
	v_mfma_f32_16x16x32_bf16 v[22:25], v[82:85], v[98:101], v[22:25]
	v_mfma_f32_16x16x32_bf16 v[14:17], v[196:199], v[98:101], v[14:17]
	v_mfma_f32_16x16x32_bf16 v[6:9], v[204:207], v[98:101], v[6:9]
	v_mfma_f32_16x16x32_bf16 v[30:33], v[70:73], v[102:105], v[30:33]
	v_mfma_f32_16x16x32_bf16 v[26:29], v[66:69], v[114:117], v[26:29]
	v_mfma_f32_16x16x32_bf16 v[22:25], v[86:89], v[102:105], v[22:25]
	v_mfma_f32_16x16x32_bf16 v[18:21], v[82:85], v[114:117], v[18:21]
	v_mfma_f32_16x16x32_bf16 v[14:17], v[200:203], v[102:105], v[14:17]
	v_mfma_f32_16x16x32_bf16 v[10:13], v[196:199], v[114:117], v[10:13]
	v_mfma_f32_16x16x32_bf16 v[6:9], v[208:211], v[102:105], v[6:9]
	v_mfma_f32_16x16x32_bf16 v[2:5], v[204:207], v[114:117], v[2:5]
	v_mfma_f32_16x16x32_bf16 v[138:141], v[70:73], v[118:121], v[26:29]
	v_mfma_f32_16x16x32_bf16 v[164:167], v[86:89], v[118:121], v[18:21]
	v_mfma_f32_16x16x32_bf16 v[170:173], v[200:203], v[118:121], v[10:13]
	v_mfma_f32_16x16x32_bf16 v[196:199], v[208:211], v[118:121], v[2:5]
	s_barrier
	ds_read_b128 v[200:203], v168
	ds_read_b128 v[204:207], v168 offset:1024
	ds_read_b128 v[208:211], v168 offset:2048
	ds_read_b128 v[232:235], v168 offset:3072
	ds_read_b128 v[2:5], v147 offset:32768
	ds_read_b128 v[10:13], v147 offset:33792
	ds_read_b128 v[18:21], v146 offset:32768
	ds_read_b128 v[34:37], v146 offset:33792
	ds_read_b128 v[236:239], v145 offset:32768
	ds_read_b128 v[240:243], v145 offset:33792
	ds_read_b128 v[244:247], v144 offset:32768
	ds_read_b128 v[248:251], v144 offset:33792
	s_waitcnt vmcnt(2)
	s_barrier
	s_waitcnt lgkmcnt(0)
	v_mfma_f32_16x16x32_bf16 v[26:29], v[2:5], v[200:203], v[126:129]
	v_mfma_f32_16x16x32_bf16 v[118:121], v[10:13], v[204:207], v[26:29]
	v_mfma_f32_16x16x32_bf16 v[26:29], v[2:5], v[208:211], v[122:125]
	v_mfma_f32_16x16x32_bf16 v[86:89], v[10:13], v[232:235], v[26:29]
	v_mfma_f32_16x16x32_bf16 v[26:29], v[18:21], v[200:203], v[130:133]
	v_mfma_f32_16x16x32_bf16 v[114:117], v[34:37], v[204:207], v[26:29]
	v_mfma_f32_16x16x32_bf16 v[26:29], v[18:21], v[208:211], v[176:179]
	v_mfma_f32_16x16x32_bf16 v[82:85], v[34:37], v[232:235], v[26:29]
	v_mfma_f32_16x16x32_bf16 v[26:29], v[236:239], v[200:203], v[110:113]
	v_mfma_f32_16x16x32_bf16 v[102:105], v[240:243], v[204:207], v[26:29]
	v_mfma_f32_16x16x32_bf16 v[26:29], v[236:239], v[208:211], v[106:109]
	v_mfma_f32_16x16x32_bf16 v[70:73], v[240:243], v[232:235], v[26:29]
	v_mfma_f32_16x16x32_bf16 v[26:29], v[244:247], v[200:203], v[212:215]
	v_mfma_f32_16x16x32_bf16 v[98:101], v[248:251], v[204:207], v[26:29]
	v_mfma_f32_16x16x32_bf16 v[26:29], v[244:247], v[208:211], v[216:219]
	v_mfma_f32_16x16x32_bf16 v[66:69], v[248:251], v[232:235], v[26:29]
	s_barrier
; #define LDA(dst, b, h) _Pragma("unroll") for (int m = 0; m < 4; ++m) _Pragma("unroll") for (int k = 0; k < 2; ++k) \
;     dst[m][k] = *reinterpret_cast<const bf16x8*>((char*)SA(b, h) + lds_byte(wr * 64 + m * 16 + fr, k * 32 + fq * 8))
; #define LDB(dst, b, h) _Pragma("unroll") for (int n = 0; n < 2; ++n) _Pragma("unroll") for (int k = 0; k < 2; ++k) \
;     dst[n][k] = *reinterpret_cast<const bf16x8*>((char*)SB(b, h) + lds_byte(wc * 32 + n * 16 + fr, k * 32 + fq * 8))
; #define MMA(ai, bj, At, Bq) do { __builtin_amdgcn_s_setprio(1); \
;     _Pragma("unroll") for (int m = 0; m < 4; ++m) _Pragma("unroll") for (int n = 0; n < 2; ++n) _Pragma("unroll") for (int k = 0; k < 2; ++k) \
;       acc[ai][bj][m][n] = __builtin_amdgcn_mfma_f32_16x16x32_bf16(At[m][k], Bq[n][k], acc[ai][bj][m][n], 0, 0, 0); \
;     __builtin_amdgcn_s_setprio(0); } while (0)
; #define WAIT_V(n) asm volatile("s_waitcnt vmcnt(" #n ")" ::: "memory")
; #define WAIT_L(n) asm volatile("s_waitcnt lgkmcnt(" #n ")" ::: "memory")
; #define BAR __builtin_amdgcn_s_barrier()
; __device__ __forceinline__ void gemm256(const u16* __restrict__ A, int lda, const u16* __restrict__ Bt, int ldb, int K,
;                                         f32x4 (&acc)[2][2][4][2], const int g_wid) {
;     ...
;     LDB(B1, 1, 1); WAIT_V(0); BAR; WAIT_L(0); MMA(0, 1, At, B1); BAR;
;     LDA(At, 1, 1); BAR; WAIT_L(0); MMA(1, 0, At, B0); MMA(1, 1, At, B1); BAR; }
;   if (wr == 0) BAR;
	ds_read_b128 v[130:133], v162
	ds_read_b128 v[174:177], v162 offset:1024
	ds_read_b128 v[212:215], v162 offset:2048
	ds_read_b128 v[160:163], v162 offset:3072
	s_waitcnt vmcnt(0)
	s_barrier
	s_waitcnt lgkmcnt(0)
	v_mfma_f32_16x16x32_bf16 v[26:29], v[2:5], v[130:133], v[94:97]
	v_mfma_f32_16x16x32_bf16 v[2:5], v[2:5], v[212:215], v[90:93]
	v_mfma_f32_16x16x32_bf16 v[58:61], v[10:13], v[174:177], v[26:29]
	v_mfma_f32_16x16x32_bf16 v[26:29], v[10:13], v[160:163], v[2:5]
	v_mfma_f32_16x16x32_bf16 v[2:5], v[18:21], v[130:133], v[180:183]
	v_mfma_f32_16x16x32_bf16 v[50:53], v[34:37], v[174:177], v[2:5]
	v_mfma_f32_16x16x32_bf16 v[2:5], v[18:21], v[212:215], v[184:187]
	v_mfma_f32_16x16x32_bf16 v[18:21], v[34:37], v[160:163], v[2:5]
	v_mfma_f32_16x16x32_bf16 v[2:5], v[236:239], v[130:133], v[78:81]
	v_mfma_f32_16x16x32_bf16 v[42:45], v[240:243], v[174:177], v[2:5]
	v_mfma_f32_16x16x32_bf16 v[2:5], v[236:239], v[212:215], v[74:77]
	v_mfma_f32_16x16x32_bf16 v[10:13], v[240:243], v[160:163], v[2:5]
	v_mfma_f32_16x16x32_bf16 v[2:5], v[244:247], v[130:133], v[188:191]
	v_mfma_f32_16x16x32_bf16 v[34:37], v[248:251], v[174:177], v[2:5]
	v_mfma_f32_16x16x32_bf16 v[2:5], v[244:247], v[212:215], v[192:195]
	v_mfma_f32_16x16x32_bf16 v[2:5], v[248:251], v[160:163], v[2:5]
	s_barrier
	ds_read_b128 v[178:181], v147 offset:49152
	ds_read_b128 v[182:185], v147 offset:50176
	ds_read_b128 v[186:189], v146 offset:49152
	ds_read_b128 v[190:193], v146 offset:50176
	ds_read_b128 v[216:219], v145 offset:49152
	ds_read_b128 v[236:239], v145 offset:50176
	ds_read_b128 v[240:243], v144 offset:49152
	ds_read_b128 v[144:147], v144 offset:50176
	s_barrier
	s_waitcnt lgkmcnt(0)
	v_mfma_f32_16x16x32_bf16 v[62:65], v[178:181], v[200:203], v[62:65]
	v_mfma_f32_16x16x32_bf16 v[54:57], v[186:189], v[200:203], v[54:57]
	v_mfma_f32_16x16x32_bf16 v[46:49], v[216:219], v[200:203], v[46:49]
	v_mfma_f32_16x16x32_bf16 v[38:41], v[240:243], v[200:203], v[38:41]
	v_mfma_f32_16x16x32_bf16 v[126:129], v[182:185], v[204:207], v[62:65]
	v_mfma_f32_16x16x32_bf16 v[62:65], v[178:181], v[208:211], v[220:223]
	v_mfma_f32_16x16x32_bf16 v[122:125], v[190:193], v[204:207], v[54:57]
	v_mfma_f32_16x16x32_bf16 v[54:57], v[186:189], v[208:211], v[224:227]
	v_mfma_f32_16x16x32_bf16 v[110:113], v[236:239], v[204:207], v[46:49]
	v_mfma_f32_16x16x32_bf16 v[46:49], v[216:219], v[208:211], v[228:231]
	v_mfma_f32_16x16x32_bf16 v[106:109], v[144:147], v[204:207], v[38:41]
	v_mfma_f32_16x16x32_bf16 v[38:41], v[240:243], v[208:211], v[134:137]
	v_mfma_f32_16x16x32_bf16 v[94:97], v[182:185], v[232:235], v[62:65]
	v_mfma_f32_16x16x32_bf16 v[90:93], v[190:193], v[232:235], v[54:57]
	v_mfma_f32_16x16x32_bf16 v[78:81], v[236:239], v[232:235], v[46:49]
	v_mfma_f32_16x16x32_bf16 v[74:77], v[144:147], v[232:235], v[38:41]
	v_mfma_f32_16x16x32_bf16 v[30:33], v[178:181], v[130:133], v[30:33]
	v_mfma_f32_16x16x32_bf16 v[22:25], v[186:189], v[130:133], v[22:25]
	v_mfma_f32_16x16x32_bf16 v[14:17], v[216:219], v[130:133], v[14:17]
	v_mfma_f32_16x16x32_bf16 v[6:9], v[240:243], v[130:133], v[6:9]
	v_mfma_f32_16x16x32_bf16 v[62:65], v[182:185], v[174:177], v[30:33]
	v_mfma_f32_16x16x32_bf16 v[30:33], v[178:181], v[212:215], v[138:141]
	v_mfma_f32_16x16x32_bf16 v[54:57], v[190:193], v[174:177], v[22:25]
	v_mfma_f32_16x16x32_bf16 v[22:25], v[186:189], v[212:215], v[164:167]
	v_mfma_f32_16x16x32_bf16 v[46:49], v[236:239], v[174:177], v[14:17]
	v_mfma_f32_16x16x32_bf16 v[14:17], v[216:219], v[212:215], v[170:173]
	v_mfma_f32_16x16x32_bf16 v[38:41], v[144:147], v[174:177], v[6:9]
	v_mfma_f32_16x16x32_bf16 v[6:9], v[240:243], v[212:215], v[196:199]
	v_mfma_f32_16x16x32_bf16 v[30:33], v[182:185], v[160:163], v[30:33]
	v_mfma_f32_16x16x32_bf16 v[22:25], v[190:193], v[160:163], v[22:25]
	v_mfma_f32_16x16x32_bf16 v[14:17], v[236:239], v[160:163], v[14:17]
	v_mfma_f32_16x16x32_bf16 v[6:9], v[144:147], v[160:163], v[6:9]
	s_setprio 0
	s_movk_i32 s11, 0x100
	v_cmp_gt_u32_e32 vcc, s11, v0
	s_barrier
	s_and_saveexec_b64 s[16:17], vcc
	s_cbranch_execz .LBB0_309
	s_barrier
	s_branch .LBB0_309

; #define STA(P, br, kt) STAGE(P, A, aoff0, aoff1, lda, br, kt)
; #define STB(P, br, kt) STAGE(P, Bt, boff0, boff1, ldb, br, kt)
; #define LDA(dst, b, h) _Pragma("unroll") for (int m = 0; m < 4; ++m) _Pragma("unroll") for (int k = 0; k < 2; ++k) \
;     dst[m][k] = *reinterpret_cast<const bf16x8*>((char*)SA(b, h) + lds_byte(wr * 64 + m * 16 + fr, k * 32 + fq * 8))
; #define LDB(dst, b, h) _Pragma("unroll") for (int n = 0; n < 2; ++n) _Pragma("unroll") for (int k = 0; k < 2; ++k) \
;     dst[n][k] = *reinterpret_cast<const bf16x8*>((char*)SB(b, h) + lds_byte(wc * 32 + n * 16 + fr, k * 32 + fq * 8))
; #define MMA(ai, bj, At, Bq) do { __builtin_amdgcn_s_setprio(1); \
;     _Pragma("unroll") for (int m = 0; m < 4; ++m) _Pragma("unroll") for (int n = 0; n < 2; ++n) _Pragma("unroll") for (int k = 0; k < 2; ++k) \
;       acc[ai][bj][m][n] = __builtin_amdgcn_mfma_f32_16x16x32_bf16(At[m][k], Bq[n][k], acc[ai][bj][m][n], 0, 0, 0); \
;     __builtin_amdgcn_s_setprio(0); } while (0)
; #define WAIT_L(n) asm volatile("s_waitcnt lgkmcnt(" #n ")" ::: "memory")
; #define BAR __builtin_amdgcn_s_barrier()
; #define SCHED __builtin_amdgcn_sched_barrier(0)
; __device__ __forceinline__ void gemm256(const u16* __restrict__ A, int lda, const u16* __restrict__ Bt, int ldb, int K,
;                                         f32x4 (&acc)[2][2][4][2], const int g_wid) {
;     ...
;     LDB(B0, 0, 0); SCHED; LDA(At, 0, 0); STA(SA(1, 1), HALF, t + 1);
;     WAIT_L(8); BAR; WAIT_L(0); MMA(0, 0, At, B0); BAR; SCHED;
;     LDB(B1, 0, 1); STB(SB(0, 0), 0, t + 2);
;     BAR; WAIT_L(0); MMA(0, 1, At, B1); BAR;
;     LDA(At, 0, 1); STA(SA(0, 0), 0, t + 2);
;     BAR; WAIT_L(0); MMA(1, 0, At, B0); BAR; SCHED;
.LBB0_341:
	ds_read_b128 v[178:181], v174
	ds_read_b128 v[182:185], v174 offset:1024
	ds_read_b128 v[186:189], v174 offset:2048
	ds_read_b128 v[190:193], v174 offset:3072
	v_add_u32_e32 v175, 0xc000, v159
	v_lshl_add_u64 v[242:243], v[138:139], 0, s[12:13]
	v_readfirstlane_b32 s15, v175
	v_lshl_add_u64 v[176:177], v[242:243], 0, s[10:11]
	s_mov_b32 m0, s15
	ds_read_b128 v[194:197], v145
	ds_read_b128 v[198:201], v145 offset:1024
	ds_read_b128 v[202:205], v144
	ds_read_b128 v[206:209], v144 offset:1024
	ds_read_b128 v[210:213], v143
	ds_read_b128 v[214:217], v143 offset:1024
	ds_read_b128 v[218:221], v142
	ds_read_b128 v[222:225], v142 offset:1024
	global_load_lds_dwordx4 v[176:177], off
	v_add_u32_e32 v176, 0xe000, v159
	v_lshl_add_u64 v[244:245], v[140:141], 0, s[12:13]
	s_add_u32 m0, m0, 0x2000
	v_lshl_add_u64 v[226:227], v[244:245], 0, s[10:11]
	global_load_lds_dwordx4 v[226:227], off
	s_waitcnt lgkmcnt(8)
	s_barrier
	s_waitcnt lgkmcnt(0)
	v_mfma_f32_16x16x32_bf16 v[126:129], v[194:197], v[178:181], v[126:129]
	v_mfma_f32_16x16x32_bf16 v[122:125], v[194:197], v[186:189], v[122:125]
	v_mfma_f32_16x16x32_bf16 v[118:121], v[202:205], v[178:181], v[118:121]
	v_mfma_f32_16x16x32_bf16 v[114:117], v[202:205], v[186:189], v[114:117]
	v_mfma_f32_16x16x32_bf16 v[110:113], v[210:213], v[178:181], v[110:113]
	v_mfma_f32_16x16x32_bf16 v[106:109], v[210:213], v[186:189], v[106:109]
	v_mfma_f32_16x16x32_bf16 v[102:105], v[218:221], v[178:181], v[102:105]
	v_mfma_f32_16x16x32_bf16 v[98:101], v[218:221], v[186:189], v[98:101]
	v_mfma_f32_16x16x32_bf16 v[126:129], v[198:201], v[182:185], v[126:129]
	v_mfma_f32_16x16x32_bf16 v[122:125], v[198:201], v[190:193], v[122:125]
	v_mfma_f32_16x16x32_bf16 v[118:121], v[206:209], v[182:185], v[118:121]
	v_mfma_f32_16x16x32_bf16 v[114:117], v[206:209], v[190:193], v[114:117]
	v_mfma_f32_16x16x32_bf16 v[110:113], v[214:217], v[182:185], v[110:113]
	v_mfma_f32_16x16x32_bf16 v[106:109], v[214:217], v[190:193], v[106:109]
	v_mfma_f32_16x16x32_bf16 v[102:105], v[222:225], v[182:185], v[102:105]
	v_mfma_f32_16x16x32_bf16 v[98:101], v[222:225], v[190:193], v[98:101]
	s_barrier
	v_lshl_add_u64 v[246:247], v[134:135], 0, s[12:13]
	v_readfirstlane_b32 s15, v146
	v_lshl_add_u64 v[248:249], v[246:247], 0, s[74:75]
	s_mov_b32 m0, s15
	ds_read_b128 v[226:229], v173
	ds_read_b128 v[230:233], v173 offset:1024
	ds_read_b128 v[234:237], v173 offset:2048
	ds_read_b128 v[238:241], v173 offset:3072
	global_load_lds_dwordx4 v[248:249], off
	v_lshl_add_u64 v[248:249], v[136:137], 0, s[12:13]
	s_add_u32 m0, m0, 0x2000
	v_lshl_add_u64 v[250:251], v[248:249], 0, s[74:75]
	global_load_lds_dwordx4 v[250:251], off
	s_barrier
	s_waitcnt lgkmcnt(0)
	v_mfma_f32_16x16x32_bf16 v[94:97], v[194:197], v[226:229], v[94:97]
	v_mfma_f32_16x16x32_bf16 v[90:93], v[194:197], v[234:237], v[90:93]
	v_mfma_f32_16x16x32_bf16 v[86:89], v[202:205], v[226:229], v[86:89]
	v_mfma_f32_16x16x32_bf16 v[82:85], v[202:205], v[234:237], v[82:85]
	v_mfma_f32_16x16x32_bf16 v[78:81], v[210:213], v[226:229], v[78:81]
	v_mfma_f32_16x16x32_bf16 v[74:77], v[210:213], v[234:237], v[74:77]
	v_mfma_f32_16x16x32_bf16 v[70:73], v[218:221], v[226:229], v[70:73]
	v_mfma_f32_16x16x32_bf16 v[66:69], v[218:221], v[234:237], v[66:69]
	v_mfma_f32_16x16x32_bf16 v[94:97], v[198:201], v[230:233], v[94:97]
	v_mfma_f32_16x16x32_bf16 v[90:93], v[198:201], v[238:241], v[90:93]
	v_mfma_f32_16x16x32_bf16 v[86:89], v[206:209], v[230:233], v[86:89]
	v_mfma_f32_16x16x32_bf16 v[82:85], v[206:209], v[238:241], v[82:85]
	v_mfma_f32_16x16x32_bf16 v[78:81], v[214:217], v[230:233], v[78:81]
	v_mfma_f32_16x16x32_bf16 v[74:77], v[214:217], v[238:241], v[74:77]
	v_mfma_f32_16x16x32_bf16 v[70:73], v[222:225], v[230:233], v[70:73]
	v_mfma_f32_16x16x32_bf16 v[66:69], v[222:225], v[238:241], v[66:69]
	v_readfirstlane_b32 s15, v159
	v_lshl_add_u64 v[250:251], v[242:243], 0, s[22:23]
	s_mov_b32 m0, s15
	s_barrier
	ds_read_b128 v[194:197], v145 offset:16384
	ds_read_b128 v[198:201], v145 offset:17408
	ds_read_b128 v[202:205], v144 offset:16384
	ds_read_b128 v[206:209], v144 offset:17408
	ds_read_b128 v[210:213], v143 offset:16384
	ds_read_b128 v[214:217], v143 offset:17408
	ds_read_b128 v[218:221], v142 offset:16384
	ds_read_b128 v[222:225], v142 offset:17408
	global_load_lds_dwordx4 v[250:251], off
	s_add_u32 m0, m0, 0x2000
	v_lshl_add_u64 v[250:251], v[244:245], 0, s[22:23]
	global_load_lds_dwordx4 v[250:251], off
	s_barrier
	s_waitcnt lgkmcnt(0)
	v_mfma_f32_16x16x32_bf16 v[62:65], v[194:197], v[178:181], v[62:65]
	v_mfma_f32_16x16x32_bf16 v[58:61], v[194:197], v[186:189], v[58:61]
	v_mfma_f32_16x16x32_bf16 v[54:57], v[202:205], v[178:181], v[54:57]
	v_mfma_f32_16x16x32_bf16 v[50:53], v[202:205], v[186:189], v[50:53]
	v_mfma_f32_16x16x32_bf16 v[46:49], v[210:213], v[178:181], v[46:49]
	v_mfma_f32_16x16x32_bf16 v[42:45], v[210:213], v[186:189], v[42:45]
	v_mfma_f32_16x16x32_bf16 v[38:41], v[218:221], v[178:181], v[38:41]
	v_mfma_f32_16x16x32_bf16 v[34:37], v[218:221], v[186:189], v[34:37]
	v_mfma_f32_16x16x32_bf16 v[62:65], v[198:201], v[182:185], v[62:65]
	v_mfma_f32_16x16x32_bf16 v[58:61], v[198:201], v[190:193], v[58:61]
	v_mfma_f32_16x16x32_bf16 v[54:57], v[206:209], v[182:185], v[54:57]
	v_mfma_f32_16x16x32_bf16 v[50:53], v[206:209], v[190:193], v[50:53]
	v_mfma_f32_16x16x32_bf16 v[46:49], v[214:217], v[182:185], v[46:49]
	v_mfma_f32_16x16x32_bf16 v[42:45], v[214:217], v[190:193], v[42:45]
	v_mfma_f32_16x16x32_bf16 v[38:41], v[222:225], v[182:185], v[38:41]
	v_mfma_f32_16x16x32_bf16 v[34:37], v[222:225], v[190:193], v[34:37]
	s_barrier
; #define STA(P, br, kt) STAGE(P, A, aoff0, aoff1, lda, br, kt)
; #define STB(P, br, kt) STAGE(P, Bt, boff0, boff1, ldb, br, kt)
; #define LDA(dst, b, h) _Pragma("unroll") for (int m = 0; m < 4; ++m) _Pragma("unroll") for (int k = 0; k < 2; ++k) \
;     dst[m][k] = *reinterpret_cast<const bf16x8*>((char*)SA(b, h) + lds_byte(wr * 64 + m * 16 + fr, k * 32 + fq * 8))
; #define LDB(dst, b, h) _Pragma("unroll") for (int n = 0; n < 2; ++n) _Pragma("unroll") for (int k = 0; k < 2; ++k) \
;     dst[n][k] = *reinterpret_cast<const bf16x8*>((char*)SB(b, h) + lds_byte(wc * 32 + n * 16 + fr, k * 32 + fq * 8))
; #define MMA(ai, bj, At, Bq) do { __builtin_amdgcn_s_setprio(1); \
;     _Pragma("unroll") for (int m = 0; m < 4; ++m) _Pragma("unroll") for (int n = 0; n < 2; ++n) _Pragma("unroll") for (int k = 0; k < 2; ++k) \
;       acc[ai][bj][m][n] = __builtin_amdgcn_mfma_f32_16x16x32_bf16(At[m][k], Bq[n][k], acc[ai][bj][m][n], 0, 0, 0); \
;     __builtin_amdgcn_s_setprio(0); } while (0)
; #define WAIT_V(n) asm volatile("s_waitcnt vmcnt(" #n ")" ::: "memory")
; #define WAIT_L(n) asm volatile("s_waitcnt lgkmcnt(" #n ")" ::: "memory")
; #define BAR __builtin_amdgcn_s_barrier()
; #define SCHED __builtin_amdgcn_sched_barrier(0)
; __device__ __forceinline__ void gemm256(const u16* __restrict__ A, int lda, const u16* __restrict__ Bt, int ldb, int K,
;                                         f32x4 (&acc)[2][2][4][2], const int g_wid) {
;     ...
;     STB(SB(0, 1), HALF, t + 2);
;     WAIT_V(6); BAR; MMA(1, 1, At, B1); BAR;
;     LDB(B0, 1, 0); SCHED; LDA(At, 1, 0); STA(SA(0, 1), HALF, t + 2);
;     WAIT_L(8); BAR; WAIT_L(0); MMA(0, 0, At, B0); BAR; SCHED;
;     LDB(B1, 1, 1); STB(SB(1, 0), 0, t + 3);
;     BAR; WAIT_L(0); MMA(0, 1, At, B1); BAR;
;     LDA(At, 1, 1); STA(SA(1, 0), 0, t + 3);
	v_readfirstlane_b32 s15, v162
	v_lshl_add_u64 v[178:179], v[246:247], 0, s[24:25]
	s_mov_b32 m0, s15
	global_load_lds_dwordx4 v[178:179], off
	s_add_u32 m0, m0, 0x2000
	v_lshl_add_u64 v[178:179], v[248:249], 0, s[24:25]
	global_load_lds_dwordx4 v[178:179], off
	s_waitcnt vmcnt(6)
	s_barrier
	v_mfma_f32_16x16x32_bf16 v[30:33], v[194:197], v[226:229], v[30:33]
	v_mfma_f32_16x16x32_bf16 v[26:29], v[194:197], v[234:237], v[26:29]
	v_mfma_f32_16x16x32_bf16 v[22:25], v[202:205], v[226:229], v[22:25]
	v_mfma_f32_16x16x32_bf16 v[18:21], v[202:205], v[234:237], v[18:21]
	v_mfma_f32_16x16x32_bf16 v[14:17], v[210:213], v[226:229], v[14:17]
	v_mfma_f32_16x16x32_bf16 v[10:13], v[210:213], v[234:237], v[10:13]
	v_mfma_f32_16x16x32_bf16 v[6:9], v[218:221], v[226:229], v[6:9]
	v_mfma_f32_16x16x32_bf16 v[2:5], v[218:221], v[234:237], v[2:5]
	v_mfma_f32_16x16x32_bf16 v[30:33], v[198:201], v[230:233], v[30:33]
	v_mfma_f32_16x16x32_bf16 v[26:29], v[198:201], v[238:241], v[26:29]
	v_mfma_f32_16x16x32_bf16 v[22:25], v[206:209], v[230:233], v[22:25]
	v_mfma_f32_16x16x32_bf16 v[18:21], v[206:209], v[238:241], v[18:21]
	v_mfma_f32_16x16x32_bf16 v[14:17], v[214:217], v[230:233], v[14:17]
	v_mfma_f32_16x16x32_bf16 v[10:13], v[214:217], v[238:241], v[10:13]
	v_mfma_f32_16x16x32_bf16 v[6:9], v[222:225], v[230:233], v[6:9]
	v_mfma_f32_16x16x32_bf16 v[2:5], v[222:225], v[238:241], v[2:5]
	s_barrier
	ds_read_b128 v[178:181], v166
	ds_read_b128 v[182:185], v166 offset:1024
	ds_read_b128 v[186:189], v166 offset:2048
	ds_read_b128 v[190:193], v166 offset:3072
	v_readfirstlane_b32 s15, v164
	v_lshl_add_u64 v[226:227], v[242:243], 0, s[26:27]
	s_mov_b32 m0, s15
	ds_read_b128 v[194:197], v145 offset:32768
	ds_read_b128 v[198:201], v145 offset:33792
	ds_read_b128 v[202:205], v144 offset:32768
	ds_read_b128 v[206:209], v144 offset:33792
	ds_read_b128 v[210:213], v143 offset:32768
	ds_read_b128 v[214:217], v143 offset:33792
	ds_read_b128 v[218:221], v142 offset:32768
	ds_read_b128 v[222:225], v142 offset:33792
	global_load_lds_dwordx4 v[226:227], off
	s_add_u32 m0, m0, 0x2000
	v_lshl_add_u64 v[226:227], v[244:245], 0, s[26:27]
	global_load_lds_dwordx4 v[226:227], off
	s_waitcnt lgkmcnt(8)
	s_barrier
	s_waitcnt lgkmcnt(0)
	v_mfma_f32_16x16x32_bf16 v[126:129], v[194:197], v[178:181], v[126:129]
	v_mfma_f32_16x16x32_bf16 v[122:125], v[194:197], v[186:189], v[122:125]
	v_mfma_f32_16x16x32_bf16 v[118:121], v[202:205], v[178:181], v[118:121]
	v_mfma_f32_16x16x32_bf16 v[114:117], v[202:205], v[186:189], v[114:117]
	v_mfma_f32_16x16x32_bf16 v[110:113], v[210:213], v[178:181], v[110:113]
	v_mfma_f32_16x16x32_bf16 v[106:109], v[210:213], v[186:189], v[106:109]
	v_mfma_f32_16x16x32_bf16 v[102:105], v[218:221], v[178:181], v[102:105]
	v_mfma_f32_16x16x32_bf16 v[98:101], v[218:221], v[186:189], v[98:101]
	v_mfma_f32_16x16x32_bf16 v[126:129], v[198:201], v[182:185], v[126:129]
	v_mfma_f32_16x16x32_bf16 v[122:125], v[198:201], v[190:193], v[122:125]
	v_mfma_f32_16x16x32_bf16 v[118:121], v[206:209], v[182:185], v[118:121]
	v_mfma_f32_16x16x32_bf16 v[114:117], v[206:209], v[190:193], v[114:117]
	v_mfma_f32_16x16x32_bf16 v[110:113], v[214:217], v[182:185], v[110:113]
	v_mfma_f32_16x16x32_bf16 v[106:109], v[214:217], v[190:193], v[106:109]
	v_mfma_f32_16x16x32_bf16 v[102:105], v[222:225], v[182:185], v[102:105]
	v_mfma_f32_16x16x32_bf16 v[98:101], v[222:225], v[190:193], v[98:101]
	s_barrier
	v_readfirstlane_b32 s15, v167
	v_lshl_add_u64 v[250:251], v[246:247], 0, s[82:83]
	s_mov_b32 m0, s15
	ds_read_b128 v[226:229], v160
	ds_read_b128 v[230:233], v160 offset:1024
	ds_read_b128 v[234:237], v160 offset:2048
	ds_read_b128 v[238:241], v160 offset:3072
	global_load_lds_dwordx4 v[250:251], off
	s_add_u32 m0, m0, 0x2000
	v_lshl_add_u64 v[250:251], v[248:249], 0, s[82:83]
	global_load_lds_dwordx4 v[250:251], off
	s_barrier
	s_waitcnt lgkmcnt(0)
	v_mfma_f32_16x16x32_bf16 v[94:97], v[194:197], v[226:229], v[94:97]
	v_mfma_f32_16x16x32_bf16 v[90:93], v[194:197], v[234:237], v[90:93]
	v_mfma_f32_16x16x32_bf16 v[86:89], v[202:205], v[226:229], v[86:89]
	v_mfma_f32_16x16x32_bf16 v[82:85], v[202:205], v[234:237], v[82:85]
	v_mfma_f32_16x16x32_bf16 v[78:81], v[210:213], v[226:229], v[78:81]
	v_mfma_f32_16x16x32_bf16 v[74:77], v[210:213], v[234:237], v[74:77]
	v_mfma_f32_16x16x32_bf16 v[70:73], v[218:221], v[226:229], v[70:73]
	v_mfma_f32_16x16x32_bf16 v[66:69], v[218:221], v[234:237], v[66:69]
	v_mfma_f32_16x16x32_bf16 v[94:97], v[198:201], v[230:233], v[94:97]
	v_mfma_f32_16x16x32_bf16 v[90:93], v[198:201], v[238:241], v[90:93]
	v_mfma_f32_16x16x32_bf16 v[86:89], v[206:209], v[230:233], v[86:89]
	v_mfma_f32_16x16x32_bf16 v[82:85], v[206:209], v[238:241], v[82:85]
	v_mfma_f32_16x16x32_bf16 v[78:81], v[214:217], v[230:233], v[78:81]
	v_mfma_f32_16x16x32_bf16 v[74:77], v[214:217], v[238:241], v[74:77]
	v_mfma_f32_16x16x32_bf16 v[70:73], v[222:225], v[230:233], v[70:73]
	v_mfma_f32_16x16x32_bf16 v[66:69], v[222:225], v[238:241], v[66:69]
	v_readfirstlane_b32 s15, v169
	v_lshl_add_u64 v[242:243], v[242:243], 0, s[28:29]
	s_mov_b32 m0, s15
	s_barrier
	ds_read_b128 v[194:197], v145 offset:49152
	ds_read_b128 v[198:201], v145 offset:50176
	ds_read_b128 v[202:205], v144 offset:49152
	ds_read_b128 v[206:209], v144 offset:50176
	ds_read_b128 v[210:213], v143 offset:49152
	ds_read_b128 v[214:217], v143 offset:50176
	ds_read_b128 v[218:221], v142 offset:49152
	ds_read_b128 v[222:225], v142 offset:50176
	global_load_lds_dwordx4 v[242:243], off
	s_add_u32 m0, m0, 0x2000
	v_lshl_add_u64 v[242:243], v[244:245], 0, s[28:29]
	global_load_lds_dwordx4 v[242:243], off
	s_barrier
; #define STA(P, br, kt) STAGE(P, A, aoff0, aoff1, lda, br, kt)
; #define STB(P, br, kt) STAGE(P, Bt, boff0, boff1, ldb, br, kt)
; #define LDA(dst, b, h) _Pragma("unroll") for (int m = 0; m < 4; ++m) _Pragma("unroll") for (int k = 0; k < 2; ++k) \
;     dst[m][k] = *reinterpret_cast<const bf16x8*>((char*)SA(b, h) + lds_byte(wr * 64 + m * 16 + fr, k * 32 + fq * 8))
; #define LDB(dst, b, h) _Pragma("unroll") for (int n = 0; n < 2; ++n) _Pragma("unroll") for (int k = 0; k < 2; ++k) \
;     dst[n][k] = *reinterpret_cast<const bf16x8*>((char*)SB(b, h) + lds_byte(wc * 32 + n * 16 + fr, k * 32 + fq * 8))
; #define MMA(ai, bj, At, Bq) do { __builtin_amdgcn_s_setprio(1); \
;     _Pragma("unroll") for (int m = 0; m < 4; ++m) _Pragma("unroll") for (int n = 0; n < 2; ++n) _Pragma("unroll") for (int k = 0; k < 2; ++k) \
;       acc[ai][bj][m][n] = __builtin_amdgcn_mfma_f32_16x16x32_bf16(At[m][k], Bq[n][k], acc[ai][bj][m][n], 0, 0, 0); \
;     __builtin_amdgcn_s_setprio(0); } while (0)
; #define WAIT_V(n) asm volatile("s_waitcnt vmcnt(" #n ")" ::: "memory")
; #define WAIT_L(n) asm volatile("s_waitcnt lgkmcnt(" #n ")" ::: "memory")
; #define BAR __builtin_amdgcn_s_barrier()
; #define SCHED __builtin_amdgcn_sched_barrier(0)
; __device__ __forceinline__ void gemm256(const u16* __restrict__ A, int lda, const u16* __restrict__ Bt, int ldb, int K,
;                                         f32x4 (&acc)[2][2][4][2], const int g_wid) {
;     ...
;     BAR; WAIT_L(0); MMA(1, 0, At, B0); BAR; SCHED;
;     STB(SB(1, 1), HALF, t + 3);
;     WAIT_V(6); BAR; MMA(1, 1, At, B1); BAR;
;   }
;   { LDB(B0, 0, 0); LDA(At, 0, 0); STA(SA(1, 1), HALF, nt - 1);
;     BAR; WAIT_L(0); MMA(0, 0, At, B0); BAR;
;     LDB(B1, 0, 1); BAR; WAIT_L(0); MMA(0, 1, At, B1); BAR;
;     LDA(At, 0, 1); WAIT_V(4); BAR; WAIT_L(0); MMA(1, 0, At, B0); MMA(1, 1, At, B1); BAR; }
	s_waitcnt lgkmcnt(0)
	v_mfma_f32_16x16x32_bf16 v[62:65], v[194:197], v[178:181], v[62:65]
	v_mfma_f32_16x16x32_bf16 v[58:61], v[194:197], v[186:189], v[58:61]
	v_mfma_f32_16x16x32_bf16 v[54:57], v[202:205], v[178:181], v[54:57]
	v_mfma_f32_16x16x32_bf16 v[50:53], v[202:205], v[186:189], v[50:53]
	v_mfma_f32_16x16x32_bf16 v[46:49], v[210:213], v[178:181], v[46:49]
	v_mfma_f32_16x16x32_bf16 v[42:45], v[210:213], v[186:189], v[42:45]
	v_mfma_f32_16x16x32_bf16 v[38:41], v[218:221], v[178:181], v[38:41]
	v_mfma_f32_16x16x32_bf16 v[34:37], v[218:221], v[186:189], v[34:37]
	v_mfma_f32_16x16x32_bf16 v[62:65], v[198:201], v[182:185], v[62:65]
	v_mfma_f32_16x16x32_bf16 v[58:61], v[198:201], v[190:193], v[58:61]
	v_mfma_f32_16x16x32_bf16 v[54:57], v[206:209], v[182:185], v[54:57]
	v_mfma_f32_16x16x32_bf16 v[50:53], v[206:209], v[190:193], v[50:53]
	v_mfma_f32_16x16x32_bf16 v[46:49], v[214:217], v[182:185], v[46:49]
	v_mfma_f32_16x16x32_bf16 v[42:45], v[214:217], v[190:193], v[42:45]
	v_mfma_f32_16x16x32_bf16 v[38:41], v[222:225], v[182:185], v[38:41]
	v_mfma_f32_16x16x32_bf16 v[34:37], v[222:225], v[190:193], v[34:37]
	s_barrier
	v_readfirstlane_b32 s15, v171
	v_lshl_add_u64 v[178:179], v[246:247], 0, s[50:51]
	s_mov_b32 m0, s15
	global_load_lds_dwordx4 v[178:179], off
	s_add_u32 m0, m0, 0x2000
	v_lshl_add_u64 v[178:179], v[248:249], 0, s[50:51]
	global_load_lds_dwordx4 v[178:179], off
	s_waitcnt vmcnt(6)
	s_barrier
	v_mfma_f32_16x16x32_bf16 v[30:33], v[194:197], v[226:229], v[30:33]
	v_mfma_f32_16x16x32_bf16 v[26:29], v[194:197], v[234:237], v[26:29]
	v_mfma_f32_16x16x32_bf16 v[22:25], v[202:205], v[226:229], v[22:25]
	v_mfma_f32_16x16x32_bf16 v[18:21], v[202:205], v[234:237], v[18:21]
	v_mfma_f32_16x16x32_bf16 v[14:17], v[210:213], v[226:229], v[14:17]
	v_mfma_f32_16x16x32_bf16 v[10:13], v[210:213], v[234:237], v[10:13]
	v_mfma_f32_16x16x32_bf16 v[6:9], v[218:221], v[226:229], v[6:9]
	v_mfma_f32_16x16x32_bf16 v[2:5], v[218:221], v[234:237], v[2:5]
	v_mfma_f32_16x16x32_bf16 v[30:33], v[198:201], v[230:233], v[30:33]
	v_mfma_f32_16x16x32_bf16 v[26:29], v[198:201], v[238:241], v[26:29]
	v_mfma_f32_16x16x32_bf16 v[22:25], v[206:209], v[230:233], v[22:25]
	v_mfma_f32_16x16x32_bf16 v[18:21], v[206:209], v[238:241], v[18:21]
	v_mfma_f32_16x16x32_bf16 v[14:17], v[214:217], v[230:233], v[14:17]
	v_mfma_f32_16x16x32_bf16 v[10:13], v[214:217], v[238:241], v[10:13]
	v_mfma_f32_16x16x32_bf16 v[6:9], v[222:225], v[230:233], v[6:9]
	v_mfma_f32_16x16x32_bf16 v[2:5], v[222:225], v[238:241], v[2:5]
	s_add_i32 s14, s14, 2
	s_add_u32 s12, s12, 0x100
	s_addc_u32 s13, s13, 0
	s_cmp_lt_u32 s14, 40
	s_barrier
	s_cbranch_scc1 .LBB0_341
	s_add_u32 s2, s2, 0xb1580
	s_addc_u32 s3, s3, 0
	v_readfirstlane_b32 s12, v175
	v_lshl_add_u64 v[130:131], v[130:131], 1, s[2:3]
	s_mov_b32 m0, s12
	ds_read_b128 v[134:137], v174
	ds_read_b128 v[138:141], v174 offset:1024
	ds_read_b128 v[162:165], v174 offset:2048
	ds_read_b128 v[168:171], v174 offset:3072
	ds_read_b128 v[178:181], v145
	ds_read_b128 v[182:185], v145 offset:1024
	ds_read_b128 v[186:189], v144
	ds_read_b128 v[190:193], v144 offset:1024
	ds_read_b128 v[194:197], v143
	ds_read_b128 v[198:201], v143 offset:1024
	ds_read_b128 v[202:205], v142
	ds_read_b128 v[206:209], v142 offset:1024
	global_load_lds_dwordx4 v[130:131], off
	v_lshl_add_u64 v[130:131], v[132:133], 1, s[2:3]
	v_readfirstlane_b32 s2, v176
	s_mov_b32 m0, s2
	s_nop 0
	global_load_lds_dwordx4 v[130:131], off
	s_barrier
	s_waitcnt lgkmcnt(0)
	v_mfma_f32_16x16x32_bf16 v[126:129], v[178:181], v[134:137], v[126:129]
	v_mfma_f32_16x16x32_bf16 v[118:121], v[186:189], v[134:137], v[118:121]
	v_mfma_f32_16x16x32_bf16 v[114:117], v[186:189], v[162:165], v[114:117]
	v_mfma_f32_16x16x32_bf16 v[110:113], v[194:197], v[134:137], v[110:113]
	v_mfma_f32_16x16x32_bf16 v[106:109], v[194:197], v[162:165], v[106:109]
	v_mfma_f32_16x16x32_bf16 v[102:105], v[202:205], v[134:137], v[102:105]
	v_mfma_f32_16x16x32_bf16 v[98:101], v[202:205], v[162:165], v[98:101]
	v_mfma_f32_16x16x32_bf16 v[126:129], v[182:185], v[138:141], v[126:129]
	v_mfma_f32_16x16x32_bf16 v[122:125], v[178:181], v[162:165], v[122:125]
	v_mfma_f32_16x16x32_bf16 v[118:121], v[190:193], v[138:141], v[118:121]
	v_mfma_f32_16x16x32_bf16 v[114:117], v[190:193], v[168:171], v[114:117]
	v_mfma_f32_16x16x32_bf16 v[110:113], v[198:201], v[138:141], v[110:113]
	v_mfma_f32_16x16x32_bf16 v[106:109], v[198:201], v[168:171], v[106:109]
	v_mfma_f32_16x16x32_bf16 v[102:105], v[206:209], v[138:141], v[102:105]
	v_mfma_f32_16x16x32_bf16 v[98:101], v[206:209], v[168:171], v[98:101]
	v_mfma_f32_16x16x32_bf16 v[130:133], v[182:185], v[168:171], v[122:125]
	s_barrier
	s_nop 0
	ds_read_b128 v[122:125], v173
	ds_read_b128 v[174:177], v173 offset:1024
	ds_read_b128 v[210:213], v173 offset:2048
	ds_read_b128 v[214:217], v173 offset:3072
	s_barrier
	s_waitcnt lgkmcnt(0)
	v_mfma_f32_16x16x32_bf16 v[78:81], v[194:197], v[122:125], v[78:81]
	v_mfma_f32_16x16x32_bf16 v[74:77], v[194:197], v[210:213], v[74:77]
	v_mfma_f32_16x16x32_bf16 v[70:73], v[202:205], v[122:125], v[70:73]
	v_mfma_f32_16x16x32_bf16 v[66:69], v[202:205], v[210:213], v[66:69]
	v_mfma_f32_16x16x32_bf16 v[94:97], v[178:181], v[122:125], v[94:97]
	v_mfma_f32_16x16x32_bf16 v[90:93], v[178:181], v[210:213], v[90:93]
	v_mfma_f32_16x16x32_bf16 v[86:89], v[186:189], v[122:125], v[86:89]
	v_mfma_f32_16x16x32_bf16 v[82:85], v[186:189], v[210:213], v[82:85]
	v_mfma_f32_16x16x32_bf16 v[78:81], v[198:201], v[174:177], v[78:81]
	v_mfma_f32_16x16x32_bf16 v[74:77], v[198:201], v[214:217], v[74:77]
	v_mfma_f32_16x16x32_bf16 v[70:73], v[206:209], v[174:177], v[70:73]
	v_mfma_f32_16x16x32_bf16 v[66:69], v[206:209], v[214:217], v[66:69]
	v_mfma_f32_16x16x32_bf16 v[218:221], v[182:185], v[174:177], v[94:97]
	v_mfma_f32_16x16x32_bf16 v[178:181], v[182:185], v[214:217], v[90:93]
	v_mfma_f32_16x16x32_bf16 v[182:185], v[190:193], v[174:177], v[86:89]
	v_mfma_f32_16x16x32_bf16 v[186:189], v[190:193], v[214:217], v[82:85]
	s_barrier
; #define LDA(dst, b, h) _Pragma("unroll") for (int m = 0; m < 4; ++m) _Pragma("unroll") for (int k = 0; k < 2; ++k) \
;     dst[m][k] = *reinterpret_cast<const bf16x8*>((char*)SA(b, h) + lds_byte(wr * 64 + m * 16 + fr, k * 32 + fq * 8))
; #define LDB(dst, b, h) _Pragma("unroll") for (int n = 0; n < 2; ++n) _Pragma("unroll") for (int k = 0; k < 2; ++k) \
;     dst[n][k] = *reinterpret_cast<const bf16x8*>((char*)SB(b, h) + lds_byte(wc * 32 + n * 16 + fr, k * 32 + fq * 8))
; #define MMA(ai, bj, At, Bq) do { __builtin_amdgcn_s_setprio(1); \
;     _Pragma("unroll") for (int m = 0; m < 4; ++m) _Pragma("unroll") for (int n = 0; n < 2; ++n) _Pragma("unroll") for (int k = 0; k < 2; ++k) \
;       acc[ai][bj][m][n] = __builtin_amdgcn_mfma_f32_16x16x32_bf16(At[m][k], Bq[n][k], acc[ai][bj][m][n], 0, 0, 0); \
;     __builtin_amdgcn_s_setprio(0); } while (0)
; #define WAIT_V(n) asm volatile("s_waitcnt vmcnt(" #n ")" ::: "memory")
; #define WAIT_L(n) asm volatile("s_waitcnt lgkmcnt(" #n ")" ::: "memory")
; #define BAR __builtin_amdgcn_s_barrier()
; __device__ __forceinline__ void gemm256(const u16* __restrict__ A, int lda, const u16* __restrict__ Bt, int ldb, int K,
;                                         f32x4 (&acc)[2][2][4][2], const int g_wid) {
;     ...
;     LDA(At, 0, 1); WAIT_V(4); BAR; WAIT_L(0); MMA(1, 0, At, B0); MMA(1, 1, At, B1); BAR; }
;   { LDB(B0, 1, 0); LDA(At, 1, 0); WAIT_V(2); BAR; WAIT_L(0); MMA(0, 0, At, B0); BAR;
	s_nop 0
	ds_read_b128 v[82:85], v145 offset:16384
	ds_read_b128 v[86:89], v145 offset:17408
	ds_read_b128 v[90:93], v144 offset:16384
	ds_read_b128 v[94:97], v144 offset:17408
	ds_read_b128 v[190:193], v143 offset:16384
	ds_read_b128 v[194:197], v143 offset:17408
	ds_read_b128 v[198:201], v142 offset:16384
	ds_read_b128 v[202:205], v142 offset:17408
	s_waitcnt vmcnt(4)
	s_barrier
	s_waitcnt lgkmcnt(0)
	v_mfma_f32_16x16x32_bf16 v[46:49], v[190:193], v[134:137], v[46:49]
	v_mfma_f32_16x16x32_bf16 v[42:45], v[190:193], v[162:165], v[42:45]
	v_mfma_f32_16x16x32_bf16 v[38:41], v[198:201], v[134:137], v[38:41]
	v_mfma_f32_16x16x32_bf16 v[34:37], v[198:201], v[162:165], v[34:37]
	v_mfma_f32_16x16x32_bf16 v[62:65], v[82:85], v[134:137], v[62:65]
	v_mfma_f32_16x16x32_bf16 v[58:61], v[82:85], v[162:165], v[58:61]
	v_mfma_f32_16x16x32_bf16 v[54:57], v[90:93], v[134:137], v[54:57]
	v_mfma_f32_16x16x32_bf16 v[50:53], v[90:93], v[162:165], v[50:53]
	v_mfma_f32_16x16x32_bf16 v[46:49], v[194:197], v[138:141], v[46:49]
	v_mfma_f32_16x16x32_bf16 v[42:45], v[194:197], v[168:171], v[42:45]
	v_mfma_f32_16x16x32_bf16 v[38:41], v[202:205], v[138:141], v[38:41]
	v_mfma_f32_16x16x32_bf16 v[34:37], v[202:205], v[168:171], v[34:37]
	v_mfma_f32_16x16x32_bf16 v[206:209], v[86:89], v[138:141], v[62:65]
	v_mfma_f32_16x16x32_bf16 v[222:225], v[86:89], v[168:171], v[58:61]
	v_mfma_f32_16x16x32_bf16 v[226:229], v[94:97], v[138:141], v[54:57]
	v_mfma_f32_16x16x32_bf16 v[230:233], v[94:97], v[168:171], v[50:53]
	v_mfma_f32_16x16x32_bf16 v[2:5], v[198:201], v[210:213], v[2:5]
	v_mfma_f32_16x16x32_bf16 v[30:33], v[82:85], v[122:125], v[30:33]
	v_mfma_f32_16x16x32_bf16 v[26:29], v[82:85], v[210:213], v[26:29]
	v_mfma_f32_16x16x32_bf16 v[22:25], v[90:93], v[122:125], v[22:25]
	v_mfma_f32_16x16x32_bf16 v[18:21], v[90:93], v[210:213], v[18:21]
	v_mfma_f32_16x16x32_bf16 v[14:17], v[190:193], v[122:125], v[14:17]
	v_mfma_f32_16x16x32_bf16 v[10:13], v[190:193], v[210:213], v[10:13]
	v_mfma_f32_16x16x32_bf16 v[6:9], v[198:201], v[122:125], v[6:9]
	v_mfma_f32_16x16x32_bf16 v[2:5], v[202:205], v[214:217], v[2:5]
	v_mfma_f32_16x16x32_bf16 v[134:137], v[86:89], v[174:177], v[30:33]
	v_mfma_f32_16x16x32_bf16 v[138:141], v[86:89], v[214:217], v[26:29]
	v_mfma_f32_16x16x32_bf16 v[162:165], v[94:97], v[174:177], v[22:25]
	v_mfma_f32_16x16x32_bf16 v[168:171], v[94:97], v[214:217], v[18:21]
	v_mfma_f32_16x16x32_bf16 v[234:237], v[194:197], v[174:177], v[14:17]
	v_mfma_f32_16x16x32_bf16 v[190:193], v[194:197], v[214:217], v[10:13]
	v_mfma_f32_16x16x32_bf16 v[172:175], v[202:205], v[174:177], v[6:9]
	s_barrier
	s_nop 0
	ds_read_b128 v[6:9], v166
	ds_read_b128 v[10:13], v166 offset:1024
	ds_read_b128 v[14:17], v166 offset:2048
	ds_read_b128 v[194:197], v166 offset:3072
	ds_read_b128 v[18:21], v145 offset:32768
	ds_read_b128 v[22:25], v145 offset:33792
	ds_read_b128 v[30:33], v144 offset:32768
	ds_read_b128 v[50:53], v144 offset:33792
	ds_read_b128 v[198:201], v143 offset:32768
	ds_read_b128 v[202:205], v143 offset:33792
	ds_read_b128 v[210:213], v142 offset:32768
	ds_read_b128 v[214:217], v142 offset:33792
	s_waitcnt vmcnt(2)
	s_barrier
	s_waitcnt lgkmcnt(0)
	v_mfma_f32_16x16x32_bf16 v[26:29], v[18:21], v[6:9], v[126:129]
	v_mfma_f32_16x16x32_bf16 v[122:125], v[22:25], v[10:13], v[26:29]
	v_mfma_f32_16x16x32_bf16 v[26:29], v[18:21], v[14:17], v[130:133]
	v_mfma_f32_16x16x32_bf16 v[90:93], v[22:25], v[194:197], v[26:29]
	v_mfma_f32_16x16x32_bf16 v[26:29], v[30:33], v[6:9], v[118:121]
	v_mfma_f32_16x16x32_bf16 v[126:129], v[50:53], v[10:13], v[26:29]
	v_mfma_f32_16x16x32_bf16 v[26:29], v[30:33], v[14:17], v[114:117]
	v_mfma_f32_16x16x32_bf16 v[94:97], v[50:53], v[194:197], v[26:29]
	v_mfma_f32_16x16x32_bf16 v[26:29], v[198:201], v[6:9], v[110:113]
	v_mfma_f32_16x16x32_bf16 v[118:121], v[202:205], v[10:13], v[26:29]
	v_mfma_f32_16x16x32_bf16 v[26:29], v[198:201], v[14:17], v[106:109]
	v_mfma_f32_16x16x32_bf16 v[86:89], v[202:205], v[194:197], v[26:29]
	v_mfma_f32_16x16x32_bf16 v[26:29], v[210:213], v[6:9], v[102:105]
	v_mfma_f32_16x16x32_bf16 v[114:117], v[214:217], v[10:13], v[26:29]
	v_mfma_f32_16x16x32_bf16 v[26:29], v[210:213], v[14:17], v[98:101]
	v_mfma_f32_16x16x32_bf16 v[82:85], v[214:217], v[194:197], v[26:29]
	s_barrier
; #define LDA(dst, b, h) _Pragma("unroll") for (int m = 0; m < 4; ++m) _Pragma("unroll") for (int k = 0; k < 2; ++k) \
;     dst[m][k] = *reinterpret_cast<const bf16x8*>((char*)SA(b, h) + lds_byte(wr * 64 + m * 16 + fr, k * 32 + fq * 8))
; #define LDB(dst, b, h) _Pragma("unroll") for (int n = 0; n < 2; ++n) _Pragma("unroll") for (int k = 0; k < 2; ++k) \
;     dst[n][k] = *reinterpret_cast<const bf16x8*>((char*)SB(b, h) + lds_byte(wc * 32 + n * 16 + fr, k * 32 + fq * 8))
; #define MMA(ai, bj, At, Bq) do { __builtin_amdgcn_s_setprio(1); \
;     _Pragma("unroll") for (int m = 0; m < 4; ++m) _Pragma("unroll") for (int n = 0; n < 2; ++n) _Pragma("unroll") for (int k = 0; k < 2; ++k) \
;       acc[ai][bj][m][n] = __builtin_amdgcn_mfma_f32_16x16x32_bf16(At[m][k], Bq[n][k], acc[ai][bj][m][n], 0, 0, 0); \
;     __builtin_amdgcn_s_setprio(0); } while (0)
; #define WAIT_V(n) asm volatile("s_waitcnt vmcnt(" #n ")" ::: "memory")
; #define WAIT_L(n) asm volatile("s_waitcnt lgkmcnt(" #n ")" ::: "memory")
; #define BAR __builtin_amdgcn_s_barrier()
; __device__ __forceinline__ void gemm256(const u16* __restrict__ A, int lda, const u16* __restrict__ Bt, int ldb, int K,
;                                         f32x4 (&acc)[2][2][4][2], const int g_wid) {
;     ...
;     LDB(B1, 1, 1); WAIT_V(0); BAR; WAIT_L(0); MMA(0, 1, At, B1); BAR;
;     LDA(At, 1, 1); BAR; WAIT_L(0); MMA(1, 0, At, B0); MMA(1, 1, At, B1); BAR; }
;   if (wr == 0) BAR;
	ds_read_b128 v[130:133], v160
	ds_read_b128 v[238:241], v160 offset:1024
	ds_read_b128 v[242:245], v160 offset:2048
	ds_read_b128 v[246:249], v160 offset:3072
	s_waitcnt vmcnt(0)
	s_barrier
	s_waitcnt lgkmcnt(0)
	v_mfma_f32_16x16x32_bf16 v[26:29], v[18:21], v[130:133], v[218:221]
	v_mfma_f32_16x16x32_bf16 v[18:21], v[18:21], v[242:245], v[178:181]
	v_mfma_f32_16x16x32_bf16 v[58:61], v[22:25], v[238:241], v[26:29]
	v_mfma_f32_16x16x32_bf16 v[26:29], v[22:25], v[246:249], v[18:21]
	v_mfma_f32_16x16x32_bf16 v[18:21], v[30:33], v[130:133], v[182:185]
	v_mfma_f32_16x16x32_bf16 v[62:65], v[50:53], v[238:241], v[18:21]
	v_mfma_f32_16x16x32_bf16 v[18:21], v[30:33], v[242:245], v[186:189]
	v_mfma_f32_16x16x32_bf16 v[30:33], v[50:53], v[246:249], v[18:21]
	v_mfma_f32_16x16x32_bf16 v[18:21], v[198:201], v[130:133], v[78:81]
	v_mfma_f32_16x16x32_bf16 v[54:57], v[202:205], v[238:241], v[18:21]
	v_mfma_f32_16x16x32_bf16 v[18:21], v[198:201], v[242:245], v[74:77]
	v_mfma_f32_16x16x32_bf16 v[22:25], v[202:205], v[246:249], v[18:21]
	v_mfma_f32_16x16x32_bf16 v[18:21], v[210:213], v[130:133], v[70:73]
	v_mfma_f32_16x16x32_bf16 v[50:53], v[214:217], v[238:241], v[18:21]
	v_mfma_f32_16x16x32_bf16 v[18:21], v[210:213], v[242:245], v[66:69]
	v_mfma_f32_16x16x32_bf16 v[18:21], v[214:217], v[246:249], v[18:21]
	s_barrier
	ds_read_b128 v[176:179], v145 offset:49152
	ds_read_b128 v[180:183], v145 offset:50176
	ds_read_b128 v[184:187], v144 offset:49152
	ds_read_b128 v[144:147], v144 offset:50176
	ds_read_b128 v[198:201], v143 offset:49152
	ds_read_b128 v[202:205], v143 offset:50176
	ds_read_b128 v[210:213], v142 offset:49152
	ds_read_b128 v[214:217], v142 offset:50176
	s_barrier
	s_waitcnt lgkmcnt(0)
	v_mfma_f32_16x16x32_bf16 v[66:69], v[176:179], v[6:9], v[206:209]
	v_mfma_f32_16x16x32_bf16 v[110:113], v[180:183], v[10:13], v[66:69]
	v_mfma_f32_16x16x32_bf16 v[66:69], v[176:179], v[14:17], v[222:225]
	v_mfma_f32_16x16x32_bf16 v[78:81], v[180:183], v[194:197], v[66:69]
	v_mfma_f32_16x16x32_bf16 v[66:69], v[184:187], v[6:9], v[226:229]
	v_mfma_f32_16x16x32_bf16 v[46:49], v[198:201], v[6:9], v[46:49]
	v_mfma_f32_16x16x32_bf16 v[6:9], v[210:213], v[6:9], v[38:41]
	v_mfma_f32_16x16x32_bf16 v[106:109], v[144:147], v[10:13], v[66:69]
	v_mfma_f32_16x16x32_bf16 v[66:69], v[184:187], v[14:17], v[230:233]
	v_mfma_f32_16x16x32_bf16 v[42:45], v[198:201], v[14:17], v[42:45]
	v_mfma_f32_16x16x32_bf16 v[98:101], v[214:217], v[10:13], v[6:9]
	v_mfma_f32_16x16x32_bf16 v[6:9], v[210:213], v[14:17], v[34:37]
	v_mfma_f32_16x16x32_bf16 v[74:77], v[144:147], v[194:197], v[66:69]
	v_mfma_f32_16x16x32_bf16 v[102:105], v[202:205], v[10:13], v[46:49]
	v_mfma_f32_16x16x32_bf16 v[70:73], v[202:205], v[194:197], v[42:45]
	v_mfma_f32_16x16x32_bf16 v[66:69], v[214:217], v[194:197], v[6:9]
	v_mfma_f32_16x16x32_bf16 v[6:9], v[176:179], v[130:133], v[134:137]
	v_mfma_f32_16x16x32_bf16 v[46:49], v[180:183], v[238:241], v[6:9]
	v_mfma_f32_16x16x32_bf16 v[6:9], v[176:179], v[242:245], v[138:141]
	v_mfma_f32_16x16x32_bf16 v[14:17], v[180:183], v[246:249], v[6:9]
	v_mfma_f32_16x16x32_bf16 v[6:9], v[184:187], v[130:133], v[162:165]
	v_mfma_f32_16x16x32_bf16 v[42:45], v[144:147], v[238:241], v[6:9]
	v_mfma_f32_16x16x32_bf16 v[6:9], v[184:187], v[242:245], v[168:171]
	v_mfma_f32_16x16x32_bf16 v[10:13], v[144:147], v[246:249], v[6:9]
	v_mfma_f32_16x16x32_bf16 v[6:9], v[198:201], v[130:133], v[234:237]
	v_mfma_f32_16x16x32_bf16 v[38:41], v[202:205], v[238:241], v[6:9]
	v_mfma_f32_16x16x32_bf16 v[6:9], v[198:201], v[242:245], v[190:193]
	v_mfma_f32_16x16x32_bf16 v[34:37], v[210:213], v[130:133], v[172:175]
	v_mfma_f32_16x16x32_bf16 v[2:5], v[210:213], v[242:245], v[2:5]
	v_mfma_f32_16x16x32_bf16 v[6:9], v[202:205], v[246:249], v[6:9]
	v_mfma_f32_16x16x32_bf16 v[34:37], v[214:217], v[238:241], v[34:37]
	v_mfma_f32_16x16x32_bf16 v[2:5], v[214:217], v[246:249], v[2:5]
	s_setprio 0
	s_movk_i32 s2, 0x100
	v_cmp_gt_u32_e32 vcc, s2, v0
	s_barrier
	s_and_saveexec_b64 s[2:3], vcc
	s_cbranch_execz .LBB0_344
	s_barrier

; #define STA(P, br, kt) STAGE(P, A, aoff0, aoff1, lda, br, kt)
; #define STB(P, br, kt) STAGE(P, Bt, boff0, boff1, ldb, br, kt)
; #define LDA(dst, b, h) _Pragma("unroll") for (int m = 0; m < 4; ++m) _Pragma("unroll") for (int k = 0; k < 2; ++k) \
;     dst[m][k] = *reinterpret_cast<const bf16x8*>((char*)SA(b, h) + lds_byte(wr * 64 + m * 16 + fr, k * 32 + fq * 8))
; #define LDB(dst, b, h) _Pragma("unroll") for (int n = 0; n < 2; ++n) _Pragma("unroll") for (int k = 0; k < 2; ++k) \
;     dst[n][k] = *reinterpret_cast<const bf16x8*>((char*)SB(b, h) + lds_byte(wc * 32 + n * 16 + fr, k * 32 + fq * 8))
; #define MMA(ai, bj, At, Bq) do { __builtin_amdgcn_s_setprio(1); \
;     _Pragma("unroll") for (int m = 0; m < 4; ++m) _Pragma("unroll") for (int n = 0; n < 2; ++n) _Pragma("unroll") for (int k = 0; k < 2; ++k) \
;       acc[ai][bj][m][n] = __builtin_amdgcn_mfma_f32_16x16x32_bf16(At[m][k], Bq[n][k], acc[ai][bj][m][n], 0, 0, 0); \
;     __builtin_amdgcn_s_setprio(0); } while (0)
; #define WAIT_L(n) asm volatile("s_waitcnt lgkmcnt(" #n ")" ::: "memory")
; #define BAR __builtin_amdgcn_s_barrier()
; #define SCHED __builtin_amdgcn_sched_barrier(0)
; __device__ __forceinline__ void gemm256(const u16* __restrict__ A, int lda, const u16* __restrict__ Bt, int ldb, int K,
;                                         f32x4 (&acc)[2][2][4][2], const int g_wid) {
;     ...
;     LDB(B0, 0, 0); SCHED; LDA(At, 0, 0); STA(SA(1, 1), HALF, t + 1);
;     WAIT_L(8); BAR; WAIT_L(0); MMA(0, 0, At, B0); BAR; SCHED;
;     LDB(B1, 0, 1); STB(SB(0, 0), 0, t + 2);
;     BAR; WAIT_L(0); MMA(0, 1, At, B1); BAR;
;     LDA(At, 0, 1); STA(SA(0, 0), 0, t + 2);
;     BAR; WAIT_L(0); MMA(1, 0, At, B0); BAR; SCHED;
.LBB0_465:
	ds_read_b128 v[180:183], v176
	ds_read_b128 v[184:187], v176 offset:1024
	ds_read_b128 v[188:191], v176 offset:2048
	ds_read_b128 v[192:195], v176 offset:3072
	v_add_u32_e32 v177, 0xc000, v162
	v_lshl_add_u64 v[244:245], v[140:141], 0, s[16:17]
	v_readfirstlane_b32 s13, v177
	v_lshl_add_u64 v[178:179], v[244:245], 0, s[68:69]
	s_mov_b32 m0, s13
	ds_read_b128 v[196:199], v147
	ds_read_b128 v[200:203], v147 offset:1024
	ds_read_b128 v[204:207], v146
	ds_read_b128 v[208:211], v146 offset:1024
	ds_read_b128 v[212:215], v145
	ds_read_b128 v[216:219], v145 offset:1024
	ds_read_b128 v[220:223], v144
	ds_read_b128 v[224:227], v144 offset:1024
	global_load_lds_dwordx4 v[178:179], off
	v_add_u32_e32 v178, 0xe000, v162
	v_lshl_add_u64 v[246:247], v[138:139], 0, s[16:17]
	s_add_u32 m0, m0, 0x2000
	v_lshl_add_u64 v[228:229], v[246:247], 0, s[68:69]
	global_load_lds_dwordx4 v[228:229], off
	s_waitcnt lgkmcnt(8)
	s_barrier
	s_waitcnt lgkmcnt(0)
	v_mfma_f32_16x16x32_bf16 v[126:129], v[196:199], v[180:183], v[126:129]
	v_mfma_f32_16x16x32_bf16 v[122:125], v[196:199], v[188:191], v[122:125]
	v_mfma_f32_16x16x32_bf16 v[118:121], v[204:207], v[180:183], v[118:121]
	v_mfma_f32_16x16x32_bf16 v[114:117], v[204:207], v[188:191], v[114:117]
	v_mfma_f32_16x16x32_bf16 v[110:113], v[212:215], v[180:183], v[110:113]
	v_mfma_f32_16x16x32_bf16 v[106:109], v[212:215], v[188:191], v[106:109]
	v_mfma_f32_16x16x32_bf16 v[102:105], v[220:223], v[180:183], v[102:105]
	v_mfma_f32_16x16x32_bf16 v[98:101], v[220:223], v[188:191], v[98:101]
	v_mfma_f32_16x16x32_bf16 v[126:129], v[200:203], v[184:187], v[126:129]
	v_mfma_f32_16x16x32_bf16 v[122:125], v[200:203], v[192:195], v[122:125]
	v_mfma_f32_16x16x32_bf16 v[118:121], v[208:211], v[184:187], v[118:121]
	v_mfma_f32_16x16x32_bf16 v[114:117], v[208:211], v[192:195], v[114:117]
	v_mfma_f32_16x16x32_bf16 v[110:113], v[216:219], v[184:187], v[110:113]
	v_mfma_f32_16x16x32_bf16 v[106:109], v[216:219], v[192:195], v[106:109]
	v_mfma_f32_16x16x32_bf16 v[102:105], v[224:227], v[184:187], v[102:105]
	v_mfma_f32_16x16x32_bf16 v[98:101], v[224:227], v[192:195], v[98:101]
	s_barrier
	v_lshl_add_u64 v[248:249], v[136:137], 0, s[16:17]
	v_readfirstlane_b32 s13, v159
	v_lshl_add_u64 v[250:251], v[248:249], 0, s[74:75]
	s_mov_b32 m0, s13
	ds_read_b128 v[228:231], v175
	ds_read_b128 v[232:235], v175 offset:1024
	ds_read_b128 v[236:239], v175 offset:2048
	ds_read_b128 v[240:243], v175 offset:3072
	global_load_lds_dwordx4 v[250:251], off
	v_lshl_add_u64 v[250:251], v[134:135], 0, s[16:17]
	s_add_u32 m0, m0, 0x2000
	v_lshl_add_u64 v[252:253], v[250:251], 0, s[74:75]
	global_load_lds_dwordx4 v[252:253], off
	s_barrier
	s_waitcnt lgkmcnt(0)
	v_mfma_f32_16x16x32_bf16 v[94:97], v[196:199], v[228:231], v[94:97]
	v_mfma_f32_16x16x32_bf16 v[90:93], v[196:199], v[236:239], v[90:93]
	v_mfma_f32_16x16x32_bf16 v[86:89], v[204:207], v[228:231], v[86:89]
	v_mfma_f32_16x16x32_bf16 v[82:85], v[204:207], v[236:239], v[82:85]
	v_mfma_f32_16x16x32_bf16 v[78:81], v[212:215], v[228:231], v[78:81]
	v_mfma_f32_16x16x32_bf16 v[74:77], v[212:215], v[236:239], v[74:77]
	v_mfma_f32_16x16x32_bf16 v[70:73], v[220:223], v[228:231], v[70:73]
	v_mfma_f32_16x16x32_bf16 v[66:69], v[220:223], v[236:239], v[66:69]
	v_mfma_f32_16x16x32_bf16 v[94:97], v[200:203], v[232:235], v[94:97]
	v_mfma_f32_16x16x32_bf16 v[90:93], v[200:203], v[240:243], v[90:93]
	v_mfma_f32_16x16x32_bf16 v[86:89], v[208:211], v[232:235], v[86:89]
	v_mfma_f32_16x16x32_bf16 v[82:85], v[208:211], v[240:243], v[82:85]
	v_mfma_f32_16x16x32_bf16 v[78:81], v[216:219], v[232:235], v[78:81]
	v_mfma_f32_16x16x32_bf16 v[74:77], v[216:219], v[240:243], v[74:77]
	v_mfma_f32_16x16x32_bf16 v[70:73], v[224:227], v[232:235], v[70:73]
	v_mfma_f32_16x16x32_bf16 v[66:69], v[224:227], v[240:243], v[66:69]
	v_readfirstlane_b32 s13, v162
	v_lshl_add_u64 v[252:253], v[244:245], 0, s[74:75]
	s_mov_b32 m0, s13
	s_barrier
	ds_read_b128 v[196:199], v147 offset:16384
	ds_read_b128 v[200:203], v147 offset:17408
	ds_read_b128 v[204:207], v146 offset:16384
	ds_read_b128 v[208:211], v146 offset:17408
	ds_read_b128 v[212:215], v145 offset:16384
	ds_read_b128 v[216:219], v145 offset:17408
	ds_read_b128 v[220:223], v144 offset:16384
	ds_read_b128 v[224:227], v144 offset:17408
	global_load_lds_dwordx4 v[252:253], off
	s_add_u32 m0, m0, 0x2000
	v_lshl_add_u64 v[252:253], v[246:247], 0, s[74:75]
	global_load_lds_dwordx4 v[252:253], off
	s_barrier
	s_waitcnt lgkmcnt(0)
	v_mfma_f32_16x16x32_bf16 v[62:65], v[196:199], v[180:183], v[62:65]
	v_mfma_f32_16x16x32_bf16 v[58:61], v[196:199], v[188:191], v[58:61]
	v_mfma_f32_16x16x32_bf16 v[54:57], v[204:207], v[180:183], v[54:57]
	v_mfma_f32_16x16x32_bf16 v[50:53], v[204:207], v[188:191], v[50:53]
	v_mfma_f32_16x16x32_bf16 v[46:49], v[212:215], v[180:183], v[46:49]
	v_mfma_f32_16x16x32_bf16 v[42:45], v[212:215], v[188:191], v[42:45]
	v_mfma_f32_16x16x32_bf16 v[38:41], v[220:223], v[180:183], v[38:41]
	v_mfma_f32_16x16x32_bf16 v[34:37], v[220:223], v[188:191], v[34:37]
	v_mfma_f32_16x16x32_bf16 v[62:65], v[200:203], v[184:187], v[62:65]
	v_mfma_f32_16x16x32_bf16 v[58:61], v[200:203], v[192:195], v[58:61]
	v_mfma_f32_16x16x32_bf16 v[54:57], v[208:211], v[184:187], v[54:57]
	v_mfma_f32_16x16x32_bf16 v[50:53], v[208:211], v[192:195], v[50:53]
	v_mfma_f32_16x16x32_bf16 v[46:49], v[216:219], v[184:187], v[46:49]
	v_mfma_f32_16x16x32_bf16 v[42:45], v[216:219], v[192:195], v[42:45]
	v_mfma_f32_16x16x32_bf16 v[38:41], v[224:227], v[184:187], v[38:41]
	v_mfma_f32_16x16x32_bf16 v[34:37], v[224:227], v[192:195], v[34:37]
	s_barrier
; #define STA(P, br, kt) STAGE(P, A, aoff0, aoff1, lda, br, kt)
; #define STB(P, br, kt) STAGE(P, Bt, boff0, boff1, ldb, br, kt)
; #define LDA(dst, b, h) _Pragma("unroll") for (int m = 0; m < 4; ++m) _Pragma("unroll") for (int k = 0; k < 2; ++k) \
;     dst[m][k] = *reinterpret_cast<const bf16x8*>((char*)SA(b, h) + lds_byte(wr * 64 + m * 16 + fr, k * 32 + fq * 8))
; #define LDB(dst, b, h) _Pragma("unroll") for (int n = 0; n < 2; ++n) _Pragma("unroll") for (int k = 0; k < 2; ++k) \
;     dst[n][k] = *reinterpret_cast<const bf16x8*>((char*)SB(b, h) + lds_byte(wc * 32 + n * 16 + fr, k * 32 + fq * 8))
; #define MMA(ai, bj, At, Bq) do { __builtin_amdgcn_s_setprio(1); \
;     _Pragma("unroll") for (int m = 0; m < 4; ++m) _Pragma("unroll") for (int n = 0; n < 2; ++n) _Pragma("unroll") for (int k = 0; k < 2; ++k) \
;       acc[ai][bj][m][n] = __builtin_amdgcn_mfma_f32_16x16x32_bf16(At[m][k], Bq[n][k], acc[ai][bj][m][n], 0, 0, 0); \
;     __builtin_amdgcn_s_setprio(0); } while (0)
; #define WAIT_V(n) asm volatile("s_waitcnt vmcnt(" #n ")" ::: "memory")
; #define WAIT_L(n) asm volatile("s_waitcnt lgkmcnt(" #n ")" ::: "memory")
; #define BAR __builtin_amdgcn_s_barrier()
; #define SCHED __builtin_amdgcn_sched_barrier(0)
; __device__ __forceinline__ void gemm256(const u16* __restrict__ A, int lda, const u16* __restrict__ Bt, int ldb, int K,
;                                         f32x4 (&acc)[2][2][4][2], const int g_wid) {
;     ...
;     STB(SB(0, 1), HALF, t + 2);
;     WAIT_V(6); BAR; MMA(1, 1, At, B1); BAR;
;     LDB(B0, 1, 0); SCHED; LDA(At, 1, 0); STA(SA(0, 1), HALF, t + 2);
;     WAIT_L(8); BAR; WAIT_L(0); MMA(0, 0, At, B0); BAR; SCHED;
;     LDB(B1, 1, 1); STB(SB(1, 0), 0, t + 3);
;     BAR; WAIT_L(0); MMA(0, 1, At, B1); BAR;
;     LDA(At, 1, 1); STA(SA(1, 0), 0, t + 3);
	v_readfirstlane_b32 s13, v164
	v_lshl_add_u64 v[180:181], v[248:249], 0, s[78:79]
	s_mov_b32 m0, s13
	global_load_lds_dwordx4 v[180:181], off
	s_add_u32 m0, m0, 0x2000
	v_lshl_add_u64 v[180:181], v[250:251], 0, s[78:79]
	global_load_lds_dwordx4 v[180:181], off
	s_waitcnt vmcnt(6)
	s_barrier
	v_mfma_f32_16x16x32_bf16 v[30:33], v[196:199], v[228:231], v[30:33]
	v_mfma_f32_16x16x32_bf16 v[26:29], v[196:199], v[236:239], v[26:29]
	v_mfma_f32_16x16x32_bf16 v[22:25], v[204:207], v[228:231], v[22:25]
	v_mfma_f32_16x16x32_bf16 v[18:21], v[204:207], v[236:239], v[18:21]
	v_mfma_f32_16x16x32_bf16 v[14:17], v[212:215], v[228:231], v[14:17]
	v_mfma_f32_16x16x32_bf16 v[10:13], v[212:215], v[236:239], v[10:13]
	v_mfma_f32_16x16x32_bf16 v[6:9], v[220:223], v[228:231], v[6:9]
	v_mfma_f32_16x16x32_bf16 v[2:5], v[220:223], v[236:239], v[2:5]
	v_mfma_f32_16x16x32_bf16 v[30:33], v[200:203], v[232:235], v[30:33]
	v_mfma_f32_16x16x32_bf16 v[26:29], v[200:203], v[240:243], v[26:29]
	v_mfma_f32_16x16x32_bf16 v[22:25], v[208:211], v[232:235], v[22:25]
	v_mfma_f32_16x16x32_bf16 v[18:21], v[208:211], v[240:243], v[18:21]
	v_mfma_f32_16x16x32_bf16 v[14:17], v[216:219], v[232:235], v[14:17]
	v_mfma_f32_16x16x32_bf16 v[10:13], v[216:219], v[240:243], v[10:13]
	v_mfma_f32_16x16x32_bf16 v[6:9], v[224:227], v[232:235], v[6:9]
	v_mfma_f32_16x16x32_bf16 v[2:5], v[224:227], v[240:243], v[2:5]
	s_barrier
	ds_read_b128 v[180:183], v167
	ds_read_b128 v[184:187], v167 offset:1024
	ds_read_b128 v[188:191], v167 offset:2048
	ds_read_b128 v[192:195], v167 offset:3072
	v_readfirstlane_b32 s13, v166
	v_lshl_add_u64 v[228:229], v[244:245], 0, s[78:79]
	s_mov_b32 m0, s13
	ds_read_b128 v[196:199], v147 offset:32768
	ds_read_b128 v[200:203], v147 offset:33792
	ds_read_b128 v[204:207], v146 offset:32768
	ds_read_b128 v[208:211], v146 offset:33792
	ds_read_b128 v[212:215], v145 offset:32768
	ds_read_b128 v[216:219], v145 offset:33792
	ds_read_b128 v[220:223], v144 offset:32768
	ds_read_b128 v[224:227], v144 offset:33792
	global_load_lds_dwordx4 v[228:229], off
	s_add_u32 m0, m0, 0x2000
	v_lshl_add_u64 v[228:229], v[246:247], 0, s[78:79]
	global_load_lds_dwordx4 v[228:229], off
	s_waitcnt lgkmcnt(8)
	s_barrier
	s_waitcnt lgkmcnt(0)
	v_mfma_f32_16x16x32_bf16 v[126:129], v[196:199], v[180:183], v[126:129]
	v_mfma_f32_16x16x32_bf16 v[122:125], v[196:199], v[188:191], v[122:125]
	v_mfma_f32_16x16x32_bf16 v[118:121], v[204:207], v[180:183], v[118:121]
	v_mfma_f32_16x16x32_bf16 v[114:117], v[204:207], v[188:191], v[114:117]
	v_mfma_f32_16x16x32_bf16 v[110:113], v[212:215], v[180:183], v[110:113]
	v_mfma_f32_16x16x32_bf16 v[106:109], v[212:215], v[188:191], v[106:109]
	v_mfma_f32_16x16x32_bf16 v[102:105], v[220:223], v[180:183], v[102:105]
	v_mfma_f32_16x16x32_bf16 v[98:101], v[220:223], v[188:191], v[98:101]
	v_mfma_f32_16x16x32_bf16 v[126:129], v[200:203], v[184:187], v[126:129]
	v_mfma_f32_16x16x32_bf16 v[122:125], v[200:203], v[192:195], v[122:125]
	v_mfma_f32_16x16x32_bf16 v[118:121], v[208:211], v[184:187], v[118:121]
	v_mfma_f32_16x16x32_bf16 v[114:117], v[208:211], v[192:195], v[114:117]
	v_mfma_f32_16x16x32_bf16 v[110:113], v[216:219], v[184:187], v[110:113]
	v_mfma_f32_16x16x32_bf16 v[106:109], v[216:219], v[192:195], v[106:109]
	v_mfma_f32_16x16x32_bf16 v[102:105], v[224:227], v[184:187], v[102:105]
	v_mfma_f32_16x16x32_bf16 v[98:101], v[224:227], v[192:195], v[98:101]
	s_barrier
	v_readfirstlane_b32 s13, v169
	v_lshl_add_u64 v[252:253], v[248:249], 0, s[82:83]
	s_mov_b32 m0, s13
	ds_read_b128 v[228:231], v161
	ds_read_b128 v[232:235], v161 offset:1024
	ds_read_b128 v[236:239], v161 offset:2048
	ds_read_b128 v[240:243], v161 offset:3072
	global_load_lds_dwordx4 v[252:253], off
	s_add_u32 m0, m0, 0x2000
	v_lshl_add_u64 v[252:253], v[250:251], 0, s[82:83]
	global_load_lds_dwordx4 v[252:253], off
	s_barrier
	s_waitcnt lgkmcnt(0)
	v_mfma_f32_16x16x32_bf16 v[94:97], v[196:199], v[228:231], v[94:97]
	v_mfma_f32_16x16x32_bf16 v[90:93], v[196:199], v[236:239], v[90:93]
	v_mfma_f32_16x16x32_bf16 v[86:89], v[204:207], v[228:231], v[86:89]
	v_mfma_f32_16x16x32_bf16 v[82:85], v[204:207], v[236:239], v[82:85]
	v_mfma_f32_16x16x32_bf16 v[78:81], v[212:215], v[228:231], v[78:81]
	v_mfma_f32_16x16x32_bf16 v[74:77], v[212:215], v[236:239], v[74:77]
	v_mfma_f32_16x16x32_bf16 v[70:73], v[220:223], v[228:231], v[70:73]
	v_mfma_f32_16x16x32_bf16 v[66:69], v[220:223], v[236:239], v[66:69]
	v_mfma_f32_16x16x32_bf16 v[94:97], v[200:203], v[232:235], v[94:97]
	v_mfma_f32_16x16x32_bf16 v[90:93], v[200:203], v[240:243], v[90:93]
	v_mfma_f32_16x16x32_bf16 v[86:89], v[208:211], v[232:235], v[86:89]
	v_mfma_f32_16x16x32_bf16 v[82:85], v[208:211], v[240:243], v[82:85]
	v_mfma_f32_16x16x32_bf16 v[78:81], v[216:219], v[232:235], v[78:81]
	v_mfma_f32_16x16x32_bf16 v[74:77], v[216:219], v[240:243], v[74:77]
	v_mfma_f32_16x16x32_bf16 v[70:73], v[224:227], v[232:235], v[70:73]
	v_mfma_f32_16x16x32_bf16 v[66:69], v[224:227], v[240:243], v[66:69]
	v_readfirstlane_b32 s13, v171
	v_lshl_add_u64 v[244:245], v[244:245], 0, s[82:83]
	s_mov_b32 m0, s13
	s_barrier
	ds_read_b128 v[196:199], v147 offset:49152
	ds_read_b128 v[200:203], v147 offset:50176
	ds_read_b128 v[204:207], v146 offset:49152
	ds_read_b128 v[208:211], v146 offset:50176
	ds_read_b128 v[212:215], v145 offset:49152
	ds_read_b128 v[216:219], v145 offset:50176
	ds_read_b128 v[220:223], v144 offset:49152
	ds_read_b128 v[224:227], v144 offset:50176
	global_load_lds_dwordx4 v[244:245], off
	s_add_u32 m0, m0, 0x2000
	v_lshl_add_u64 v[244:245], v[246:247], 0, s[82:83]
	global_load_lds_dwordx4 v[244:245], off
	s_barrier
; #define STA(P, br, kt) STAGE(P, A, aoff0, aoff1, lda, br, kt)
; #define STB(P, br, kt) STAGE(P, Bt, boff0, boff1, ldb, br, kt)
; #define LDA(dst, b, h) _Pragma("unroll") for (int m = 0; m < 4; ++m) _Pragma("unroll") for (int k = 0; k < 2; ++k) \
;     dst[m][k] = *reinterpret_cast<const bf16x8*>((char*)SA(b, h) + lds_byte(wr * 64 + m * 16 + fr, k * 32 + fq * 8))
; #define LDB(dst, b, h) _Pragma("unroll") for (int n = 0; n < 2; ++n) _Pragma("unroll") for (int k = 0; k < 2; ++k) \
;     dst[n][k] = *reinterpret_cast<const bf16x8*>((char*)SB(b, h) + lds_byte(wc * 32 + n * 16 + fr, k * 32 + fq * 8))
; #define MMA(ai, bj, At, Bq) do { __builtin_amdgcn_s_setprio(1); \
;     _Pragma("unroll") for (int m = 0; m < 4; ++m) _Pragma("unroll") for (int n = 0; n < 2; ++n) _Pragma("unroll") for (int k = 0; k < 2; ++k) \
;       acc[ai][bj][m][n] = __builtin_amdgcn_mfma_f32_16x16x32_bf16(At[m][k], Bq[n][k], acc[ai][bj][m][n], 0, 0, 0); \
;     __builtin_amdgcn_s_setprio(0); } while (0)
; #define WAIT_V(n) asm volatile("s_waitcnt vmcnt(" #n ")" ::: "memory")
; #define WAIT_L(n) asm volatile("s_waitcnt lgkmcnt(" #n ")" ::: "memory")
; #define BAR __builtin_amdgcn_s_barrier()
; #define SCHED __builtin_amdgcn_sched_barrier(0)
; __device__ __forceinline__ void gemm256(const u16* __restrict__ A, int lda, const u16* __restrict__ Bt, int ldb, int K,
;                                         f32x4 (&acc)[2][2][4][2], const int g_wid) {
;     ...
;     BAR; WAIT_L(0); MMA(1, 0, At, B0); BAR; SCHED;
;     STB(SB(1, 1), HALF, t + 3);
;     WAIT_V(6); BAR; MMA(1, 1, At, B1); BAR;
;   }
;   { LDB(B0, 0, 0); LDA(At, 0, 0); STA(SA(1, 1), HALF, nt - 1);
;     BAR; WAIT_L(0); MMA(0, 0, At, B0); BAR;
;     LDB(B1, 0, 1); BAR; WAIT_L(0); MMA(0, 1, At, B1); BAR;
;     LDA(At, 0, 1); WAIT_V(4); BAR; WAIT_L(0); MMA(1, 0, At, B0); MMA(1, 1, At, B1); BAR; }
	s_waitcnt lgkmcnt(0)
	v_mfma_f32_16x16x32_bf16 v[62:65], v[196:199], v[180:183], v[62:65]
	v_mfma_f32_16x16x32_bf16 v[58:61], v[196:199], v[188:191], v[58:61]
	v_mfma_f32_16x16x32_bf16 v[54:57], v[204:207], v[180:183], v[54:57]
	v_mfma_f32_16x16x32_bf16 v[50:53], v[204:207], v[188:191], v[50:53]
	v_mfma_f32_16x16x32_bf16 v[46:49], v[212:215], v[180:183], v[46:49]
	v_mfma_f32_16x16x32_bf16 v[42:45], v[212:215], v[188:191], v[42:45]
	v_mfma_f32_16x16x32_bf16 v[38:41], v[220:223], v[180:183], v[38:41]
	v_mfma_f32_16x16x32_bf16 v[34:37], v[220:223], v[188:191], v[34:37]
	v_mfma_f32_16x16x32_bf16 v[62:65], v[200:203], v[184:187], v[62:65]
	v_mfma_f32_16x16x32_bf16 v[58:61], v[200:203], v[192:195], v[58:61]
	v_mfma_f32_16x16x32_bf16 v[54:57], v[208:211], v[184:187], v[54:57]
	v_mfma_f32_16x16x32_bf16 v[50:53], v[208:211], v[192:195], v[50:53]
	v_mfma_f32_16x16x32_bf16 v[46:49], v[216:219], v[184:187], v[46:49]
	v_mfma_f32_16x16x32_bf16 v[42:45], v[216:219], v[192:195], v[42:45]
	v_mfma_f32_16x16x32_bf16 v[38:41], v[224:227], v[184:187], v[38:41]
	v_mfma_f32_16x16x32_bf16 v[34:37], v[224:227], v[192:195], v[34:37]
	s_barrier
	v_readfirstlane_b32 s13, v173
	v_lshl_add_u64 v[180:181], v[248:249], 0, s[86:87]
	s_mov_b32 m0, s13
	global_load_lds_dwordx4 v[180:181], off
	s_add_u32 m0, m0, 0x2000
	v_lshl_add_u64 v[180:181], v[250:251], 0, s[86:87]
	global_load_lds_dwordx4 v[180:181], off
	s_waitcnt vmcnt(6)
	s_barrier
	v_mfma_f32_16x16x32_bf16 v[30:33], v[196:199], v[228:231], v[30:33]
	v_mfma_f32_16x16x32_bf16 v[26:29], v[196:199], v[236:239], v[26:29]
	v_mfma_f32_16x16x32_bf16 v[22:25], v[204:207], v[228:231], v[22:25]
	v_mfma_f32_16x16x32_bf16 v[18:21], v[204:207], v[236:239], v[18:21]
	v_mfma_f32_16x16x32_bf16 v[14:17], v[212:215], v[228:231], v[14:17]
	v_mfma_f32_16x16x32_bf16 v[10:13], v[212:215], v[236:239], v[10:13]
	v_mfma_f32_16x16x32_bf16 v[6:9], v[220:223], v[228:231], v[6:9]
	v_mfma_f32_16x16x32_bf16 v[2:5], v[220:223], v[236:239], v[2:5]
	v_mfma_f32_16x16x32_bf16 v[30:33], v[200:203], v[232:235], v[30:33]
	v_mfma_f32_16x16x32_bf16 v[26:29], v[200:203], v[240:243], v[26:29]
	v_mfma_f32_16x16x32_bf16 v[22:25], v[208:211], v[232:235], v[22:25]
	v_mfma_f32_16x16x32_bf16 v[18:21], v[208:211], v[240:243], v[18:21]
	v_mfma_f32_16x16x32_bf16 v[14:17], v[216:219], v[232:235], v[14:17]
	v_mfma_f32_16x16x32_bf16 v[10:13], v[216:219], v[240:243], v[10:13]
	v_mfma_f32_16x16x32_bf16 v[6:9], v[224:227], v[232:235], v[6:9]
	v_mfma_f32_16x16x32_bf16 v[2:5], v[224:227], v[240:243], v[2:5]
	s_add_i32 s9, s9, 2
	s_add_u32 s16, s16, 0x100
	s_addc_u32 s17, s17, 0
	s_cmp_lt_u32 s9, 12
	s_barrier
	s_cbranch_scc1 .LBB0_465
	s_add_u32 s14, s14, 0x40780
	s_addc_u32 s15, s15, 0
	v_readfirstlane_b32 s9, v177
	v_lshl_add_u64 v[132:133], v[132:133], 1, s[14:15]
	s_mov_b32 m0, s9
	v_readfirstlane_b32 s9, v178
	ds_read_b128 v[134:137], v176
	ds_read_b128 v[138:141], v176 offset:1024
	ds_read_b128 v[162:165], v176 offset:2048
	ds_read_b128 v[168:171], v176 offset:3072
	ds_read_b128 v[180:183], v147
	ds_read_b128 v[184:187], v147 offset:1024
	ds_read_b128 v[188:191], v146
	ds_read_b128 v[192:195], v146 offset:1024
	ds_read_b128 v[196:199], v145
	ds_read_b128 v[200:203], v145 offset:1024
	ds_read_b128 v[204:207], v144
	ds_read_b128 v[208:211], v144 offset:1024
	global_load_lds_dwordx4 v[132:133], off
	v_lshl_add_u64 v[130:131], v[130:131], 1, s[14:15]
	s_mov_b32 m0, s9
	s_nop 0
	global_load_lds_dwordx4 v[130:131], off
	s_barrier
	s_waitcnt lgkmcnt(0)
	v_mfma_f32_16x16x32_bf16 v[126:129], v[180:183], v[134:137], v[126:129]
	v_mfma_f32_16x16x32_bf16 v[118:121], v[188:191], v[134:137], v[118:121]
	v_mfma_f32_16x16x32_bf16 v[114:117], v[188:191], v[162:165], v[114:117]
	v_mfma_f32_16x16x32_bf16 v[102:105], v[204:207], v[134:137], v[102:105]
	v_mfma_f32_16x16x32_bf16 v[126:129], v[184:187], v[138:141], v[126:129]
	v_mfma_f32_16x16x32_bf16 v[122:125], v[180:183], v[162:165], v[122:125]
	v_mfma_f32_16x16x32_bf16 v[118:121], v[192:195], v[138:141], v[118:121]
	v_mfma_f32_16x16x32_bf16 v[114:117], v[192:195], v[168:171], v[114:117]
	v_mfma_f32_16x16x32_bf16 v[110:113], v[196:199], v[134:137], v[110:113]
	v_mfma_f32_16x16x32_bf16 v[106:109], v[196:199], v[162:165], v[106:109]
	v_mfma_f32_16x16x32_bf16 v[102:105], v[208:211], v[138:141], v[102:105]
	v_mfma_f32_16x16x32_bf16 v[98:101], v[204:207], v[162:165], v[98:101]
	v_mfma_f32_16x16x32_bf16 v[130:133], v[184:187], v[168:171], v[122:125]
	v_mfma_f32_16x16x32_bf16 v[176:179], v[200:203], v[138:141], v[110:113]
	v_mfma_f32_16x16x32_bf16 v[212:215], v[200:203], v[168:171], v[106:109]
	v_mfma_f32_16x16x32_bf16 v[216:219], v[208:211], v[168:171], v[98:101]
	s_barrier
	s_nop 1
	ds_read_b128 v[98:101], v175
	ds_read_b128 v[106:109], v175 offset:1024
	ds_read_b128 v[110:113], v175 offset:2048
	ds_read_b128 v[122:125], v175 offset:3072
	s_barrier
	s_waitcnt lgkmcnt(0)
	v_mfma_f32_16x16x32_bf16 v[94:97], v[180:183], v[98:101], v[94:97]
	v_mfma_f32_16x16x32_bf16 v[86:89], v[188:191], v[98:101], v[86:89]
	v_mfma_f32_16x16x32_bf16 v[82:85], v[188:191], v[110:113], v[82:85]
	v_mfma_f32_16x16x32_bf16 v[70:73], v[204:207], v[98:101], v[70:73]
	v_mfma_f32_16x16x32_bf16 v[94:97], v[184:187], v[106:109], v[94:97]
	v_mfma_f32_16x16x32_bf16 v[90:93], v[180:183], v[110:113], v[90:93]
	v_mfma_f32_16x16x32_bf16 v[86:89], v[192:195], v[106:109], v[86:89]
	v_mfma_f32_16x16x32_bf16 v[82:85], v[192:195], v[122:125], v[82:85]
	v_mfma_f32_16x16x32_bf16 v[78:81], v[196:199], v[98:101], v[78:81]
	v_mfma_f32_16x16x32_bf16 v[74:77], v[196:199], v[110:113], v[74:77]
	v_mfma_f32_16x16x32_bf16 v[70:73], v[208:211], v[106:109], v[70:73]
	v_mfma_f32_16x16x32_bf16 v[66:69], v[204:207], v[110:113], v[66:69]
	v_mfma_f32_16x16x32_bf16 v[172:175], v[184:187], v[122:125], v[90:93]
	v_mfma_f32_16x16x32_bf16 v[180:183], v[200:203], v[106:109], v[78:81]
	v_mfma_f32_16x16x32_bf16 v[184:187], v[200:203], v[122:125], v[74:77]
	v_mfma_f32_16x16x32_bf16 v[188:191], v[208:211], v[122:125], v[66:69]
	s_barrier
; #define LDA(dst, b, h) _Pragma("unroll") for (int m = 0; m < 4; ++m) _Pragma("unroll") for (int k = 0; k < 2; ++k) \
;     dst[m][k] = *reinterpret_cast<const bf16x8*>((char*)SA(b, h) + lds_byte(wr * 64 + m * 16 + fr, k * 32 + fq * 8))
; #define LDB(dst, b, h) _Pragma("unroll") for (int n = 0; n < 2; ++n) _Pragma("unroll") for (int k = 0; k < 2; ++k) \
;     dst[n][k] = *reinterpret_cast<const bf16x8*>((char*)SB(b, h) + lds_byte(wc * 32 + n * 16 + fr, k * 32 + fq * 8))
; #define MMA(ai, bj, At, Bq) do { __builtin_amdgcn_s_setprio(1); \
;     _Pragma("unroll") for (int m = 0; m < 4; ++m) _Pragma("unroll") for (int n = 0; n < 2; ++n) _Pragma("unroll") for (int k = 0; k < 2; ++k) \
;       acc[ai][bj][m][n] = __builtin_amdgcn_mfma_f32_16x16x32_bf16(At[m][k], Bq[n][k], acc[ai][bj][m][n], 0, 0, 0); \
;     __builtin_amdgcn_s_setprio(0); } while (0)
; #define WAIT_V(n) asm volatile("s_waitcnt vmcnt(" #n ")" ::: "memory")
; #define WAIT_L(n) asm volatile("s_waitcnt lgkmcnt(" #n ")" ::: "memory")
; #define BAR __builtin_amdgcn_s_barrier()
; __device__ __forceinline__ void gemm256(const u16* __restrict__ A, int lda, const u16* __restrict__ Bt, int ldb, int K,
;                                         f32x4 (&acc)[2][2][4][2], const int g_wid) {
;     ...
;     LDA(At, 0, 1); WAIT_V(4); BAR; WAIT_L(0); MMA(1, 0, At, B0); MMA(1, 1, At, B1); BAR; }
;   { LDB(B0, 1, 0); LDA(At, 1, 0); WAIT_V(2); BAR; WAIT_L(0); MMA(0, 0, At, B0); BAR;
	s_nop 1
	ds_read_b128 v[66:69], v147 offset:16384
	ds_read_b128 v[74:77], v147 offset:17408
	ds_read_b128 v[78:81], v146 offset:16384
	ds_read_b128 v[90:93], v146 offset:17408
	ds_read_b128 v[192:195], v145 offset:16384
	ds_read_b128 v[196:199], v145 offset:17408
	ds_read_b128 v[200:203], v144 offset:16384
	ds_read_b128 v[204:207], v144 offset:17408
	s_waitcnt vmcnt(4)
	s_barrier
	s_waitcnt lgkmcnt(0)
	v_mfma_f32_16x16x32_bf16 v[62:65], v[66:69], v[134:137], v[62:65]
	v_mfma_f32_16x16x32_bf16 v[54:57], v[78:81], v[134:137], v[54:57]
	v_mfma_f32_16x16x32_bf16 v[46:49], v[192:195], v[134:137], v[46:49]
	v_mfma_f32_16x16x32_bf16 v[38:41], v[200:203], v[134:137], v[38:41]
	v_mfma_f32_16x16x32_bf16 v[62:65], v[74:77], v[138:141], v[62:65]
	v_mfma_f32_16x16x32_bf16 v[58:61], v[66:69], v[162:165], v[58:61]
	v_mfma_f32_16x16x32_bf16 v[54:57], v[90:93], v[138:141], v[54:57]
	v_mfma_f32_16x16x32_bf16 v[50:53], v[78:81], v[162:165], v[50:53]
	v_mfma_f32_16x16x32_bf16 v[46:49], v[196:199], v[138:141], v[46:49]
	v_mfma_f32_16x16x32_bf16 v[42:45], v[192:195], v[162:165], v[42:45]
	v_mfma_f32_16x16x32_bf16 v[38:41], v[204:207], v[138:141], v[38:41]
	v_mfma_f32_16x16x32_bf16 v[34:37], v[200:203], v[162:165], v[34:37]
	v_mfma_f32_16x16x32_bf16 v[208:211], v[74:77], v[168:171], v[58:61]
	v_mfma_f32_16x16x32_bf16 v[220:223], v[90:93], v[168:171], v[50:53]
	v_mfma_f32_16x16x32_bf16 v[224:227], v[196:199], v[168:171], v[42:45]
	v_mfma_f32_16x16x32_bf16 v[134:137], v[204:207], v[168:171], v[34:37]
	v_mfma_f32_16x16x32_bf16 v[30:33], v[66:69], v[98:101], v[30:33]
	v_mfma_f32_16x16x32_bf16 v[22:25], v[78:81], v[98:101], v[22:25]
	v_mfma_f32_16x16x32_bf16 v[14:17], v[192:195], v[98:101], v[14:17]
	v_mfma_f32_16x16x32_bf16 v[6:9], v[200:203], v[98:101], v[6:9]
	v_mfma_f32_16x16x32_bf16 v[30:33], v[74:77], v[106:109], v[30:33]
	v_mfma_f32_16x16x32_bf16 v[26:29], v[66:69], v[110:113], v[26:29]
	v_mfma_f32_16x16x32_bf16 v[22:25], v[90:93], v[106:109], v[22:25]
	v_mfma_f32_16x16x32_bf16 v[18:21], v[78:81], v[110:113], v[18:21]
	v_mfma_f32_16x16x32_bf16 v[14:17], v[196:199], v[106:109], v[14:17]
	v_mfma_f32_16x16x32_bf16 v[10:13], v[192:195], v[110:113], v[10:13]
	v_mfma_f32_16x16x32_bf16 v[6:9], v[204:207], v[106:109], v[6:9]
	v_mfma_f32_16x16x32_bf16 v[2:5], v[200:203], v[110:113], v[2:5]
	v_mfma_f32_16x16x32_bf16 v[138:141], v[74:77], v[122:125], v[26:29]
	v_mfma_f32_16x16x32_bf16 v[162:165], v[90:93], v[122:125], v[18:21]
	v_mfma_f32_16x16x32_bf16 v[168:171], v[196:199], v[122:125], v[10:13]
	v_mfma_f32_16x16x32_bf16 v[192:195], v[204:207], v[122:125], v[2:5]
	s_barrier
	ds_read_b128 v[196:199], v167
	ds_read_b128 v[200:203], v167 offset:1024
	ds_read_b128 v[204:207], v167 offset:2048
	ds_read_b128 v[228:231], v167 offset:3072
	ds_read_b128 v[2:5], v147 offset:32768
	ds_read_b128 v[10:13], v147 offset:33792
	ds_read_b128 v[18:21], v146 offset:32768
	ds_read_b128 v[34:37], v146 offset:33792
	ds_read_b128 v[232:235], v145 offset:32768
	ds_read_b128 v[236:239], v145 offset:33792
	ds_read_b128 v[240:243], v144 offset:32768
	ds_read_b128 v[244:247], v144 offset:33792
	s_waitcnt vmcnt(2)
	s_barrier
	s_waitcnt lgkmcnt(0)
	v_mfma_f32_16x16x32_bf16 v[26:29], v[2:5], v[196:199], v[126:129]
	v_mfma_f32_16x16x32_bf16 v[122:125], v[10:13], v[200:203], v[26:29]
	v_mfma_f32_16x16x32_bf16 v[26:29], v[2:5], v[204:207], v[130:133]
	v_mfma_f32_16x16x32_bf16 v[90:93], v[10:13], v[228:231], v[26:29]
	v_mfma_f32_16x16x32_bf16 v[26:29], v[18:21], v[196:199], v[118:121]
	v_mfma_f32_16x16x32_bf16 v[110:113], v[34:37], v[200:203], v[26:29]
	v_mfma_f32_16x16x32_bf16 v[26:29], v[18:21], v[204:207], v[114:117]
	v_mfma_f32_16x16x32_bf16 v[78:81], v[34:37], v[228:231], v[26:29]
	v_mfma_f32_16x16x32_bf16 v[26:29], v[232:235], v[196:199], v[176:179]
	v_mfma_f32_16x16x32_bf16 v[106:109], v[236:239], v[200:203], v[26:29]
	v_mfma_f32_16x16x32_bf16 v[26:29], v[232:235], v[204:207], v[212:215]
	v_mfma_f32_16x16x32_bf16 v[74:77], v[236:239], v[228:231], v[26:29]
	v_mfma_f32_16x16x32_bf16 v[26:29], v[240:243], v[196:199], v[102:105]
	v_mfma_f32_16x16x32_bf16 v[98:101], v[244:247], v[200:203], v[26:29]
	v_mfma_f32_16x16x32_bf16 v[26:29], v[240:243], v[204:207], v[216:219]
	v_mfma_f32_16x16x32_bf16 v[66:69], v[244:247], v[228:231], v[26:29]
	s_barrier
; #define LDA(dst, b, h) _Pragma("unroll") for (int m = 0; m < 4; ++m) _Pragma("unroll") for (int k = 0; k < 2; ++k) \
;     dst[m][k] = *reinterpret_cast<const bf16x8*>((char*)SA(b, h) + lds_byte(wr * 64 + m * 16 + fr, k * 32 + fq * 8))
; #define LDB(dst, b, h) _Pragma("unroll") for (int n = 0; n < 2; ++n) _Pragma("unroll") for (int k = 0; k < 2; ++k) \
;     dst[n][k] = *reinterpret_cast<const bf16x8*>((char*)SB(b, h) + lds_byte(wc * 32 + n * 16 + fr, k * 32 + fq * 8))
; #define MMA(ai, bj, At, Bq) do { __builtin_amdgcn_s_setprio(1); \
;     _Pragma("unroll") for (int m = 0; m < 4; ++m) _Pragma("unroll") for (int n = 0; n < 2; ++n) _Pragma("unroll") for (int k = 0; k < 2; ++k) \
;       acc[ai][bj][m][n] = __builtin_amdgcn_mfma_f32_16x16x32_bf16(At[m][k], Bq[n][k], acc[ai][bj][m][n], 0, 0, 0); \
;     __builtin_amdgcn_s_setprio(0); } while (0)
; #define WAIT_V(n) asm volatile("s_waitcnt vmcnt(" #n ")" ::: "memory")
; #define WAIT_L(n) asm volatile("s_waitcnt lgkmcnt(" #n ")" ::: "memory")
; #define BAR __builtin_amdgcn_s_barrier()
; __device__ __forceinline__ void gemm256(const u16* __restrict__ A, int lda, const u16* __restrict__ Bt, int ldb, int K,
;                                         f32x4 (&acc)[2][2][4][2], const int g_wid) {
;     ...
;     LDB(B1, 1, 1); WAIT_V(0); BAR; WAIT_L(0); MMA(0, 1, At, B1); BAR;
;     LDA(At, 1, 1); BAR; WAIT_L(0); MMA(1, 0, At, B0); MMA(1, 1, At, B1); BAR; }
;   if (wr == 0) BAR;
	ds_read_b128 v[130:133], v161
	ds_read_b128 v[176:179], v161 offset:1024
	ds_read_b128 v[212:215], v161 offset:2048
	ds_read_b128 v[216:219], v161 offset:3072
	s_waitcnt vmcnt(0)
	s_barrier
	s_waitcnt lgkmcnt(0)
	v_mfma_f32_16x16x32_bf16 v[26:29], v[2:5], v[130:133], v[94:97]
	v_mfma_f32_16x16x32_bf16 v[2:5], v[2:5], v[212:215], v[172:175]
	v_mfma_f32_16x16x32_bf16 v[58:61], v[10:13], v[176:179], v[26:29]
	v_mfma_f32_16x16x32_bf16 v[26:29], v[10:13], v[216:219], v[2:5]
	v_mfma_f32_16x16x32_bf16 v[2:5], v[18:21], v[130:133], v[86:89]
	v_mfma_f32_16x16x32_bf16 v[50:53], v[34:37], v[176:179], v[2:5]
	v_mfma_f32_16x16x32_bf16 v[2:5], v[18:21], v[212:215], v[82:85]
	v_mfma_f32_16x16x32_bf16 v[18:21], v[34:37], v[216:219], v[2:5]
	v_mfma_f32_16x16x32_bf16 v[2:5], v[232:235], v[130:133], v[180:183]
	v_mfma_f32_16x16x32_bf16 v[42:45], v[236:239], v[176:179], v[2:5]
	v_mfma_f32_16x16x32_bf16 v[2:5], v[232:235], v[212:215], v[184:187]
	v_mfma_f32_16x16x32_bf16 v[10:13], v[236:239], v[216:219], v[2:5]
	v_mfma_f32_16x16x32_bf16 v[2:5], v[240:243], v[130:133], v[70:73]
	v_mfma_f32_16x16x32_bf16 v[34:37], v[244:247], v[176:179], v[2:5]
	v_mfma_f32_16x16x32_bf16 v[2:5], v[240:243], v[212:215], v[188:191]
	v_mfma_f32_16x16x32_bf16 v[2:5], v[244:247], v[216:219], v[2:5]
	s_barrier
	ds_read_b128 v[172:175], v147 offset:49152
	ds_read_b128 v[180:183], v147 offset:50176
	ds_read_b128 v[184:187], v146 offset:49152
	ds_read_b128 v[188:191], v146 offset:50176
	ds_read_b128 v[232:235], v145 offset:49152
	ds_read_b128 v[236:239], v145 offset:50176
	ds_read_b128 v[240:243], v144 offset:49152
	ds_read_b128 v[144:147], v144 offset:50176
	s_barrier
	s_waitcnt lgkmcnt(0)
	v_mfma_f32_16x16x32_bf16 v[62:65], v[172:175], v[196:199], v[62:65]
	v_mfma_f32_16x16x32_bf16 v[54:57], v[184:187], v[196:199], v[54:57]
	v_mfma_f32_16x16x32_bf16 v[46:49], v[232:235], v[196:199], v[46:49]
	v_mfma_f32_16x16x32_bf16 v[38:41], v[240:243], v[196:199], v[38:41]
	v_mfma_f32_16x16x32_bf16 v[126:129], v[180:183], v[200:203], v[62:65]
	v_mfma_f32_16x16x32_bf16 v[62:65], v[172:175], v[204:207], v[208:211]
	v_mfma_f32_16x16x32_bf16 v[118:121], v[188:191], v[200:203], v[54:57]
	v_mfma_f32_16x16x32_bf16 v[54:57], v[184:187], v[204:207], v[220:223]
	v_mfma_f32_16x16x32_bf16 v[114:117], v[236:239], v[200:203], v[46:49]
	v_mfma_f32_16x16x32_bf16 v[46:49], v[232:235], v[204:207], v[224:227]
	v_mfma_f32_16x16x32_bf16 v[102:105], v[144:147], v[200:203], v[38:41]
	v_mfma_f32_16x16x32_bf16 v[38:41], v[240:243], v[204:207], v[134:137]
	v_mfma_f32_16x16x32_bf16 v[94:97], v[180:183], v[228:231], v[62:65]
	v_mfma_f32_16x16x32_bf16 v[86:89], v[188:191], v[228:231], v[54:57]
	v_mfma_f32_16x16x32_bf16 v[82:85], v[236:239], v[228:231], v[46:49]
	v_mfma_f32_16x16x32_bf16 v[70:73], v[144:147], v[228:231], v[38:41]
	v_mfma_f32_16x16x32_bf16 v[30:33], v[172:175], v[130:133], v[30:33]
	v_mfma_f32_16x16x32_bf16 v[22:25], v[184:187], v[130:133], v[22:25]
	v_mfma_f32_16x16x32_bf16 v[14:17], v[232:235], v[130:133], v[14:17]
	v_mfma_f32_16x16x32_bf16 v[6:9], v[240:243], v[130:133], v[6:9]
	v_mfma_f32_16x16x32_bf16 v[62:65], v[180:183], v[176:179], v[30:33]
	v_mfma_f32_16x16x32_bf16 v[30:33], v[172:175], v[212:215], v[138:141]
	v_mfma_f32_16x16x32_bf16 v[54:57], v[188:191], v[176:179], v[22:25]
	v_mfma_f32_16x16x32_bf16 v[22:25], v[184:187], v[212:215], v[162:165]
	v_mfma_f32_16x16x32_bf16 v[46:49], v[236:239], v[176:179], v[14:17]
	v_mfma_f32_16x16x32_bf16 v[14:17], v[232:235], v[212:215], v[168:171]
	v_mfma_f32_16x16x32_bf16 v[38:41], v[144:147], v[176:179], v[6:9]
	v_mfma_f32_16x16x32_bf16 v[6:9], v[240:243], v[212:215], v[192:195]
	v_mfma_f32_16x16x32_bf16 v[30:33], v[180:183], v[216:219], v[30:33]
	v_mfma_f32_16x16x32_bf16 v[22:25], v[188:191], v[216:219], v[22:25]
	v_mfma_f32_16x16x32_bf16 v[14:17], v[236:239], v[216:219], v[14:17]
	v_mfma_f32_16x16x32_bf16 v[6:9], v[144:147], v[216:219], v[6:9]
	s_setprio 0
	s_movk_i32 s9, 0x100
	v_cmp_gt_u32_e32 vcc, s9, v0
	s_barrier
	s_and_saveexec_b64 s[14:15], vcc
	s_cbranch_execz .LBB0_455
	s_barrier
	s_branch .LBB0_455

; #define STA(P, br, kt) STAGE(P, A, aoff0, aoff1, lda, br, kt)
; #define STB(P, br, kt) STAGE(P, Bt, boff0, boff1, ldb, br, kt)
; #define LDA(dst, b, h) _Pragma("unroll") for (int m = 0; m < 4; ++m) _Pragma("unroll") for (int k = 0; k < 2; ++k) \
;     dst[m][k] = *reinterpret_cast<const bf16x8*>((char*)SA(b, h) + lds_byte(wr * 64 + m * 16 + fr, k * 32 + fq * 8))
; #define LDB(dst, b, h) _Pragma("unroll") for (int n = 0; n < 2; ++n) _Pragma("unroll") for (int k = 0; k < 2; ++k) \
;     dst[n][k] = *reinterpret_cast<const bf16x8*>((char*)SB(b, h) + lds_byte(wc * 32 + n * 16 + fr, k * 32 + fq * 8))
; #define MMA(ai, bj, At, Bq) do { __builtin_amdgcn_s_setprio(1); \
;     _Pragma("unroll") for (int m = 0; m < 4; ++m) _Pragma("unroll") for (int n = 0; n < 2; ++n) _Pragma("unroll") for (int k = 0; k < 2; ++k) \
;       acc[ai][bj][m][n] = __builtin_amdgcn_mfma_f32_16x16x32_bf16(At[m][k], Bq[n][k], acc[ai][bj][m][n], 0, 0, 0); \
;     __builtin_amdgcn_s_setprio(0); } while (0)
; #define WAIT_V(n) asm volatile("s_waitcnt vmcnt(" #n ")" ::: "memory")
; #define WAIT_L(n) asm volatile("s_waitcnt lgkmcnt(" #n ")" ::: "memory")
; #define BAR __builtin_amdgcn_s_barrier()
; #define SCHED __builtin_amdgcn_sched_barrier(0)
; __device__ __forceinline__ void gemm256(const u16* __restrict__ A, int lda, const u16* __restrict__ Bt, int ldb, int K,
;                                         f32x4 (&acc)[2][2][4][2], const int g_wid) {
;     ...
;   for (int t = 0; t < nt - 2; t += 2) {
;     LDB(B0, 0, 0); SCHED; LDA(At, 0, 0); STA(SA(1, 1), HALF, t + 1);
;     WAIT_L(8); BAR; WAIT_L(0); MMA(0, 0, At, B0); BAR; SCHED;
;     LDB(B1, 0, 1); STB(SB(0, 0), 0, t + 2);
;     BAR; WAIT_L(0); MMA(0, 1, At, B1); BAR;
;     LDA(At, 0, 1); STA(SA(0, 0), 0, t + 2);
;     BAR; WAIT_L(0); MMA(1, 0, At, B0); BAR; SCHED;
;     STB(SB(0, 1), HALF, t + 2);
;     WAIT_V(6); BAR; MMA(1, 1, At, B1); BAR;
.LBB0_488:
	ds_read_b128 v[178:181], v174
	ds_read_b128 v[182:185], v174 offset:1024
	ds_read_b128 v[186:189], v174 offset:2048
	ds_read_b128 v[190:193], v174 offset:3072
	v_add_u32_e32 v175, 0xc000, v159
	v_lshl_add_u64 v[242:243], v[138:139], 0, s[12:13]
	v_readfirstlane_b32 s9, v175
	v_lshl_add_u64 v[176:177], v[242:243], 0, s[44:45]
	s_mov_b32 m0, s9
	ds_read_b128 v[194:197], v145
	ds_read_b128 v[198:201], v145 offset:1024
	ds_read_b128 v[202:205], v144
	ds_read_b128 v[206:209], v144 offset:1024
	ds_read_b128 v[210:213], v143
	ds_read_b128 v[214:217], v143 offset:1024
	ds_read_b128 v[218:221], v142
	ds_read_b128 v[222:225], v142 offset:1024
	global_load_lds_dwordx4 v[176:177], off
	v_add_u32_e32 v176, 0xe000, v159
	v_lshl_add_u64 v[244:245], v[140:141], 0, s[12:13]
	s_add_u32 m0, m0, 0x2000
	v_lshl_add_u64 v[226:227], v[244:245], 0, s[44:45]
	global_load_lds_dwordx4 v[226:227], off
	s_waitcnt lgkmcnt(8)
	s_barrier
	s_waitcnt lgkmcnt(0)
	v_mfma_f32_16x16x32_bf16 v[126:129], v[194:197], v[178:181], v[126:129]
	v_mfma_f32_16x16x32_bf16 v[122:125], v[194:197], v[186:189], v[122:125]
	v_mfma_f32_16x16x32_bf16 v[118:121], v[202:205], v[178:181], v[118:121]
	v_mfma_f32_16x16x32_bf16 v[114:117], v[202:205], v[186:189], v[114:117]
	v_mfma_f32_16x16x32_bf16 v[110:113], v[210:213], v[178:181], v[110:113]
	v_mfma_f32_16x16x32_bf16 v[106:109], v[210:213], v[186:189], v[106:109]
	v_mfma_f32_16x16x32_bf16 v[102:105], v[218:221], v[178:181], v[102:105]
	v_mfma_f32_16x16x32_bf16 v[98:101], v[218:221], v[186:189], v[98:101]
	v_mfma_f32_16x16x32_bf16 v[126:129], v[198:201], v[182:185], v[126:129]
	v_mfma_f32_16x16x32_bf16 v[122:125], v[198:201], v[190:193], v[122:125]
	v_mfma_f32_16x16x32_bf16 v[118:121], v[206:209], v[182:185], v[118:121]
	v_mfma_f32_16x16x32_bf16 v[114:117], v[206:209], v[190:193], v[114:117]
	v_mfma_f32_16x16x32_bf16 v[110:113], v[214:217], v[182:185], v[110:113]
	v_mfma_f32_16x16x32_bf16 v[106:109], v[214:217], v[190:193], v[106:109]
	v_mfma_f32_16x16x32_bf16 v[102:105], v[222:225], v[182:185], v[102:105]
	v_mfma_f32_16x16x32_bf16 v[98:101], v[222:225], v[190:193], v[98:101]
	s_barrier
	v_lshl_add_u64 v[246:247], v[134:135], 0, s[12:13]
	v_readfirstlane_b32 s9, v146
	v_lshl_add_u64 v[248:249], v[246:247], 0, s[64:65]
	s_mov_b32 m0, s9
	ds_read_b128 v[226:229], v173
	ds_read_b128 v[230:233], v173 offset:1024
	ds_read_b128 v[234:237], v173 offset:2048
	ds_read_b128 v[238:241], v173 offset:3072
	global_load_lds_dwordx4 v[248:249], off
	v_lshl_add_u64 v[248:249], v[136:137], 0, s[12:13]
	s_add_u32 m0, m0, 0x2000
	v_lshl_add_u64 v[250:251], v[248:249], 0, s[64:65]
	global_load_lds_dwordx4 v[250:251], off
	s_barrier
	s_waitcnt lgkmcnt(0)
	v_mfma_f32_16x16x32_bf16 v[94:97], v[194:197], v[226:229], v[94:97]
	v_mfma_f32_16x16x32_bf16 v[90:93], v[194:197], v[234:237], v[90:93]
	v_mfma_f32_16x16x32_bf16 v[86:89], v[202:205], v[226:229], v[86:89]
	v_mfma_f32_16x16x32_bf16 v[82:85], v[202:205], v[234:237], v[82:85]
	v_mfma_f32_16x16x32_bf16 v[78:81], v[210:213], v[226:229], v[78:81]
	v_mfma_f32_16x16x32_bf16 v[74:77], v[210:213], v[234:237], v[74:77]
	v_mfma_f32_16x16x32_bf16 v[70:73], v[218:221], v[226:229], v[70:73]
	v_mfma_f32_16x16x32_bf16 v[66:69], v[218:221], v[234:237], v[66:69]
	v_mfma_f32_16x16x32_bf16 v[94:97], v[198:201], v[230:233], v[94:97]
	v_mfma_f32_16x16x32_bf16 v[90:93], v[198:201], v[238:241], v[90:93]
	v_mfma_f32_16x16x32_bf16 v[86:89], v[206:209], v[230:233], v[86:89]
	v_mfma_f32_16x16x32_bf16 v[82:85], v[206:209], v[238:241], v[82:85]
	v_mfma_f32_16x16x32_bf16 v[78:81], v[214:217], v[230:233], v[78:81]
	v_mfma_f32_16x16x32_bf16 v[74:77], v[214:217], v[238:241], v[74:77]
	v_mfma_f32_16x16x32_bf16 v[70:73], v[222:225], v[230:233], v[70:73]
	v_mfma_f32_16x16x32_bf16 v[66:69], v[222:225], v[238:241], v[66:69]
	v_readfirstlane_b32 s9, v159
	v_lshl_add_u64 v[250:251], v[242:243], 0, s[70:71]
	s_mov_b32 m0, s9
	s_barrier
	ds_read_b128 v[194:197], v145 offset:16384
	ds_read_b128 v[198:201], v145 offset:17408
	ds_read_b128 v[202:205], v144 offset:16384
	ds_read_b128 v[206:209], v144 offset:17408
	ds_read_b128 v[210:213], v143 offset:16384
	ds_read_b128 v[214:217], v143 offset:17408
	ds_read_b128 v[218:221], v142 offset:16384
	ds_read_b128 v[222:225], v142 offset:17408
	global_load_lds_dwordx4 v[250:251], off
	s_add_u32 m0, m0, 0x2000
	v_lshl_add_u64 v[250:251], v[244:245], 0, s[70:71]
	global_load_lds_dwordx4 v[250:251], off
	s_barrier
	s_waitcnt lgkmcnt(0)
	v_mfma_f32_16x16x32_bf16 v[62:65], v[194:197], v[178:181], v[62:65]
	v_mfma_f32_16x16x32_bf16 v[58:61], v[194:197], v[186:189], v[58:61]
	v_mfma_f32_16x16x32_bf16 v[54:57], v[202:205], v[178:181], v[54:57]
	v_mfma_f32_16x16x32_bf16 v[50:53], v[202:205], v[186:189], v[50:53]
	v_mfma_f32_16x16x32_bf16 v[46:49], v[210:213], v[178:181], v[46:49]
	v_mfma_f32_16x16x32_bf16 v[42:45], v[210:213], v[186:189], v[42:45]
	v_mfma_f32_16x16x32_bf16 v[38:41], v[218:221], v[178:181], v[38:41]
	v_mfma_f32_16x16x32_bf16 v[34:37], v[218:221], v[186:189], v[34:37]
	v_mfma_f32_16x16x32_bf16 v[62:65], v[198:201], v[182:185], v[62:65]
	v_mfma_f32_16x16x32_bf16 v[58:61], v[198:201], v[190:193], v[58:61]
	v_mfma_f32_16x16x32_bf16 v[54:57], v[206:209], v[182:185], v[54:57]
	v_mfma_f32_16x16x32_bf16 v[50:53], v[206:209], v[190:193], v[50:53]
	v_mfma_f32_16x16x32_bf16 v[46:49], v[214:217], v[182:185], v[46:49]
	v_mfma_f32_16x16x32_bf16 v[42:45], v[214:217], v[190:193], v[42:45]
	v_mfma_f32_16x16x32_bf16 v[38:41], v[222:225], v[182:185], v[38:41]
	v_mfma_f32_16x16x32_bf16 v[34:37], v[222:225], v[190:193], v[34:37]
	s_barrier
; #define STA(P, br, kt) STAGE(P, A, aoff0, aoff1, lda, br, kt)
; #define STB(P, br, kt) STAGE(P, Bt, boff0, boff1, ldb, br, kt)
; #define LDA(dst, b, h) _Pragma("unroll") for (int m = 0; m < 4; ++m) _Pragma("unroll") for (int k = 0; k < 2; ++k) \
;     dst[m][k] = *reinterpret_cast<const bf16x8*>((char*)SA(b, h) + lds_byte(wr * 64 + m * 16 + fr, k * 32 + fq * 8))
; #define LDB(dst, b, h) _Pragma("unroll") for (int n = 0; n < 2; ++n) _Pragma("unroll") for (int k = 0; k < 2; ++k) \
;     dst[n][k] = *reinterpret_cast<const bf16x8*>((char*)SB(b, h) + lds_byte(wc * 32 + n * 16 + fr, k * 32 + fq * 8))
; #define MMA(ai, bj, At, Bq) do { __builtin_amdgcn_s_setprio(1); \
;     _Pragma("unroll") for (int m = 0; m < 4; ++m) _Pragma("unroll") for (int n = 0; n < 2; ++n) _Pragma("unroll") for (int k = 0; k < 2; ++k) \
;       acc[ai][bj][m][n] = __builtin_amdgcn_mfma_f32_16x16x32_bf16(At[m][k], Bq[n][k], acc[ai][bj][m][n], 0, 0, 0); \
;     __builtin_amdgcn_s_setprio(0); } while (0)
; #define WAIT_L(n) asm volatile("s_waitcnt lgkmcnt(" #n ")" ::: "memory")
; #define BAR __builtin_amdgcn_s_barrier()
; #define SCHED __builtin_amdgcn_sched_barrier(0)
; __device__ __forceinline__ void gemm256(const u16* __restrict__ A, int lda, const u16* __restrict__ Bt, int ldb, int K,
;                                         f32x4 (&acc)[2][2][4][2], const int g_wid) {
;     ...
;     LDB(B0, 1, 0); SCHED; LDA(At, 1, 0); STA(SA(0, 1), HALF, t + 2);
;     WAIT_L(8); BAR; WAIT_L(0); MMA(0, 0, At, B0); BAR; SCHED;
;     LDB(B1, 1, 1); STB(SB(1, 0), 0, t + 3);
;     BAR; WAIT_L(0); MMA(0, 1, At, B1); BAR;
;     LDA(At, 1, 1); STA(SA(1, 0), 0, t + 3);
	v_readfirstlane_b32 s9, v162
	v_lshl_add_u64 v[178:179], v[246:247], 0, s[0:1]
	s_mov_b32 m0, s9
	global_load_lds_dwordx4 v[178:179], off
	s_add_u32 m0, m0, 0x2000
	v_lshl_add_u64 v[178:179], v[248:249], 0, s[0:1]
	global_load_lds_dwordx4 v[178:179], off
	s_waitcnt vmcnt(6)
	s_barrier
	v_mfma_f32_16x16x32_bf16 v[30:33], v[194:197], v[226:229], v[30:33]
	v_mfma_f32_16x16x32_bf16 v[26:29], v[194:197], v[234:237], v[26:29]
	v_mfma_f32_16x16x32_bf16 v[22:25], v[202:205], v[226:229], v[22:25]
	v_mfma_f32_16x16x32_bf16 v[18:21], v[202:205], v[234:237], v[18:21]
	v_mfma_f32_16x16x32_bf16 v[14:17], v[210:213], v[226:229], v[14:17]
	v_mfma_f32_16x16x32_bf16 v[10:13], v[210:213], v[234:237], v[10:13]
	v_mfma_f32_16x16x32_bf16 v[6:9], v[218:221], v[226:229], v[6:9]
	v_mfma_f32_16x16x32_bf16 v[2:5], v[218:221], v[234:237], v[2:5]
	v_mfma_f32_16x16x32_bf16 v[30:33], v[198:201], v[230:233], v[30:33]
	v_mfma_f32_16x16x32_bf16 v[26:29], v[198:201], v[238:241], v[26:29]
	v_mfma_f32_16x16x32_bf16 v[22:25], v[206:209], v[230:233], v[22:25]
	v_mfma_f32_16x16x32_bf16 v[18:21], v[206:209], v[238:241], v[18:21]
	v_mfma_f32_16x16x32_bf16 v[14:17], v[214:217], v[230:233], v[14:17]
	v_mfma_f32_16x16x32_bf16 v[10:13], v[214:217], v[238:241], v[10:13]
	v_mfma_f32_16x16x32_bf16 v[6:9], v[222:225], v[230:233], v[6:9]
	v_mfma_f32_16x16x32_bf16 v[2:5], v[222:225], v[238:241], v[2:5]
	s_barrier
	ds_read_b128 v[178:181], v166
	ds_read_b128 v[182:185], v166 offset:1024
	ds_read_b128 v[186:189], v166 offset:2048
	ds_read_b128 v[190:193], v166 offset:3072
	v_readfirstlane_b32 s9, v164
	v_lshl_add_u64 v[226:227], v[242:243], 0, s[52:53]
	s_mov_b32 m0, s9
	ds_read_b128 v[194:197], v145 offset:32768
	ds_read_b128 v[198:201], v145 offset:33792
	ds_read_b128 v[202:205], v144 offset:32768
	ds_read_b128 v[206:209], v144 offset:33792
	ds_read_b128 v[210:213], v143 offset:32768
	ds_read_b128 v[214:217], v143 offset:33792
	ds_read_b128 v[218:221], v142 offset:32768
	ds_read_b128 v[222:225], v142 offset:33792
	global_load_lds_dwordx4 v[226:227], off
	s_add_u32 m0, m0, 0x2000
	v_lshl_add_u64 v[226:227], v[244:245], 0, s[52:53]
	global_load_lds_dwordx4 v[226:227], off
	s_waitcnt lgkmcnt(8)
	s_barrier
	s_waitcnt lgkmcnt(0)
	v_mfma_f32_16x16x32_bf16 v[126:129], v[194:197], v[178:181], v[126:129]
	v_mfma_f32_16x16x32_bf16 v[122:125], v[194:197], v[186:189], v[122:125]
	v_mfma_f32_16x16x32_bf16 v[118:121], v[202:205], v[178:181], v[118:121]
	v_mfma_f32_16x16x32_bf16 v[114:117], v[202:205], v[186:189], v[114:117]
	v_mfma_f32_16x16x32_bf16 v[110:113], v[210:213], v[178:181], v[110:113]
	v_mfma_f32_16x16x32_bf16 v[106:109], v[210:213], v[186:189], v[106:109]
	v_mfma_f32_16x16x32_bf16 v[102:105], v[218:221], v[178:181], v[102:105]
	v_mfma_f32_16x16x32_bf16 v[98:101], v[218:221], v[186:189], v[98:101]
	v_mfma_f32_16x16x32_bf16 v[126:129], v[198:201], v[182:185], v[126:129]
	v_mfma_f32_16x16x32_bf16 v[122:125], v[198:201], v[190:193], v[122:125]
	v_mfma_f32_16x16x32_bf16 v[118:121], v[206:209], v[182:185], v[118:121]
	v_mfma_f32_16x16x32_bf16 v[114:117], v[206:209], v[190:193], v[114:117]
	v_mfma_f32_16x16x32_bf16 v[110:113], v[214:217], v[182:185], v[110:113]
	v_mfma_f32_16x16x32_bf16 v[106:109], v[214:217], v[190:193], v[106:109]
	v_mfma_f32_16x16x32_bf16 v[102:105], v[222:225], v[182:185], v[102:105]
	v_mfma_f32_16x16x32_bf16 v[98:101], v[222:225], v[190:193], v[98:101]
	s_barrier
	v_readfirstlane_b32 s9, v167
	v_lshl_add_u64 v[250:251], v[246:247], 0, s[58:59]
	s_mov_b32 m0, s9
	ds_read_b128 v[226:229], v160
	ds_read_b128 v[230:233], v160 offset:1024
	ds_read_b128 v[234:237], v160 offset:2048
	ds_read_b128 v[238:241], v160 offset:3072
	global_load_lds_dwordx4 v[250:251], off
	s_add_u32 m0, m0, 0x2000
	v_lshl_add_u64 v[250:251], v[248:249], 0, s[58:59]
	global_load_lds_dwordx4 v[250:251], off
	s_barrier
	s_waitcnt lgkmcnt(0)
	v_mfma_f32_16x16x32_bf16 v[94:97], v[194:197], v[226:229], v[94:97]
	v_mfma_f32_16x16x32_bf16 v[90:93], v[194:197], v[234:237], v[90:93]
	v_mfma_f32_16x16x32_bf16 v[86:89], v[202:205], v[226:229], v[86:89]
	v_mfma_f32_16x16x32_bf16 v[82:85], v[202:205], v[234:237], v[82:85]
	v_mfma_f32_16x16x32_bf16 v[78:81], v[210:213], v[226:229], v[78:81]
	v_mfma_f32_16x16x32_bf16 v[74:77], v[210:213], v[234:237], v[74:77]
	v_mfma_f32_16x16x32_bf16 v[70:73], v[218:221], v[226:229], v[70:73]
	v_mfma_f32_16x16x32_bf16 v[66:69], v[218:221], v[234:237], v[66:69]
	v_mfma_f32_16x16x32_bf16 v[94:97], v[198:201], v[230:233], v[94:97]
	v_mfma_f32_16x16x32_bf16 v[90:93], v[198:201], v[238:241], v[90:93]
	v_mfma_f32_16x16x32_bf16 v[86:89], v[206:209], v[230:233], v[86:89]
	v_mfma_f32_16x16x32_bf16 v[82:85], v[206:209], v[238:241], v[82:85]
	v_mfma_f32_16x16x32_bf16 v[78:81], v[214:217], v[230:233], v[78:81]
	v_mfma_f32_16x16x32_bf16 v[74:77], v[214:217], v[238:241], v[74:77]
	v_mfma_f32_16x16x32_bf16 v[70:73], v[222:225], v[230:233], v[70:73]
	v_mfma_f32_16x16x32_bf16 v[66:69], v[222:225], v[238:241], v[66:69]
	v_readfirstlane_b32 s9, v169
	v_lshl_add_u64 v[242:243], v[242:243], 0, s[60:61]
	s_mov_b32 m0, s9
	s_barrier
	ds_read_b128 v[194:197], v145 offset:49152
	ds_read_b128 v[198:201], v145 offset:50176
	ds_read_b128 v[202:205], v144 offset:49152
	ds_read_b128 v[206:209], v144 offset:50176
	ds_read_b128 v[210:213], v143 offset:49152
	ds_read_b128 v[214:217], v143 offset:50176
	ds_read_b128 v[218:221], v142 offset:49152
	ds_read_b128 v[222:225], v142 offset:50176
	global_load_lds_dwordx4 v[242:243], off
	s_add_u32 m0, m0, 0x2000
	v_lshl_add_u64 v[242:243], v[244:245], 0, s[60:61]
	global_load_lds_dwordx4 v[242:243], off
	s_barrier
; #define STA(P, br, kt) STAGE(P, A, aoff0, aoff1, lda, br, kt)
; #define STB(P, br, kt) STAGE(P, Bt, boff0, boff1, ldb, br, kt)
; #define LDA(dst, b, h) _Pragma("unroll") for (int m = 0; m < 4; ++m) _Pragma("unroll") for (int k = 0; k < 2; ++k) \
;     dst[m][k] = *reinterpret_cast<const bf16x8*>((char*)SA(b, h) + lds_byte(wr * 64 + m * 16 + fr, k * 32 + fq * 8))
; #define LDB(dst, b, h) _Pragma("unroll") for (int n = 0; n < 2; ++n) _Pragma("unroll") for (int k = 0; k < 2; ++k) \
;     dst[n][k] = *reinterpret_cast<const bf16x8*>((char*)SB(b, h) + lds_byte(wc * 32 + n * 16 + fr, k * 32 + fq * 8))
; #define MMA(ai, bj, At, Bq) do { __builtin_amdgcn_s_setprio(1); \
;     _Pragma("unroll") for (int m = 0; m < 4; ++m) _Pragma("unroll") for (int n = 0; n < 2; ++n) _Pragma("unroll") for (int k = 0; k < 2; ++k) \
;       acc[ai][bj][m][n] = __builtin_amdgcn_mfma_f32_16x16x32_bf16(At[m][k], Bq[n][k], acc[ai][bj][m][n], 0, 0, 0); \
;     __builtin_amdgcn_s_setprio(0); } while (0)
; #define WAIT_V(n) asm volatile("s_waitcnt vmcnt(" #n ")" ::: "memory")
; #define WAIT_L(n) asm volatile("s_waitcnt lgkmcnt(" #n ")" ::: "memory")
; #define BAR __builtin_amdgcn_s_barrier()
; #define SCHED __builtin_amdgcn_sched_barrier(0)
; __device__ __forceinline__ void gemm256(const u16* __restrict__ A, int lda, const u16* __restrict__ Bt, int ldb, int K,
;                                         f32x4 (&acc)[2][2][4][2], const int g_wid) {
;     ...
;     BAR; WAIT_L(0); MMA(1, 0, At, B0); BAR; SCHED;
;     STB(SB(1, 1), HALF, t + 3);
;     WAIT_V(6); BAR; MMA(1, 1, At, B1); BAR;
;   }
;   { LDB(B0, 0, 0); LDA(At, 0, 0); STA(SA(1, 1), HALF, nt - 1);
;     BAR; WAIT_L(0); MMA(0, 0, At, B0); BAR;
	s_waitcnt lgkmcnt(0)
	v_mfma_f32_16x16x32_bf16 v[62:65], v[194:197], v[178:181], v[62:65]
	v_mfma_f32_16x16x32_bf16 v[58:61], v[194:197], v[186:189], v[58:61]
	v_mfma_f32_16x16x32_bf16 v[54:57], v[202:205], v[178:181], v[54:57]
	v_mfma_f32_16x16x32_bf16 v[50:53], v[202:205], v[186:189], v[50:53]
	v_mfma_f32_16x16x32_bf16 v[46:49], v[210:213], v[178:181], v[46:49]
	v_mfma_f32_16x16x32_bf16 v[42:45], v[210:213], v[186:189], v[42:45]
	v_mfma_f32_16x16x32_bf16 v[38:41], v[218:221], v[178:181], v[38:41]
	v_mfma_f32_16x16x32_bf16 v[34:37], v[218:221], v[186:189], v[34:37]
	v_mfma_f32_16x16x32_bf16 v[62:65], v[198:201], v[182:185], v[62:65]
	v_mfma_f32_16x16x32_bf16 v[58:61], v[198:201], v[190:193], v[58:61]
	v_mfma_f32_16x16x32_bf16 v[54:57], v[206:209], v[182:185], v[54:57]
	v_mfma_f32_16x16x32_bf16 v[50:53], v[206:209], v[190:193], v[50:53]
	v_mfma_f32_16x16x32_bf16 v[46:49], v[214:217], v[182:185], v[46:49]
	v_mfma_f32_16x16x32_bf16 v[42:45], v[214:217], v[190:193], v[42:45]
	v_mfma_f32_16x16x32_bf16 v[38:41], v[222:225], v[182:185], v[38:41]
	v_mfma_f32_16x16x32_bf16 v[34:37], v[222:225], v[190:193], v[34:37]
	s_barrier
	v_readfirstlane_b32 s9, v171
	v_lshl_add_u64 v[178:179], v[246:247], 0, s[48:49]
	s_mov_b32 m0, s9
	global_load_lds_dwordx4 v[178:179], off
	s_add_u32 m0, m0, 0x2000
	v_lshl_add_u64 v[178:179], v[248:249], 0, s[48:49]
	global_load_lds_dwordx4 v[178:179], off
	s_waitcnt vmcnt(6)
	s_barrier
	v_mfma_f32_16x16x32_bf16 v[30:33], v[194:197], v[226:229], v[30:33]
	v_mfma_f32_16x16x32_bf16 v[26:29], v[194:197], v[234:237], v[26:29]
	v_mfma_f32_16x16x32_bf16 v[22:25], v[202:205], v[226:229], v[22:25]
	v_mfma_f32_16x16x32_bf16 v[18:21], v[202:205], v[234:237], v[18:21]
	v_mfma_f32_16x16x32_bf16 v[14:17], v[210:213], v[226:229], v[14:17]
	v_mfma_f32_16x16x32_bf16 v[10:13], v[210:213], v[234:237], v[10:13]
	v_mfma_f32_16x16x32_bf16 v[6:9], v[218:221], v[226:229], v[6:9]
	v_mfma_f32_16x16x32_bf16 v[2:5], v[218:221], v[234:237], v[2:5]
	v_mfma_f32_16x16x32_bf16 v[30:33], v[198:201], v[230:233], v[30:33]
	v_mfma_f32_16x16x32_bf16 v[26:29], v[198:201], v[238:241], v[26:29]
	v_mfma_f32_16x16x32_bf16 v[22:25], v[206:209], v[230:233], v[22:25]
	v_mfma_f32_16x16x32_bf16 v[18:21], v[206:209], v[238:241], v[18:21]
	v_mfma_f32_16x16x32_bf16 v[14:17], v[214:217], v[230:233], v[14:17]
	v_mfma_f32_16x16x32_bf16 v[10:13], v[214:217], v[238:241], v[10:13]
	v_mfma_f32_16x16x32_bf16 v[6:9], v[222:225], v[230:233], v[6:9]
	v_mfma_f32_16x16x32_bf16 v[2:5], v[222:225], v[238:241], v[2:5]
	s_add_i32 s3, s3, 2
	s_add_u32 s12, s12, 0x100
	s_addc_u32 s13, s13, 0
	s_cmp_lt_u32 s3, 12
	s_barrier
	s_cbranch_scc1 .LBB0_488
	s_add_u32 s10, s10, 0x40780
	s_addc_u32 s11, s11, 0
	v_readfirstlane_b32 s3, v175
	v_lshl_add_u64 v[132:133], v[132:133], 1, s[10:11]
	s_mov_b32 m0, s3
	v_readfirstlane_b32 s3, v176
	ds_read_b128 v[134:137], v174
	ds_read_b128 v[138:141], v174 offset:1024
	ds_read_b128 v[162:165], v174 offset:2048
	ds_read_b128 v[168:171], v174 offset:3072
	ds_read_b128 v[178:181], v145
	ds_read_b128 v[182:185], v145 offset:1024
	ds_read_b128 v[186:189], v144
	ds_read_b128 v[190:193], v144 offset:1024
	ds_read_b128 v[194:197], v143
	ds_read_b128 v[198:201], v143 offset:1024
	ds_read_b128 v[202:205], v142
	ds_read_b128 v[206:209], v142 offset:1024
	global_load_lds_dwordx4 v[132:133], off
	v_lshl_add_u64 v[130:131], v[130:131], 1, s[10:11]
	s_mov_b32 m0, s3
	s_nop 0
	global_load_lds_dwordx4 v[130:131], off
	s_barrier
	s_waitcnt lgkmcnt(0)
	v_mfma_f32_16x16x32_bf16 v[126:129], v[178:181], v[134:137], v[126:129]
	v_mfma_f32_16x16x32_bf16 v[118:121], v[186:189], v[134:137], v[118:121]
	v_mfma_f32_16x16x32_bf16 v[114:117], v[186:189], v[162:165], v[114:117]
	v_mfma_f32_16x16x32_bf16 v[110:113], v[194:197], v[134:137], v[110:113]
	v_mfma_f32_16x16x32_bf16 v[106:109], v[194:197], v[162:165], v[106:109]
	v_mfma_f32_16x16x32_bf16 v[102:105], v[202:205], v[134:137], v[102:105]
	v_mfma_f32_16x16x32_bf16 v[98:101], v[202:205], v[162:165], v[98:101]
	v_mfma_f32_16x16x32_bf16 v[126:129], v[182:185], v[138:141], v[126:129]
	v_mfma_f32_16x16x32_bf16 v[122:125], v[178:181], v[162:165], v[122:125]
	v_mfma_f32_16x16x32_bf16 v[118:121], v[190:193], v[138:141], v[118:121]
	v_mfma_f32_16x16x32_bf16 v[114:117], v[190:193], v[168:171], v[114:117]
	v_mfma_f32_16x16x32_bf16 v[110:113], v[198:201], v[138:141], v[110:113]
	v_mfma_f32_16x16x32_bf16 v[106:109], v[198:201], v[168:171], v[106:109]
	v_mfma_f32_16x16x32_bf16 v[102:105], v[206:209], v[138:141], v[102:105]
	v_mfma_f32_16x16x32_bf16 v[98:101], v[206:209], v[168:171], v[98:101]
	v_mfma_f32_16x16x32_bf16 v[130:133], v[182:185], v[168:171], v[122:125]
	s_barrier
	s_nop 0
	ds_read_b128 v[122:125], v173
	ds_read_b128 v[174:177], v173 offset:1024
	ds_read_b128 v[210:213], v173 offset:2048
	ds_read_b128 v[214:217], v173 offset:3072
	s_barrier
	s_waitcnt lgkmcnt(0)
	v_mfma_f32_16x16x32_bf16 v[78:81], v[194:197], v[122:125], v[78:81]
	v_mfma_f32_16x16x32_bf16 v[74:77], v[194:197], v[210:213], v[74:77]
	v_mfma_f32_16x16x32_bf16 v[70:73], v[202:205], v[122:125], v[70:73]
	v_mfma_f32_16x16x32_bf16 v[66:69], v[202:205], v[210:213], v[66:69]
	v_mfma_f32_16x16x32_bf16 v[94:97], v[178:181], v[122:125], v[94:97]
	v_mfma_f32_16x16x32_bf16 v[90:93], v[178:181], v[210:213], v[90:93]
	v_mfma_f32_16x16x32_bf16 v[86:89], v[186:189], v[122:125], v[86:89]
	v_mfma_f32_16x16x32_bf16 v[82:85], v[186:189], v[210:213], v[82:85]
	v_mfma_f32_16x16x32_bf16 v[78:81], v[198:201], v[174:177], v[78:81]
	v_mfma_f32_16x16x32_bf16 v[74:77], v[198:201], v[214:217], v[74:77]
	v_mfma_f32_16x16x32_bf16 v[70:73], v[206:209], v[174:177], v[70:73]
	v_mfma_f32_16x16x32_bf16 v[66:69], v[206:209], v[214:217], v[66:69]
	v_mfma_f32_16x16x32_bf16 v[218:221], v[182:185], v[174:177], v[94:97]
	v_mfma_f32_16x16x32_bf16 v[178:181], v[182:185], v[214:217], v[90:93]
	v_mfma_f32_16x16x32_bf16 v[182:185], v[190:193], v[174:177], v[86:89]
	v_mfma_f32_16x16x32_bf16 v[186:189], v[190:193], v[214:217], v[82:85]
	s_barrier
; #define LDA(dst, b, h) _Pragma("unroll") for (int m = 0; m < 4; ++m) _Pragma("unroll") for (int k = 0; k < 2; ++k) \
;     dst[m][k] = *reinterpret_cast<const bf16x8*>((char*)SA(b, h) + lds_byte(wr * 64 + m * 16 + fr, k * 32 + fq * 8))
; #define LDB(dst, b, h) _Pragma("unroll") for (int n = 0; n < 2; ++n) _Pragma("unroll") for (int k = 0; k < 2; ++k) \
;     dst[n][k] = *reinterpret_cast<const bf16x8*>((char*)SB(b, h) + lds_byte(wc * 32 + n * 16 + fr, k * 32 + fq * 8))
; #define MMA(ai, bj, At, Bq) do { __builtin_amdgcn_s_setprio(1); \
;     _Pragma("unroll") for (int m = 0; m < 4; ++m) _Pragma("unroll") for (int n = 0; n < 2; ++n) _Pragma("unroll") for (int k = 0; k < 2; ++k) \
;       acc[ai][bj][m][n] = __builtin_amdgcn_mfma_f32_16x16x32_bf16(At[m][k], Bq[n][k], acc[ai][bj][m][n], 0, 0, 0); \
;     __builtin_amdgcn_s_setprio(0); } while (0)
; #define WAIT_V(n) asm volatile("s_waitcnt vmcnt(" #n ")" ::: "memory")
; #define WAIT_L(n) asm volatile("s_waitcnt lgkmcnt(" #n ")" ::: "memory")
; #define BAR __builtin_amdgcn_s_barrier()
; __device__ __forceinline__ void gemm256(const u16* __restrict__ A, int lda, const u16* __restrict__ Bt, int ldb, int K,
;                                         f32x4 (&acc)[2][2][4][2], const int g_wid) {
;     ...
;     LDA(At, 0, 1); WAIT_V(4); BAR; WAIT_L(0); MMA(1, 0, At, B0); MMA(1, 1, At, B1); BAR; }
;   { LDB(B0, 1, 0); LDA(At, 1, 0); WAIT_V(2); BAR; WAIT_L(0); MMA(0, 0, At, B0); BAR;
	s_nop 0
	ds_read_b128 v[82:85], v145 offset:16384
	ds_read_b128 v[86:89], v145 offset:17408
	ds_read_b128 v[90:93], v144 offset:16384
	ds_read_b128 v[94:97], v144 offset:17408
	ds_read_b128 v[190:193], v143 offset:16384
	ds_read_b128 v[194:197], v143 offset:17408
	ds_read_b128 v[198:201], v142 offset:16384
	ds_read_b128 v[202:205], v142 offset:17408
	s_waitcnt vmcnt(4)
	s_barrier
	s_waitcnt lgkmcnt(0)
	v_mfma_f32_16x16x32_bf16 v[46:49], v[190:193], v[134:137], v[46:49]
	v_mfma_f32_16x16x32_bf16 v[42:45], v[190:193], v[162:165], v[42:45]
	v_mfma_f32_16x16x32_bf16 v[38:41], v[198:201], v[134:137], v[38:41]
	v_mfma_f32_16x16x32_bf16 v[34:37], v[198:201], v[162:165], v[34:37]
	v_mfma_f32_16x16x32_bf16 v[62:65], v[82:85], v[134:137], v[62:65]
	v_mfma_f32_16x16x32_bf16 v[58:61], v[82:85], v[162:165], v[58:61]
	v_mfma_f32_16x16x32_bf16 v[54:57], v[90:93], v[134:137], v[54:57]
	v_mfma_f32_16x16x32_bf16 v[50:53], v[90:93], v[162:165], v[50:53]
	v_mfma_f32_16x16x32_bf16 v[46:49], v[194:197], v[138:141], v[46:49]
	v_mfma_f32_16x16x32_bf16 v[42:45], v[194:197], v[168:171], v[42:45]
	v_mfma_f32_16x16x32_bf16 v[38:41], v[202:205], v[138:141], v[38:41]
	v_mfma_f32_16x16x32_bf16 v[34:37], v[202:205], v[168:171], v[34:37]
	v_mfma_f32_16x16x32_bf16 v[206:209], v[86:89], v[138:141], v[62:65]
	v_mfma_f32_16x16x32_bf16 v[222:225], v[86:89], v[168:171], v[58:61]
	v_mfma_f32_16x16x32_bf16 v[226:229], v[94:97], v[138:141], v[54:57]
	v_mfma_f32_16x16x32_bf16 v[230:233], v[94:97], v[168:171], v[50:53]
	v_mfma_f32_16x16x32_bf16 v[2:5], v[198:201], v[210:213], v[2:5]
	v_mfma_f32_16x16x32_bf16 v[30:33], v[82:85], v[122:125], v[30:33]
	v_mfma_f32_16x16x32_bf16 v[26:29], v[82:85], v[210:213], v[26:29]
	v_mfma_f32_16x16x32_bf16 v[22:25], v[90:93], v[122:125], v[22:25]
	v_mfma_f32_16x16x32_bf16 v[18:21], v[90:93], v[210:213], v[18:21]
	v_mfma_f32_16x16x32_bf16 v[14:17], v[190:193], v[122:125], v[14:17]
	v_mfma_f32_16x16x32_bf16 v[10:13], v[190:193], v[210:213], v[10:13]
	v_mfma_f32_16x16x32_bf16 v[6:9], v[198:201], v[122:125], v[6:9]
	v_mfma_f32_16x16x32_bf16 v[2:5], v[202:205], v[214:217], v[2:5]
	v_mfma_f32_16x16x32_bf16 v[134:137], v[86:89], v[174:177], v[30:33]
	v_mfma_f32_16x16x32_bf16 v[138:141], v[86:89], v[214:217], v[26:29]
	v_mfma_f32_16x16x32_bf16 v[162:165], v[94:97], v[174:177], v[22:25]
	v_mfma_f32_16x16x32_bf16 v[168:171], v[94:97], v[214:217], v[18:21]
	v_mfma_f32_16x16x32_bf16 v[234:237], v[194:197], v[174:177], v[14:17]
	v_mfma_f32_16x16x32_bf16 v[190:193], v[194:197], v[214:217], v[10:13]
	v_mfma_f32_16x16x32_bf16 v[172:175], v[202:205], v[174:177], v[6:9]
	s_barrier
	s_nop 0
	ds_read_b128 v[6:9], v166
	ds_read_b128 v[10:13], v166 offset:1024
	ds_read_b128 v[14:17], v166 offset:2048
	ds_read_b128 v[194:197], v166 offset:3072
	ds_read_b128 v[18:21], v145 offset:32768
	ds_read_b128 v[22:25], v145 offset:33792
	ds_read_b128 v[30:33], v144 offset:32768
	ds_read_b128 v[50:53], v144 offset:33792
	ds_read_b128 v[198:201], v143 offset:32768
	ds_read_b128 v[202:205], v143 offset:33792
	ds_read_b128 v[210:213], v142 offset:32768
	ds_read_b128 v[214:217], v142 offset:33792
	s_waitcnt vmcnt(2)
	s_barrier
	s_waitcnt lgkmcnt(0)
	v_mfma_f32_16x16x32_bf16 v[26:29], v[18:21], v[6:9], v[126:129]
	v_mfma_f32_16x16x32_bf16 v[122:125], v[22:25], v[10:13], v[26:29]
	v_mfma_f32_16x16x32_bf16 v[26:29], v[18:21], v[14:17], v[130:133]
	v_mfma_f32_16x16x32_bf16 v[90:93], v[22:25], v[194:197], v[26:29]
	v_mfma_f32_16x16x32_bf16 v[26:29], v[30:33], v[6:9], v[118:121]
	v_mfma_f32_16x16x32_bf16 v[126:129], v[50:53], v[10:13], v[26:29]
	v_mfma_f32_16x16x32_bf16 v[26:29], v[30:33], v[14:17], v[114:117]
	v_mfma_f32_16x16x32_bf16 v[94:97], v[50:53], v[194:197], v[26:29]
	v_mfma_f32_16x16x32_bf16 v[26:29], v[198:201], v[6:9], v[110:113]
	v_mfma_f32_16x16x32_bf16 v[118:121], v[202:205], v[10:13], v[26:29]
	v_mfma_f32_16x16x32_bf16 v[26:29], v[198:201], v[14:17], v[106:109]
	v_mfma_f32_16x16x32_bf16 v[86:89], v[202:205], v[194:197], v[26:29]
	v_mfma_f32_16x16x32_bf16 v[26:29], v[210:213], v[6:9], v[102:105]
	v_mfma_f32_16x16x32_bf16 v[114:117], v[214:217], v[10:13], v[26:29]
	v_mfma_f32_16x16x32_bf16 v[26:29], v[210:213], v[14:17], v[98:101]
	v_mfma_f32_16x16x32_bf16 v[82:85], v[214:217], v[194:197], v[26:29]
	s_barrier
; #define LDA(dst, b, h) _Pragma("unroll") for (int m = 0; m < 4; ++m) _Pragma("unroll") for (int k = 0; k < 2; ++k) \
;     dst[m][k] = *reinterpret_cast<const bf16x8*>((char*)SA(b, h) + lds_byte(wr * 64 + m * 16 + fr, k * 32 + fq * 8))
; #define LDB(dst, b, h) _Pragma("unroll") for (int n = 0; n < 2; ++n) _Pragma("unroll") for (int k = 0; k < 2; ++k) \
;     dst[n][k] = *reinterpret_cast<const bf16x8*>((char*)SB(b, h) + lds_byte(wc * 32 + n * 16 + fr, k * 32 + fq * 8))
; #define MMA(ai, bj, At, Bq) do { __builtin_amdgcn_s_setprio(1); \
;     _Pragma("unroll") for (int m = 0; m < 4; ++m) _Pragma("unroll") for (int n = 0; n < 2; ++n) _Pragma("unroll") for (int k = 0; k < 2; ++k) \
;       acc[ai][bj][m][n] = __builtin_amdgcn_mfma_f32_16x16x32_bf16(At[m][k], Bq[n][k], acc[ai][bj][m][n], 0, 0, 0); \
;     __builtin_amdgcn_s_setprio(0); } while (0)
; #define WAIT_V(n) asm volatile("s_waitcnt vmcnt(" #n ")" ::: "memory")
; #define WAIT_L(n) asm volatile("s_waitcnt lgkmcnt(" #n ")" ::: "memory")
; #define BAR __builtin_amdgcn_s_barrier()
; __device__ __forceinline__ void gemm256(const u16* __restrict__ A, int lda, const u16* __restrict__ Bt, int ldb, int K,
;                                         f32x4 (&acc)[2][2][4][2], const int g_wid) {
;     ...
;     LDB(B1, 1, 1); WAIT_V(0); BAR; WAIT_L(0); MMA(0, 1, At, B1); BAR;
;     LDA(At, 1, 1); BAR; WAIT_L(0); MMA(1, 0, At, B0); MMA(1, 1, At, B1); BAR; }
;   if (wr == 0) BAR;
	ds_read_b128 v[130:133], v160
	ds_read_b128 v[238:241], v160 offset:1024
	ds_read_b128 v[242:245], v160 offset:2048
	ds_read_b128 v[246:249], v160 offset:3072
	s_waitcnt vmcnt(0)
	s_barrier
	s_waitcnt lgkmcnt(0)
	v_mfma_f32_16x16x32_bf16 v[26:29], v[18:21], v[130:133], v[218:221]
	v_mfma_f32_16x16x32_bf16 v[18:21], v[18:21], v[242:245], v[178:181]
	v_mfma_f32_16x16x32_bf16 v[58:61], v[22:25], v[238:241], v[26:29]
	v_mfma_f32_16x16x32_bf16 v[26:29], v[22:25], v[246:249], v[18:21]
	v_mfma_f32_16x16x32_bf16 v[18:21], v[30:33], v[130:133], v[182:185]
	v_mfma_f32_16x16x32_bf16 v[62:65], v[50:53], v[238:241], v[18:21]
	v_mfma_f32_16x16x32_bf16 v[18:21], v[30:33], v[242:245], v[186:189]
	v_mfma_f32_16x16x32_bf16 v[30:33], v[50:53], v[246:249], v[18:21]
	v_mfma_f32_16x16x32_bf16 v[18:21], v[198:201], v[130:133], v[78:81]
	v_mfma_f32_16x16x32_bf16 v[54:57], v[202:205], v[238:241], v[18:21]
	v_mfma_f32_16x16x32_bf16 v[18:21], v[198:201], v[242:245], v[74:77]
	v_mfma_f32_16x16x32_bf16 v[22:25], v[202:205], v[246:249], v[18:21]
	v_mfma_f32_16x16x32_bf16 v[18:21], v[210:213], v[130:133], v[70:73]
	v_mfma_f32_16x16x32_bf16 v[50:53], v[214:217], v[238:241], v[18:21]
	v_mfma_f32_16x16x32_bf16 v[18:21], v[210:213], v[242:245], v[66:69]
	v_mfma_f32_16x16x32_bf16 v[18:21], v[214:217], v[246:249], v[18:21]
	s_barrier
	ds_read_b128 v[176:179], v145 offset:49152
	ds_read_b128 v[180:183], v145 offset:50176
	ds_read_b128 v[184:187], v144 offset:49152
	ds_read_b128 v[144:147], v144 offset:50176
	ds_read_b128 v[198:201], v143 offset:49152
	ds_read_b128 v[202:205], v143 offset:50176
	ds_read_b128 v[210:213], v142 offset:49152
	ds_read_b128 v[214:217], v142 offset:50176
	s_barrier
	s_waitcnt lgkmcnt(0)
	v_mfma_f32_16x16x32_bf16 v[66:69], v[176:179], v[6:9], v[206:209]
	v_mfma_f32_16x16x32_bf16 v[110:113], v[180:183], v[10:13], v[66:69]
	v_mfma_f32_16x16x32_bf16 v[66:69], v[176:179], v[14:17], v[222:225]
	v_mfma_f32_16x16x32_bf16 v[78:81], v[180:183], v[194:197], v[66:69]
	v_mfma_f32_16x16x32_bf16 v[66:69], v[184:187], v[6:9], v[226:229]
	v_mfma_f32_16x16x32_bf16 v[46:49], v[198:201], v[6:9], v[46:49]
	v_mfma_f32_16x16x32_bf16 v[6:9], v[210:213], v[6:9], v[38:41]
	v_mfma_f32_16x16x32_bf16 v[106:109], v[144:147], v[10:13], v[66:69]
	v_mfma_f32_16x16x32_bf16 v[66:69], v[184:187], v[14:17], v[230:233]
	v_mfma_f32_16x16x32_bf16 v[42:45], v[198:201], v[14:17], v[42:45]
	v_mfma_f32_16x16x32_bf16 v[98:101], v[214:217], v[10:13], v[6:9]
	v_mfma_f32_16x16x32_bf16 v[6:9], v[210:213], v[14:17], v[34:37]
	v_mfma_f32_16x16x32_bf16 v[74:77], v[144:147], v[194:197], v[66:69]
	v_mfma_f32_16x16x32_bf16 v[102:105], v[202:205], v[10:13], v[46:49]
	v_mfma_f32_16x16x32_bf16 v[70:73], v[202:205], v[194:197], v[42:45]
	v_mfma_f32_16x16x32_bf16 v[66:69], v[214:217], v[194:197], v[6:9]
	v_mfma_f32_16x16x32_bf16 v[6:9], v[176:179], v[130:133], v[134:137]
	v_mfma_f32_16x16x32_bf16 v[46:49], v[180:183], v[238:241], v[6:9]
	v_mfma_f32_16x16x32_bf16 v[6:9], v[176:179], v[242:245], v[138:141]
	v_mfma_f32_16x16x32_bf16 v[14:17], v[180:183], v[246:249], v[6:9]
	v_mfma_f32_16x16x32_bf16 v[6:9], v[184:187], v[130:133], v[162:165]
	v_mfma_f32_16x16x32_bf16 v[42:45], v[144:147], v[238:241], v[6:9]
	v_mfma_f32_16x16x32_bf16 v[6:9], v[184:187], v[242:245], v[168:171]
	v_mfma_f32_16x16x32_bf16 v[10:13], v[144:147], v[246:249], v[6:9]
	v_mfma_f32_16x16x32_bf16 v[6:9], v[198:201], v[130:133], v[234:237]
	v_mfma_f32_16x16x32_bf16 v[38:41], v[202:205], v[238:241], v[6:9]
	v_mfma_f32_16x16x32_bf16 v[6:9], v[198:201], v[242:245], v[190:193]
	v_mfma_f32_16x16x32_bf16 v[34:37], v[210:213], v[130:133], v[172:175]
	v_mfma_f32_16x16x32_bf16 v[2:5], v[210:213], v[242:245], v[2:5]
	v_mfma_f32_16x16x32_bf16 v[6:9], v[202:205], v[246:249], v[6:9]
	v_mfma_f32_16x16x32_bf16 v[34:37], v[214:217], v[238:241], v[34:37]
	v_mfma_f32_16x16x32_bf16 v[2:5], v[214:217], v[246:249], v[2:5]
	s_setprio 0
	s_movk_i32 s3, 0x100
	v_cmp_gt_u32_e32 vcc, s3, v0
	s_barrier
	s_and_saveexec_b64 s[10:11], vcc
	s_cbranch_execz .LBB0_491
	s_barrier
